# baseline (speedup 1.0000x reference)
; __device__ __forceinline__ int crow(int r, int hf) { return (r & 3) + 8 * (r >> 2) + 4 * hf; }
; __device__ __forceinline__ int tosort(float f) { int b = __float_as_int(f); return b ^ ((b >> 31) & 0x7fffffff); }
; template <int PP>
; __device__ __forceinline__ void select_half(const Params& p, const u16* Subs, int t, int hh, int lc, int hf, int* lists) {
;   bf16x8 qf[8];
;   const u16* qrow = p.qp + (size_t)t * 2048 + hh * 256 + PP * 128 + hf * 8;
; #pragma unroll
;   for (int ks = 0; ks < 8; ++ks) qf[ks] = *(const bf16x8*)(qrow + ks * 16);
;   int keys[64];
; #pragma unroll
;   for (int nb = 0; nb < 4; ++nb) {
;     f32x16 acc;
; #pragma unroll
;     for (int r = 0; r < 16; ++r) acc[r] = 0.f;
; #pragma unroll
;     for (int ks = 0; ks < 8; ++ks) {
;       bf16x8 a = *(const bf16x8*)(Subs + (PP * 128 + nb * 32 + lc) * 136 + ks * 16 + hf * 8);
;       acc = mfma32(a, qf[ks], acc);
;     }
; #pragma unroll
;     for (int r = 0; r < 16; ++r) keys[nb * 16 + r] = (tosort(acc[r]) & ~127) | (nb * 32 + crow(r, hf));
; __device__ __forceinline__ void phase_select(const Params& p, int layer, char* smraw) {
;     ...
;   for (int item = blockIdx.x; item < MT * 8; item += gridDim.x) {
;     const int mt = item >> 3, hh = item & 7;
;     const int tl = mt * 128 + w * 32 + lc;
;     const int t = tl < T ? tl : T - 1;
;     int lists[32];
;     select_half<0>(p, Subs, t, hh, lc, hf, lists);
;     select_half<1>(p, Subs, t, hh, lc, hf, lists);
.LBB0_631:
	s_and_b32 s0, s20, 0xffffff80
	v_add_u32_e32 v0, s0, v98
	v_cmp_gt_i32_e32 vcc, s22, v0
	s_and_b32 s38, s37, 7
	s_lshl_b32 s0, s38, 9
	v_cndmask_b32_e32 v94, v167, v0, vcc
	v_ashrrev_i32_e32 v95, 31, v94
	v_lshlrev_b64 v[0:1], 12, v[94:95]
	v_lshl_add_u64 v[0:1], s[68:69], 0, v[0:1]
	v_lshl_add_u64 v[0:1], v[0:1], 0, s[0:1]
	v_lshl_add_u64 v[96:97], v[0:1], 0, v[92:93]
	global_load_dwordx4 v[60:63], v[96:97], off
	global_load_dwordx4 v[56:59], v[96:97], off offset:32
	global_load_dwordx4 v[84:87], v[96:97], off offset:64
	global_load_dwordx4 v[76:79], v[96:97], off offset:96
	global_load_dwordx4 v[80:83], v[96:97], off offset:128
	ds_read_b128 v[0:3], v168
	ds_read_b128 v[64:67], v168 offset:32
	s_waitcnt vmcnt(4) lgkmcnt(1)
	v_mfma_f32_32x32x16_bf16 v[32:47], v[0:3], v[60:63], 0
	ds_read_b128 v[0:3], v168 offset:8704
	ds_read_b128 v[68:71], v168 offset:8736
	s_waitcnt lgkmcnt(1)
	v_mfma_f32_32x32x16_bf16 v[16:31], v[0:3], v[60:63], 0
	ds_read_b128 v[0:3], v168 offset:17408
	ds_read_b128 v[72:75], v168 offset:17440
	s_waitcnt vmcnt(3)
	v_mfma_f32_32x32x16_bf16 v[32:47], v[64:67], v[56:59], v[32:47]
	s_waitcnt lgkmcnt(2)
	v_mfma_f32_32x32x16_bf16 v[16:31], v[68:71], v[56:59], v[16:31]
	ds_read_b128 v[64:67], v168 offset:64
	ds_read_b128 v[68:71], v168 offset:96
	s_waitcnt lgkmcnt(3)
	v_mfma_f32_32x32x16_bf16 v[0:15], v[0:3], v[60:63], 0
	s_waitcnt lgkmcnt(2)
	v_mfma_f32_32x32x16_bf16 v[0:15], v[72:75], v[56:59], v[0:15]
	s_waitcnt vmcnt(2) lgkmcnt(1)
	v_mfma_f32_32x32x16_bf16 v[32:47], v[64:67], v[84:87], v[32:47]
	ds_read_b128 v[64:67], v168 offset:8768
	ds_read_b128 v[170:173], v168 offset:8800
	s_waitcnt lgkmcnt(1)
	v_mfma_f32_32x32x16_bf16 v[16:31], v[64:67], v[84:87], v[16:31]
	ds_read_b128 v[64:67], v168 offset:17472
	ds_read_b128 v[174:177], v168 offset:17504
	global_load_dwordx4 v[72:75], v[96:97], off offset:160
	s_waitcnt vmcnt(2)
	v_mfma_f32_32x32x16_bf16 v[32:47], v[68:71], v[76:79], v[32:47]
	s_waitcnt lgkmcnt(1)
	v_mfma_f32_32x32x16_bf16 v[0:15], v[64:67], v[84:87], v[0:15]
	v_mfma_f32_32x32x16_bf16 v[16:31], v[170:173], v[76:79], v[16:31]
	ds_read_b128 v[64:67], v168 offset:128
	ds_read_b128 v[170:173], v168 offset:160
	s_waitcnt lgkmcnt(2)
	v_mfma_f32_32x32x16_bf16 v[0:15], v[174:177], v[76:79], v[0:15]
	s_waitcnt vmcnt(1) lgkmcnt(1)
	v_mfma_f32_32x32x16_bf16 v[32:47], v[64:67], v[80:83], v[32:47]
	ds_read_b128 v[64:67], v168 offset:8832
	ds_read_b128 v[178:181], v168 offset:8864
	global_load_dwordx4 v[68:71], v[96:97], off offset:192
	s_waitcnt lgkmcnt(1)
	v_mfma_f32_32x32x16_bf16 v[16:31], v[64:67], v[80:83], v[16:31]
	global_load_dwordx4 v[64:67], v[96:97], off offset:224
	s_waitcnt vmcnt(2)
	v_mfma_f32_32x32x16_bf16 v[32:47], v[170:173], v[72:75], v[32:47]
	s_waitcnt lgkmcnt(0)
	v_mfma_f32_32x32x16_bf16 v[16:31], v[178:181], v[72:75], v[16:31]
	ds_read_b128 v[170:173], v168 offset:192
	ds_read_b128 v[178:181], v168 offset:224
	s_waitcnt vmcnt(1) lgkmcnt(1)
	v_mfma_f32_32x32x16_bf16 v[32:47], v[170:173], v[68:71], v[32:47]
	ds_read_b128 v[170:173], v168 offset:8896
	ds_read_b128 v[182:185], v168 offset:8928
	s_waitcnt lgkmcnt(1)
	v_mfma_f32_32x32x16_bf16 v[16:31], v[170:173], v[68:71], v[16:31]
	s_waitcnt vmcnt(0)
	v_mfma_f32_32x32x16_bf16 v[32:47], v[178:181], v[64:67], v[32:47]
	s_waitcnt lgkmcnt(0)
	v_mfma_f32_32x32x16_bf16 v[16:31], v[182:185], v[64:67], v[16:31]
	s_nop 9
	v_ashrrev_i32_e32 v173, 31, v36
	v_ashrrev_i32_e32 v178, 31, v37
	v_and_b32_e32 v36, 0xffffff80, v36
	v_and_b32_e32 v37, 0xffffff80, v37
	v_ashrrev_i32_e32 v185, 31, v44
	v_and_b32_e32 v173, 0x7fffff80, v173
	v_and_b32_e32 v178, 0x7fffff80, v178
	v_ashrrev_i32_e32 v190, 31, v16
	v_ashrrev_i32_e32 v192, 31, v17
	v_and_b32_e32 v16, 0xffffff80, v16
	v_and_b32_e32 v17, 0xffffff80, v17
	v_ashrrev_i32_e32 v199, 31, v24
	v_and_b32_e32 v190, 0x7fffff80, v190
	v_and_b32_e32 v192, 0x7fffff80, v192
	v_ashrrev_i32_e32 v179, 31, v38
	v_ashrrev_i32_e32 v180, 31, v39
	v_ashrrev_i32_e32 v181, 31, v40
	v_and_b32_e32 v44, 0xffffff80, v44
	v_ashrrev_i32_e32 v193, 31, v18
	v_ashrrev_i32_e32 v194, 31, v19
	v_ashrrev_i32_e32 v195, 31, v20
	v_and_b32_e32 v185, 0x7fffff80, v185
	v_bitop3_b32 v36, v173, v105, v36 bitop3:0xde
	v_bitop3_b32 v37, v178, v106, v37 bitop3:0xde
	v_bitop3_b32 v173, v190, v117, v16 bitop3:0xde
	v_bitop3_b32 v178, v192, v118, v17 bitop3:0xde
	v_and_b32_e32 v16, 0x7fffff80, v199
	v_and_b32_e32 v17, 0xffffff80, v24
	v_and_b32_e32 v38, 0xffffff80, v38
	v_and_b32_e32 v39, 0xffffff80, v39
	v_and_b32_e32 v40, 0xffffff80, v40
	v_and_b32_e32 v18, 0xffffff80, v18
	v_and_b32_e32 v19, 0xffffff80, v19
	v_and_b32_e32 v20, 0xffffff80, v20
	v_and_b32_e32 v179, 0x7fffff80, v179
	v_and_b32_e32 v180, 0x7fffff80, v180
	v_and_b32_e32 v181, 0x7fffff80, v181
	v_and_b32_e32 v193, 0x7fffff80, v193
	v_and_b32_e32 v194, 0x7fffff80, v194
	v_and_b32_e32 v195, 0x7fffff80, v195
	v_bitop3_b32 v44, v185, v113, v44 bitop3:0xde
	v_bitop3_b32 v185, v16, v125, v17 bitop3:0xde
	v_ashrrev_i32_e32 v16, 31, v25
	v_bitop3_b32 v38, v179, v107, v38 bitop3:0xde
	v_bitop3_b32 v39, v180, v108, v39 bitop3:0xde
	v_bitop3_b32 v40, v181, v109, v40 bitop3:0xde
	v_bitop3_b32 v179, v193, v119, v18 bitop3:0xde
	v_bitop3_b32 v180, v194, v120, v19 bitop3:0xde
	v_bitop3_b32 v181, v195, v121, v20 bitop3:0xde
	v_and_b32_e32 v20, 0x7fffff80, v16
	ds_read_b128 v[16:19], v168 offset:17536
	v_ashrrev_i32_e32 v182, 31, v41
	v_ashrrev_i32_e32 v196, 31, v21
	v_and_b32_e32 v41, 0xffffff80, v41
	v_and_b32_e32 v21, 0xffffff80, v21
	v_and_b32_e32 v182, 0x7fffff80, v182
	v_and_b32_e32 v196, 0x7fffff80, v196
	v_bitop3_b32 v41, v182, v110, v41 bitop3:0xde
	v_bitop3_b32 v182, v196, v122, v21 bitop3:0xde
	v_and_b32_e32 v21, 0xffffff80, v25
	v_ashrrev_i32_e32 v183, 31, v42
	v_ashrrev_i32_e32 v184, 31, v43
	v_ashrrev_i32_e32 v197, 31, v22
	v_ashrrev_i32_e32 v198, 31, v23
	v_bitop3_b32 v174, v20, v126, v21 bitop3:0xde
	v_ashrrev_i32_e32 v20, 31, v26
	v_and_b32_e32 v42, 0xffffff80, v42
	v_and_b32_e32 v43, 0xffffff80, v43
	v_and_b32_e32 v22, 0xffffff80, v22
	v_and_b32_e32 v23, 0xffffff80, v23
	v_and_b32_e32 v183, 0x7fffff80, v183
	v_and_b32_e32 v184, 0x7fffff80, v184
	v_and_b32_e32 v197, 0x7fffff80, v197
	v_and_b32_e32 v198, 0x7fffff80, v198
	v_and_b32_e32 v20, 0x7fffff80, v20
	v_and_b32_e32 v21, 0xffffff80, v26
	v_bitop3_b32 v42, v183, v111, v42 bitop3:0xde
	v_bitop3_b32 v43, v184, v112, v43 bitop3:0xde
	v_bitop3_b32 v183, v197, v123, v22 bitop3:0xde
	v_bitop3_b32 v184, v198, v124, v23 bitop3:0xde
	v_bitop3_b32 v175, v20, v127, v21 bitop3:0xde
	ds_read_b128 v[20:23], v168 offset:17568
	s_waitcnt lgkmcnt(1)
; __device__ __forceinline__ int crow(int r, int hf) { return (r & 3) + 8 * (r >> 2) + 4 * hf; }
; __device__ __forceinline__ int tosort(float f) { int b = __float_as_int(f); return b ^ ((b >> 31) & 0x7fffffff); }
; template <int PP>
; __device__ __forceinline__ void select_half(const Params& p, const u16* Subs, int t, int hh, int lc, int hf, int* lists) {
;     ...
;     for (int ks = 0; ks < 8; ++ks) {
;       bf16x8 a = *(const bf16x8*)(Subs + (PP * 128 + nb * 32 + lc) * 136 + ks * 16 + hf * 8);
;       acc = mfma32(a, qf[ks], acc);
;     }
; #pragma unroll
;     for (int r = 0; r < 16; ++r) keys[nb * 16 + r] = (tosort(acc[r]) & ~127) | (nb * 32 + crow(r, hf));
	v_mfma_f32_32x32x16_bf16 v[0:15], v[16:19], v[80:83], v[0:15]
	v_ashrrev_i32_e32 v24, 31, v27
	v_and_b32_e32 v16, 0x7fffff80, v24
	v_and_b32_e32 v17, 0xffffff80, v27
	v_bitop3_b32 v176, v16, v128, v17 bitop3:0xde
	v_ashrrev_i32_e32 v16, 31, v28
	v_and_b32_e32 v24, 0x7fffff80, v16
	ds_read_b128 v[16:19], v168 offset:17600
	s_waitcnt lgkmcnt(1)
	v_mfma_f32_32x32x16_bf16 v[0:15], v[20:23], v[72:75], v[0:15]
	v_ashrrev_i32_e32 v186, 31, v45
	v_ashrrev_i32_e32 v20, 31, v29
	v_and_b32_e32 v45, 0xffffff80, v45
	v_and_b32_e32 v186, 0x7fffff80, v186
	v_and_b32_e32 v20, 0x7fffff80, v20
	v_and_b32_e32 v21, 0xffffff80, v29
	v_bitop3_b32 v45, v186, v114, v45 bitop3:0xde
	v_bitop3_b32 v186, v20, v130, v21 bitop3:0xde
	ds_read_b128 v[20:23], v168 offset:17632
	s_waitcnt lgkmcnt(1)
	v_mfma_f32_32x32x16_bf16 v[0:15], v[16:19], v[68:71], v[0:15]
	v_and_b32_e32 v25, 0xffffff80, v28
	v_ashrrev_i32_e32 v187, 31, v46
	v_bitop3_b32 v177, v24, v129, v25 bitop3:0xde
	v_ashrrev_i32_e32 v24, 31, v30
	v_and_b32_e32 v46, 0xffffff80, v46
	v_and_b32_e32 v187, 0x7fffff80, v187
	v_and_b32_e32 v16, 0x7fffff80, v24
	s_waitcnt lgkmcnt(0)
	v_mfma_f32_32x32x16_bf16 v[0:15], v[20:23], v[64:67], v[0:15]
	v_and_b32_e32 v17, 0xffffff80, v30
	v_ashrrev_i32_e32 v188, 31, v47
	v_bitop3_b32 v46, v187, v115, v46 bitop3:0xde
	v_bitop3_b32 v187, v16, v131, v17 bitop3:0xde
	v_ashrrev_i32_e32 v16, 31, v31
	v_and_b32_e32 v47, 0xffffff80, v47
	v_and_b32_e32 v188, 0x7fffff80, v188
	v_and_b32_e32 v16, 0x7fffff80, v16
	v_and_b32_e32 v17, 0xffffff80, v31
	v_bitop3_b32 v47, v188, v116, v47 bitop3:0xde
	v_bitop3_b32 v188, v16, v132, v17 bitop3:0xde
	s_nop 0
	v_ashrrev_i32_e32 v16, 31, v0
	v_and_b32_e32 v16, 0x7fffff80, v16
	v_and_b32_e32 v0, 0xffffff80, v0
	v_bitop3_b32 v190, v16, v133, v0 bitop3:0xde
	v_ashrrev_i32_e32 v0, 31, v1
	ds_read_b128 v[16:19], v168 offset:26112
	v_and_b32_e32 v0, 0x7fffff80, v0
	v_and_b32_e32 v1, 0xffffff80, v1
	v_bitop3_b32 v192, v0, v134, v1 bitop3:0xde
	v_ashrrev_i32_e32 v0, 31, v2
	v_and_b32_e32 v0, 0x7fffff80, v0
	v_and_b32_e32 v1, 0xffffff80, v2
	v_bitop3_b32 v193, v0, v135, v1 bitop3:0xde
	v_ashrrev_i32_e32 v0, 31, v3
	v_and_b32_e32 v0, 0x7fffff80, v0
	v_and_b32_e32 v1, 0xffffff80, v3
	v_bitop3_b32 v194, v0, v136, v1 bitop3:0xde
	v_ashrrev_i32_e32 v0, 31, v4
	v_and_b32_e32 v0, 0x7fffff80, v0
	v_and_b32_e32 v1, 0xffffff80, v4
	v_bitop3_b32 v195, v0, v137, v1 bitop3:0xde
	ds_read_b128 v[0:3], v168 offset:26144
	s_waitcnt lgkmcnt(1)
	v_mfma_f32_32x32x16_bf16 v[16:31], v[16:19], v[60:63], 0
	v_ashrrev_i32_e32 v90, 31, v32
	v_ashrrev_i32_e32 v170, 31, v33
	v_ashrrev_i32_e32 v171, 31, v34
	v_ashrrev_i32_e32 v172, 31, v35
	v_and_b32_e32 v32, 0xffffff80, v32
	v_and_b32_e32 v33, 0xffffff80, v33
	v_and_b32_e32 v34, 0xffffff80, v34
	v_and_b32_e32 v35, 0xffffff80, v35
	v_and_b32_e32 v90, 0x7fffff80, v90
	v_and_b32_e32 v170, 0x7fffff80, v170
	v_and_b32_e32 v171, 0x7fffff80, v171
	v_and_b32_e32 v172, 0x7fffff80, v172
	v_bitop3_b32 v90, v90, v99, v32 bitop3:0xde
	v_bitop3_b32 v170, v170, v102, v33 bitop3:0xde
	v_bitop3_b32 v171, v171, v103, v34 bitop3:0xde
	v_bitop3_b32 v172, v172, v104, v35 bitop3:0xde
	ds_read_b128 v[32:35], v168 offset:26176
	s_waitcnt lgkmcnt(1)
	v_mfma_f32_32x32x16_bf16 v[16:31], v[0:3], v[56:59], v[16:31]
	v_ashrrev_i32_e32 v0, 31, v7
	v_and_b32_e32 v0, 0x7fffff80, v0
	v_and_b32_e32 v1, 0xffffff80, v7
	v_bitop3_b32 v57, v0, v140, v1 bitop3:0xde
	ds_read_b128 v[0:3], v168 offset:26208
	v_ashrrev_i32_e32 v4, 31, v5
	v_and_b32_e32 v4, 0x7fffff80, v4
	s_waitcnt lgkmcnt(1)
	v_mfma_f32_32x32x16_bf16 v[16:31], v[32:35], v[84:87], v[16:31]
	v_and_b32_e32 v5, 0xffffff80, v5
	v_bitop3_b32 v60, v4, v138, v5 bitop3:0xde
	v_ashrrev_i32_e32 v4, 31, v6
	v_and_b32_e32 v4, 0x7fffff80, v4
	v_and_b32_e32 v5, 0xffffff80, v6
	v_bitop3_b32 v56, v4, v139, v5 bitop3:0xde
	v_ashrrev_i32_e32 v4, 31, v8
	v_and_b32_e32 v4, 0x7fffff80, v4
	v_and_b32_e32 v5, 0xffffff80, v8
	v_bitop3_b32 v8, v4, v141, v5 bitop3:0xde
	v_ashrrev_i32_e32 v4, 31, v9
	v_and_b32_e32 v32, 0x7fffff80, v4
	ds_read_b128 v[4:7], v168 offset:26240
	s_waitcnt lgkmcnt(1)
	v_mfma_f32_32x32x16_bf16 v[16:31], v[0:3], v[76:79], v[16:31]
	v_ashrrev_i32_e32 v0, 31, v10
	v_and_b32_e32 v0, 0x7fffff80, v0
	v_and_b32_e32 v1, 0xffffff80, v10
	v_bitop3_b32 v10, v0, v143, v1 bitop3:0xde
	ds_read_b128 v[0:3], v168 offset:26272
	v_and_b32_e32 v9, 0xffffff80, v9
	v_bitop3_b32 v9, v32, v142, v9 bitop3:0xde
	s_waitcnt lgkmcnt(1)
	v_mfma_f32_32x32x16_bf16 v[16:31], v[4:7], v[80:83], v[16:31]
	v_ashrrev_i32_e32 v32, 31, v11
	v_and_b32_e32 v4, 0x7fffff80, v32
	v_and_b32_e32 v5, 0xffffff80, v11
	v_bitop3_b32 v11, v4, v144, v5 bitop3:0xde
	v_ashrrev_i32_e32 v4, 31, v12
	v_and_b32_e32 v32, 0x7fffff80, v4
	ds_read_b128 v[4:7], v168 offset:26304
	s_waitcnt lgkmcnt(1)
	v_mfma_f32_32x32x16_bf16 v[16:31], v[0:3], v[72:75], v[16:31]
	v_ashrrev_i32_e32 v0, 31, v13
	v_and_b32_e32 v0, 0x7fffff80, v0
	v_and_b32_e32 v1, 0xffffff80, v13
	v_bitop3_b32 v13, v0, v146, v1 bitop3:0xde
	ds_read_b128 v[0:3], v168 offset:26336
	v_and_b32_e32 v12, 0xffffff80, v12
	v_bitop3_b32 v12, v32, v145, v12 bitop3:0xde
	s_waitcnt lgkmcnt(1)
	v_mfma_f32_32x32x16_bf16 v[16:31], v[4:7], v[68:71], v[16:31]
	v_ashrrev_i32_e32 v32, 31, v14
	v_and_b32_e32 v4, 0x7fffff80, v32
	v_and_b32_e32 v5, 0xffffff80, v14
	v_bitop3_b32 v4, v4, v147, v5 bitop3:0xde
	v_ashrrev_i32_e32 v5, 31, v15
	v_and_b32_e32 v5, 0x7fffff80, v5
	v_and_b32_e32 v6, 0xffffff80, v15
	s_waitcnt lgkmcnt(0)
; __device__ __forceinline__ int crow(int r, int hf) { return (r & 3) + 8 * (r >> 2) + 4 * hf; }
; __device__ __forceinline__ int tosort(float f) { int b = __float_as_int(f); return b ^ ((b >> 31) & 0x7fffffff); }
; template <int OFF>
; __device__ __forceinline__ void sort16_desc(int* a) {
; #pragma unroll
;   for (int ks = 1; ks <= 4; ++ks) {
; #pragma unroll
;     ...
; #pragma unroll
;       for (int i = 0; i < 16; ++i) {
;         const int k = 1 << ks, j = 1 << js;
;         const int l2 = i ^ j;
;         if (l2 > i) { if ((i & k) == 0) cas_desc(a[OFF + i], a[OFF + l2]); else cas_desc(a[OFF + l2], a[OFF + i]); }
;       }
;     }
;   }
; }
; template <int PP>
; __device__ __forceinline__ void select_half(const Params& p, const u16* Subs, int t, int hh, int lc, int hf, int* lists) {
;     ...
;     for (int ks = 0; ks < 8; ++ks) {
;       bf16x8 a = *(const bf16x8*)(Subs + (PP * 128 + nb * 32 + lc) * 136 + ks * 16 + hf * 8);
;       acc = mfma32(a, qf[ks], acc);
;     }
; #pragma unroll
;     for (int r = 0; r < 16; ++r) keys[nb * 16 + r] = (tosort(acc[r]) & ~127) | (nb * 32 + crow(r, hf));
	v_mfma_f32_32x32x16_bf16 v[16:31], v[0:3], v[64:67], v[16:31]
	v_bitop3_b32 v5, v5, v148, v6 bitop3:0xde
	v_max_i32_e32 v32, v40, v41
	v_min_i32_e32 v33, v40, v41
	v_max_i32_e32 v34, v43, v42
	v_min_i32_e32 v35, v43, v42
	v_max_i32_e32 v58, v173, v178
	v_min_i32_e32 v59, v173, v178
	s_nop 4
	v_ashrrev_i32_e32 v0, 31, v16
	v_and_b32_e32 v0, 0x7fffff80, v0
	v_and_b32_e32 v1, 0xffffff80, v16
	v_bitop3_b32 v0, v0, v149, v1 bitop3:0xde
	v_ashrrev_i32_e32 v1, 31, v17
	v_and_b32_e32 v1, 0x7fffff80, v1
	v_and_b32_e32 v2, 0xffffff80, v17
	v_bitop3_b32 v1, v1, v150, v2 bitop3:0xde
	v_ashrrev_i32_e32 v2, 31, v18
	v_and_b32_e32 v2, 0x7fffff80, v2
	v_and_b32_e32 v3, 0xffffff80, v18
	v_bitop3_b32 v2, v2, v151, v3 bitop3:0xde
	v_ashrrev_i32_e32 v3, 31, v19
	v_and_b32_e32 v3, 0x7fffff80, v3
	v_and_b32_e32 v6, 0xffffff80, v19
	v_bitop3_b32 v3, v3, v152, v6 bitop3:0xde
	v_ashrrev_i32_e32 v6, 31, v20
	v_and_b32_e32 v6, 0x7fffff80, v6
	v_and_b32_e32 v7, 0xffffff80, v20
	v_bitop3_b32 v6, v6, v153, v7 bitop3:0xde
	v_ashrrev_i32_e32 v7, 31, v21
	v_and_b32_e32 v7, 0x7fffff80, v7
	v_and_b32_e32 v14, 0xffffff80, v21
	v_bitop3_b32 v7, v7, v154, v14 bitop3:0xde
	v_ashrrev_i32_e32 v14, 31, v22
	v_and_b32_e32 v14, 0x7fffff80, v14
	v_and_b32_e32 v15, 0xffffff80, v22
	v_bitop3_b32 v14, v14, v155, v15 bitop3:0xde
	v_ashrrev_i32_e32 v15, 31, v23
	v_and_b32_e32 v15, 0x7fffff80, v15
	v_and_b32_e32 v16, 0xffffff80, v23
	v_bitop3_b32 v15, v15, v156, v16 bitop3:0xde
	v_ashrrev_i32_e32 v16, 31, v24
	v_and_b32_e32 v16, 0x7fffff80, v16
	v_and_b32_e32 v17, 0xffffff80, v24
	v_bitop3_b32 v16, v16, v157, v17 bitop3:0xde
	v_ashrrev_i32_e32 v17, 31, v25
	v_and_b32_e32 v17, 0x7fffff80, v17
	v_and_b32_e32 v18, 0xffffff80, v25
	v_bitop3_b32 v17, v17, v158, v18 bitop3:0xde
	v_ashrrev_i32_e32 v18, 31, v26
	v_and_b32_e32 v18, 0x7fffff80, v18
	v_and_b32_e32 v19, 0xffffff80, v26
	v_bitop3_b32 v18, v18, v159, v19 bitop3:0xde
	v_ashrrev_i32_e32 v19, 31, v27
	v_and_b32_e32 v19, 0x7fffff80, v19
	v_and_b32_e32 v20, 0xffffff80, v27
	v_bitop3_b32 v19, v19, v160, v20 bitop3:0xde
	v_ashrrev_i32_e32 v20, 31, v28
	v_and_b32_e32 v20, 0x7fffff80, v20
	v_and_b32_e32 v21, 0xffffff80, v28
	v_bitop3_b32 v20, v20, v161, v21 bitop3:0xde
	v_ashrrev_i32_e32 v21, 31, v29
	v_and_b32_e32 v21, 0x7fffff80, v21
	v_and_b32_e32 v22, 0xffffff80, v29
	v_bitop3_b32 v21, v21, v162, v22 bitop3:0xde
	v_ashrrev_i32_e32 v22, 31, v30
	v_and_b32_e32 v22, 0x7fffff80, v22
	v_and_b32_e32 v23, 0xffffff80, v30
	v_bitop3_b32 v22, v22, v163, v23 bitop3:0xde
	v_ashrrev_i32_e32 v23, 31, v31
	v_and_b32_e32 v23, 0x7fffff80, v23
	v_and_b32_e32 v24, 0xffffff80, v31
	v_bitop3_b32 v23, v23, v164, v24 bitop3:0xde
	v_max_i32_e32 v24, v90, v170
	v_min_i32_e32 v25, v90, v170
	v_max_i32_e32 v26, v172, v171
	v_min_i32_e32 v27, v172, v171
	v_max_i32_e32 v28, v36, v37
	v_min_i32_e32 v29, v36, v37
	v_max_i32_e32 v30, v39, v38
	v_min_i32_e32 v31, v39, v38
	v_max_i32_e32 v36, v44, v45
	v_min_i32_e32 v37, v44, v45
	v_max_i32_e32 v38, v47, v46
	v_min_i32_e32 v39, v47, v46
	v_max_i32_e32 v61, v180, v179
	v_min_i32_e32 v62, v180, v179
	v_max_i32_e32 v63, v181, v182
	v_min_i32_e32 v64, v181, v182
	v_max_i32_e32 v65, v184, v183
	v_min_i32_e32 v66, v184, v183
	v_max_i32_e32 v67, v185, v174
	v_min_i32_e32 v68, v185, v174
	v_max_i32_e32 v69, v176, v175
	v_min_i32_e32 v70, v176, v175
	v_max_i32_e32 v71, v177, v186
	v_min_i32_e32 v72, v177, v186
	v_max_i32_e32 v73, v188, v187
	v_min_i32_e32 v74, v188, v187
	v_max_i32_e32 v40, v24, v27
	v_min_i32_e32 v24, v24, v27
	v_max_i32_e32 v27, v25, v26
	v_min_i32_e32 v25, v25, v26
	v_max_i32_e32 v26, v31, v28
	v_min_i32_e32 v28, v31, v28
	v_max_i32_e32 v31, v30, v29
	v_min_i32_e32 v29, v30, v29
	v_max_i32_e32 v30, v32, v35
	v_min_i32_e32 v32, v32, v35
	v_max_i32_e32 v35, v33, v34
	v_min_i32_e32 v33, v33, v34
	v_max_i32_e32 v34, v39, v36
	v_min_i32_e32 v36, v39, v36
	v_max_i32_e32 v39, v38, v37
	v_min_i32_e32 v37, v38, v37
	v_max_i32_e32 v75, v58, v62
	v_min_i32_e32 v58, v58, v62
	v_max_i32_e32 v62, v59, v61
	v_min_i32_e32 v59, v59, v61
	v_max_i32_e32 v61, v66, v63
	v_min_i32_e32 v63, v66, v63
	v_max_i32_e32 v66, v65, v64
	v_min_i32_e32 v64, v65, v64
	v_max_i32_e32 v65, v67, v70
	v_min_i32_e32 v67, v67, v70
	v_max_i32_e32 v70, v68, v69
	v_min_i32_e32 v68, v68, v69
	v_max_i32_e32 v69, v74, v71
	v_min_i32_e32 v71, v74, v71
	v_max_i32_e32 v74, v73, v72
	v_min_i32_e32 v72, v73, v72
	v_max_i32_e32 v38, v40, v27
	v_min_i32_e32 v27, v40, v27
	v_max_i32_e32 v40, v24, v25
	v_min_i32_e32 v24, v24, v25
	v_max_i32_e32 v25, v29, v28
	v_min_i32_e32 v28, v29, v28
	v_max_i32_e32 v29, v31, v26
	v_min_i32_e32 v26, v31, v26
	v_max_i32_e32 v31, v30, v35
	v_min_i32_e32 v30, v30, v35
	v_max_i32_e32 v35, v32, v33
	v_min_i32_e32 v32, v32, v33
	v_max_i32_e32 v33, v37, v36
	v_min_i32_e32 v36, v37, v36
	v_max_i32_e32 v37, v39, v34
	v_min_i32_e32 v34, v39, v34
	v_max_i32_e32 v73, v75, v62
	v_min_i32_e32 v62, v75, v62
	v_max_i32_e32 v75, v58, v59
	v_min_i32_e32 v58, v58, v59
	v_max_i32_e32 v59, v64, v63
	v_min_i32_e32 v63, v64, v63
	v_max_i32_e32 v64, v66, v61
	v_min_i32_e32 v61, v66, v61
	v_max_i32_e32 v66, v65, v70
	v_min_i32_e32 v65, v65, v70
	v_max_i32_e32 v70, v67, v68
	v_min_i32_e32 v67, v67, v68
	v_max_i32_e32 v68, v72, v71
	v_min_i32_e32 v71, v72, v71
	v_max_i32_e32 v72, v74, v69
	v_min_i32_e32 v69, v74, v69
	v_max_i32_e32 v39, v38, v28
	v_min_i32_e32 v28, v38, v28
	v_max_i32_e32 v38, v27, v25
	v_min_i32_e32 v25, v27, v25
	v_max_i32_e32 v27, v40, v26
	v_min_i32_e32 v26, v40, v26
	v_max_i32_e32 v40, v24, v29
	v_min_i32_e32 v24, v24, v29
	v_max_i32_e32 v29, v36, v31
	v_min_i32_e32 v31, v36, v31
	v_max_i32_e32 v36, v33, v30
	v_min_i32_e32 v30, v33, v30
; template <int OFF>
; __device__ __forceinline__ void sort16_desc(int* a) {
; #pragma unroll
;   for (int ks = 1; ks <= 4; ++ks) {
; #pragma unroll
;     ...
; #pragma unroll
;       for (int i = 0; i < 16; ++i) {
;         const int k = 1 << ks, j = 1 << js;
;         const int l2 = i ^ j;
;         if (l2 > i) { if ((i & k) == 0) cas_desc(a[OFF + i], a[OFF + l2]); else cas_desc(a[OFF + l2], a[OFF + i]); }
;       }
;     }
;   }
; }
; template <int OA, int OB>
; __device__ __forceinline__ void merge16(int* a, const int* b) {
; #pragma unroll
;   for (int i = 0; i < 16; ++i) a[OA + i] = max(a[OA + i], b[OB + 15 - i]);
; #pragma unroll
;     ...
; #pragma unroll
;     for (int i = 0; i < 16; ++i) {
;       const int j = 1 << js; const int l2 = i ^ j;
;       if (l2 > i) cas_desc(a[OA + i], a[OA + l2]);
;     }
;   }
; }
	v_max_i32_e32 v33, v34, v35
	v_min_i32_e32 v34, v34, v35
	v_max_i32_e32 v35, v37, v32
	v_min_i32_e32 v32, v37, v32
	v_max_i32_e32 v74, v73, v63
	v_min_i32_e32 v63, v73, v63
	v_max_i32_e32 v73, v62, v59
	v_min_i32_e32 v59, v62, v59
	v_max_i32_e32 v62, v75, v61
	v_min_i32_e32 v61, v75, v61
	v_max_i32_e32 v75, v58, v64
	v_min_i32_e32 v58, v58, v64
	v_max_i32_e32 v64, v71, v66
	v_min_i32_e32 v66, v71, v66
	v_max_i32_e32 v71, v68, v65
	v_min_i32_e32 v65, v68, v65
	v_max_i32_e32 v68, v69, v70
	v_min_i32_e32 v69, v69, v70
	v_max_i32_e32 v70, v72, v67
	v_min_i32_e32 v67, v72, v67
	v_max_i32_e32 v37, v39, v27
	v_min_i32_e32 v27, v39, v27
	v_max_i32_e32 v39, v38, v40
	v_min_i32_e32 v38, v38, v40
	v_max_i32_e32 v40, v28, v26
	v_min_i32_e32 v26, v28, v26
	v_max_i32_e32 v28, v25, v24
	v_min_i32_e32 v24, v25, v24
	v_max_i32_e32 v25, v34, v31
	v_min_i32_e32 v31, v34, v31
	v_max_i32_e32 v34, v32, v30
	v_min_i32_e32 v30, v32, v30
	v_max_i32_e32 v32, v33, v29
	v_min_i32_e32 v29, v33, v29
	v_max_i32_e32 v33, v35, v36
	v_min_i32_e32 v35, v35, v36
	v_max_i32_e32 v72, v74, v62
	v_min_i32_e32 v62, v74, v62
	v_max_i32_e32 v74, v73, v75
	v_min_i32_e32 v73, v73, v75
	v_max_i32_e32 v75, v63, v61
	v_min_i32_e32 v61, v63, v61
	v_max_i32_e32 v63, v59, v58
	v_min_i32_e32 v58, v59, v58
	v_max_i32_e32 v59, v69, v66
	v_min_i32_e32 v66, v69, v66
	v_max_i32_e32 v69, v67, v65
	v_min_i32_e32 v65, v67, v65
	v_max_i32_e32 v67, v68, v64
	v_min_i32_e32 v64, v68, v64
	v_max_i32_e32 v68, v70, v71
	v_min_i32_e32 v70, v70, v71
	v_max_i32_e32 v36, v37, v39
	v_min_i32_e32 v37, v37, v39
	v_max_i32_e32 v39, v27, v38
	v_min_i32_e32 v27, v27, v38
	v_max_i32_e32 v38, v40, v28
	v_min_i32_e32 v28, v40, v28
	v_max_i32_e32 v40, v26, v24
	v_min_i32_e32 v24, v26, v24
	v_max_i32_e32 v26, v30, v31
	v_min_i32_e32 v30, v30, v31
	v_max_i32_e32 v31, v34, v25
	v_min_i32_e32 v25, v34, v25
	v_max_i32_e32 v34, v35, v29
	v_min_i32_e32 v29, v35, v29
	v_max_i32_e32 v35, v33, v32
	v_min_i32_e32 v32, v33, v32
	v_max_i32_e32 v71, v72, v74
	v_min_i32_e32 v72, v72, v74
	v_max_i32_e32 v74, v62, v73
	v_min_i32_e32 v62, v62, v73
	v_max_i32_e32 v73, v75, v63
	v_min_i32_e32 v63, v75, v63
	v_max_i32_e32 v75, v61, v58
	v_min_i32_e32 v58, v61, v58
	v_max_i32_e32 v61, v65, v66
	v_min_i32_e32 v65, v65, v66
	v_max_i32_e32 v66, v69, v59
	v_min_i32_e32 v59, v69, v59
	v_max_i32_e32 v69, v70, v64
	v_min_i32_e32 v64, v70, v64
	v_max_i32_e32 v70, v68, v67
	v_min_i32_e32 v67, v68, v67
	v_max_i32_e32 v33, v36, v30
	v_min_i32_e32 v30, v36, v30
	v_max_i32_e32 v36, v37, v26
	v_min_i32_e32 v26, v37, v26
	v_max_i32_e32 v37, v39, v25
	v_min_i32_e32 v25, v39, v25
	v_max_i32_e32 v39, v27, v31
	v_min_i32_e32 v27, v27, v31
	v_max_i32_e32 v31, v38, v29
	v_min_i32_e32 v29, v38, v29
	v_max_i32_e32 v38, v28, v34
	v_min_i32_e32 v28, v28, v34
	v_max_i32_e32 v34, v40, v32
	v_min_i32_e32 v32, v40, v32
	v_max_i32_e32 v40, v24, v35
	v_min_i32_e32 v24, v24, v35
	v_max_i32_e32 v68, v71, v65
	v_min_i32_e32 v65, v71, v65
	v_max_i32_e32 v71, v72, v61
	v_min_i32_e32 v61, v72, v61
	v_max_i32_e32 v72, v74, v59
	v_min_i32_e32 v59, v74, v59
	v_max_i32_e32 v74, v62, v66
	v_min_i32_e32 v62, v62, v66
	v_max_i32_e32 v66, v73, v64
	v_min_i32_e32 v64, v73, v64
	v_max_i32_e32 v73, v63, v69
	v_min_i32_e32 v63, v63, v69
	v_max_i32_e32 v69, v75, v67
	v_min_i32_e32 v67, v75, v67
	v_max_i32_e32 v75, v58, v70
	v_min_i32_e32 v58, v58, v70
	v_max_i32_e32 v35, v33, v31
	v_min_i32_e32 v31, v33, v31
	v_max_i32_e32 v33, v36, v38
	v_min_i32_e32 v36, v36, v38
	v_max_i32_e32 v38, v37, v34
	v_min_i32_e32 v34, v37, v34
	v_max_i32_e32 v37, v39, v40
	v_min_i32_e32 v39, v39, v40
	v_max_i32_e32 v40, v30, v29
	v_min_i32_e32 v29, v30, v29
	v_max_i32_e32 v30, v26, v28
	v_min_i32_e32 v26, v26, v28
	v_max_i32_e32 v28, v25, v32
	v_min_i32_e32 v25, v25, v32
	v_max_i32_e32 v32, v27, v24
	v_min_i32_e32 v24, v27, v24
	v_max_i32_e32 v70, v68, v66
	v_min_i32_e32 v66, v68, v66
	v_max_i32_e32 v68, v71, v73
	v_min_i32_e32 v71, v71, v73
	v_max_i32_e32 v73, v72, v69
	v_min_i32_e32 v69, v72, v69
	v_max_i32_e32 v72, v74, v75
	v_min_i32_e32 v74, v74, v75
	v_max_i32_e32 v75, v65, v64
	v_min_i32_e32 v64, v65, v64
	v_max_i32_e32 v65, v61, v63
	v_min_i32_e32 v61, v61, v63
	v_max_i32_e32 v63, v59, v67
	v_min_i32_e32 v59, v59, v67
	v_max_i32_e32 v67, v62, v58
	v_min_i32_e32 v58, v62, v58
	v_max_i32_e32 v27, v35, v38
	v_min_i32_e32 v35, v35, v38
	v_max_i32_e32 v38, v33, v37
	v_min_i32_e32 v33, v33, v37
	v_max_i32_e32 v37, v31, v34
	v_min_i32_e32 v31, v31, v34
	v_max_i32_e32 v34, v36, v39
	v_min_i32_e32 v36, v36, v39
	v_max_i32_e32 v39, v40, v28
	v_min_i32_e32 v28, v40, v28
	v_max_i32_e32 v40, v30, v32
	v_min_i32_e32 v30, v30, v32
	v_max_i32_e32 v32, v29, v25
	v_min_i32_e32 v25, v29, v25
	v_max_i32_e32 v29, v26, v24
	v_max_i32_e32 v62, v70, v73
	v_min_i32_e32 v70, v70, v73
	v_max_i32_e32 v73, v68, v72
	v_min_i32_e32 v68, v68, v72
	v_max_i32_e32 v72, v66, v69
	v_min_i32_e32 v66, v66, v69
	v_max_i32_e32 v69, v71, v74
	v_min_i32_e32 v71, v71, v74
	v_max_i32_e32 v74, v75, v63
	v_min_i32_e32 v63, v75, v63
	v_max_i32_e32 v75, v65, v67
	v_min_i32_e32 v65, v65, v67
	v_max_i32_e32 v67, v64, v59
	v_min_i32_e32 v59, v64, v59
	v_max_i32_e32 v64, v61, v58
	v_min_i32_e32 v58, v61, v58
	v_min_i32_e32 v44, v39, v40
	v_min_i32_e32 v45, v28, v30
	v_min_i32_e32 v46, v32, v29
	v_min_i32_e32 v76, v70, v68
	v_min_i32_e32 v77, v72, v69
	v_min_i32_e32 v78, v66, v71
	v_min_i32_e32 v82, v59, v58
	v_min_i32_e32 v24, v26, v24
	v_min_i32_e32 v26, v27, v38
	v_max3_i32 v27, v27, v38, v82
	v_max3_i32 v38, v39, v40, v78
	v_max3_i32 v39, v44, v66, v71
	v_max3_i32 v28, v28, v30, v77
	v_max3_i32 v30, v45, v72, v69
	v_max3_i32 v29, v32, v29, v76
; template <int OFF>
; __device__ __forceinline__ void sort16_desc(int* a) {
; #pragma unroll
;   for (int ks = 1; ks <= 4; ++ks) {
; #pragma unroll
;     ...
; #pragma unroll
;       for (int i = 0; i < 16; ++i) {
;         const int k = 1 << ks, j = 1 << js;
;         const int l2 = i ^ j;
;         if (l2 > i) { if ((i & k) == 0) cas_desc(a[OFF + i], a[OFF + l2]); else cas_desc(a[OFF + l2], a[OFF + i]); }
;       }
;     }
;   }
; }
; template <int OA, int OB>
; __device__ __forceinline__ void merge16(int* a, const int* b) {
; #pragma unroll
;   for (int i = 0; i < 16; ++i) a[OA + i] = max(a[OA + i], b[OB + 15 - i]);
; #pragma unroll
;     ...
; #pragma unroll
;     for (int i = 0; i < 16; ++i) {
;       const int j = 1 << js; const int l2 = i ^ j;
;       if (l2 > i) cas_desc(a[OA + i], a[OA + l2]);
;     }
;   }
; }
; template <int PP>
; __device__ __forceinline__ void select_half(const Params& p, const u16* Subs, int t, int hh, int lc, int hf, int* lists) {
;     ...
;   const u16* qrow = p.qp + (size_t)t * 2048 + hh * 256 + PP * 128 + hf * 8;
; #pragma unroll
;   for (int ks = 0; ks < 8; ++ks) qf[ks] = *(const bf16x8*)(qrow + ks * 16);
	v_max3_i32 v32, v46, v70, v68
	global_load_dwordx4 v[68:71], v[96:97], off offset:256
	v_max_i32_e32 v177, v0, v1
	v_min_i32_e32 v0, v0, v1
	v_max_i32_e32 v1, v3, v2
	v_min_i32_e32 v2, v3, v2
	v_max_i32_e32 v3, v6, v7
	v_min_i32_e32 v6, v6, v7
	v_max_i32_e32 v7, v15, v14
	v_min_i32_e32 v14, v15, v14
	v_max_i32_e32 v15, v16, v17
	v_min_i32_e32 v16, v16, v17
	v_max_i32_e32 v17, v19, v18
	v_min_i32_e32 v18, v19, v18
	v_max_i32_e32 v19, v20, v21
	v_min_i32_e32 v20, v20, v21
	v_max_i32_e32 v21, v23, v22
	v_min_i32_e32 v22, v23, v22
	v_min_i32_e32 v41, v35, v33
	v_min_i32_e32 v42, v37, v34
	v_min_i32_e32 v80, v63, v65
	v_min_i32_e32 v81, v67, v64
	v_max_i32_e32 v83, v190, v192
	v_min_i32_e32 v84, v190, v192
	v_max_i32_e32 v85, v194, v193
	v_min_i32_e32 v86, v194, v193
	v_max_i32_e32 v87, v195, v60
	v_min_i32_e32 v60, v195, v60
	v_max_i32_e32 v90, v57, v56
	v_min_i32_e32 v56, v57, v56
	v_max_i32_e32 v57, v8, v9
	v_min_i32_e32 v8, v8, v9
	v_max_i32_e32 v9, v11, v10
	v_min_i32_e32 v10, v11, v10
	v_max_i32_e32 v11, v12, v13
	v_min_i32_e32 v12, v12, v13
	v_max_i32_e32 v13, v5, v4
	v_min_i32_e32 v4, v5, v4
	v_max_i32_e32 v23, v177, v2
	v_min_i32_e32 v2, v177, v2
	v_max_i32_e32 v177, v0, v1
	v_min_i32_e32 v0, v0, v1
	v_max_i32_e32 v1, v14, v3
	v_min_i32_e32 v3, v14, v3
	v_max_i32_e32 v14, v7, v6
	v_min_i32_e32 v6, v7, v6
	v_max_i32_e32 v7, v15, v18
	v_min_i32_e32 v15, v15, v18
	v_max_i32_e32 v18, v16, v17
	v_min_i32_e32 v16, v16, v17
	v_max_i32_e32 v17, v22, v19
	v_min_i32_e32 v19, v22, v19
	v_max_i32_e32 v22, v21, v20
	v_min_i32_e32 v20, v21, v20
	v_max_i32_e32 v5, v83, v86
	v_min_i32_e32 v83, v83, v86
	v_max_i32_e32 v86, v84, v85
	v_min_i32_e32 v84, v84, v85
	v_max_i32_e32 v85, v56, v87
	v_min_i32_e32 v56, v56, v87
	v_max_i32_e32 v87, v90, v60
	v_min_i32_e32 v60, v90, v60
	v_max_i32_e32 v90, v57, v10
	v_min_i32_e32 v10, v57, v10
	v_max_i32_e32 v57, v8, v9
	v_min_i32_e32 v8, v8, v9
	v_max_i32_e32 v9, v4, v11
	v_min_i32_e32 v4, v4, v11
	v_max_i32_e32 v11, v13, v12
	v_min_i32_e32 v12, v13, v12
	v_max_i32_e32 v21, v23, v177
	v_min_i32_e32 v23, v23, v177
	v_max_i32_e32 v177, v2, v0
	v_min_i32_e32 v0, v2, v0
	v_max_i32_e32 v2, v6, v3
	v_min_i32_e32 v3, v6, v3
	v_max_i32_e32 v6, v14, v1
	v_min_i32_e32 v1, v14, v1
	v_max_i32_e32 v14, v7, v18
	v_min_i32_e32 v7, v7, v18
	v_max_i32_e32 v18, v15, v16
	v_min_i32_e32 v15, v15, v16
	v_max_i32_e32 v16, v20, v19
	v_min_i32_e32 v19, v20, v19
	v_max_i32_e32 v20, v22, v17
	v_min_i32_e32 v17, v22, v17
	v_max3_i32 v33, v35, v33, v81
	v_max3_i32 v35, v41, v67, v64
	v_max3_i32 v34, v37, v34, v80
	v_max3_i32 v37, v42, v63, v65
	global_load_dwordx4 v[64:67], v[96:97], off offset:288
	v_max_i32_e32 v13, v5, v86
	v_min_i32_e32 v5, v5, v86
	v_max_i32_e32 v86, v83, v84
	v_min_i32_e32 v83, v83, v84
	v_max_i32_e32 v84, v60, v56
	v_min_i32_e32 v56, v60, v56
	v_max_i32_e32 v60, v87, v85
	v_min_i32_e32 v85, v87, v85
	v_max_i32_e32 v87, v90, v57
	v_min_i32_e32 v57, v90, v57
	v_max_i32_e32 v90, v10, v8
	v_min_i32_e32 v8, v10, v8
	v_max_i32_e32 v10, v12, v4
	v_min_i32_e32 v4, v12, v4
	v_max_i32_e32 v12, v11, v9
	v_min_i32_e32 v9, v11, v9
	v_max_i32_e32 v22, v21, v3
	v_min_i32_e32 v3, v21, v3
	v_max_i32_e32 v21, v23, v2
	v_min_i32_e32 v2, v23, v2
	v_max_i32_e32 v23, v177, v1
	v_min_i32_e32 v1, v177, v1
	v_max_i32_e32 v177, v0, v6
	v_min_i32_e32 v0, v0, v6
	v_max_i32_e32 v6, v19, v14
	v_min_i32_e32 v14, v19, v14
	v_max_i32_e32 v19, v16, v7
	v_min_i32_e32 v7, v16, v7
	v_max_i32_e32 v16, v17, v18
	v_min_i32_e32 v17, v17, v18
	v_max_i32_e32 v18, v20, v15
	v_min_i32_e32 v15, v20, v15
	v_max_i32_e32 v11, v13, v56
	v_min_i32_e32 v13, v13, v56
	v_max_i32_e32 v56, v5, v84
	v_min_i32_e32 v5, v5, v84
	v_max_i32_e32 v84, v86, v85
	v_min_i32_e32 v85, v86, v85
	v_max_i32_e32 v86, v83, v60
	v_min_i32_e32 v60, v83, v60
	v_max_i32_e32 v83, v4, v87
	v_min_i32_e32 v4, v4, v87
	v_max_i32_e32 v87, v10, v57
	v_min_i32_e32 v10, v10, v57
	v_max_i32_e32 v57, v9, v90
	v_min_i32_e32 v9, v9, v90
	v_max_i32_e32 v90, v12, v8
	v_min_i32_e32 v8, v12, v8
	v_max_i32_e32 v20, v22, v23
	v_min_i32_e32 v22, v22, v23
	v_max_i32_e32 v23, v21, v177
	v_min_i32_e32 v21, v21, v177
	v_max_i32_e32 v177, v3, v1
	v_min_i32_e32 v1, v3, v1
	v_max_i32_e32 v3, v2, v0
	v_min_i32_e32 v0, v2, v0
	v_max_i32_e32 v2, v17, v14
	v_min_i32_e32 v14, v17, v14
	v_max_i32_e32 v17, v15, v7
	v_min_i32_e32 v7, v15, v7
	v_max_i32_e32 v15, v16, v6
	v_min_i32_e32 v6, v16, v6
	v_max_i32_e32 v16, v18, v19
	v_min_i32_e32 v18, v18, v19
	v_max_i32_e32 v12, v11, v84
	v_min_i32_e32 v11, v11, v84
	v_max_i32_e32 v84, v56, v86
	v_min_i32_e32 v56, v56, v86
	v_max_i32_e32 v86, v13, v85
	v_min_i32_e32 v13, v13, v85
	v_max_i32_e32 v85, v5, v60
	v_min_i32_e32 v5, v5, v60
	v_max_i32_e32 v60, v9, v4
	v_min_i32_e32 v4, v9, v4
	v_max_i32_e32 v9, v8, v10
	v_min_i32_e32 v8, v8, v10
	v_max_i32_e32 v10, v57, v83
	v_min_i32_e32 v57, v57, v83
	v_max_i32_e32 v83, v90, v87
	v_min_i32_e32 v87, v90, v87
	v_max_i32_e32 v19, v20, v23
	v_min_i32_e32 v20, v20, v23
	v_max_i32_e32 v23, v22, v21
	v_min_i32_e32 v21, v22, v21
	v_max_i32_e32 v22, v177, v3
	v_min_i32_e32 v3, v177, v3
	v_max_i32_e32 v177, v1, v0
	v_min_i32_e32 v0, v1, v0
	v_max_i32_e32 v1, v7, v14
	v_min_i32_e32 v7, v7, v14
	v_max_i32_e32 v14, v17, v2
	v_min_i32_e32 v2, v17, v2
	v_max_i32_e32 v17, v18, v6
	v_min_i32_e32 v6, v18, v6
	v_max_i32_e32 v18, v16, v15
	v_min_i32_e32 v15, v16, v15
	v_max_i32_e32 v90, v12, v84
	v_min_i32_e32 v12, v12, v84
	v_max_i32_e32 v84, v11, v56
	v_min_i32_e32 v11, v11, v56
	v_max_i32_e32 v56, v86, v85
	v_min_i32_e32 v85, v86, v85
	v_max_i32_e32 v86, v13, v5
	v_min_i32_e32 v5, v13, v5
	v_max_i32_e32 v13, v8, v4
	v_min_i32_e32 v4, v8, v4
; template <int OFF>
; __device__ __forceinline__ void sort16_desc(int* a) {
; #pragma unroll
;   for (int ks = 1; ks <= 4; ++ks) {
; #pragma unroll
;     ...
; #pragma unroll
;       for (int i = 0; i < 16; ++i) {
;         const int k = 1 << ks, j = 1 << js;
;         const int l2 = i ^ j;
;         if (l2 > i) { if ((i & k) == 0) cas_desc(a[OFF + i], a[OFF + l2]); else cas_desc(a[OFF + l2], a[OFF + i]); }
;       }
;     }
;   }
; }
; template <int OA, int OB>
; __device__ __forceinline__ void merge16(int* a, const int* b) {
; #pragma unroll
;   for (int i = 0; i < 16; ++i) a[OA + i] = max(a[OA + i], b[OB + 15 - i]);
; #pragma unroll
;     ...
; #pragma unroll
;     for (int i = 0; i < 16; ++i) {
;       const int j = 1 << js; const int l2 = i ^ j;
;       if (l2 > i) cas_desc(a[OA + i], a[OA + l2]);
;     }
;   }
; }
; template <int PP>
; __device__ __forceinline__ void select_half(const Params& p, const u16* Subs, int t, int hh, int lc, int hf, int* lists) {
;     ...
;   const u16* qrow = p.qp + (size_t)t * 2048 + hh * 256 + PP * 128 + hf * 8;
; #pragma unroll
;   for (int ks = 0; ks < 8; ++ks) qf[ks] = *(const bf16x8*)(qrow + ks * 16);
	v_max_i32_e32 v8, v9, v60
	v_min_i32_e32 v9, v9, v60
	v_max_i32_e32 v60, v87, v57
	v_min_i32_e32 v57, v87, v57
	v_max_i32_e32 v87, v83, v10
	v_min_i32_e32 v10, v83, v10
	v_max_i32_e32 v16, v19, v7
	v_min_i32_e32 v7, v19, v7
	v_max_i32_e32 v19, v20, v1
	v_min_i32_e32 v1, v20, v1
	v_max_i32_e32 v20, v23, v2
	v_min_i32_e32 v2, v23, v2
	v_max_i32_e32 v23, v21, v14
	v_min_i32_e32 v14, v21, v14
	v_max_i32_e32 v21, v22, v6
	v_min_i32_e32 v6, v22, v6
	v_max_i32_e32 v22, v3, v17
	v_min_i32_e32 v3, v3, v17
	v_max_i32_e32 v17, v177, v15
	v_min_i32_e32 v15, v177, v15
	v_max_i32_e32 v177, v0, v18
	v_max_i32_e32 v83, v90, v4
	v_min_i32_e32 v4, v90, v4
	v_max_i32_e32 v90, v12, v13
	v_min_i32_e32 v12, v12, v13
	v_max_i32_e32 v13, v84, v9
	v_min_i32_e32 v9, v84, v9
	v_max_i32_e32 v84, v11, v8
	v_min_i32_e32 v8, v11, v8
	v_max_i32_e32 v11, v56, v57
	v_min_i32_e32 v56, v56, v57
	v_max_i32_e32 v57, v85, v60
	v_min_i32_e32 v60, v85, v60
	v_max_i32_e32 v85, v86, v10
	v_min_i32_e32 v10, v86, v10
	v_max_i32_e32 v86, v5, v87
	v_min_i32_e32 v5, v5, v87
	v_min_i32_e32 v0, v0, v18
	v_max_i32_e32 v18, v16, v21
	v_min_i32_e32 v16, v16, v21
	v_max_i32_e32 v21, v19, v22
	v_min_i32_e32 v19, v19, v22
	v_max_i32_e32 v22, v20, v17
	v_min_i32_e32 v17, v20, v17
	v_max_i32_e32 v20, v23, v177
	v_min_i32_e32 v23, v23, v177
	v_max_i32_e32 v87, v83, v11
	v_min_i32_e32 v11, v83, v11
	v_max_i32_e32 v83, v90, v57
	v_min_i32_e32 v57, v90, v57
	v_max_i32_e32 v90, v13, v85
	v_min_i32_e32 v13, v13, v85
	v_max_i32_e32 v85, v84, v86
	v_min_i32_e32 v84, v84, v86
	v_max_i32_e32 v86, v4, v56
	v_min_i32_e32 v4, v4, v56
	v_max_i32_e32 v56, v12, v60
	v_min_i32_e32 v12, v12, v60
	v_max_i32_e32 v60, v9, v10
	v_min_i32_e32 v9, v9, v10
	v_max_i32_e32 v10, v8, v5
	v_max_i32_e32 v177, v7, v6
	v_min_i32_e32 v6, v7, v6
	v_max_i32_e32 v7, v1, v3
	v_min_i32_e32 v1, v1, v3
	v_max_i32_e32 v3, v2, v15
	v_min_i32_e32 v2, v2, v15
	v_max_i32_e32 v15, v14, v0
	v_min_i32_e32 v0, v14, v0
	v_max_i32_e32 v14, v18, v22
	v_min_i32_e32 v18, v18, v22
	v_max_i32_e32 v22, v21, v20
	v_min_i32_e32 v20, v21, v20
	v_max_i32_e32 v21, v16, v17
	v_min_i32_e32 v16, v16, v17
	v_max_i32_e32 v17, v19, v23
	v_min_i32_e32 v47, v25, v24
	v_min_i32_e32 v61, v62, v73
	v_min_i32_e32 v5, v8, v5
	v_max_i32_e32 v8, v87, v90
	v_min_i32_e32 v87, v87, v90
	v_max_i32_e32 v90, v83, v85
	v_min_i32_e32 v83, v83, v85
	v_max_i32_e32 v85, v11, v13
	v_min_i32_e32 v11, v11, v13
	v_max_i32_e32 v13, v57, v84
	v_min_i32_e32 v57, v57, v84
	v_max_i32_e32 v84, v86, v60
	v_min_i32_e32 v60, v86, v60
	v_max_i32_e32 v86, v56, v10
	v_min_i32_e32 v10, v56, v10
	v_min_i32_e32 v179, v21, v17
	v_min_i32_e32 v174, v60, v10
	v_max3_i32 v24, v25, v24, v61
	v_max3_i32 v25, v47, v62, v73
	v_max3_i32 v10, v60, v10, v179
	global_load_dwordx4 v[60:63], v[96:97], off offset:320
	v_min_i32_e32 v19, v19, v23
	v_max_i32_e32 v23, v177, v3
	v_min_i32_e32 v3, v177, v3
	v_max_i32_e32 v177, v7, v15
	v_max_i32_e32 v56, v4, v9
	v_min_i32_e32 v4, v4, v9
	v_max_i32_e32 v9, v12, v5
	v_min_i32_e32 v171, v85, v13
	v_min_i32_e32 v7, v7, v15
	v_min_i32_e32 v178, v18, v20
	v_min_i32_e32 v181, v23, v177
	v_min_i32_e32 v172, v11, v57
	v_min_i32_e32 v175, v56, v9
	v_min_i32_e32 v182, v3, v7
	v_max3_i32 v26, v26, v59, v58
	v_max3_i32 v3, v171, v3, v7
	v_max3_i32 v7, v11, v57, v181
	v_max3_i32 v9, v56, v9, v178
	global_load_dwordx4 v[56:59], v[96:97], off offset:352
	v_min_i32_e32 v43, v31, v36
	v_min_i32_e32 v79, v74, v75
	v_min_i32_e32 v5, v12, v5
	v_max_i32_e32 v15, v6, v2
	v_min_i32_e32 v2, v6, v2
	v_max_i32_e32 v6, v1, v0
	v_min_i32_e32 v0, v1, v0
	v_min_i32_e32 v12, v8, v90
	v_min_i32_e32 v170, v87, v83
	v_min_i32_e32 v173, v84, v86
	v_min_i32_e32 v176, v4, v5
	v_min_i32_e32 v1, v14, v22
	v_min_i32_e32 v180, v16, v19
	v_min_i32_e32 v183, v15, v6
	v_min_i32_e32 v184, v2, v0
	v_max3_i32 v31, v31, v36, v79
	v_max3_i32 v36, v43, v74, v75
	v_max_i32_e32 v40, v27, v38
	v_min_i32_e32 v27, v27, v38
	v_max_i32_e32 v38, v26, v39
	v_min_i32_e32 v26, v26, v39
	v_max_i32_e32 v39, v33, v28
	v_min_i32_e32 v28, v33, v28
	v_max_i32_e32 v33, v35, v30
	v_min_i32_e32 v30, v35, v30
	v_max_i32_e32 v35, v34, v29
	v_min_i32_e32 v29, v34, v29
	v_max_i32_e32 v34, v37, v32
	v_min_i32_e32 v32, v37, v32
	v_max_i32_e32 v37, v31, v24
	v_min_i32_e32 v24, v31, v24
	v_max_i32_e32 v31, v36, v25
	v_min_i32_e32 v25, v36, v25
	v_max3_i32 v8, v8, v90, v184
	v_max3_i32 v0, v12, v2, v0
	v_max3_i32 v2, v87, v83, v183
	v_max3_i32 v6, v170, v15, v6
	v_max3_i32 v12, v85, v13, v182
	v_max3_i32 v11, v172, v23, v177
	v_max3_i32 v13, v84, v86, v180
	v_max3_i32 v15, v173, v16, v19
	v_max3_i32 v16, v174, v21, v17
	v_max3_i32 v17, v175, v18, v20
	v_max3_i32 v1, v4, v5, v1
	v_max3_i32 v4, v176, v14, v22
	v_max_i32_e32 v36, v40, v35
	v_min_i32_e32 v35, v40, v35
	v_max_i32_e32 v40, v38, v34
	v_min_i32_e32 v34, v38, v34
	v_max_i32_e32 v38, v39, v37
	v_min_i32_e32 v37, v39, v37
	v_max_i32_e32 v39, v33, v31
	v_min_i32_e32 v31, v33, v31
	v_max_i32_e32 v33, v27, v29
	v_min_i32_e32 v27, v27, v29
	v_max_i32_e32 v29, v26, v32
	v_min_i32_e32 v26, v26, v32
	v_max_i32_e32 v32, v28, v24
	v_min_i32_e32 v24, v28, v24
	v_max_i32_e32 v28, v30, v25
	v_min_i32_e32 v25, v30, v25
	v_max_i32_e32 v5, v8, v13
	v_min_i32_e32 v8, v8, v13
	v_max_i32_e32 v13, v0, v15
	v_min_i32_e32 v0, v0, v15
	v_max_i32_e32 v14, v2, v10
	v_min_i32_e32 v2, v2, v10
	v_max_i32_e32 v10, v6, v16
	v_min_i32_e32 v6, v6, v16
	v_max_i32_e32 v15, v12, v9
	v_min_i32_e32 v9, v12, v9
	v_max_i32_e32 v12, v3, v17
	v_max_i32_e32 v16, v7, v1
	v_min_i32_e32 v1, v7, v1
	v_max_i32_e32 v7, v11, v4
	v_max_i32_e32 v30, v36, v38
	v_min_i32_e32 v36, v36, v38
	v_max_i32_e32 v38, v40, v39
	v_min_i32_e32 v39, v40, v39
; __device__ __forceinline__ int crow(int r, int hf) { return (r & 3) + 8 * (r >> 2) + 4 * hf; }
; __device__ __forceinline__ int tosort(float f) { int b = __float_as_int(f); return b ^ ((b >> 31) & 0x7fffffff); }
; template <int OA, int OB>
; __device__ __forceinline__ void merge16(int* a, const int* b) {
; #pragma unroll
;   for (int i = 0; i < 16; ++i) a[OA + i] = max(a[OA + i], b[OB + 15 - i]);
; #pragma unroll
;     ...
; #pragma unroll
;     for (int i = 0; i < 16; ++i) {
;       const int j = 1 << js; const int l2 = i ^ j;
;       if (l2 > i) cas_desc(a[OA + i], a[OA + l2]);
;     }
;   }
; }
; template <int PP>
; __device__ __forceinline__ void select_half(const Params& p, const u16* Subs, int t, int hh, int lc, int hf, int* lists) {
;   bf16x8 qf[8];
;   const u16* qrow = p.qp + (size_t)t * 2048 + hh * 256 + PP * 128 + hf * 8;
; #pragma unroll
;   for (int ks = 0; ks < 8; ++ks) qf[ks] = *(const bf16x8*)(qrow + ks * 16);
;   int keys[64];
; #pragma unroll
;   for (int nb = 0; nb < 4; ++nb) {
;     f32x16 acc;
; #pragma unroll
;     for (int r = 0; r < 16; ++r) acc[r] = 0.f;
; #pragma unroll
;     for (int ks = 0; ks < 8; ++ks) {
;       bf16x8 a = *(const bf16x8*)(Subs + (PP * 128 + nb * 32 + lc) * 136 + ks * 16 + hf * 8);
;       acc = mfma32(a, qf[ks], acc);
;     }
; #pragma unroll
;     for (int r = 0; r < 16; ++r) keys[nb * 16 + r] = (tosort(acc[r]) & ~127) | (nb * 32 + crow(r, hf));
;   }
;   sort16_desc<0>(keys); sort16_desc<16>(keys); sort16_desc<32>(keys); sort16_desc<48>(keys);
;   merge16<0, 16>(keys, keys); merge16<32, 48>(keys, keys); merge16<0, 32>(keys, keys);
;   int other[16];
; #pragma unroll
;   for (int i = 0; i < 16; ++i) other[i] = __shfl_xor(keys[i], 32);
;   merge16<0, 0>(keys, other);
; #pragma unroll
;   for (int i = 0; i < 16; ++i) lists[PP * 16 + i] = keys[i];
	v_max_i32_e32 v40, v35, v37
	v_min_i32_e32 v35, v35, v37
	v_max_i32_e32 v37, v34, v31
	v_min_i32_e32 v31, v34, v31
	v_max_i32_e32 v34, v33, v32
	v_min_i32_e32 v32, v33, v32
	v_max_i32_e32 v33, v29, v28
	v_min_i32_e32 v28, v29, v28
	v_max_i32_e32 v29, v27, v24
	v_min_i32_e32 v24, v27, v24
	v_max_i32_e32 v27, v26, v25
	v_min_i32_e32 v25, v26, v25
	v_min_i32_e32 v3, v3, v17
	v_min_i32_e32 v4, v11, v4
	v_max_i32_e32 v11, v5, v15
	v_min_i32_e32 v5, v5, v15
	v_max_i32_e32 v15, v13, v12
	v_min_i32_e32 v12, v13, v12
	v_max_i32_e32 v13, v14, v16
	v_min_i32_e32 v14, v14, v16
	v_max_i32_e32 v16, v10, v7
	v_min_i32_e32 v7, v10, v7
	v_min_i32_e32 v44, v34, v33
	v_min_i32_e32 v45, v32, v28
	v_min_i32_e32 v46, v29, v27
	v_min_i32_e32 v47, v24, v25
	v_max_i32_e32 v10, v8, v9
	v_min_i32_e32 v8, v8, v9
	v_max_i32_e32 v9, v0, v3
	v_min_i32_e32 v0, v0, v3
	v_max_i32_e32 v3, v2, v1
	v_min_i32_e32 v1, v2, v1
	v_max_i32_e32 v2, v6, v4
	v_min_i32_e32 v4, v6, v4
	v_max_i32_e32 v6, v11, v13
	v_min_i32_e32 v11, v11, v13
	v_max_i32_e32 v13, v15, v16
	v_min_i32_e32 v15, v15, v16
	v_max_i32_e32 v16, v5, v14
	v_min_i32_e32 v5, v5, v14
	v_max_i32_e32 v14, v12, v7
	v_min_i32_e32 v7, v12, v7
	v_max_i32_e32 v12, v10, v3
	v_min_i32_e32 v3, v10, v3
	v_max_i32_e32 v10, v9, v2
	v_min_i32_e32 v2, v9, v2
	v_max_i32_e32 v9, v8, v1
	v_min_i32_e32 v1, v8, v1
	v_max_i32_e32 v8, v0, v4
	v_min_i32_e32 v0, v0, v4
	v_min_i32_e32 v4, v6, v13
	v_min_i32_e32 v17, v11, v15
	v_min_i32_e32 v18, v16, v14
	v_min_i32_e32 v19, v5, v7
	v_max3_i32 v5, v44, v5, v7
	v_max3_i32 v14, v45, v16, v14
	v_max3_i32 v11, v46, v11, v15
	v_max3_i32 v6, v47, v6, v13
	global_load_dwordx4 v[44:47], v[96:97], off offset:384
	v_min_i32_e32 v41, v36, v39
	v_min_i32_e32 v42, v40, v37
	v_min_i32_e32 v43, v35, v31
	v_min_i32_e32 v21, v3, v2
	v_min_i32_e32 v20, v12, v10
	v_min_i32_e32 v22, v9, v8
	v_max3_i32 v8, v41, v9, v8
	v_max3_i32 v9, v40, v37, v21
	v_max3_i32 v2, v42, v3, v2
	v_max3_i32 v10, v43, v12, v10
	global_load_dwordx4 v[40:43], v[96:97], off offset:416
	v_min_i32_e32 v26, v30, v38
	v_min_i32_e32 v23, v1, v0
	v_max3_i32 v23, v30, v38, v23
	v_max3_i32 v0, v26, v1, v0
	v_max3_i32 v1, v36, v39, v22
	global_load_dwordx4 v[36:39], v[96:97], off offset:448
	v_max3_i32 v3, v35, v31, v20
	v_max3_i32 v12, v34, v33, v19
	v_max3_i32 v7, v32, v28, v18
	global_load_dwordx4 v[32:35], v[96:97], off offset:480
	v_max3_i32 v16, v29, v27, v17
	v_max3_i32 v4, v24, v25, v4
	v_max_i32_e32 v13, v23, v12
	v_min_i32_e32 v12, v23, v12
	v_max_i32_e32 v15, v0, v5
	v_min_i32_e32 v0, v0, v5
	v_max_i32_e32 v5, v1, v7
	v_min_i32_e32 v1, v1, v7
	v_max_i32_e32 v7, v8, v14
	v_min_i32_e32 v8, v8, v14
	v_max_i32_e32 v14, v9, v16
	v_min_i32_e32 v9, v9, v16
	v_max_i32_e32 v16, v2, v11
	v_min_i32_e32 v2, v2, v11
	v_max_i32_e32 v11, v3, v4
	v_min_i32_e32 v3, v3, v4
	v_max_i32_e32 v4, v10, v6
	v_min_i32_e32 v6, v10, v6
	v_max_i32_e32 v10, v13, v14
	v_min_i32_e32 v13, v13, v14
	v_max_i32_e32 v14, v15, v16
	v_min_i32_e32 v15, v15, v16
	v_max_i32_e32 v16, v5, v11
	v_min_i32_e32 v5, v5, v11
	v_max_i32_e32 v11, v7, v4
	v_min_i32_e32 v4, v7, v4
	v_max_i32_e32 v7, v12, v9
	v_min_i32_e32 v9, v12, v9
	v_max_i32_e32 v12, v0, v2
	v_min_i32_e32 v0, v0, v2
	v_max_i32_e32 v2, v1, v3
	v_min_i32_e32 v1, v1, v3
	v_max_i32_e32 v3, v8, v6
	v_min_i32_e32 v6, v8, v6
	v_max_i32_e32 v8, v10, v16
	v_min_i32_e32 v10, v10, v16
	v_max_i32_e32 v16, v14, v11
	v_min_i32_e32 v11, v14, v11
	v_max_i32_e32 v14, v13, v5
	v_min_i32_e32 v5, v13, v5
	v_max_i32_e32 v13, v15, v4
	v_min_i32_e32 v4, v15, v4
	v_max_i32_e32 v15, v7, v2
	v_min_i32_e32 v2, v7, v2
	v_max_i32_e32 v7, v12, v3
	v_min_i32_e32 v3, v12, v3
	v_max_i32_e32 v12, v9, v1
	v_min_i32_e32 v1, v9, v1
	v_max_i32_e32 v9, v0, v6
	v_min_i32_e32 v0, v0, v6
	v_max_i32_e32 v6, v8, v16
	v_min_i32_e32 v8, v8, v16
	v_max_i32_e32 v16, v10, v11
	v_min_i32_e32 v10, v10, v11
	v_max_i32_e32 v11, v14, v13
	v_min_i32_e32 v13, v14, v13
	v_max_i32_e32 v14, v5, v4
	v_min_i32_e32 v4, v5, v4
	v_max_i32_e32 v5, v15, v7
	v_min_i32_e32 v7, v15, v7
	v_max_i32_e32 v15, v2, v3
	v_min_i32_e32 v2, v2, v3
	v_max_i32_e32 v3, v12, v9
	v_min_i32_e32 v9, v12, v9
	v_max_i32_e32 v12, v1, v0
	v_min_i32_e32 v0, v1, v0
	ds_bpermute_b32 v19, v100, v10
	ds_bpermute_b32 v20, v100, v11
	ds_bpermute_b32 v23, v100, v4
	ds_bpermute_b32 v27, v100, v0
	ds_bpermute_b32 v29, v100, v2
	ds_bpermute_b32 v31, v100, v3
	ds_bpermute_b32 v1, v100, v6
	ds_bpermute_b32 v17, v100, v8
	ds_bpermute_b32 v18, v100, v16
	ds_bpermute_b32 v22, v100, v14
	ds_bpermute_b32 v26, v100, v15
	ds_bpermute_b32 v24, v100, v5
	s_waitcnt lgkmcnt(8)
	v_max_i32_e32 v6, v6, v27
	s_waitcnt lgkmcnt(6)
	v_max_i32_e32 v10, v10, v31
	v_max_i32_e32 v11, v11, v29
	v_max_i32_e32 v5, v5, v23
	v_max_i32_e32 v2, v2, v20
	v_max_i32_e32 v3, v3, v19
	ds_bpermute_b32 v21, v100, v13
	ds_bpermute_b32 v25, v100, v7
	ds_bpermute_b32 v28, v100, v12
	ds_bpermute_b32 v30, v100, v9
	s_waitcnt lgkmcnt(5)
	v_max_i32_e32 v13, v13, v26
	v_max_i32_e32 v7, v7, v22
	v_max_i32_e32 v9, v9, v18
	v_max_i32_e32 v12, v12, v17
	v_max_i32_e32 v17, v0, v1
	v_max_i32_e32 v18, v6, v5
	v_min_i32_e32 v20, v6, v5
	v_max_i32_e32 v22, v10, v2
	v_min_i32_e32 v26, v10, v2
	v_max_i32_e32 v6, v11, v3
	v_min_i32_e32 v23, v11, v3
	ds_read_b128 v[0:3], v101 offset:34816
	s_waitcnt lgkmcnt(2)
	v_max_i32_e32 v8, v8, v28
	s_waitcnt lgkmcnt(1)
	v_max_i32_e32 v16, v16, v30
	v_max_i32_e32 v4, v4, v24
	v_max_i32_e32 v15, v15, v21
	v_max_i32_e32 v14, v14, v25
	v_max_i32_e32 v5, v8, v7
	v_min_i32_e32 v24, v8, v7
	v_max_i32_e32 v21, v16, v15
	v_min_i32_e32 v25, v16, v15
	v_max_i32_e32 v7, v13, v9
	v_max_i32_e32 v30, v4, v17
	v_min_i32_e32 v31, v4, v17
	v_max_i32_e32 v72, v18, v6
	v_min_i32_e32 v73, v18, v6
	ds_read_b128 v[16:19], v101 offset:34848
	v_min_i32_e32 v27, v13, v9
	v_max_i32_e32 v28, v14, v12
	v_min_i32_e32 v29, v14, v12
	v_max_i32_e32 v74, v5, v7
	v_min_i32_e32 v75, v5, v7
	s_waitcnt vmcnt(7) lgkmcnt(1)
; __device__ __forceinline__ int crow(int r, int hf) { return (r & 3) + 8 * (r >> 2) + 4 * hf; }
; __device__ __forceinline__ int tosort(float f) { int b = __float_as_int(f); return b ^ ((b >> 31) & 0x7fffffff); }
; template <int OA, int OB>
; __device__ __forceinline__ void merge16(int* a, const int* b) {
; #pragma unroll
;   for (int i = 0; i < 16; ++i) a[OA + i] = max(a[OA + i], b[OB + 15 - i]);
; #pragma unroll
;     ...
; #pragma unroll
;     for (int i = 0; i < 16; ++i) {
;       const int j = 1 << js; const int l2 = i ^ j;
;       if (l2 > i) cas_desc(a[OA + i], a[OA + l2]);
;     }
;   }
; }
; template <int PP>
; __device__ __forceinline__ void select_half(const Params& p, const u16* Subs, int t, int hh, int lc, int hf, int* lists) {
;     ...
;     for (int ks = 0; ks < 8; ++ks) {
;       bf16x8 a = *(const bf16x8*)(Subs + (PP * 128 + nb * 32 + lc) * 136 + ks * 16 + hf * 8);
;       acc = mfma32(a, qf[ks], acc);
;     }
; #pragma unroll
;     for (int r = 0; r < 16; ++r) keys[nb * 16 + r] = (tosort(acc[r]) & ~127) | (nb * 32 + crow(r, hf));
	v_mfma_f32_32x32x16_bf16 v[0:15], v[0:3], v[68:71], 0
	v_max_i32_e32 v76, v21, v28
	v_min_i32_e32 v28, v21, v28
	v_max_i32_e32 v77, v22, v30
	v_min_i32_e32 v30, v22, v30
	v_max_i32_e32 v78, v20, v23
	v_min_i32_e32 v79, v20, v23
	ds_read_b128 v[20:23], v101 offset:34880
	s_waitcnt vmcnt(6) lgkmcnt(1)
	v_mfma_f32_32x32x16_bf16 v[0:15], v[16:19], v[64:67], v[0:15]
	ds_read_b128 v[16:19], v101 offset:34912
	v_max_i32_e32 v80, v24, v27
	v_min_i32_e32 v24, v24, v27
	v_max_i32_e32 v27, v25, v29
	v_min_i32_e32 v25, v25, v29
	v_max_i32_e32 v29, v26, v31
	v_min_i32_e32 v26, v26, v31
	s_waitcnt vmcnt(5) lgkmcnt(1)
	v_mfma_f32_32x32x16_bf16 v[0:15], v[20:23], v[60:63], v[0:15]
	ds_read_b128 v[20:23], v101 offset:34944
	v_max_i32_e32 v31, v72, v76
	v_min_i32_e32 v72, v72, v76
	v_max_i32_e32 v76, v74, v77
	v_min_i32_e32 v74, v74, v77
	v_max_i32_e32 v77, v73, v28
	v_min_i32_e32 v28, v73, v28
	s_waitcnt vmcnt(4) lgkmcnt(1)
	v_mfma_f32_32x32x16_bf16 v[0:15], v[16:19], v[56:59], v[0:15]
	ds_read_b128 v[16:19], v101 offset:34976
	v_max_i32_e32 v73, v75, v30
	v_min_i32_e32 v30, v75, v30
	v_max_i32_e32 v75, v78, v27
	v_max_i32_e32 v90, v80, v29
	v_min_i32_e32 v27, v78, v27
	v_max_i32_e32 v96, v79, v25
	s_waitcnt vmcnt(3) lgkmcnt(1)
	v_mfma_f32_32x32x16_bf16 v[0:15], v[20:23], v[44:47], v[0:15]
	ds_read_b128 v[20:23], v101 offset:35008
	v_min_i32_e32 v25, v79, v25
	v_max_i32_e32 v78, v75, v90
	v_min_i32_e32 v79, v75, v90
	v_max_i32_e32 v97, v24, v26
	v_max_i32_e32 v84, v72, v74
	v_min_i32_e32 v85, v72, v74
	s_waitcnt vmcnt(2) lgkmcnt(1)
	v_mfma_f32_32x32x16_bf16 v[0:15], v[16:19], v[40:43], v[0:15]
	ds_read_b128 v[16:19], v101 offset:35040
	v_max_i32_e32 v75, v96, v97
	v_min_i32_e32 v74, v96, v97
	v_min_i32_e32 v29, v80, v29
	v_min_i32_e32 v24, v24, v26
	v_max_i32_e32 v87, v31, v76
	v_min_i32_e32 v86, v31, v76
	s_waitcnt vmcnt(1) lgkmcnt(1)
	v_mfma_f32_32x32x16_bf16 v[0:15], v[20:23], v[36:39], v[0:15]
	v_max_i32_e32 v83, v77, v73
	v_min_i32_e32 v82, v77, v73
	v_max_i32_e32 v81, v28, v30
	v_min_i32_e32 v80, v28, v30
	v_max_i32_e32 v77, v27, v29
	v_min_i32_e32 v76, v27, v29
	v_max_i32_e32 v73, v25, v24
	s_waitcnt vmcnt(0) lgkmcnt(0)
	v_mfma_f32_32x32x16_bf16 v[0:15], v[16:19], v[32:35], v[0:15]
	v_min_i32_e32 v72, v25, v24
	ds_read_b128 v[170:173], v101 offset:43584
	s_nop 9
	v_ashrrev_i32_e32 v16, 31, v0
	v_and_b32_e32 v16, 0x7fffff80, v16
	v_and_b32_e32 v0, 0xffffff80, v0
	v_bitop3_b32 v90, v16, v99, v0 bitop3:0xde
	v_ashrrev_i32_e32 v0, 31, v1
	ds_read_b128 v[16:19], v101 offset:43520
	v_and_b32_e32 v0, 0x7fffff80, v0
	v_and_b32_e32 v1, 0xffffff80, v1
	v_bitop3_b32 v96, v0, v102, v1 bitop3:0xde
	v_ashrrev_i32_e32 v0, 31, v2
	v_and_b32_e32 v0, 0x7fffff80, v0
	v_and_b32_e32 v1, 0xffffff80, v2
	v_bitop3_b32 v97, v0, v103, v1 bitop3:0xde
	v_ashrrev_i32_e32 v0, 31, v3
	v_and_b32_e32 v0, 0x7fffff80, v0
	v_and_b32_e32 v1, 0xffffff80, v3
	v_bitop3_b32 v174, v0, v104, v1 bitop3:0xde
	v_ashrrev_i32_e32 v0, 31, v4
	v_and_b32_e32 v0, 0x7fffff80, v0
	v_and_b32_e32 v1, 0xffffff80, v4
	v_bitop3_b32 v175, v0, v105, v1 bitop3:0xde
	ds_read_b128 v[0:3], v101 offset:43552
	s_waitcnt lgkmcnt(1)
	v_mfma_f32_32x32x16_bf16 v[16:31], v[16:19], v[68:71], 0
	v_ashrrev_i32_e32 v4, 31, v5
	v_and_b32_e32 v4, 0x7fffff80, v4
	v_and_b32_e32 v5, 0xffffff80, v5
	v_bitop3_b32 v176, v4, v106, v5 bitop3:0xde
	v_ashrrev_i32_e32 v4, 31, v6
	v_and_b32_e32 v4, 0x7fffff80, v4
	v_and_b32_e32 v5, 0xffffff80, v6
	s_waitcnt lgkmcnt(0)
	v_mfma_f32_32x32x16_bf16 v[16:31], v[0:3], v[64:67], v[16:31]
	v_ashrrev_i32_e32 v0, 31, v7
	v_and_b32_e32 v0, 0x7fffff80, v0
	v_and_b32_e32 v1, 0xffffff80, v7
	v_bitop3_b32 v178, v0, v108, v1 bitop3:0xde
	ds_read_b128 v[0:3], v101 offset:43616
	v_bitop3_b32 v177, v4, v107, v5 bitop3:0xde
	v_ashrrev_i32_e32 v4, 31, v8
	v_mfma_f32_32x32x16_bf16 v[16:31], v[170:173], v[60:63], v[16:31]
	v_and_b32_e32 v4, 0x7fffff80, v4
	v_and_b32_e32 v5, 0xffffff80, v8
	v_bitop3_b32 v179, v4, v109, v5 bitop3:0xde
	v_ashrrev_i32_e32 v4, 31, v9
	v_and_b32_e32 v8, 0x7fffff80, v4
	ds_read_b128 v[4:7], v101 offset:43648
	v_and_b32_e32 v9, 0xffffff80, v9
	s_waitcnt lgkmcnt(1)
	v_mfma_f32_32x32x16_bf16 v[16:31], v[0:3], v[56:59], v[16:31]
	v_ashrrev_i32_e32 v0, 31, v10
	v_and_b32_e32 v0, 0x7fffff80, v0
	v_and_b32_e32 v1, 0xffffff80, v10
	v_bitop3_b32 v181, v0, v111, v1 bitop3:0xde
	ds_read_b128 v[0:3], v101 offset:43680
	v_bitop3_b32 v180, v8, v110, v9 bitop3:0xde
	v_ashrrev_i32_e32 v8, 31, v11
	s_waitcnt lgkmcnt(1)
	v_mfma_f32_32x32x16_bf16 v[16:31], v[4:7], v[44:47], v[16:31]
	v_and_b32_e32 v4, 0x7fffff80, v8
	v_and_b32_e32 v5, 0xffffff80, v11
	v_bitop3_b32 v182, v4, v112, v5 bitop3:0xde
	v_ashrrev_i32_e32 v4, 31, v12
	v_and_b32_e32 v8, 0x7fffff80, v4
	ds_read_b128 v[4:7], v101 offset:43712
	v_and_b32_e32 v9, 0xffffff80, v12
	s_waitcnt lgkmcnt(1)
	v_mfma_f32_32x32x16_bf16 v[16:31], v[0:3], v[40:43], v[16:31]
	v_ashrrev_i32_e32 v0, 31, v13
	v_and_b32_e32 v0, 0x7fffff80, v0
	v_and_b32_e32 v1, 0xffffff80, v13
	v_bitop3_b32 v184, v0, v114, v1 bitop3:0xde
	ds_read_b128 v[0:3], v101 offset:43744
	v_bitop3_b32 v183, v8, v113, v9 bitop3:0xde
	v_ashrrev_i32_e32 v8, 31, v14
	s_waitcnt lgkmcnt(1)
	v_mfma_f32_32x32x16_bf16 v[16:31], v[4:7], v[36:39], v[16:31]
	v_and_b32_e32 v4, 0x7fffff80, v8
	v_and_b32_e32 v5, 0xffffff80, v14
	v_bitop3_b32 v185, v4, v115, v5 bitop3:0xde
	v_ashrrev_i32_e32 v4, 31, v15
	v_and_b32_e32 v4, 0x7fffff80, v4
	v_and_b32_e32 v5, 0xffffff80, v15
	v_bitop3_b32 v186, v4, v116, v5 bitop3:0xde
	s_waitcnt lgkmcnt(0)
; __device__ __forceinline__ int crow(int r, int hf) { return (r & 3) + 8 * (r >> 2) + 4 * hf; }
; __device__ __forceinline__ int tosort(float f) { int b = __float_as_int(f); return b ^ ((b >> 31) & 0x7fffffff); }
; template <int PP>
; __device__ __forceinline__ void select_half(const Params& p, const u16* Subs, int t, int hh, int lc, int hf, int* lists) {
;     ...
;     for (int ks = 0; ks < 8; ++ks) {
;       bf16x8 a = *(const bf16x8*)(Subs + (PP * 128 + nb * 32 + lc) * 136 + ks * 16 + hf * 8);
;       acc = mfma32(a, qf[ks], acc);
;     }
; #pragma unroll
;     for (int r = 0; r < 16; ++r) keys[nb * 16 + r] = (tosort(acc[r]) & ~127) | (nb * 32 + crow(r, hf));
	v_mfma_f32_32x32x16_bf16 v[16:31], v[0:3], v[32:35], v[16:31]
	ds_read_b128 v[170:173], v101 offset:52288
	s_nop 10
	v_ashrrev_i32_e32 v0, 31, v16
	v_and_b32_e32 v0, 0x7fffff80, v0
	v_and_b32_e32 v1, 0xffffff80, v16
	v_bitop3_b32 v187, v0, v117, v1 bitop3:0xde
	v_ashrrev_i32_e32 v0, 31, v17
	v_and_b32_e32 v0, 0x7fffff80, v0
	v_and_b32_e32 v1, 0xffffff80, v17
	v_bitop3_b32 v188, v0, v118, v1 bitop3:0xde
	v_ashrrev_i32_e32 v0, 31, v18
	v_and_b32_e32 v0, 0x7fffff80, v0
	v_and_b32_e32 v1, 0xffffff80, v18
	v_bitop3_b32 v190, v0, v119, v1 bitop3:0xde
	v_ashrrev_i32_e32 v0, 31, v19
	v_and_b32_e32 v4, 0x7fffff80, v0
	ds_read_b128 v[0:3], v101 offset:52224
	v_and_b32_e32 v5, 0xffffff80, v19
	v_bitop3_b32 v192, v4, v120, v5 bitop3:0xde
	v_ashrrev_i32_e32 v4, 31, v20
	v_and_b32_e32 v4, 0x7fffff80, v4
	v_and_b32_e32 v5, 0xffffff80, v20
	ds_read_b128 v[16:19], v101 offset:52256
	v_bitop3_b32 v193, v4, v121, v5 bitop3:0xde
	s_waitcnt lgkmcnt(1)
	v_mfma_f32_32x32x16_bf16 v[0:15], v[0:3], v[68:71], 0
	v_ashrrev_i32_e32 v20, 31, v21
	v_and_b32_e32 v20, 0x7fffff80, v20
	v_and_b32_e32 v21, 0xffffff80, v21
	v_bitop3_b32 v194, v20, v122, v21 bitop3:0xde
	v_ashrrev_i32_e32 v20, 31, v22
	v_and_b32_e32 v20, 0x7fffff80, v20
	v_and_b32_e32 v21, 0xffffff80, v22
	s_waitcnt lgkmcnt(0)
	v_mfma_f32_32x32x16_bf16 v[0:15], v[16:19], v[64:67], v[0:15]
	v_ashrrev_i32_e32 v16, 31, v23
	v_and_b32_e32 v16, 0x7fffff80, v16
	v_and_b32_e32 v17, 0xffffff80, v23
	v_bitop3_b32 v196, v16, v124, v17 bitop3:0xde
	ds_read_b128 v[16:19], v101 offset:52320
	v_bitop3_b32 v195, v20, v123, v21 bitop3:0xde
	v_ashrrev_i32_e32 v20, 31, v24
	v_mfma_f32_32x32x16_bf16 v[0:15], v[170:173], v[60:63], v[0:15]
	v_and_b32_e32 v20, 0x7fffff80, v20
	v_and_b32_e32 v21, 0xffffff80, v24
	v_bitop3_b32 v170, v20, v125, v21 bitop3:0xde
	v_ashrrev_i32_e32 v20, 31, v25
	v_and_b32_e32 v24, 0x7fffff80, v20
	ds_read_b128 v[20:23], v101 offset:52352
	v_and_b32_e32 v25, 0xffffff80, v25
	s_waitcnt lgkmcnt(1)
	v_mfma_f32_32x32x16_bf16 v[0:15], v[16:19], v[56:59], v[0:15]
	v_ashrrev_i32_e32 v16, 31, v26
	v_and_b32_e32 v16, 0x7fffff80, v16
	v_and_b32_e32 v17, 0xffffff80, v26
	v_bitop3_b32 v172, v16, v127, v17 bitop3:0xde
	ds_read_b128 v[16:19], v101 offset:52384
	v_bitop3_b32 v171, v24, v126, v25 bitop3:0xde
	v_ashrrev_i32_e32 v24, 31, v27
	s_waitcnt lgkmcnt(1)
	v_mfma_f32_32x32x16_bf16 v[0:15], v[20:23], v[44:47], v[0:15]
	v_and_b32_e32 v20, 0x7fffff80, v24
	v_and_b32_e32 v21, 0xffffff80, v27
	v_bitop3_b32 v173, v20, v128, v21 bitop3:0xde
	v_ashrrev_i32_e32 v20, 31, v28
	v_and_b32_e32 v24, 0x7fffff80, v20
	ds_read_b128 v[20:23], v101 offset:52416
	v_and_b32_e32 v25, 0xffffff80, v28
	s_waitcnt lgkmcnt(1)
	v_mfma_f32_32x32x16_bf16 v[0:15], v[16:19], v[40:43], v[0:15]
	v_ashrrev_i32_e32 v16, 31, v29
	v_and_b32_e32 v16, 0x7fffff80, v16
	v_and_b32_e32 v17, 0xffffff80, v29
	v_bitop3_b32 v198, v16, v130, v17 bitop3:0xde
	ds_read_b128 v[16:19], v101 offset:52448
	v_bitop3_b32 v197, v24, v129, v25 bitop3:0xde
	v_ashrrev_i32_e32 v24, 31, v30
	s_waitcnt lgkmcnt(1)
	v_mfma_f32_32x32x16_bf16 v[0:15], v[20:23], v[36:39], v[0:15]
	v_and_b32_e32 v20, 0x7fffff80, v24
	v_and_b32_e32 v21, 0xffffff80, v30
	v_bitop3_b32 v199, v20, v131, v21 bitop3:0xde
	v_ashrrev_i32_e32 v20, 31, v31
	v_and_b32_e32 v20, 0x7fffff80, v20
	v_and_b32_e32 v21, 0xffffff80, v31
	v_bitop3_b32 v200, v20, v132, v21 bitop3:0xde
	s_waitcnt lgkmcnt(0)
	v_mfma_f32_32x32x16_bf16 v[0:15], v[16:19], v[32:35], v[0:15]
	s_nop 11
	v_ashrrev_i32_e32 v16, 31, v0
	v_and_b32_e32 v16, 0x7fffff80, v16
	v_and_b32_e32 v0, 0xffffff80, v0
	v_bitop3_b32 v201, v16, v133, v0 bitop3:0xde
	v_ashrrev_i32_e32 v0, 31, v1
	ds_read_b128 v[16:19], v101 offset:60928
	v_and_b32_e32 v0, 0x7fffff80, v0
	v_and_b32_e32 v1, 0xffffff80, v1
	v_bitop3_b32 v202, v0, v134, v1 bitop3:0xde
	v_ashrrev_i32_e32 v0, 31, v2
	v_and_b32_e32 v0, 0x7fffff80, v0
	v_and_b32_e32 v1, 0xffffff80, v2
	v_bitop3_b32 v203, v0, v135, v1 bitop3:0xde
	v_ashrrev_i32_e32 v0, 31, v3
	v_and_b32_e32 v0, 0x7fffff80, v0
	v_and_b32_e32 v1, 0xffffff80, v3
	v_bitop3_b32 v204, v0, v136, v1 bitop3:0xde
	v_ashrrev_i32_e32 v0, 31, v4
	v_and_b32_e32 v0, 0x7fffff80, v0
	v_and_b32_e32 v1, 0xffffff80, v4
	v_bitop3_b32 v205, v0, v137, v1 bitop3:0xde
	ds_read_b128 v[0:3], v101 offset:60960
	s_waitcnt lgkmcnt(1)
	v_mfma_f32_32x32x16_bf16 v[16:31], v[16:19], v[68:71], 0
	ds_read_b128 v[68:71], v101 offset:60992
	v_ashrrev_i32_e32 v4, 31, v5
	v_and_b32_e32 v4, 0x7fffff80, v4
	v_and_b32_e32 v5, 0xffffff80, v5
	v_bitop3_b32 v206, v4, v138, v5 bitop3:0xde
	v_ashrrev_i32_e32 v4, 31, v6
	v_and_b32_e32 v4, 0x7fffff80, v4
	s_waitcnt lgkmcnt(1)
	v_mfma_f32_32x32x16_bf16 v[16:31], v[0:3], v[64:67], v[16:31]
	v_ashrrev_i32_e32 v0, 31, v7
	v_and_b32_e32 v0, 0x7fffff80, v0
	v_and_b32_e32 v1, 0xffffff80, v7
	v_bitop3_b32 v65, v0, v140, v1 bitop3:0xde
	ds_read_b128 v[0:3], v101 offset:61024
	v_and_b32_e32 v5, 0xffffff80, v6
	v_bitop3_b32 v64, v4, v139, v5 bitop3:0xde
	s_waitcnt lgkmcnt(1)
	v_mfma_f32_32x32x16_bf16 v[16:31], v[68:71], v[60:63], v[16:31]
	v_ashrrev_i32_e32 v4, 31, v8
	v_and_b32_e32 v4, 0x7fffff80, v4
	v_and_b32_e32 v5, 0xffffff80, v8
	v_bitop3_b32 v8, v4, v141, v5 bitop3:0xde
	v_ashrrev_i32_e32 v4, 31, v9
	v_and_b32_e32 v60, 0x7fffff80, v4
	ds_read_b128 v[4:7], v101 offset:61056
	s_waitcnt lgkmcnt(1)
	v_mfma_f32_32x32x16_bf16 v[16:31], v[0:3], v[56:59], v[16:31]
	v_ashrrev_i32_e32 v0, 31, v10
	v_and_b32_e32 v0, 0x7fffff80, v0
	v_and_b32_e32 v1, 0xffffff80, v10
	v_bitop3_b32 v10, v0, v143, v1 bitop3:0xde
	ds_read_b128 v[0:3], v101 offset:61088
	v_ashrrev_i32_e32 v56, 31, v11
	v_and_b32_e32 v9, 0xffffff80, v9
	s_waitcnt lgkmcnt(1)
; __device__ __forceinline__ int crow(int r, int hf) { return (r & 3) + 8 * (r >> 2) + 4 * hf; }
; __device__ __forceinline__ int tosort(float f) { int b = __float_as_int(f); return b ^ ((b >> 31) & 0x7fffffff); }
; template <int OFF>
; __device__ __forceinline__ void sort16_desc(int* a) {
; #pragma unroll
;   for (int ks = 1; ks <= 4; ++ks) {
; #pragma unroll
;     ...
; #pragma unroll
;       for (int i = 0; i < 16; ++i) {
;         const int k = 1 << ks, j = 1 << js;
;         const int l2 = i ^ j;
;         if (l2 > i) { if ((i & k) == 0) cas_desc(a[OFF + i], a[OFF + l2]); else cas_desc(a[OFF + l2], a[OFF + i]); }
;       }
;     }
;   }
; }
; template <int PP>
; __device__ __forceinline__ void select_half(const Params& p, const u16* Subs, int t, int hh, int lc, int hf, int* lists) {
;     ...
;     for (int ks = 0; ks < 8; ++ks) {
;       bf16x8 a = *(const bf16x8*)(Subs + (PP * 128 + nb * 32 + lc) * 136 + ks * 16 + hf * 8);
;       acc = mfma32(a, qf[ks], acc);
;     }
; #pragma unroll
;     for (int r = 0; r < 16; ++r) keys[nb * 16 + r] = (tosort(acc[r]) & ~127) | (nb * 32 + crow(r, hf));
	v_mfma_f32_32x32x16_bf16 v[16:31], v[4:7], v[44:47], v[16:31]
	v_and_b32_e32 v4, 0x7fffff80, v56
	v_and_b32_e32 v5, 0xffffff80, v11
	v_bitop3_b32 v11, v4, v144, v5 bitop3:0xde
	v_ashrrev_i32_e32 v4, 31, v12
	v_and_b32_e32 v44, 0x7fffff80, v4
	ds_read_b128 v[4:7], v101 offset:61120
	v_and_b32_e32 v12, 0xffffff80, v12
	s_waitcnt lgkmcnt(1)
	v_mfma_f32_32x32x16_bf16 v[16:31], v[0:3], v[40:43], v[16:31]
	v_ashrrev_i32_e32 v0, 31, v13
	v_and_b32_e32 v0, 0x7fffff80, v0
	v_and_b32_e32 v1, 0xffffff80, v13
	v_bitop3_b32 v13, v0, v146, v1 bitop3:0xde
	ds_read_b128 v[0:3], v101 offset:61152
	v_ashrrev_i32_e32 v40, 31, v14
	v_bitop3_b32 v9, v60, v142, v9 bitop3:0xde
	s_waitcnt lgkmcnt(1)
	v_mfma_f32_32x32x16_bf16 v[16:31], v[4:7], v[36:39], v[16:31]
	v_and_b32_e32 v4, 0x7fffff80, v40
	v_and_b32_e32 v5, 0xffffff80, v14
	v_bitop3_b32 v4, v4, v147, v5 bitop3:0xde
	v_ashrrev_i32_e32 v5, 31, v15
	v_and_b32_e32 v5, 0x7fffff80, v5
	v_and_b32_e32 v6, 0xffffff80, v15
	v_bitop3_b32 v5, v5, v148, v6 bitop3:0xde
	s_waitcnt lgkmcnt(0)
	v_mfma_f32_32x32x16_bf16 v[16:31], v[0:3], v[32:35], v[16:31]
	v_bitop3_b32 v12, v44, v145, v12 bitop3:0xde
	v_max_i32_e32 v32, v179, v180
	v_min_i32_e32 v33, v179, v180
	v_max_i32_e32 v34, v182, v181
	v_min_i32_e32 v35, v182, v181
	v_max_i32_e32 v36, v183, v184
	v_min_i32_e32 v37, v183, v184
	s_nop 4
	v_ashrrev_i32_e32 v0, 31, v16
	v_and_b32_e32 v0, 0x7fffff80, v0
	v_and_b32_e32 v1, 0xffffff80, v16
	v_bitop3_b32 v0, v0, v149, v1 bitop3:0xde
	v_ashrrev_i32_e32 v1, 31, v17
	v_and_b32_e32 v1, 0x7fffff80, v1
	v_and_b32_e32 v2, 0xffffff80, v17
	v_bitop3_b32 v1, v1, v150, v2 bitop3:0xde
	v_ashrrev_i32_e32 v2, 31, v18
	v_and_b32_e32 v2, 0x7fffff80, v2
	v_and_b32_e32 v3, 0xffffff80, v18
	v_bitop3_b32 v2, v2, v151, v3 bitop3:0xde
	v_ashrrev_i32_e32 v3, 31, v19
	v_and_b32_e32 v3, 0x7fffff80, v3
	v_and_b32_e32 v6, 0xffffff80, v19
	v_bitop3_b32 v3, v3, v152, v6 bitop3:0xde
	v_ashrrev_i32_e32 v6, 31, v20
	v_and_b32_e32 v6, 0x7fffff80, v6
	v_and_b32_e32 v7, 0xffffff80, v20
	v_bitop3_b32 v6, v6, v153, v7 bitop3:0xde
	v_ashrrev_i32_e32 v7, 31, v21
	v_and_b32_e32 v7, 0x7fffff80, v7
	v_and_b32_e32 v14, 0xffffff80, v21
	v_bitop3_b32 v7, v7, v154, v14 bitop3:0xde
	v_ashrrev_i32_e32 v14, 31, v22
	v_and_b32_e32 v14, 0x7fffff80, v14
	v_and_b32_e32 v15, 0xffffff80, v22
	v_bitop3_b32 v14, v14, v155, v15 bitop3:0xde
	v_ashrrev_i32_e32 v15, 31, v23
	v_and_b32_e32 v15, 0x7fffff80, v15
	v_and_b32_e32 v16, 0xffffff80, v23
	v_bitop3_b32 v15, v15, v156, v16 bitop3:0xde
	v_ashrrev_i32_e32 v16, 31, v24
	v_and_b32_e32 v16, 0x7fffff80, v16
	v_and_b32_e32 v17, 0xffffff80, v24
	v_bitop3_b32 v16, v16, v157, v17 bitop3:0xde
	v_ashrrev_i32_e32 v17, 31, v25
	v_and_b32_e32 v17, 0x7fffff80, v17
	v_and_b32_e32 v18, 0xffffff80, v25
	v_bitop3_b32 v17, v17, v158, v18 bitop3:0xde
	v_ashrrev_i32_e32 v18, 31, v26
	v_and_b32_e32 v18, 0x7fffff80, v18
	v_and_b32_e32 v19, 0xffffff80, v26
	v_bitop3_b32 v18, v18, v159, v19 bitop3:0xde
	v_ashrrev_i32_e32 v19, 31, v27
	v_and_b32_e32 v19, 0x7fffff80, v19
	v_and_b32_e32 v20, 0xffffff80, v27
	v_bitop3_b32 v19, v19, v160, v20 bitop3:0xde
	v_ashrrev_i32_e32 v20, 31, v28
	v_and_b32_e32 v20, 0x7fffff80, v20
	v_and_b32_e32 v21, 0xffffff80, v28
	v_bitop3_b32 v20, v20, v161, v21 bitop3:0xde
	v_ashrrev_i32_e32 v21, 31, v29
	v_and_b32_e32 v21, 0x7fffff80, v21
	v_and_b32_e32 v22, 0xffffff80, v29
	v_bitop3_b32 v21, v21, v162, v22 bitop3:0xde
	v_ashrrev_i32_e32 v22, 31, v30
	v_and_b32_e32 v22, 0x7fffff80, v22
	v_and_b32_e32 v23, 0xffffff80, v30
	v_bitop3_b32 v22, v22, v163, v23 bitop3:0xde
	v_ashrrev_i32_e32 v23, 31, v31
	v_and_b32_e32 v23, 0x7fffff80, v23
	v_and_b32_e32 v24, 0xffffff80, v31
	v_bitop3_b32 v23, v23, v164, v24 bitop3:0xde
	v_max_i32_e32 v24, v90, v96
	v_min_i32_e32 v25, v90, v96
	v_max_i32_e32 v26, v174, v97
	v_min_i32_e32 v27, v174, v97
	v_max_i32_e32 v28, v175, v176
	v_min_i32_e32 v29, v175, v176
	v_max_i32_e32 v30, v178, v177
	v_min_i32_e32 v31, v178, v177
	v_max_i32_e32 v38, v186, v185
	v_min_i32_e32 v39, v186, v185
	v_max_i32_e32 v56, v187, v188
	v_min_i32_e32 v57, v187, v188
	v_max_i32_e32 v58, v192, v190
	v_min_i32_e32 v59, v192, v190
	v_max_i32_e32 v60, v193, v194
	v_min_i32_e32 v61, v193, v194
	v_max_i32_e32 v62, v196, v195
	v_min_i32_e32 v63, v196, v195
	v_max_i32_e32 v66, v170, v171
	v_min_i32_e32 v67, v170, v171
	v_max_i32_e32 v68, v173, v172
	v_min_i32_e32 v69, v173, v172
	v_max_i32_e32 v70, v197, v198
	v_min_i32_e32 v71, v197, v198
	v_max_i32_e32 v90, v200, v199
	v_min_i32_e32 v96, v200, v199
	v_max_i32_e32 v177, v201, v202
	v_min_i32_e32 v178, v201, v202
	v_max_i32_e32 v179, v204, v203
	v_min_i32_e32 v180, v204, v203
	v_max_i32_e32 v181, v205, v206
	v_min_i32_e32 v182, v205, v206
	v_max_i32_e32 v183, v65, v64
	v_min_i32_e32 v64, v65, v64
	v_max_i32_e32 v65, v8, v9
	v_min_i32_e32 v8, v8, v9
	v_max_i32_e32 v9, v11, v10
	v_min_i32_e32 v10, v11, v10
	v_max_i32_e32 v11, v12, v13
	v_min_i32_e32 v12, v12, v13
	v_max_i32_e32 v13, v5, v4
	v_min_i32_e32 v4, v5, v4
	v_max_i32_e32 v193, v0, v1
	v_min_i32_e32 v0, v0, v1
	v_max_i32_e32 v1, v3, v2
	v_min_i32_e32 v2, v3, v2
	v_max_i32_e32 v3, v6, v7
	v_min_i32_e32 v6, v6, v7
	v_max_i32_e32 v7, v15, v14
	v_min_i32_e32 v14, v15, v14
	v_max_i32_e32 v15, v16, v17
	v_min_i32_e32 v16, v16, v17
	v_max_i32_e32 v17, v19, v18
	v_min_i32_e32 v18, v19, v18
	v_max_i32_e32 v19, v20, v21
	v_min_i32_e32 v20, v20, v21
	v_max_i32_e32 v21, v23, v22
	v_min_i32_e32 v22, v23, v22
	v_max_i32_e32 v40, v24, v27
	v_min_i32_e32 v24, v24, v27
	v_max_i32_e32 v27, v25, v26
	v_min_i32_e32 v25, v25, v26
	v_max_i32_e32 v26, v31, v28
	v_min_i32_e32 v28, v31, v28
	v_max_i32_e32 v31, v30, v29
	v_min_i32_e32 v29, v30, v29
; template <int OFF>
; __device__ __forceinline__ void sort16_desc(int* a) {
; #pragma unroll
;   for (int ks = 1; ks <= 4; ++ks) {
; #pragma unroll
;     ...
; #pragma unroll
;       for (int i = 0; i < 16; ++i) {
;         const int k = 1 << ks, j = 1 << js;
;         const int l2 = i ^ j;
;         if (l2 > i) { if ((i & k) == 0) cas_desc(a[OFF + i], a[OFF + l2]); else cas_desc(a[OFF + l2], a[OFF + i]); }
;       }
;     }
;   }
; }
	v_max_i32_e32 v30, v32, v35
	v_min_i32_e32 v32, v32, v35
	v_max_i32_e32 v35, v33, v34
	v_min_i32_e32 v33, v33, v34
	v_max_i32_e32 v34, v39, v36
	v_min_i32_e32 v36, v39, v36
	v_max_i32_e32 v39, v38, v37
	v_min_i32_e32 v37, v38, v37
	v_max_i32_e32 v97, v56, v59
	v_min_i32_e32 v56, v56, v59
	v_max_i32_e32 v59, v57, v58
	v_min_i32_e32 v57, v57, v58
	v_max_i32_e32 v58, v63, v60
	v_min_i32_e32 v60, v63, v60
	v_max_i32_e32 v63, v62, v61
	v_min_i32_e32 v61, v62, v61
	v_max_i32_e32 v62, v66, v69
	v_min_i32_e32 v66, v66, v69
	v_max_i32_e32 v69, v67, v68
	v_min_i32_e32 v67, v67, v68
	v_max_i32_e32 v68, v96, v70
	v_min_i32_e32 v70, v96, v70
	v_max_i32_e32 v96, v90, v71
	v_min_i32_e32 v71, v90, v71
	v_max_i32_e32 v5, v177, v180
	v_min_i32_e32 v177, v177, v180
	v_max_i32_e32 v180, v178, v179
	v_min_i32_e32 v178, v178, v179
	v_max_i32_e32 v179, v64, v181
	v_min_i32_e32 v64, v64, v181
	v_max_i32_e32 v181, v183, v182
	v_min_i32_e32 v182, v183, v182
	v_max_i32_e32 v183, v65, v10
	v_min_i32_e32 v10, v65, v10
	v_max_i32_e32 v65, v8, v9
	v_min_i32_e32 v8, v8, v9
	v_max_i32_e32 v9, v4, v11
	v_min_i32_e32 v4, v4, v11
	v_max_i32_e32 v11, v13, v12
	v_min_i32_e32 v12, v13, v12
	v_max_i32_e32 v23, v193, v2
	v_min_i32_e32 v2, v193, v2
	v_max_i32_e32 v193, v0, v1
	v_min_i32_e32 v0, v0, v1
	v_max_i32_e32 v1, v14, v3
	v_min_i32_e32 v3, v14, v3
	v_max_i32_e32 v14, v7, v6
	v_min_i32_e32 v6, v7, v6
	v_max_i32_e32 v7, v15, v18
	v_min_i32_e32 v15, v15, v18
	v_max_i32_e32 v18, v16, v17
	v_min_i32_e32 v16, v16, v17
	v_max_i32_e32 v17, v22, v19
	v_min_i32_e32 v19, v22, v19
	v_max_i32_e32 v22, v21, v20
	v_min_i32_e32 v20, v21, v20
	v_max_i32_e32 v38, v40, v27
	v_min_i32_e32 v27, v40, v27
	v_max_i32_e32 v40, v24, v25
	v_min_i32_e32 v24, v24, v25
	v_max_i32_e32 v25, v29, v28
	v_min_i32_e32 v28, v29, v28
	v_max_i32_e32 v29, v31, v26
	v_min_i32_e32 v26, v31, v26
	v_max_i32_e32 v31, v30, v35
	v_min_i32_e32 v30, v30, v35
	v_max_i32_e32 v35, v32, v33
	v_min_i32_e32 v32, v32, v33
	v_max_i32_e32 v33, v37, v36
	v_min_i32_e32 v36, v37, v36
	v_max_i32_e32 v37, v39, v34
	v_min_i32_e32 v34, v39, v34
	v_max_i32_e32 v90, v97, v59
	v_min_i32_e32 v59, v97, v59
	v_max_i32_e32 v97, v56, v57
	v_min_i32_e32 v56, v56, v57
	v_max_i32_e32 v57, v61, v60
	v_min_i32_e32 v60, v61, v60
	v_max_i32_e32 v61, v63, v58
	v_min_i32_e32 v58, v63, v58
	v_max_i32_e32 v63, v62, v69
	v_min_i32_e32 v62, v62, v69
	v_max_i32_e32 v69, v66, v67
	v_min_i32_e32 v66, v66, v67
	v_max_i32_e32 v67, v71, v70
	v_min_i32_e32 v70, v71, v70
	v_max_i32_e32 v71, v96, v68
	v_min_i32_e32 v68, v96, v68
	v_max_i32_e32 v13, v5, v180
	v_min_i32_e32 v5, v5, v180
	v_max_i32_e32 v180, v177, v178
	v_min_i32_e32 v177, v177, v178
	v_max_i32_e32 v178, v182, v64
	v_min_i32_e32 v64, v182, v64
	v_max_i32_e32 v182, v181, v179
	v_min_i32_e32 v179, v181, v179
	v_max_i32_e32 v181, v183, v65
	v_min_i32_e32 v65, v183, v65
	v_max_i32_e32 v183, v10, v8
	v_min_i32_e32 v8, v10, v8
	v_max_i32_e32 v10, v12, v4
	v_min_i32_e32 v4, v12, v4
	v_max_i32_e32 v12, v11, v9
	v_min_i32_e32 v9, v11, v9
	v_max_i32_e32 v21, v23, v193
	v_min_i32_e32 v23, v23, v193
	v_max_i32_e32 v193, v2, v0
	v_min_i32_e32 v0, v2, v0
	v_max_i32_e32 v2, v6, v3
	v_min_i32_e32 v3, v6, v3
	v_max_i32_e32 v6, v14, v1
	v_min_i32_e32 v1, v14, v1
	v_max_i32_e32 v14, v7, v18
	v_min_i32_e32 v7, v7, v18
	v_max_i32_e32 v18, v15, v16
	v_min_i32_e32 v15, v15, v16
	v_max_i32_e32 v16, v20, v19
	v_min_i32_e32 v19, v20, v19
	v_max_i32_e32 v20, v22, v17
	v_min_i32_e32 v17, v22, v17
	v_max_i32_e32 v39, v38, v28
	v_min_i32_e32 v28, v38, v28
	v_max_i32_e32 v38, v27, v25
	v_min_i32_e32 v25, v27, v25
	v_max_i32_e32 v27, v40, v26
	v_min_i32_e32 v26, v40, v26
	v_max_i32_e32 v40, v24, v29
	v_min_i32_e32 v24, v24, v29
	v_max_i32_e32 v29, v36, v31
	v_min_i32_e32 v31, v36, v31
	v_max_i32_e32 v36, v33, v30
	v_min_i32_e32 v30, v33, v30
	v_max_i32_e32 v33, v34, v35
	v_min_i32_e32 v34, v34, v35
	v_max_i32_e32 v35, v37, v32
	v_min_i32_e32 v32, v37, v32
	v_max_i32_e32 v96, v90, v60
	v_min_i32_e32 v60, v90, v60
	v_max_i32_e32 v90, v59, v57
	v_min_i32_e32 v57, v59, v57
	v_max_i32_e32 v59, v97, v58
	v_min_i32_e32 v58, v97, v58
	v_max_i32_e32 v97, v56, v61
	v_min_i32_e32 v56, v56, v61
	v_max_i32_e32 v61, v70, v63
	v_min_i32_e32 v63, v70, v63
	v_max_i32_e32 v70, v67, v62
	v_min_i32_e32 v62, v67, v62
	v_max_i32_e32 v67, v68, v69
	v_min_i32_e32 v68, v68, v69
	v_max_i32_e32 v69, v71, v66
	v_min_i32_e32 v66, v71, v66
	v_max_i32_e32 v11, v13, v64
	v_min_i32_e32 v13, v13, v64
	v_max_i32_e32 v64, v5, v178
	v_min_i32_e32 v5, v5, v178
	v_max_i32_e32 v178, v180, v179
	v_min_i32_e32 v179, v180, v179
	v_max_i32_e32 v180, v177, v182
	v_min_i32_e32 v177, v177, v182
	v_max_i32_e32 v182, v4, v181
	v_min_i32_e32 v4, v4, v181
	v_max_i32_e32 v181, v10, v65
	v_min_i32_e32 v10, v10, v65
	v_max_i32_e32 v65, v9, v183
	v_min_i32_e32 v9, v9, v183
	v_max_i32_e32 v183, v12, v8
	v_min_i32_e32 v8, v12, v8
	v_max_i32_e32 v22, v21, v3
	v_min_i32_e32 v3, v21, v3
	v_max_i32_e32 v21, v23, v2
	v_min_i32_e32 v2, v23, v2
	v_max_i32_e32 v23, v193, v1
	v_min_i32_e32 v1, v193, v1
	v_max_i32_e32 v193, v0, v6
	v_min_i32_e32 v0, v0, v6
	v_max_i32_e32 v6, v19, v14
	v_min_i32_e32 v14, v19, v14
	v_max_i32_e32 v19, v16, v7
	v_min_i32_e32 v7, v16, v7
	v_max_i32_e32 v16, v17, v18
	v_min_i32_e32 v17, v17, v18
	v_max_i32_e32 v18, v20, v15
	v_min_i32_e32 v15, v20, v15
	v_max_i32_e32 v37, v39, v27
	v_min_i32_e32 v27, v39, v27
	v_max_i32_e32 v39, v38, v40
	v_min_i32_e32 v38, v38, v40
	v_max_i32_e32 v40, v28, v26
	v_min_i32_e32 v26, v28, v26
	v_max_i32_e32 v28, v25, v24
	v_min_i32_e32 v24, v25, v24
	v_max_i32_e32 v25, v34, v31
	v_min_i32_e32 v31, v34, v31
	v_max_i32_e32 v34, v32, v30
; template <int OFF>
; __device__ __forceinline__ void sort16_desc(int* a) {
; #pragma unroll
;   for (int ks = 1; ks <= 4; ++ks) {
; #pragma unroll
;     ...
; #pragma unroll
;       for (int i = 0; i < 16; ++i) {
;         const int k = 1 << ks, j = 1 << js;
;         const int l2 = i ^ j;
;         if (l2 > i) { if ((i & k) == 0) cas_desc(a[OFF + i], a[OFF + l2]); else cas_desc(a[OFF + l2], a[OFF + i]); }
;       }
;     }
;   }
; }
	v_min_i32_e32 v30, v32, v30
	v_max_i32_e32 v32, v33, v29
	v_min_i32_e32 v29, v33, v29
	v_max_i32_e32 v33, v35, v36
	v_min_i32_e32 v35, v35, v36
	v_max_i32_e32 v71, v96, v59
	v_min_i32_e32 v59, v96, v59
	v_max_i32_e32 v96, v90, v97
	v_min_i32_e32 v90, v90, v97
	v_max_i32_e32 v97, v60, v58
	v_min_i32_e32 v58, v60, v58
	v_max_i32_e32 v60, v57, v56
	v_min_i32_e32 v56, v57, v56
	v_max_i32_e32 v57, v68, v63
	v_min_i32_e32 v63, v68, v63
	v_max_i32_e32 v68, v66, v62
	v_min_i32_e32 v62, v66, v62
	v_max_i32_e32 v66, v67, v61
	v_min_i32_e32 v61, v67, v61
	v_max_i32_e32 v67, v69, v70
	v_min_i32_e32 v69, v69, v70
	v_max_i32_e32 v12, v11, v178
	v_min_i32_e32 v11, v11, v178
	v_max_i32_e32 v178, v64, v180
	v_min_i32_e32 v64, v64, v180
	v_max_i32_e32 v180, v13, v179
	v_min_i32_e32 v13, v13, v179
	v_max_i32_e32 v179, v5, v177
	v_min_i32_e32 v5, v5, v177
	v_max_i32_e32 v177, v9, v4
	v_min_i32_e32 v4, v9, v4
	v_max_i32_e32 v9, v8, v10
	v_min_i32_e32 v8, v8, v10
	v_max_i32_e32 v10, v65, v182
	v_min_i32_e32 v65, v65, v182
	v_max_i32_e32 v182, v183, v181
	v_min_i32_e32 v181, v183, v181
	v_max_i32_e32 v20, v22, v23
	v_min_i32_e32 v22, v22, v23
	v_max_i32_e32 v23, v21, v193
	v_min_i32_e32 v21, v21, v193
	v_max_i32_e32 v193, v3, v1
	v_min_i32_e32 v1, v3, v1
	v_max_i32_e32 v3, v2, v0
	v_min_i32_e32 v0, v2, v0
	v_max_i32_e32 v2, v17, v14
	v_min_i32_e32 v14, v17, v14
	v_max_i32_e32 v17, v15, v7
	v_min_i32_e32 v7, v15, v7
	v_max_i32_e32 v15, v16, v6
	v_min_i32_e32 v6, v16, v6
	v_max_i32_e32 v16, v18, v19
	v_min_i32_e32 v18, v18, v19
	v_max_i32_e32 v36, v37, v39
	v_min_i32_e32 v37, v37, v39
	v_max_i32_e32 v39, v27, v38
	v_min_i32_e32 v27, v27, v38
	v_max_i32_e32 v38, v40, v28
	v_min_i32_e32 v28, v40, v28
	v_max_i32_e32 v40, v26, v24
	v_min_i32_e32 v24, v26, v24
	v_max_i32_e32 v26, v30, v31
	v_min_i32_e32 v30, v30, v31
	v_max_i32_e32 v31, v34, v25
	v_min_i32_e32 v25, v34, v25
	v_max_i32_e32 v34, v35, v29
	v_min_i32_e32 v29, v35, v29
	v_max_i32_e32 v35, v33, v32
	v_min_i32_e32 v32, v33, v32
	v_max_i32_e32 v70, v71, v96
	v_min_i32_e32 v71, v71, v96
	v_max_i32_e32 v96, v59, v90
	v_min_i32_e32 v59, v59, v90
	v_max_i32_e32 v90, v97, v60
	v_min_i32_e32 v60, v97, v60
	v_max_i32_e32 v97, v58, v56
	v_min_i32_e32 v56, v58, v56
	v_max_i32_e32 v58, v62, v63
	v_min_i32_e32 v62, v62, v63
	v_max_i32_e32 v63, v68, v57
	v_min_i32_e32 v57, v68, v57
	v_max_i32_e32 v68, v69, v61
	v_min_i32_e32 v61, v69, v61
	v_max_i32_e32 v69, v67, v66
	v_min_i32_e32 v66, v67, v66
	v_max_i32_e32 v183, v12, v178
	v_min_i32_e32 v12, v12, v178
	v_max_i32_e32 v178, v11, v64
	v_min_i32_e32 v11, v11, v64
	v_max_i32_e32 v64, v180, v179
	v_min_i32_e32 v179, v180, v179
	v_max_i32_e32 v180, v13, v5
	v_min_i32_e32 v5, v13, v5
	v_max_i32_e32 v13, v8, v4
	v_min_i32_e32 v4, v8, v4
	v_max_i32_e32 v8, v9, v177
	v_min_i32_e32 v9, v9, v177
	v_max_i32_e32 v177, v181, v65
	v_min_i32_e32 v65, v181, v65
	v_max_i32_e32 v181, v182, v10
	v_min_i32_e32 v10, v182, v10
	v_max_i32_e32 v19, v20, v23
	v_min_i32_e32 v20, v20, v23
	v_max_i32_e32 v23, v22, v21
	v_min_i32_e32 v21, v22, v21
	v_max_i32_e32 v22, v193, v3
	v_min_i32_e32 v3, v193, v3
	v_max_i32_e32 v193, v1, v0
	v_min_i32_e32 v0, v1, v0
	v_max_i32_e32 v1, v7, v14
	v_min_i32_e32 v7, v7, v14
	v_max_i32_e32 v14, v17, v2
	v_min_i32_e32 v2, v17, v2
	v_max_i32_e32 v17, v18, v6
	v_min_i32_e32 v6, v18, v6
	v_max_i32_e32 v18, v16, v15
	v_min_i32_e32 v15, v16, v15
	v_max_i32_e32 v33, v36, v30
	v_min_i32_e32 v30, v36, v30
	v_max_i32_e32 v36, v37, v26
	v_min_i32_e32 v26, v37, v26
	v_max_i32_e32 v37, v39, v25
	v_min_i32_e32 v25, v39, v25
	v_max_i32_e32 v39, v27, v31
	v_min_i32_e32 v27, v27, v31
	v_max_i32_e32 v31, v38, v29
	v_min_i32_e32 v29, v38, v29
	v_max_i32_e32 v38, v28, v34
	v_min_i32_e32 v28, v28, v34
	v_max_i32_e32 v34, v40, v32
	v_min_i32_e32 v32, v40, v32
	v_max_i32_e32 v40, v24, v35
	v_min_i32_e32 v24, v24, v35
	v_max_i32_e32 v67, v70, v62
	v_min_i32_e32 v62, v70, v62
	v_max_i32_e32 v70, v71, v58
	v_min_i32_e32 v58, v71, v58
	v_max_i32_e32 v71, v96, v57
	v_min_i32_e32 v57, v96, v57
	v_max_i32_e32 v96, v59, v63
	v_min_i32_e32 v59, v59, v63
	v_max_i32_e32 v63, v90, v61
	v_min_i32_e32 v61, v90, v61
	v_max_i32_e32 v90, v60, v68
	v_min_i32_e32 v60, v60, v68
	v_max_i32_e32 v68, v97, v66
	v_min_i32_e32 v66, v97, v66
	v_max_i32_e32 v97, v56, v69
	v_min_i32_e32 v56, v56, v69
	v_max_i32_e32 v182, v183, v4
	v_min_i32_e32 v4, v183, v4
	v_max_i32_e32 v183, v12, v13
	v_min_i32_e32 v12, v12, v13
	v_max_i32_e32 v13, v178, v9
	v_min_i32_e32 v9, v178, v9
	v_max_i32_e32 v178, v11, v8
	v_min_i32_e32 v8, v11, v8
	v_max_i32_e32 v11, v64, v65
	v_min_i32_e32 v64, v64, v65
	v_max_i32_e32 v65, v179, v177
	v_min_i32_e32 v177, v179, v177
	v_max_i32_e32 v179, v180, v10
	v_min_i32_e32 v10, v180, v10
	v_max_i32_e32 v180, v5, v181
	v_min_i32_e32 v5, v5, v181
	v_max_i32_e32 v16, v19, v7
	v_min_i32_e32 v7, v19, v7
	v_max_i32_e32 v19, v20, v1
	v_min_i32_e32 v1, v20, v1
	v_max_i32_e32 v20, v23, v2
	v_min_i32_e32 v2, v23, v2
	v_max_i32_e32 v23, v21, v14
	v_min_i32_e32 v14, v21, v14
	v_max_i32_e32 v21, v22, v6
	v_min_i32_e32 v6, v22, v6
	v_max_i32_e32 v22, v3, v17
	v_min_i32_e32 v3, v3, v17
	v_max_i32_e32 v17, v193, v15
	v_min_i32_e32 v15, v193, v15
	v_max_i32_e32 v193, v0, v18
	v_min_i32_e32 v0, v0, v18
	v_max_i32_e32 v35, v33, v31
	v_min_i32_e32 v31, v33, v31
	v_max_i32_e32 v33, v36, v38
	v_min_i32_e32 v36, v36, v38
	v_max_i32_e32 v38, v37, v34
	v_min_i32_e32 v34, v37, v34
	v_max_i32_e32 v37, v39, v40
	v_min_i32_e32 v39, v39, v40
	v_max_i32_e32 v40, v30, v29
	v_min_i32_e32 v29, v30, v29
	v_max_i32_e32 v30, v26, v28
	v_min_i32_e32 v26, v26, v28
	v_max_i32_e32 v28, v25, v32
	v_min_i32_e32 v25, v25, v32
; template <int OFF>
; __device__ __forceinline__ void sort16_desc(int* a) {
; #pragma unroll
;   for (int ks = 1; ks <= 4; ++ks) {
; #pragma unroll
;     ...
; #pragma unroll
;       for (int i = 0; i < 16; ++i) {
;         const int k = 1 << ks, j = 1 << js;
;         const int l2 = i ^ j;
;         if (l2 > i) { if ((i & k) == 0) cas_desc(a[OFF + i], a[OFF + l2]); else cas_desc(a[OFF + l2], a[OFF + i]); }
;       }
;     }
;   }
; }
; template <int OA, int OB>
; __device__ __forceinline__ void merge16(int* a, const int* b) {
; #pragma unroll
;   for (int i = 0; i < 16; ++i) a[OA + i] = max(a[OA + i], b[OB + 15 - i]);
; #pragma unroll
;     ...
; #pragma unroll
;     for (int i = 0; i < 16; ++i) {
;       const int j = 1 << js; const int l2 = i ^ j;
;       if (l2 > i) cas_desc(a[OA + i], a[OA + l2]);
;     }
;   }
; }
; template <int PP>
; __device__ __forceinline__ void select_half(const Params& p, const u16* Subs, int t, int hh, int lc, int hf, int* lists) {
;     ...
;   sort16_desc<0>(keys); sort16_desc<16>(keys); sort16_desc<32>(keys); sort16_desc<48>(keys);
;   merge16<0, 16>(keys, keys); merge16<32, 48>(keys, keys); merge16<0, 32>(keys, keys);
	v_max_i32_e32 v32, v27, v24
	v_min_i32_e32 v24, v27, v24
	v_max_i32_e32 v69, v67, v63
	v_min_i32_e32 v63, v67, v63
	v_max_i32_e32 v67, v70, v90
	v_min_i32_e32 v70, v70, v90
	v_max_i32_e32 v90, v71, v68
	v_min_i32_e32 v68, v71, v68
	v_max_i32_e32 v71, v96, v97
	v_min_i32_e32 v96, v96, v97
	v_max_i32_e32 v97, v62, v61
	v_min_i32_e32 v61, v62, v61
	v_max_i32_e32 v62, v58, v60
	v_min_i32_e32 v58, v58, v60
	v_max_i32_e32 v60, v57, v66
	v_min_i32_e32 v57, v57, v66
	v_max_i32_e32 v66, v59, v56
	v_min_i32_e32 v56, v59, v56
	v_max_i32_e32 v181, v182, v11
	v_min_i32_e32 v11, v182, v11
	v_max_i32_e32 v182, v183, v65
	v_min_i32_e32 v65, v183, v65
	v_max_i32_e32 v183, v13, v179
	v_min_i32_e32 v13, v13, v179
	v_max_i32_e32 v179, v178, v180
	v_min_i32_e32 v178, v178, v180
	v_max_i32_e32 v180, v4, v64
	v_min_i32_e32 v4, v4, v64
	v_max_i32_e32 v64, v12, v177
	v_min_i32_e32 v12, v12, v177
	v_max_i32_e32 v177, v9, v10
	v_min_i32_e32 v9, v9, v10
	v_max_i32_e32 v10, v8, v5
	v_min_i32_e32 v5, v8, v5
	v_max_i32_e32 v18, v16, v21
	v_min_i32_e32 v16, v16, v21
	v_max_i32_e32 v21, v19, v22
	v_min_i32_e32 v19, v19, v22
	v_max_i32_e32 v22, v20, v17
	v_min_i32_e32 v17, v20, v17
	v_max_i32_e32 v20, v23, v193
	v_min_i32_e32 v23, v23, v193
	v_max_i32_e32 v193, v7, v6
	v_min_i32_e32 v6, v7, v6
	v_max_i32_e32 v7, v1, v3
	v_min_i32_e32 v1, v1, v3
	v_max_i32_e32 v3, v2, v15
	v_min_i32_e32 v2, v2, v15
	v_max_i32_e32 v15, v14, v0
	v_min_i32_e32 v0, v14, v0
	v_max_i32_e32 v27, v35, v38
	v_min_i32_e32 v35, v35, v38
	v_max_i32_e32 v38, v33, v37
	v_min_i32_e32 v33, v33, v37
	v_max_i32_e32 v37, v31, v34
	v_min_i32_e32 v31, v31, v34
	v_max_i32_e32 v34, v36, v39
	v_min_i32_e32 v36, v36, v39
	v_max_i32_e32 v39, v40, v28
	v_min_i32_e32 v28, v40, v28
	v_max_i32_e32 v40, v30, v32
	v_min_i32_e32 v30, v30, v32
	v_max_i32_e32 v32, v29, v25
	v_min_i32_e32 v25, v29, v25
	v_max_i32_e32 v29, v26, v24
	v_min_i32_e32 v24, v26, v24
	v_max_i32_e32 v59, v69, v90
	v_min_i32_e32 v69, v69, v90
	v_max_i32_e32 v90, v67, v71
	v_min_i32_e32 v67, v67, v71
	v_max_i32_e32 v71, v63, v68
	v_min_i32_e32 v63, v63, v68
	v_max_i32_e32 v68, v70, v96
	v_min_i32_e32 v70, v70, v96
	v_max_i32_e32 v96, v97, v60
	v_min_i32_e32 v60, v97, v60
	v_max_i32_e32 v97, v62, v66
	v_min_i32_e32 v62, v62, v66
	v_max_i32_e32 v66, v61, v57
	v_min_i32_e32 v57, v61, v57
	v_max_i32_e32 v61, v58, v56
	v_min_i32_e32 v56, v58, v56
	v_max_i32_e32 v8, v181, v183
	v_min_i32_e32 v181, v181, v183
	v_max_i32_e32 v183, v182, v179
	v_min_i32_e32 v179, v182, v179
	v_max_i32_e32 v182, v11, v13
	v_min_i32_e32 v11, v11, v13
	v_max_i32_e32 v13, v65, v178
	v_min_i32_e32 v65, v65, v178
	v_max_i32_e32 v178, v180, v177
	v_min_i32_e32 v177, v180, v177
	v_max_i32_e32 v180, v64, v10
	v_min_i32_e32 v10, v64, v10
	v_max_i32_e32 v64, v4, v9
	v_min_i32_e32 v4, v4, v9
	v_max_i32_e32 v9, v12, v5
	v_min_i32_e32 v5, v12, v5
	v_max_i32_e32 v14, v18, v22
	v_min_i32_e32 v18, v18, v22
	v_max_i32_e32 v22, v21, v20
	v_min_i32_e32 v20, v21, v20
	v_max_i32_e32 v21, v16, v17
	v_min_i32_e32 v16, v16, v17
	v_max_i32_e32 v17, v19, v23
	v_min_i32_e32 v19, v19, v23
	v_max_i32_e32 v23, v193, v3
	v_min_i32_e32 v3, v193, v3
	v_max_i32_e32 v193, v7, v15
	v_min_i32_e32 v7, v7, v15
	v_max_i32_e32 v15, v6, v2
	v_min_i32_e32 v2, v6, v2
	v_max_i32_e32 v6, v1, v0
	v_min_i32_e32 v0, v1, v0
	v_min_i32_e32 v26, v27, v38
	v_min_i32_e32 v41, v35, v33
	v_min_i32_e32 v42, v37, v34
	v_min_i32_e32 v43, v31, v36
	v_min_i32_e32 v44, v39, v40
	v_min_i32_e32 v45, v28, v30
	v_min_i32_e32 v46, v32, v29
	v_min_i32_e32 v47, v25, v24
	v_min_i32_e32 v58, v59, v90
	v_min_i32_e32 v170, v69, v67
	v_min_i32_e32 v171, v71, v68
	v_min_i32_e32 v172, v63, v70
	v_min_i32_e32 v173, v96, v97
	v_min_i32_e32 v174, v60, v62
	v_min_i32_e32 v175, v66, v61
	v_min_i32_e32 v176, v57, v56
	v_min_i32_e32 v12, v8, v183
	v_min_i32_e32 v184, v181, v179
	v_min_i32_e32 v185, v182, v13
	v_min_i32_e32 v186, v11, v65
	v_min_i32_e32 v187, v178, v180
	v_min_i32_e32 v188, v177, v10
	v_min_i32_e32 v190, v64, v9
	v_min_i32_e32 v192, v4, v5
	v_min_i32_e32 v1, v14, v22
	v_min_i32_e32 v194, v18, v20
	v_min_i32_e32 v195, v21, v17
	v_min_i32_e32 v196, v16, v19
	v_min_i32_e32 v197, v23, v193
	v_min_i32_e32 v198, v3, v7
	v_min_i32_e32 v199, v15, v6
	v_min_i32_e32 v200, v2, v0
	v_max3_i32 v27, v27, v38, v176
	v_max3_i32 v26, v26, v57, v56
	v_max3_i32 v33, v35, v33, v175
	v_max3_i32 v35, v41, v66, v61
	v_max3_i32 v34, v37, v34, v174
	v_max3_i32 v37, v42, v60, v62
	v_max3_i32 v31, v31, v36, v173
	v_max3_i32 v36, v43, v96, v97
	v_max3_i32 v38, v39, v40, v172
	v_max3_i32 v39, v44, v63, v70
	v_max3_i32 v28, v28, v30, v171
	v_max3_i32 v30, v45, v71, v68
	v_max3_i32 v29, v32, v29, v170
	v_max3_i32 v32, v46, v69, v67
	v_max3_i32 v24, v25, v24, v58
	v_max3_i32 v25, v47, v59, v90
	v_max3_i32 v8, v8, v183, v200
	v_max3_i32 v0, v12, v2, v0
	v_max3_i32 v2, v181, v179, v199
	v_max3_i32 v6, v184, v15, v6
	v_max3_i32 v12, v182, v13, v198
	v_max3_i32 v3, v185, v3, v7
	v_max3_i32 v7, v11, v65, v197
	v_max3_i32 v11, v186, v23, v193
	v_max3_i32 v13, v178, v180, v196
	v_max3_i32 v15, v187, v16, v19
	v_max3_i32 v10, v177, v10, v195
	v_max3_i32 v16, v188, v21, v17
	v_max3_i32 v9, v64, v9, v194
	v_max3_i32 v17, v190, v18, v20
	v_max3_i32 v1, v4, v5, v1
	v_max3_i32 v4, v192, v14, v22
	v_max_i32_e32 v40, v27, v38
	v_min_i32_e32 v27, v27, v38
	v_max_i32_e32 v38, v26, v39
	v_min_i32_e32 v26, v26, v39
	v_max_i32_e32 v39, v33, v28
	v_min_i32_e32 v28, v33, v28
	v_max_i32_e32 v33, v35, v30
	v_min_i32_e32 v30, v35, v30
	v_max_i32_e32 v35, v34, v29
	v_min_i32_e32 v29, v34, v29
	v_max_i32_e32 v34, v37, v32
	v_min_i32_e32 v32, v37, v32
	v_max_i32_e32 v37, v31, v24
	v_min_i32_e32 v24, v31, v24
; template <int OA, int OB>
; __device__ __forceinline__ void merge16(int* a, const int* b) {
; #pragma unroll
;   for (int i = 0; i < 16; ++i) a[OA + i] = max(a[OA + i], b[OB + 15 - i]);
; #pragma unroll
;     ...
; #pragma unroll
;     for (int i = 0; i < 16; ++i) {
;       const int j = 1 << js; const int l2 = i ^ j;
;       if (l2 > i) cas_desc(a[OA + i], a[OA + l2]);
;     }
;   }
; }
; template <int PP>
; __device__ __forceinline__ void select_half(const Params& p, const u16* Subs, int t, int hh, int lc, int hf, int* lists) {
;     ...
;   merge16<0, 16>(keys, keys); merge16<32, 48>(keys, keys); merge16<0, 32>(keys, keys);
;   int other[16];
; #pragma unroll
;   for (int i = 0; i < 16; ++i) other[i] = __shfl_xor(keys[i], 32);
;   merge16<0, 0>(keys, other);
	v_max_i32_e32 v31, v36, v25
	v_min_i32_e32 v25, v36, v25
	v_max_i32_e32 v5, v8, v13
	v_min_i32_e32 v8, v8, v13
	v_max_i32_e32 v13, v0, v15
	v_min_i32_e32 v0, v0, v15
	v_max_i32_e32 v14, v2, v10
	v_min_i32_e32 v2, v2, v10
	v_max_i32_e32 v10, v6, v16
	v_min_i32_e32 v6, v6, v16
	v_max_i32_e32 v15, v12, v9
	v_min_i32_e32 v9, v12, v9
	v_max_i32_e32 v12, v3, v17
	v_min_i32_e32 v3, v3, v17
	v_max_i32_e32 v16, v7, v1
	v_min_i32_e32 v1, v7, v1
	v_max_i32_e32 v7, v11, v4
	v_min_i32_e32 v4, v11, v4
	v_max_i32_e32 v36, v40, v35
	v_min_i32_e32 v35, v40, v35
	v_max_i32_e32 v40, v38, v34
	v_min_i32_e32 v34, v38, v34
	v_max_i32_e32 v38, v39, v37
	v_min_i32_e32 v37, v39, v37
	v_max_i32_e32 v39, v33, v31
	v_min_i32_e32 v31, v33, v31
	v_max_i32_e32 v33, v27, v29
	v_min_i32_e32 v27, v27, v29
	v_max_i32_e32 v29, v26, v32
	v_min_i32_e32 v26, v26, v32
	v_max_i32_e32 v32, v28, v24
	v_min_i32_e32 v24, v28, v24
	v_max_i32_e32 v28, v30, v25
	v_min_i32_e32 v25, v30, v25
	v_max_i32_e32 v11, v5, v15
	v_min_i32_e32 v5, v5, v15
	v_max_i32_e32 v15, v13, v12
	v_min_i32_e32 v12, v13, v12
	v_max_i32_e32 v13, v14, v16
	v_min_i32_e32 v14, v14, v16
	v_max_i32_e32 v16, v10, v7
	v_min_i32_e32 v7, v10, v7
	v_max_i32_e32 v10, v8, v9
	v_min_i32_e32 v8, v8, v9
	v_max_i32_e32 v9, v0, v3
	v_min_i32_e32 v0, v0, v3
	v_max_i32_e32 v3, v2, v1
	v_min_i32_e32 v1, v2, v1
	v_max_i32_e32 v2, v6, v4
	v_min_i32_e32 v4, v6, v4
	v_max_i32_e32 v30, v36, v38
	v_min_i32_e32 v36, v36, v38
	v_max_i32_e32 v38, v40, v39
	v_min_i32_e32 v39, v40, v39
	v_max_i32_e32 v40, v35, v37
	v_min_i32_e32 v35, v35, v37
	v_max_i32_e32 v37, v34, v31
	v_min_i32_e32 v31, v34, v31
	v_max_i32_e32 v34, v33, v32
	v_min_i32_e32 v32, v33, v32
	v_max_i32_e32 v33, v29, v28
	v_min_i32_e32 v28, v29, v28
	v_max_i32_e32 v29, v27, v24
	v_min_i32_e32 v24, v27, v24
	v_max_i32_e32 v27, v26, v25
	v_min_i32_e32 v25, v26, v25
	v_max_i32_e32 v6, v11, v13
	v_min_i32_e32 v11, v11, v13
	v_max_i32_e32 v13, v15, v16
	v_min_i32_e32 v15, v15, v16
	v_max_i32_e32 v16, v5, v14
	v_min_i32_e32 v5, v5, v14
	v_max_i32_e32 v14, v12, v7
	v_min_i32_e32 v7, v12, v7
	v_max_i32_e32 v12, v10, v3
	v_min_i32_e32 v3, v10, v3
	v_max_i32_e32 v10, v9, v2
	v_min_i32_e32 v2, v9, v2
	v_max_i32_e32 v9, v8, v1
	v_min_i32_e32 v1, v8, v1
	v_max_i32_e32 v8, v0, v4
	v_min_i32_e32 v0, v0, v4
	v_min_i32_e32 v26, v30, v38
	v_min_i32_e32 v41, v36, v39
	v_min_i32_e32 v42, v40, v37
	v_min_i32_e32 v43, v35, v31
	v_min_i32_e32 v44, v34, v33
	v_min_i32_e32 v45, v32, v28
	v_min_i32_e32 v46, v29, v27
	v_min_i32_e32 v47, v24, v25
	v_min_i32_e32 v4, v6, v13
	v_min_i32_e32 v17, v11, v15
	v_min_i32_e32 v18, v16, v14
	v_min_i32_e32 v19, v5, v7
	v_min_i32_e32 v20, v12, v10
	v_min_i32_e32 v21, v3, v2
	v_min_i32_e32 v22, v9, v8
	v_min_i32_e32 v23, v1, v0
	v_max3_i32 v23, v30, v38, v23
	v_max3_i32 v0, v26, v1, v0
	v_max3_i32 v1, v36, v39, v22
	v_max3_i32 v8, v41, v9, v8
	v_max3_i32 v9, v40, v37, v21
	v_max3_i32 v2, v42, v3, v2
	v_max3_i32 v3, v35, v31, v20
	v_max3_i32 v10, v43, v12, v10
	v_max3_i32 v12, v34, v33, v19
	v_max3_i32 v5, v44, v5, v7
	v_max3_i32 v7, v32, v28, v18
	v_max3_i32 v14, v45, v16, v14
	v_max3_i32 v16, v29, v27, v17
	v_max3_i32 v11, v46, v11, v15
	v_max3_i32 v4, v24, v25, v4
	v_max3_i32 v6, v47, v6, v13
	v_max_i32_e32 v13, v23, v12
	v_min_i32_e32 v12, v23, v12
	v_max_i32_e32 v15, v0, v5
	v_min_i32_e32 v0, v0, v5
	v_max_i32_e32 v5, v1, v7
	v_min_i32_e32 v1, v1, v7
	v_max_i32_e32 v7, v8, v14
	v_min_i32_e32 v8, v8, v14
	v_max_i32_e32 v14, v9, v16
	v_min_i32_e32 v9, v9, v16
	v_max_i32_e32 v16, v2, v11
	v_min_i32_e32 v2, v2, v11
	v_max_i32_e32 v11, v3, v4
	v_min_i32_e32 v3, v3, v4
	v_max_i32_e32 v4, v10, v6
	v_min_i32_e32 v6, v10, v6
	v_max_i32_e32 v10, v13, v14
	v_min_i32_e32 v13, v13, v14
	v_max_i32_e32 v14, v15, v16
	v_min_i32_e32 v15, v15, v16
	v_max_i32_e32 v16, v5, v11
	v_min_i32_e32 v5, v5, v11
	v_max_i32_e32 v11, v7, v4
	v_min_i32_e32 v4, v7, v4
	v_max_i32_e32 v7, v12, v9
	v_min_i32_e32 v9, v12, v9
	v_max_i32_e32 v12, v0, v2
	v_min_i32_e32 v0, v0, v2
	v_max_i32_e32 v2, v1, v3
	v_min_i32_e32 v1, v1, v3
	v_max_i32_e32 v3, v8, v6
	v_min_i32_e32 v6, v8, v6
	v_max_i32_e32 v8, v10, v16
	v_min_i32_e32 v10, v10, v16
	v_max_i32_e32 v16, v14, v11
	v_min_i32_e32 v11, v14, v11
	v_max_i32_e32 v14, v13, v5
	v_min_i32_e32 v5, v13, v5
	v_max_i32_e32 v13, v15, v4
	v_min_i32_e32 v4, v15, v4
	v_max_i32_e32 v15, v7, v2
	v_min_i32_e32 v2, v7, v2
	v_max_i32_e32 v7, v12, v3
	v_min_i32_e32 v3, v12, v3
	v_max_i32_e32 v12, v9, v1
	v_min_i32_e32 v1, v9, v1
	v_max_i32_e32 v9, v0, v6
	v_min_i32_e32 v0, v0, v6
	v_max_i32_e32 v6, v8, v16
	v_min_i32_e32 v8, v8, v16
	v_max_i32_e32 v16, v10, v11
	v_min_i32_e32 v10, v10, v11
	v_max_i32_e32 v11, v14, v13
	v_min_i32_e32 v13, v14, v13
	v_max_i32_e32 v14, v5, v4
	v_min_i32_e32 v4, v5, v4
	v_max_i32_e32 v5, v15, v7
	v_min_i32_e32 v7, v15, v7
	v_max_i32_e32 v15, v2, v3
	v_min_i32_e32 v2, v2, v3
	v_max_i32_e32 v3, v12, v9
	v_min_i32_e32 v9, v12, v9
	v_max_i32_e32 v12, v1, v0
	v_min_i32_e32 v0, v1, v0
	ds_bpermute_b32 v1, v100, v6
	ds_bpermute_b32 v17, v100, v8
	ds_bpermute_b32 v18, v100, v16
	ds_bpermute_b32 v19, v100, v10
	ds_bpermute_b32 v20, v100, v11
	ds_bpermute_b32 v21, v100, v13
	ds_bpermute_b32 v22, v100, v14
	ds_bpermute_b32 v23, v100, v4
	ds_bpermute_b32 v24, v100, v5
	ds_bpermute_b32 v25, v100, v7
	ds_bpermute_b32 v26, v100, v15
	ds_bpermute_b32 v27, v100, v0
	ds_bpermute_b32 v28, v100, v12
	ds_bpermute_b32 v29, v100, v9
	ds_bpermute_b32 v30, v100, v3
	ds_bpermute_b32 v31, v100, v2
	s_waitcnt lgkmcnt(4)
	v_max_i32_e32 v6, v6, v27
	s_waitcnt lgkmcnt(3)
	v_max_i32_e32 v8, v8, v28
	s_waitcnt lgkmcnt(2)
	v_max_i32_e32 v16, v16, v29
	s_waitcnt lgkmcnt(1)
; __device__ __forceinline__ int tosort(float f) { int b = __float_as_int(f); return b ^ ((b >> 31) & 0x7fffffff); }
; __device__ __forceinline__ float fromsort(int b) { return __int_as_float(b ^ ((b >> 31) & 0x7fffffff)); }
; __device__ __forceinline__ int bsel(int m, int a, int b) { return (a & ~m) | (b & m); }
; template <int PP>
; __device__ __forceinline__ void select_half(const Params& p, const u16* Subs, int t, int hh, int lc, int hf, int* lists) {
;     ...
;   merge16<0, 16>(keys, keys); merge16<32, 48>(keys, keys); merge16<0, 32>(keys, keys);
;   int other[16];
; #pragma unroll
;   for (int i = 0; i < 16; ++i) other[i] = __shfl_xor(keys[i], 32);
;   merge16<0, 0>(keys, other);
; #pragma unroll
;   for (int i = 0; i < 16; ++i) lists[PP * 16 + i] = keys[i];
; __device__ __forceinline__ void phase_select(const Params& p, int layer, char* smraw) {
;     ...
;     for (int i = 0; i < 16; ++i) { f1[i] = fromsort(lists[i] & ~127); f2[i] = fromsort(lists[16 + i] & ~127); }
;     int cand[32];
; #pragma unroll
;     for (int c = 0; c < 32; ++c) {
;       constexpr int IMIN = (int)0x80000000;
;       const int ia = candA_i(c), ja = candA_j(c), ib = candB_i(c), jb = candB_j(c);
;       int ka = IMIN, kb2 = IMIN;
;       if (ia >= 0) ka = (tosort(f1[ia >= 0 ? ia : 0] + f2[ja]) & ~255) | (ia << 4) | ja;
;       if (ib >= 0) kb2 = (tosort(f1[ib >= 0 ? ib : 0] + f2[jb]) & ~255) | (ib << 4) | jb;
;       cand[c] = bsel(hmask, ka, kb2);
;     }
	v_max_i32_e32 v10, v10, v30
	s_waitcnt lgkmcnt(0)
	v_max_i32_e32 v11, v11, v31
	v_max_i32_e32 v13, v13, v26
	v_max_i32_e32 v14, v14, v25
	v_max_i32_e32 v4, v4, v24
	v_max_i32_e32 v5, v5, v23
	v_max_i32_e32 v7, v7, v22
	v_max_i32_e32 v15, v15, v21
	v_max_i32_e32 v2, v2, v20
	v_max_i32_e32 v3, v3, v19
	v_max_i32_e32 v9, v9, v18
	v_max_i32_e32 v12, v12, v17
	v_max_i32_e32 v0, v0, v1
	v_max_i32_e32 v1, v6, v5
	v_min_i32_e32 v5, v6, v5
	v_max_i32_e32 v6, v8, v7
	v_min_i32_e32 v7, v8, v7
	v_max_i32_e32 v8, v16, v15
	v_min_i32_e32 v15, v16, v15
	v_max_i32_e32 v16, v10, v2
	v_min_i32_e32 v2, v10, v2
	v_max_i32_e32 v10, v11, v3
	v_min_i32_e32 v3, v11, v3
	v_max_i32_e32 v11, v13, v9
	v_min_i32_e32 v9, v13, v9
	v_max_i32_e32 v13, v14, v12
	v_min_i32_e32 v12, v14, v12
	v_max_i32_e32 v14, v4, v0
	v_min_i32_e32 v0, v4, v0
	v_max_i32_e32 v4, v1, v10
	v_min_i32_e32 v1, v1, v10
	v_max_i32_e32 v10, v6, v11
	v_min_i32_e32 v6, v6, v11
	v_max_i32_e32 v11, v8, v13
	v_min_i32_e32 v8, v8, v13
	v_max_i32_e32 v13, v16, v14
	v_min_i32_e32 v14, v16, v14
	v_max_i32_e32 v16, v5, v3
	v_min_i32_e32 v3, v5, v3
	v_max_i32_e32 v5, v7, v9
	v_min_i32_e32 v7, v7, v9
	v_max_i32_e32 v9, v15, v12
	v_min_i32_e32 v12, v15, v12
	v_max_i32_e32 v15, v2, v0
	v_min_i32_e32 v0, v2, v0
	v_max_i32_e32 v2, v4, v11
	v_min_i32_e32 v4, v4, v11
	v_max_i32_e32 v11, v10, v13
	v_min_i32_e32 v10, v10, v13
	v_max_i32_e32 v13, v1, v8
	v_min_i32_e32 v1, v1, v8
	v_max_i32_e32 v8, v6, v14
	v_min_i32_e32 v6, v6, v14
	v_max_i32_e32 v14, v16, v9
	v_min_i32_e32 v9, v16, v9
	v_max_i32_e32 v16, v5, v15
	v_min_i32_e32 v5, v5, v15
	v_max_i32_e32 v15, v3, v12
	v_min_i32_e32 v3, v3, v12
	v_max_i32_e32 v12, v7, v0
	v_min_i32_e32 v0, v7, v0
	v_max_i32_e32 v29, v4, v10
	v_max_i32_e32 v23, v14, v16
	v_min_i32_e32 v22, v14, v16
	v_max_i32_e32 v17, v3, v0
	v_min_i32_e32 v16, v3, v0
	v_ashrrev_i32_e32 v3, 31, v85
	v_max_i32_e32 v31, v2, v11
	v_min_i32_e32 v30, v2, v11
	v_max_i32_e32 v25, v1, v6
	v_min_i32_e32 v24, v1, v6
	v_and_b32_e32 v1, 0xffffff80, v85
	v_ashrrev_i32_e32 v2, 31, v29
	v_and_b32_e32 v3, 0x7fffffff, v3
	v_min_i32_e32 v28, v4, v10
	v_max_i32_e32 v27, v13, v8
	v_min_i32_e32 v26, v13, v8
	v_and_b32_e32 v0, 0xffffff80, v29
	v_and_b32_e32 v2, 0x7fffffff, v2
	v_xor_b32_e32 v8, v3, v1
	v_ashrrev_i32_e32 v3, 31, v84
	v_xor_b32_e32 v4, v2, v0
	v_and_b32_e32 v1, 0xffffff80, v84
	v_ashrrev_i32_e32 v2, 31, v28
	v_and_b32_e32 v3, 0x7fffffff, v3
	v_and_b32_e32 v0, 0xffffff80, v28
	v_and_b32_e32 v2, 0x7fffffff, v2
	v_xor_b32_e32 v10, v3, v1
	v_ashrrev_i32_e32 v1, 31, v30
	v_ashrrev_i32_e32 v3, 31, v81
	v_xor_b32_e32 v11, v2, v0
	v_and_b32_e32 v0, 0xffffff80, v30
	v_and_b32_e32 v2, 0xffffff80, v81
	v_and_b32_e32 v1, 0x7fffffff, v1
	v_and_b32_e32 v3, 0x7fffffff, v3
	v_ashrrev_i32_e32 v6, 31, v86
	v_max_i32_e32 v21, v9, v5
	v_min_i32_e32 v20, v9, v5
	v_xor_b32_e32 v1, v1, v0
	v_xor_b32_e32 v0, v3, v2
	v_and_b32_e32 v3, 0xffffff80, v86
	v_ashrrev_i32_e32 v5, 31, v25
	v_and_b32_e32 v6, 0x7fffffff, v6
	v_and_b32_e32 v2, 0xffffff80, v25
	v_and_b32_e32 v5, 0x7fffffff, v5
	v_xor_b32_e32 v32, v6, v3
	v_ashrrev_i32_e32 v3, 31, v31
	v_ashrrev_i32_e32 v6, 31, v80
	v_xor_b32_e32 v33, v5, v2
	v_and_b32_e32 v2, 0xffffff80, v31
	v_and_b32_e32 v5, 0xffffff80, v80
	v_and_b32_e32 v3, 0x7fffffff, v3
	v_and_b32_e32 v6, 0x7fffffff, v6
	v_xor_b32_e32 v3, v3, v2
	v_xor_b32_e32 v2, v6, v5
	v_and_b32_e32 v5, 0xffffff80, v78
	v_ashrrev_i32_e32 v6, 31, v78
	v_max_i32_e32 v19, v15, v12
	v_min_i32_e32 v18, v15, v12
	v_bitop3_b32 v12, v6, v5, s23 bitop3:0x6c
	v_and_b32_e32 v5, 0xffffff80, v79
	v_ashrrev_i32_e32 v6, 31, v79
	v_bitop3_b32 v15, v6, v5, s23 bitop3:0x6c
	v_and_b32_e32 v5, 0xffffff80, v22
	v_ashrrev_i32_e32 v6, 31, v22
	v_bitop3_b32 v34, v6, v5, s23 bitop3:0x6c
	v_and_b32_e32 v5, 0xffffff80, v77
	v_ashrrev_i32_e32 v6, 31, v77
	v_bitop3_b32 v13, v6, v5, s23 bitop3:0x6c
	v_and_b32_e32 v5, 0xffffff80, v21
	v_ashrrev_i32_e32 v6, 31, v21
	v_bitop3_b32 v36, v6, v5, s23 bitop3:0x6c
	v_and_b32_e32 v5, 0xffffff80, v20
	v_ashrrev_i32_e32 v6, 31, v20
	v_bitop3_b32 v38, v6, v5, s23 bitop3:0x6c
	v_and_b32_e32 v5, 0xffffff80, v19
	v_ashrrev_i32_e32 v6, 31, v19
	v_bitop3_b32 v40, v6, v5, s23 bitop3:0x6c
	v_and_b32_e32 v5, 0xffffff80, v74
	v_ashrrev_i32_e32 v6, 31, v74
	v_bitop3_b32 v62, v6, v5, s23 bitop3:0x6c
	v_and_b32_e32 v5, 0xffffff80, v18
	v_ashrrev_i32_e32 v6, 31, v18
	v_bitop3_b32 v43, v6, v5, s23 bitop3:0x6c
	v_and_b32_e32 v5, 0xffffff80, v73
	v_ashrrev_i32_e32 v6, 31, v73
	v_bitop3_b32 v63, v6, v5, s23 bitop3:0x6c
	v_and_b32_e32 v5, 0xffffff80, v17
	v_ashrrev_i32_e32 v6, 31, v17
	v_bitop3_b32 v45, v6, v5, s23 bitop3:0x6c
	v_and_b32_e32 v5, 0xffffff80, v72
	v_ashrrev_i32_e32 v6, 31, v72
	v_ashrrev_i32_e32 v7, 31, v16
	v_ashrrev_i32_e32 v9, 31, v87
	v_bitop3_b32 v64, v6, v5, s23 bitop3:0x6c
	v_and_b32_e32 v5, 0xffffff80, v16
	v_and_b32_e32 v6, 0xffffff80, v87
	v_and_b32_e32 v7, 0x7fffffff, v7
	v_and_b32_e32 v9, 0x7fffffff, v9
	v_xor_b32_e32 v47, v7, v5
	v_xor_b32_e32 v46, v9, v6
	v_pk_add_f32 v[6:7], v[2:3], v[46:47] op_sel:[1,0] op_sel_hi:[0,1]
	v_ashrrev_i32_e32 v5, 31, v6
	v_and_b32_e32 v6, 0xffffff00, v6
	v_bitop3_b32 v5, v5, v6, s24 bitop3:0x6c
	v_mov_b32_e32 v56, v46
	v_mov_b32_e32 v57, v32
	v_mov_b32_e32 v6, v1
	v_mov_b32_e32 v7, v3
	v_pk_add_f32 v[58:59], v[56:57], v[6:7]
	v_cndmask_b32_e64 v5, 0, v5, s[6:7]
	v_ashrrev_i32_e32 v9, 31, v59
	v_and_b32_e32 v9, 0x7fffff00, v9
	v_and_b32_e32 v14, 0xffffff00, v59
	v_bitop3_b32 v9, v9, 16, v14 bitop3:0xde
	v_and_or_b32 v65, v9, v48, v5
	v_ashrrev_i32_e32 v5, 31, v58
	v_and_b32_e32 v5, 0x7fffff00, v5
	v_and_b32_e32 v9, 0xffffff00, v58
	v_bitop3_b32 v5, v5, 1, v9 bitop3:0xde
; __device__ __forceinline__ int tosort(float f) { int b = __float_as_int(f); return b ^ ((b >> 31) & 0x7fffffff); }
; __device__ __forceinline__ float fromsort(int b) { return __int_as_float(b ^ ((b >> 31) & 0x7fffffff)); }
; __device__ __forceinline__ int bsel(int m, int a, int b) { return (a & ~m) | (b & m); }
; __device__ __forceinline__ void phase_select(const Params& p, int layer, char* smraw) {
;     ...
; #pragma unroll
;     for (int c = 0; c < 32; ++c) {
;       constexpr int IMIN = (int)0x80000000;
;       const int ia = candA_i(c), ja = candA_j(c), ib = candB_i(c), jb = candB_j(c);
;       int ka = IMIN, kb2 = IMIN;
;       if (ia >= 0) ka = (tosort(f1[ia >= 0 ? ia : 0] + f2[ja]) & ~255) | (ia << 4) | ja;
;       if (ib >= 0) kb2 = (tosort(f1[ib >= 0 ? ib : 0] + f2[jb]) & ~255) | (ib << 4) | jb;
;       cand[c] = bsel(hmask, ka, kb2);
;     }
	v_cndmask_b32_e64 v9, 0, v5, s[6:7]
	v_mov_b32_e32 v5, v1
	v_pk_add_f32 v[58:59], v[56:57], v[4:5]
	v_ashrrev_i32_e32 v35, 31, v27
	v_ashrrev_i32_e32 v5, 31, v59
	v_and_b32_e32 v5, 0x7fffff00, v5
	v_and_b32_e32 v14, 0xffffff00, v59
	v_bitop3_b32 v5, v5, 17, v14 bitop3:0xde
	v_and_or_b32 v66, v5, v48, v9
	v_ashrrev_i32_e32 v5, 31, v58
	v_and_b32_e32 v9, 0xffffff00, v58
	v_mov_b32_e32 v58, v11
	v_mov_b32_e32 v59, v4
	v_and_b32_e32 v5, 0x7fffff00, v5
	v_pk_add_f32 v[58:59], v[56:57], v[58:59]
	v_bitop3_b32 v5, v5, 2, v9 bitop3:0xde
	v_ashrrev_i32_e32 v9, 31, v59
	v_and_b32_e32 v9, 0x7fffff00, v9
	v_and_b32_e32 v14, 0xffffff00, v59
	v_cndmask_b32_e64 v5, 0, v5, s[6:7]
	v_bitop3_b32 v9, v9, 18, v14 bitop3:0xde
	v_and_or_b32 v67, v9, v48, v5
	v_ashrrev_i32_e32 v5, 31, v58
	v_and_b32_e32 v5, 0x7fffff00, v5
	v_and_b32_e32 v9, 0xffffff00, v58
	v_bitop3_b32 v5, v5, 3, v9 bitop3:0xde
	v_and_b32_e32 v9, 0xffffff80, v27
	v_and_b32_e32 v35, 0x7fffffff, v35
	v_xor_b32_e32 v59, v35, v9
	v_mov_b32_e32 v60, v59
	v_mov_b32_e32 v61, v11
	v_ashrrev_i32_e32 v37, 31, v26
	v_pk_add_f32 v[60:61], v[56:57], v[60:61]
	v_and_b32_e32 v14, 0xffffff80, v26
	v_and_b32_e32 v37, 0x7fffffff, v37
	v_ashrrev_i32_e32 v9, 31, v61
	v_xor_b32_e32 v58, v37, v14
	v_and_b32_e32 v9, 0x7fffff00, v9
	v_and_b32_e32 v14, 0xffffff00, v61
	v_cndmask_b32_e64 v5, 0, v5, s[6:7]
	v_bitop3_b32 v9, v9, 19, v14 bitop3:0xde
	v_and_or_b32 v68, v9, v48, v5
	v_ashrrev_i32_e32 v5, 31, v60
	v_and_b32_e32 v5, 0x7fffff00, v5
	v_and_b32_e32 v9, 0xffffff00, v60
	v_pk_add_f32 v[60:61], v[56:57], v[58:59]
	v_bitop3_b32 v5, v5, 4, v9 bitop3:0xde
	v_ashrrev_i32_e32 v9, 31, v61
	v_and_b32_e32 v9, 0x7fffff00, v9
	v_and_b32_e32 v14, 0xffffff00, v61
	v_bitop3_b32 v9, v9, 20, v14 bitop3:0xde
	v_cndmask_b32_e64 v5, 0, v5, s[6:7]
	v_and_or_b32 v69, v9, v48, v5
	v_ashrrev_i32_e32 v5, 31, v60
	v_and_b32_e32 v9, 0xffffff00, v60
	v_mov_b32_e32 v60, v58
	v_mov_b32_e32 v61, v46
	v_and_b32_e32 v5, 0x7fffff00, v5
	v_pk_add_f32 v[60:61], v[32:33], v[60:61]
	v_bitop3_b32 v5, v5, 5, v9 bitop3:0xde
	v_ashrrev_i32_e32 v9, 31, v60
	v_and_b32_e32 v9, 0x7fffff00, v9
	v_and_b32_e32 v14, 0xffffff00, v60
	v_cndmask_b32_e64 v5, 0, v5, s[6:7]
	v_bitop3_b32 v9, v9, 21, v14 bitop3:0xde
	v_and_or_b32 v70, v9, v48, v5
	v_ashrrev_i32_e32 v5, 31, v61
	v_and_b32_e32 v5, 0x7fffff00, v5
	v_and_b32_e32 v9, 0xffffff00, v61
	v_ashrrev_i32_e32 v32, 31, v24
	v_bitop3_b32 v5, v5, 6, v9 bitop3:0xde
	v_and_b32_e32 v9, 0xffffff80, v24
	v_and_b32_e32 v32, 0x7fffffff, v32
	v_xor_b32_e32 v61, v32, v9
	v_mov_b32_e32 v32, v61
	v_ashrrev_i32_e32 v35, 31, v23
	v_pk_add_f32 v[32:33], v[56:57], v[32:33]
	v_and_b32_e32 v14, 0xffffff80, v23
	v_and_b32_e32 v35, 0x7fffffff, v35
	v_ashrrev_i32_e32 v9, 31, v33
	v_xor_b32_e32 v60, v35, v14
	v_and_b32_e32 v9, 0x7fffff00, v9
	v_and_b32_e32 v14, 0xffffff00, v33
	v_cndmask_b32_e64 v5, 0, v5, s[6:7]
	v_bitop3_b32 v9, v9, 22, v14 bitop3:0xde
	v_and_or_b32 v71, v9, v48, v5
	v_ashrrev_i32_e32 v5, 31, v32
	v_and_b32_e32 v5, 0x7fffff00, v5
	v_and_b32_e32 v9, 0xffffff00, v32
	v_pk_add_f32 v[32:33], v[56:57], v[60:61]
	v_bitop3_b32 v5, v5, 7, v9 bitop3:0xde
	v_ashrrev_i32_e32 v9, 31, v33
	v_and_b32_e32 v9, 0x7fffff00, v9
	v_and_b32_e32 v14, 0xffffff00, v33
	v_bitop3_b32 v9, v9, 23, v14 bitop3:0xde
	v_cndmask_b32_e64 v5, 0, v5, s[6:7]
	v_and_or_b32 v56, v9, v48, v5
	v_ashrrev_i32_e32 v5, 31, v32
	v_and_b32_e32 v9, 0xffffff00, v32
	v_mov_b32_e32 v32, v46
	v_mov_b32_e32 v33, v10
	v_mov_b32_e32 v35, v3
	v_and_b32_e32 v5, 0x7fffff00, v5
	v_pk_add_f32 v[34:35], v[32:33], v[34:35]
	v_bitop3_b32 v5, v5, 8, v9 bitop3:0xde
	v_ashrrev_i32_e32 v9, 31, v35
	v_and_b32_e32 v9, 0x7fffff00, v9
	v_and_b32_e32 v14, 0xffffff00, v35
	v_cndmask_b32_e64 v5, 0, v5, s[6:7]
	v_bitop3_b32 v9, v9, 32, v14 bitop3:0xde
	v_and_or_b32 v57, v9, v48, v5
	v_ashrrev_i32_e32 v5, 31, v34
	v_mov_b32_e32 v37, v1
	v_and_b32_e32 v5, 0x7fffff00, v5
	v_and_b32_e32 v9, 0xffffff00, v34
	v_pk_add_f32 v[34:35], v[32:33], v[36:37]
	v_bitop3_b32 v5, v5, 9, v9 bitop3:0xde
	v_ashrrev_i32_e32 v9, 31, v35
	v_and_b32_e32 v9, 0x7fffff00, v9
	v_and_b32_e32 v14, 0xffffff00, v35
	v_cndmask_b32_e64 v5, 0, v5, s[6:7]
	v_bitop3_b32 v9, v9, 33, v14 bitop3:0xde
	v_and_or_b32 v36, v9, v48, v5
	v_ashrrev_i32_e32 v5, 31, v34
	v_mov_b32_e32 v39, v4
	v_and_b32_e32 v5, 0x7fffff00, v5
	v_and_b32_e32 v9, 0xffffff00, v34
	v_pk_add_f32 v[34:35], v[32:33], v[38:39]
	v_bitop3_b32 v5, v5, 10, v9 bitop3:0xde
	v_ashrrev_i32_e32 v9, 31, v35
	v_and_b32_e32 v9, 0x7fffff00, v9
	v_and_b32_e32 v14, 0xffffff00, v35
	v_cndmask_b32_e64 v5, 0, v5, s[6:7]
	v_bitop3_b32 v9, v9, 34, v14 bitop3:0xde
	v_and_or_b32 v35, v9, v48, v5
	v_ashrrev_i32_e32 v5, 31, v34
	v_mov_b32_e32 v41, v11
	v_and_b32_e32 v5, 0x7fffff00, v5
	v_and_b32_e32 v9, 0xffffff00, v34
	v_pk_add_f32 v[32:33], v[32:33], v[40:41]
	v_bitop3_b32 v5, v5, 11, v9 bitop3:0xde
	v_ashrrev_i32_e32 v9, 31, v33
	v_and_b32_e32 v9, 0x7fffff00, v9
	v_and_b32_e32 v14, 0xffffff00, v33
	v_cndmask_b32_e64 v5, 0, v5, s[6:7]
	v_bitop3_b32 v9, v9, 35, v14 bitop3:0xde
	v_and_or_b32 v34, v9, v48, v5
	v_ashrrev_i32_e32 v5, 31, v32
	v_and_b32_e32 v5, 0x7fffff00, v5
	v_and_b32_e32 v9, 0xffffff00, v32
	v_pk_add_f32 v[32:33], v[58:59], v[10:11] op_sel:[1,0] op_sel_hi:[0,1]
	v_bitop3_b32 v5, v5, 12, v9 bitop3:0xde
	v_ashrrev_i32_e32 v9, 31, v32
	v_and_b32_e32 v9, 0x7fffff00, v9
	v_and_b32_e32 v10, 0xffffff00, v32
	v_bitop3_b32 v9, v9, 36, v10 bitop3:0xde
	v_cndmask_b32_e64 v5, 0, v5, s[6:7]
	v_and_or_b32 v37, v9, v48, v5
	v_mov_b32_e32 v9, v46
	v_mov_b32_e32 v42, v3
	v_pk_add_f32 v[32:33], v[42:43], v[8:9]
	v_mov_b32_e32 v44, v1
	v_ashrrev_i32_e32 v5, 31, v33
	v_and_b32_e32 v5, 0x7fffff00, v5
; __device__ __forceinline__ int tosort(float f) { int b = __float_as_int(f); return b ^ ((b >> 31) & 0x7fffffff); }
; __device__ __forceinline__ int bsel(int m, int a, int b) { return (a & ~m) | (b & m); }
; __device__ __forceinline__ void phase_select(const Params& p, int layer, char* smraw) {
;     ...
; #pragma unroll
;     for (int c = 0; c < 32; ++c) {
;       constexpr int IMIN = (int)0x80000000;
;       const int ia = candA_i(c), ja = candA_j(c), ib = candB_i(c), jb = candB_j(c);
;       int ka = IMIN, kb2 = IMIN;
;       if (ia >= 0) ka = (tosort(f1[ia >= 0 ? ia : 0] + f2[ja]) & ~255) | (ia << 4) | ja;
;       if (ib >= 0) kb2 = (tosort(f1[ib >= 0 ? ib : 0] + f2[jb]) & ~255) | (ib << 4) | jb;
;       cand[c] = bsel(hmask, ka, kb2);
;     }
;     sort16_desc<0>(cand); sort16_desc<16>(cand);
	v_and_b32_e32 v10, 0xffffff00, v33
	v_bitop3_b32 v5, v5, 13, v10 bitop3:0xde
	v_ashrrev_i32_e32 v10, 31, v32
	v_and_b32_e32 v10, 0x7fffff00, v10
	v_and_b32_e32 v14, 0xffffff00, v32
	v_bitop3_b32 v10, v10, 48, v14 bitop3:0xde
	v_cndmask_b32_e64 v5, 0, v5, s[6:7]
	v_pk_add_f32 v[32:33], v[44:45], v[8:9]
	v_and_or_b32 v38, v10, v48, v5
	v_ashrrev_i32_e32 v5, 31, v33
	v_and_b32_e32 v5, 0x7fffff00, v5
	v_and_b32_e32 v10, 0xffffff00, v33
	v_bitop3_b32 v5, v5, 14, v10 bitop3:0xde
	v_ashrrev_i32_e32 v10, 31, v32
	v_and_b32_e32 v10, 0x7fffff00, v10
	v_and_b32_e32 v14, 0xffffff00, v32
	v_bitop3_b32 v10, v10, 49, v14 bitop3:0xde
	v_cndmask_b32_e64 v5, 0, v5, s[6:7]
	v_and_or_b32 v39, v10, v48, v5
	v_mov_b32_e32 v5, v47
	v_pk_add_f32 v[32:33], v[8:9], v[4:5]
	v_min_i32_e32 v40, v56, v71
	v_ashrrev_i32_e32 v5, 31, v33
	v_and_b32_e32 v5, 0x7fffff00, v5
	v_and_b32_e32 v9, 0xffffff00, v33
	v_bitop3_b32 v5, v5, 15, v9 bitop3:0xde
	v_ashrrev_i32_e32 v9, 31, v32
	v_and_b32_e32 v9, 0x7fffff00, v9
	v_and_b32_e32 v10, 0xffffff00, v32
	v_bitop3_b32 v9, v9, 50, v10 bitop3:0xde
	v_cndmask_b32_e64 v5, 0, v5, s[6:7]
	v_and_or_b32 v32, v9, v48, v5
	v_mov_b32_e32 v9, v12
	v_mov_b32_e32 v10, v11
	v_mov_b32_e32 v11, v3
	v_pk_add_f32 v[8:9], v[8:9], v[10:11]
	v_ashrrev_i32_e32 v10, 31, v83
	v_ashrrev_i32_e32 v5, 31, v9
	v_and_b32_e32 v5, 0x7fffff00, v5
	v_and_b32_e32 v9, 0xffffff00, v9
	v_bitop3_b32 v5, v5, s25, v9 bitop3:0xde
	v_ashrrev_i32_e32 v9, 31, v8
	v_and_b32_e32 v9, 0x7fffff00, v9
	v_and_b32_e32 v8, 0xffffff00, v8
	v_bitop3_b32 v8, v9, 51, v8 bitop3:0xde
	v_cndmask_b32_e64 v5, 0, v5, s[6:7]
	v_and_or_b32 v33, v8, v48, v5
	v_and_b32_e32 v8, 0xffffff80, v83
	v_and_b32_e32 v10, 0x7fffffff, v10
	v_xor_b32_e32 v8, v10, v8
	v_ashrrev_i32_e32 v9, 31, v76
	v_mov_b32_e32 v14, v8
	v_and_b32_e32 v5, 0xffffff80, v76
	v_and_b32_e32 v9, 0x7fffffff, v9
	v_pk_add_f32 v[10:11], v[2:3], v[14:15] op_sel:[1,0]
	v_xor_b32_e32 v9, v9, v5
	v_ashrrev_i32_e32 v5, 31, v11
	v_and_b32_e32 v5, 0x7fffff00, v5
	v_and_b32_e32 v11, 0xffffff00, v11
	v_bitop3_b32 v5, v5, s26, v11 bitop3:0xde
	v_ashrrev_i32_e32 v11, 31, v10
	v_and_b32_e32 v11, 0x7fffff00, v11
	v_and_b32_e32 v10, 0xffffff00, v10
	v_cndmask_b32_e64 v5, 0, v5, s[6:7]
	v_bitop3_b32 v10, v11, 64, v10 bitop3:0xde
	v_mov_b32_e32 v12, v8
	v_and_or_b32 v14, v10, v48, v5
	v_pk_add_f32 v[10:11], v[12:13], v[6:7]
	v_min_i32_e32 v13, v69, v70
	v_ashrrev_i32_e32 v5, 31, v11
	v_and_b32_e32 v5, 0x7fffff00, v5
	v_and_b32_e32 v11, 0xffffff00, v11
	v_bitop3_b32 v5, v5, s27, v11 bitop3:0xde
	v_ashrrev_i32_e32 v11, 31, v10
	v_and_b32_e32 v11, 0x7fffff00, v11
	v_and_b32_e32 v10, 0xffffff00, v10
	v_cndmask_b32_e64 v5, 0, v5, s[6:7]
	v_bitop3_b32 v10, v11, s10, v10 bitop3:0xde
	v_and_or_b32 v10, v10, v48, v5
	v_mov_b32_e32 v5, v3
	v_pk_add_f32 v[4:5], v[8:9], v[4:5]
	v_ashrrev_i32_e32 v9, 31, v82
	v_ashrrev_i32_e32 v8, 31, v5
	v_and_b32_e32 v8, 0x7fffff00, v8
	v_and_b32_e32 v5, 0xffffff00, v5
	v_bitop3_b32 v5, v8, s28, v5 bitop3:0xde
	v_ashrrev_i32_e32 v8, 31, v4
	v_and_b32_e32 v8, 0x7fffff00, v8
	v_and_b32_e32 v4, 0xffffff00, v4
	v_bitop3_b32 v4, v8, s11, v4 bitop3:0xde
	v_cndmask_b32_e64 v5, 0, v5, s[6:7]
	v_and_or_b32 v11, v4, v48, v5
	v_ashrrev_i32_e32 v5, 31, v75
	v_and_b32_e32 v4, 0xffffff80, v75
	v_and_b32_e32 v8, 0xffffff80, v82
	v_and_b32_e32 v5, 0x7fffffff, v5
	v_and_b32_e32 v9, 0x7fffffff, v9
	v_xor_b32_e32 v5, v5, v4
	v_xor_b32_e32 v4, v9, v8
	v_pk_add_f32 v[8:9], v[2:3], v[4:5] op_sel:[1,0]
	v_pk_add_f32 v[4:5], v[0:1], v[4:5] op_sel:[1,0] op_sel_hi:[0,1]
	v_ashrrev_i32_e32 v12, 31, v9
	v_and_b32_e32 v12, 0x7fffff00, v12
	v_and_b32_e32 v9, 0xffffff00, v9
	v_bitop3_b32 v9, v12, s29, v9 bitop3:0xde
	v_ashrrev_i32_e32 v12, 31, v8
	v_and_b32_e32 v12, 0x7fffff00, v12
	v_and_b32_e32 v8, 0xffffff00, v8
	v_bitop3_b32 v8, v12, s12, v8 bitop3:0xde
	v_cndmask_b32_e64 v9, 0, v9, s[6:7]
	v_and_or_b32 v8, v8, v48, v9
	v_add_f32_e32 v9, v3, v62
	v_ashrrev_i32_e32 v12, 31, v9
	v_and_b32_e32 v12, 0x7fffff00, v12
	v_and_b32_e32 v9, 0xffffff00, v9
	v_ashrrev_i32_e32 v1, 31, v4
	v_bitop3_b32 v9, v12, s30, v9 bitop3:0xde
	v_and_b32_e32 v1, 0x7fffff00, v1
	v_and_b32_e32 v4, 0xffffff00, v4
	v_bitop3_b32 v1, v1, s13, v4 bitop3:0xde
	v_cndmask_b32_e64 v4, 0, v9, s[6:7]
	v_and_or_b32 v9, v1, v48, v4
	v_mov_b32_e32 v1, v63
	v_pk_add_f32 v[4:5], v[2:3], v[0:1] op_sel:[1,0]
	v_max_i32_e32 v12, v69, v70
	v_ashrrev_i32_e32 v1, 31, v5
	v_and_b32_e32 v1, 0x7fffff00, v1
	v_and_b32_e32 v5, 0xffffff00, v5
	v_bitop3_b32 v1, v1, s31, v5 bitop3:0xde
	v_ashrrev_i32_e32 v5, 31, v4
	v_and_b32_e32 v5, 0x7fffff00, v5
	v_and_b32_e32 v4, 0xffffff00, v4
	v_bitop3_b32 v4, v5, s14, v4 bitop3:0xde
	v_cndmask_b32_e64 v1, 0, v1, s[6:7]
	v_and_or_b32 v4, v4, v48, v1
	v_mov_b32_e32 v1, v64
	v_pk_add_f32 v[0:1], v[0:1], v[6:7]
	v_max_i32_e32 v15, v56, v71
	v_ashrrev_i32_e32 v5, 31, v1
	v_and_b32_e32 v5, 0x7fffff00, v5
	v_and_b32_e32 v1, 0xffffff00, v1
	v_bitop3_b32 v1, v5, s34, v1 bitop3:0xde
	v_ashrrev_i32_e32 v5, 31, v0
	v_and_b32_e32 v5, 0x7fffff00, v5
	v_and_b32_e32 v0, 0xffffff00, v0
	v_bitop3_b32 v0, v5, s15, v0 bitop3:0xde
	v_cndmask_b32_e64 v1, 0, v1, s[6:7]
	v_and_or_b32 v5, v0, v48, v1
	v_pk_add_f32 v[0:1], v[2:3], v[6:7] op_sel_hi:[0,1]
	v_ashrrev_i32_e32 v2, 31, v1
	v_and_b32_e32 v2, 0x7fffff00, v2
	v_and_b32_e32 v1, 0xffffff00, v1
	v_bitop3_b32 v1, v2, s18, v1 bitop3:0xde
	v_ashrrev_i32_e32 v2, 31, v0
	v_and_b32_e32 v2, 0x7fffff00, v2
	v_and_b32_e32 v0, 0xffffff00, v0
	v_bitop3_b32 v0, v2, s19, v0 bitop3:0xde
	v_and_or_b32 v1, v1, v48, v165
	v_and_or_b32 v0, v0, v48, v165
	v_max_i32_e32 v2, v65, v66
	v_min_i32_e32 v3, v65, v66
	v_max_i32_e32 v6, v68, v67
	v_min_i32_e32 v7, v68, v67
; template <int OFF>
; __device__ __forceinline__ void sort16_desc(int* a) {
; #pragma unroll
;   for (int ks = 1; ks <= 4; ++ks) {
; #pragma unroll
;     ...
; #pragma unroll
;       for (int i = 0; i < 16; ++i) {
;         const int k = 1 << ks, j = 1 << js;
;         const int l2 = i ^ j;
;         if (l2 > i) { if ((i & k) == 0) cas_desc(a[OFF + i], a[OFF + l2]); else cas_desc(a[OFF + l2], a[OFF + i]); }
;       }
;     }
;   }
; }
; __device__ __forceinline__ void phase_select(const Params& p, int layer, char* smraw) {
;     ...
;     sort16_desc<0>(cand); sort16_desc<16>(cand);
	v_max_i32_e32 v41, v57, v36
	v_min_i32_e32 v36, v57, v36
	v_max_i32_e32 v42, v34, v35
	v_min_i32_e32 v34, v34, v35
	v_max_i32_e32 v35, v37, v38
	v_min_i32_e32 v37, v37, v38
	v_max_i32_e32 v38, v32, v39
	v_min_i32_e32 v32, v32, v39
	v_max_i32_e32 v58, v33, v14
	v_min_i32_e32 v14, v33, v14
	v_max_i32_e32 v33, v11, v10
	v_min_i32_e32 v10, v11, v10
	v_max_i32_e32 v11, v8, v9
	v_min_i32_e32 v8, v8, v9
	v_max_i32_e32 v9, v5, v4
	v_min_i32_e32 v4, v5, v4
	v_max_i32_e32 v5, v1, v0
	v_min_i32_e32 v0, v1, v0
	v_max_i32_e32 v39, v2, v7
	v_min_i32_e32 v2, v2, v7
	v_max_i32_e32 v7, v3, v6
	v_min_i32_e32 v3, v3, v6
	v_max_i32_e32 v6, v40, v12
	v_min_i32_e32 v12, v40, v12
	v_max_i32_e32 v40, v15, v13
	v_min_i32_e32 v13, v15, v13
	v_max_i32_e32 v15, v41, v34
	v_min_i32_e32 v34, v41, v34
	v_max_i32_e32 v41, v36, v42
	v_min_i32_e32 v36, v36, v42
	v_max_i32_e32 v42, v32, v35
	v_min_i32_e32 v32, v32, v35
	v_max_i32_e32 v35, v38, v37
	v_min_i32_e32 v37, v38, v37
	v_max_i32_e32 v1, v58, v10
	v_min_i32_e32 v10, v58, v10
	v_max_i32_e32 v58, v14, v33
	v_min_i32_e32 v14, v14, v33
	v_max_i32_e32 v33, v4, v11
	v_min_i32_e32 v4, v4, v11
	v_max_i32_e32 v11, v9, v8
	v_min_i32_e32 v8, v9, v8
	v_max_i32_e32 v9, v5, v166
	v_min_i32_e32 v5, v5, v166
	v_max_i32_e32 v59, v0, v166
	v_min_i32_e32 v0, v0, v166
	v_max_i32_e32 v38, v39, v7
	v_min_i32_e32 v7, v39, v7
	v_max_i32_e32 v39, v2, v3
	v_min_i32_e32 v2, v2, v3
	v_max_i32_e32 v3, v13, v12
	v_min_i32_e32 v12, v13, v12
	v_max_i32_e32 v13, v40, v6
	v_min_i32_e32 v6, v40, v6
	v_max_i32_e32 v40, v15, v41
	v_min_i32_e32 v15, v15, v41
	v_max_i32_e32 v41, v34, v36
	v_min_i32_e32 v34, v34, v36
	v_max_i32_e32 v36, v37, v32
	v_min_i32_e32 v32, v37, v32
	v_max_i32_e32 v37, v35, v42
	v_min_i32_e32 v35, v35, v42
	v_max_i32_e32 v60, v1, v58
	v_min_i32_e32 v1, v1, v58
	v_max_i32_e32 v58, v10, v14
	v_min_i32_e32 v10, v10, v14
	v_max_i32_e32 v14, v8, v4
	v_min_i32_e32 v4, v8, v4
	v_max_i32_e32 v8, v11, v33
	v_min_i32_e32 v11, v11, v33
	v_max_i32_e32 v33, v9, v59
	v_min_i32_e32 v9, v9, v59
	v_max_i32_e32 v59, v5, v0
	v_min_i32_e32 v0, v5, v0
	v_max_i32_e32 v42, v38, v12
	v_min_i32_e32 v12, v38, v12
	v_max_i32_e32 v38, v7, v3
	v_min_i32_e32 v3, v7, v3
	v_max_i32_e32 v7, v39, v6
	v_min_i32_e32 v6, v39, v6
	v_max_i32_e32 v39, v2, v13
	v_min_i32_e32 v2, v2, v13
	v_max_i32_e32 v13, v32, v40
	v_min_i32_e32 v32, v32, v40
	v_max_i32_e32 v40, v36, v15
	v_min_i32_e32 v15, v36, v15
	v_max_i32_e32 v36, v35, v41
	v_min_i32_e32 v35, v35, v41
	v_max_i32_e32 v41, v37, v34
	v_min_i32_e32 v34, v37, v34
	v_max_i32_e32 v5, v60, v4
	v_min_i32_e32 v4, v60, v4
	v_max_i32_e32 v60, v1, v14
	v_min_i32_e32 v1, v1, v14
	v_max_i32_e32 v14, v58, v11
	v_min_i32_e32 v11, v58, v11
	v_max_i32_e32 v58, v10, v8
	v_min_i32_e32 v8, v10, v8
	v_max_i32_e32 v10, v166, v33
	v_min_i32_e32 v33, v166, v33
	v_max_i32_e32 v61, v166, v9
	v_min_i32_e32 v9, v166, v9
	v_max_i32_e32 v62, v166, v59
	v_min_i32_e32 v59, v166, v59
	v_max_i32_e32 v63, v166, v0
	v_min_i32_e32 v0, v166, v0
	v_max_i32_e32 v37, v42, v7
	v_min_i32_e32 v7, v42, v7
	v_max_i32_e32 v42, v38, v39
	v_min_i32_e32 v38, v38, v39
	v_max_i32_e32 v39, v12, v6
	v_min_i32_e32 v6, v12, v6
	v_max_i32_e32 v12, v3, v2
	v_min_i32_e32 v2, v3, v2
	v_max_i32_e32 v3, v35, v32
	v_min_i32_e32 v32, v35, v32
	v_max_i32_e32 v35, v34, v15
	v_min_i32_e32 v15, v34, v15
	v_max_i32_e32 v34, v36, v13
	v_min_i32_e32 v13, v36, v13
	v_max_i32_e32 v36, v41, v40
	v_min_i32_e32 v40, v41, v40
	v_max_i32_e32 v64, v5, v14
	v_min_i32_e32 v5, v5, v14
	v_max_i32_e32 v14, v60, v58
	v_min_i32_e32 v58, v60, v58
	v_max_i32_e32 v60, v4, v11
	v_min_i32_e32 v4, v4, v11
	v_max_i32_e32 v11, v1, v8
	v_min_i32_e32 v1, v1, v8
	v_max_i32_e32 v8, v59, v33
	v_min_i32_e32 v33, v59, v33
	v_max_i32_e32 v59, v0, v9
	v_min_i32_e32 v0, v0, v9
	v_max_i32_e32 v9, v62, v10
	v_min_i32_e32 v10, v62, v10
	v_max_i32_e32 v62, v63, v61
	v_min_i32_e32 v61, v63, v61
	v_max_i32_e32 v41, v37, v42
	v_min_i32_e32 v37, v37, v42
	v_max_i32_e32 v42, v7, v38
	v_min_i32_e32 v7, v7, v38
	v_max_i32_e32 v38, v39, v12
	v_min_i32_e32 v12, v39, v12
	v_max_i32_e32 v39, v6, v2
	v_min_i32_e32 v2, v6, v2
	v_max_i32_e32 v6, v15, v32
	v_min_i32_e32 v15, v15, v32
	v_max_i32_e32 v32, v35, v3
	v_min_i32_e32 v3, v35, v3
	v_max_i32_e32 v35, v40, v13
	v_min_i32_e32 v13, v40, v13
	v_max_i32_e32 v40, v36, v34
	v_min_i32_e32 v34, v36, v34
	v_max_i32_e32 v63, v64, v14
	v_min_i32_e32 v14, v64, v14
	v_max_i32_e32 v64, v5, v58
	v_min_i32_e32 v5, v5, v58
	v_max_i32_e32 v58, v60, v11
	v_min_i32_e32 v11, v60, v11
	v_max_i32_e32 v60, v4, v1
	v_min_i32_e32 v1, v4, v1
	v_max_i32_e32 v4, v0, v33
	v_min_i32_e32 v0, v0, v33
	v_max_i32_e32 v33, v59, v8
	v_min_i32_e32 v8, v59, v8
	v_max_i32_e32 v59, v61, v10
	v_min_i32_e32 v10, v61, v10
	v_max_i32_e32 v61, v62, v9
	v_min_i32_e32 v9, v62, v9
	v_max_i32_e32 v36, v41, v15
	v_min_i32_e32 v15, v41, v15
	v_max_i32_e32 v41, v37, v6
	v_min_i32_e32 v6, v37, v6
	v_max_i32_e32 v37, v42, v3
	v_min_i32_e32 v3, v42, v3
	v_max_i32_e32 v42, v7, v32
	v_min_i32_e32 v7, v7, v32
	v_max_i32_e32 v32, v38, v13
	v_min_i32_e32 v13, v38, v13
	v_max_i32_e32 v38, v12, v35
	v_min_i32_e32 v12, v12, v35
	v_max_i32_e32 v35, v39, v34
	v_min_i32_e32 v34, v39, v34
	v_max_i32_e32 v39, v2, v40
	v_min_i32_e32 v2, v2, v40
	v_max_i32_e32 v62, v63, v0
	v_min_i32_e32 v0, v63, v0
	v_max_i32_e32 v63, v14, v4
	v_min_i32_e32 v4, v14, v4
	v_max_i32_e32 v14, v64, v8
	v_min_i32_e32 v8, v64, v8
	v_max_i32_e32 v64, v5, v33
	v_min_i32_e32 v5, v5, v33
	v_max_i32_e32 v33, v58, v10
	v_min_i32_e32 v10, v58, v10
	v_max_i32_e32 v58, v11, v59
	v_min_i32_e32 v11, v11, v59
	v_max_i32_e32 v59, v60, v9
	v_min_i32_e32 v9, v60, v9
	v_max_i32_e32 v60, v1, v61
; template <int OFF>
; __device__ __forceinline__ void sort16_desc(int* a) {
; #pragma unroll
;   for (int ks = 1; ks <= 4; ++ks) {
; #pragma unroll
;     ...
; #pragma unroll
;       for (int i = 0; i < 16; ++i) {
;         const int k = 1 << ks, j = 1 << js;
;         const int l2 = i ^ j;
;         if (l2 > i) { if ((i & k) == 0) cas_desc(a[OFF + i], a[OFF + l2]); else cas_desc(a[OFF + l2], a[OFF + i]); }
;       }
;     }
;   }
; }
; template <int OA, int OB>
; __device__ __forceinline__ void merge16(int* a, const int* b) {
; #pragma unroll
;   for (int i = 0; i < 16; ++i) a[OA + i] = max(a[OA + i], b[OB + 15 - i]);
; #pragma unroll
;     ...
; #pragma unroll
;     for (int i = 0; i < 16; ++i) {
;       const int j = 1 << js; const int l2 = i ^ j;
;       if (l2 > i) cas_desc(a[OA + i], a[OA + l2]);
;     }
;   }
; }
; __device__ __forceinline__ void phase_select(const Params& p, int layer, char* smraw) {
;     ...
;     sort16_desc<0>(cand); sort16_desc<16>(cand);
;     merge16<0, 16>(cand, cand);
;     {
;       int other[16];
; #pragma unroll
;       for (int i = 0; i < 16; ++i) other[i] = __shfl_xor(cand[i], 32);
;       merge16<0, 0>(cand, other);
	v_min_i32_e32 v1, v1, v61
	v_max_i32_e32 v40, v36, v32
	v_min_i32_e32 v32, v36, v32
	v_max_i32_e32 v36, v41, v38
	v_min_i32_e32 v38, v41, v38
	v_max_i32_e32 v41, v37, v35
	v_min_i32_e32 v35, v37, v35
	v_max_i32_e32 v37, v42, v39
	v_min_i32_e32 v39, v42, v39
	v_max_i32_e32 v42, v15, v13
	v_min_i32_e32 v13, v15, v13
	v_max_i32_e32 v15, v6, v12
	v_min_i32_e32 v6, v6, v12
	v_max_i32_e32 v12, v3, v34
	v_min_i32_e32 v3, v3, v34
	v_max_i32_e32 v34, v7, v2
	v_min_i32_e32 v2, v7, v2
	v_max_i32_e32 v61, v62, v33
	v_min_i32_e32 v33, v62, v33
	v_max_i32_e32 v62, v63, v58
	v_min_i32_e32 v58, v63, v58
	v_max_i32_e32 v63, v14, v59
	v_min_i32_e32 v14, v14, v59
	v_max_i32_e32 v59, v64, v60
	v_min_i32_e32 v60, v64, v60
	v_max_i32_e32 v64, v0, v10
	v_min_i32_e32 v0, v0, v10
	v_max_i32_e32 v10, v4, v11
	v_min_i32_e32 v4, v4, v11
	v_max_i32_e32 v11, v8, v9
	v_min_i32_e32 v8, v8, v9
	v_max_i32_e32 v9, v5, v1
	v_min_i32_e32 v1, v5, v1
	v_max_i32_e32 v7, v40, v41
	v_min_i32_e32 v40, v40, v41
	v_max_i32_e32 v41, v36, v37
	v_min_i32_e32 v36, v36, v37
	v_max_i32_e32 v37, v32, v35
	v_min_i32_e32 v32, v32, v35
	v_max_i32_e32 v35, v38, v39
	v_min_i32_e32 v38, v38, v39
	v_max_i32_e32 v39, v42, v12
	v_min_i32_e32 v12, v42, v12
	v_max_i32_e32 v42, v15, v34
	v_min_i32_e32 v15, v15, v34
	v_max_i32_e32 v34, v13, v3
	v_min_i32_e32 v3, v13, v3
	v_max_i32_e32 v13, v6, v2
	v_min_i32_e32 v2, v6, v2
	v_max_i32_e32 v5, v61, v63
	v_min_i32_e32 v61, v61, v63
	v_max_i32_e32 v63, v62, v59
	v_min_i32_e32 v59, v62, v59
	v_max_i32_e32 v62, v33, v14
	v_min_i32_e32 v14, v33, v14
	v_max_i32_e32 v33, v58, v60
	v_min_i32_e32 v58, v58, v60
	v_max_i32_e32 v60, v64, v11
	v_min_i32_e32 v11, v64, v11
	v_max_i32_e32 v64, v10, v9
	v_min_i32_e32 v9, v10, v9
	v_max_i32_e32 v10, v0, v8
	v_min_i32_e32 v0, v0, v8
	v_max_i32_e32 v8, v4, v1
	v_min_i32_e32 v1, v4, v1
	v_min_i32_e32 v6, v7, v41
	v_min_i32_e32 v43, v40, v36
	v_min_i32_e32 v44, v37, v35
	v_min_i32_e32 v45, v32, v38
	v_min_i32_e32 v46, v39, v42
	v_min_i32_e32 v47, v12, v15
	v_min_i32_e32 v56, v34, v13
	v_min_i32_e32 v57, v3, v2
	v_min_i32_e32 v4, v5, v63
	v_min_i32_e32 v65, v61, v59
	v_min_i32_e32 v66, v62, v33
	v_min_i32_e32 v67, v14, v58
	v_min_i32_e32 v68, v60, v64
	v_min_i32_e32 v69, v11, v9
	v_min_i32_e32 v70, v10, v8
	v_min_i32_e32 v71, v0, v1
	v_max3_i32 v7, v7, v41, v71
	v_max3_i32 v0, v6, v0, v1
	v_max3_i32 v1, v40, v36, v70
	v_max3_i32 v6, v43, v10, v8
	v_max3_i32 v8, v37, v35, v69
	v_max3_i32 v9, v44, v11, v9
	v_max3_i32 v10, v32, v38, v68
	v_max3_i32 v11, v45, v60, v64
	v_max3_i32 v32, v39, v42, v67
	v_max3_i32 v14, v46, v14, v58
	v_max3_i32 v12, v12, v15, v66
	v_max3_i32 v15, v47, v62, v33
	v_max3_i32 v13, v34, v13, v65
	v_max3_i32 v33, v56, v61, v59
	v_max3_i32 v2, v3, v2, v4
	v_max3_i32 v3, v57, v5, v63
	v_max_i32_e32 v4, v7, v32
	v_min_i32_e32 v5, v7, v32
	v_max_i32_e32 v7, v0, v14
	v_min_i32_e32 v0, v0, v14
	v_max_i32_e32 v14, v1, v12
	v_min_i32_e32 v1, v1, v12
	v_max_i32_e32 v12, v6, v15
	v_min_i32_e32 v6, v6, v15
	v_max_i32_e32 v15, v8, v13
	v_min_i32_e32 v8, v8, v13
	v_max_i32_e32 v13, v9, v33
	v_min_i32_e32 v9, v9, v33
	v_max_i32_e32 v32, v10, v2
	v_min_i32_e32 v2, v10, v2
	v_max_i32_e32 v10, v11, v3
	v_min_i32_e32 v3, v11, v3
	v_max_i32_e32 v11, v4, v15
	v_min_i32_e32 v4, v4, v15
	v_max_i32_e32 v15, v7, v13
	v_min_i32_e32 v7, v7, v13
	v_max_i32_e32 v13, v14, v32
	v_min_i32_e32 v14, v14, v32
	v_max_i32_e32 v32, v12, v10
	v_min_i32_e32 v10, v12, v10
	v_max_i32_e32 v12, v5, v8
	v_min_i32_e32 v5, v5, v8
	v_max_i32_e32 v8, v0, v9
	v_min_i32_e32 v0, v0, v9
	v_max_i32_e32 v9, v1, v2
	v_min_i32_e32 v1, v1, v2
	v_max_i32_e32 v2, v6, v3
	v_min_i32_e32 v3, v6, v3
	v_max_i32_e32 v6, v11, v13
	v_min_i32_e32 v11, v11, v13
	v_max_i32_e32 v13, v15, v32
	v_min_i32_e32 v15, v15, v32
	v_max_i32_e32 v32, v4, v14
	v_min_i32_e32 v4, v4, v14
	v_max_i32_e32 v14, v7, v10
	v_min_i32_e32 v7, v7, v10
	v_max_i32_e32 v10, v12, v9
	v_min_i32_e32 v9, v12, v9
	v_max_i32_e32 v12, v8, v2
	v_min_i32_e32 v2, v8, v2
	v_max_i32_e32 v8, v5, v1
	v_min_i32_e32 v1, v5, v1
	v_max_i32_e32 v5, v0, v3
	v_min_i32_e32 v0, v0, v3
	v_max_i32_e32 v3, v6, v13
	v_min_i32_e32 v6, v6, v13
	v_max_i32_e32 v13, v11, v15
	v_min_i32_e32 v11, v11, v15
	v_max_i32_e32 v15, v32, v14
	v_min_i32_e32 v14, v32, v14
	v_max_i32_e32 v32, v4, v7
	v_min_i32_e32 v4, v4, v7
	v_max_i32_e32 v7, v10, v12
	v_min_i32_e32 v10, v10, v12
	v_max_i32_e32 v12, v9, v2
	v_min_i32_e32 v2, v9, v2
	v_max_i32_e32 v9, v8, v5
	v_min_i32_e32 v5, v8, v5
	v_max_i32_e32 v8, v1, v0
	v_min_i32_e32 v0, v1, v0
	ds_bpermute_b32 v1, v100, v3
	ds_bpermute_b32 v33, v100, v6
	ds_bpermute_b32 v34, v100, v13
	ds_bpermute_b32 v35, v100, v11
	ds_bpermute_b32 v36, v100, v15
	ds_bpermute_b32 v37, v100, v14
	ds_bpermute_b32 v38, v100, v32
	ds_bpermute_b32 v39, v100, v4
	ds_bpermute_b32 v40, v100, v7
	ds_bpermute_b32 v41, v100, v10
	ds_bpermute_b32 v42, v100, v12
	ds_bpermute_b32 v43, v100, v0
	ds_bpermute_b32 v44, v100, v8
	ds_bpermute_b32 v45, v100, v5
	ds_bpermute_b32 v46, v100, v9
	ds_bpermute_b32 v47, v100, v2
	s_waitcnt lgkmcnt(4)
	v_max_i32_e32 v3, v3, v43
	s_waitcnt lgkmcnt(3)
	v_max_i32_e32 v6, v6, v44
	s_waitcnt lgkmcnt(2)
	v_max_i32_e32 v13, v13, v45
	s_waitcnt lgkmcnt(1)
	v_max_i32_e32 v11, v11, v46
	s_waitcnt lgkmcnt(0)
; __device__ __forceinline__ float fromsort(int b) { return __int_as_float(b ^ ((b >> 31) & 0x7fffffff)); }
; __device__ __forceinline__ int bsel(int m, int a, int b) { return (a & ~m) | (b & m); }
; __device__ __forceinline__ void phase_select(const Params& p, int layer, char* smraw) {
;     ...
;       merge16<0, 0>(cand, other);
;     }
;     float g[16]; float gsum = 0.f;
;     const float smax = fromsort(cand[0] & ~255);
; #pragma unroll
;     for (int k = 0; k < 16; ++k) { g[k] = __expf(fromsort(cand[k] & ~255) - smax); gsum += g[k]; }
;     const float ginv = 1.f / gsum;
;     {
;       u32x4 pk;
; #pragma unroll
;       for (int q4 = 0; q4 < 4; ++q4) {
;         unsigned v = 0;
; #pragma unroll
;         for (int m = 0; m < 4; ++m) {
;           int kk = bsel(hmask, lists[q4 * 4 + m], lists[16 + q4 * 4 + m]);
;           v |= (unsigned)(kk & 127) << (8 * m);
;         }
;         pk[q4] = v;
;       }
;       *(u32x4*)(myscr + hf * 16) = pk;
;     }
;     __builtin_amdgcn_fence(__ATOMIC_RELEASE, "wavefront");
;     __builtin_amdgcn_wave_barrier();
;     __builtin_amdgcn_fence(__ATOMIC_ACQUIRE, "wavefront");
;     asm volatile("" ::: "memory");
;     int oi[8]; float ow[8];
; #pragma unroll
;     for (int m = 0; m < 8; ++m) {
;       const int key = bsel(hmask, cand[m], cand[8 + m]);
;       const int i1 = (key >> 4) & 15, j1 = key & 15;
;       const int n1 = myscr[i1], n2 = myscr[16 + j1];
;       oi[m] = n1 * 128 + n2;
;       ow[m] = __int_as_float(bsel(hmask, __float_as_int(g[m]), __float_as_int(g[8 + m]))) * ginv;
	v_max_i32_e32 v15, v15, v47
	v_max_i32_e32 v14, v14, v42
	v_max_i32_e32 v32, v32, v41
	v_max_i32_e32 v4, v4, v40
	v_max_i32_e32 v7, v7, v39
	v_max_i32_e32 v10, v10, v38
	v_max_i32_e32 v12, v12, v37
	v_max_i32_e32 v2, v2, v36
	v_max_i32_e32 v9, v9, v35
	v_max_i32_e32 v5, v5, v34
	v_max_i32_e32 v8, v8, v33
	v_max_i32_e32 v0, v0, v1
	v_max_i32_e32 v1, v3, v7
	v_min_i32_e32 v3, v3, v7
	v_max_i32_e32 v7, v6, v10
	v_min_i32_e32 v6, v6, v10
	v_max_i32_e32 v10, v13, v12
	v_min_i32_e32 v12, v13, v12
	v_max_i32_e32 v13, v11, v2
	v_min_i32_e32 v2, v11, v2
	v_max_i32_e32 v11, v15, v9
	v_min_i32_e32 v9, v15, v9
	v_max_i32_e32 v15, v14, v5
	v_min_i32_e32 v5, v14, v5
	v_max_i32_e32 v14, v32, v8
	v_min_i32_e32 v8, v32, v8
	v_max_i32_e32 v32, v4, v0
	v_min_i32_e32 v0, v4, v0
	v_max_i32_e32 v4, v1, v11
	v_min_i32_e32 v1, v1, v11
	v_max_i32_e32 v11, v7, v15
	v_min_i32_e32 v7, v7, v15
	v_max_i32_e32 v15, v10, v14
	v_min_i32_e32 v10, v10, v14
	v_max_i32_e32 v14, v13, v32
	v_min_i32_e32 v13, v13, v32
	v_max_i32_e32 v32, v3, v9
	v_min_i32_e32 v3, v3, v9
	v_max_i32_e32 v9, v6, v5
	v_min_i32_e32 v5, v6, v5
	v_max_i32_e32 v6, v12, v8
	v_min_i32_e32 v8, v12, v8
	v_max_i32_e32 v12, v2, v0
	v_min_i32_e32 v0, v2, v0
	v_max_i32_e32 v2, v4, v15
	v_min_i32_e32 v4, v4, v15
	v_max_i32_e32 v15, v11, v14
	v_min_i32_e32 v11, v11, v14
	v_max_i32_e32 v33, v1, v10
	v_min_i32_e32 v1, v1, v10
	v_max_i32_e32 v10, v7, v13
	v_min_i32_e32 v7, v7, v13
	v_max_i32_e32 v34, v32, v6
	v_min_i32_e32 v32, v32, v6
	v_max_i32_e32 v6, v9, v12
	v_min_i32_e32 v35, v9, v12
	v_max_i32_e32 v36, v3, v8
	v_min_i32_e32 v37, v3, v8
	v_max_i32_e32 v3, v5, v0
	v_min_i32_e32 v38, v5, v0
	v_max_i32_e32 v14, v4, v11
	v_min_i32_e32 v13, v4, v11
	v_max_i32_e32 v12, v33, v10
	v_min_i32_e32 v11, v33, v10
	v_max_i32_e32 v10, v1, v7
	v_min_i32_e32 v9, v1, v7
	v_max_i32_e32 v8, v34, v6
	v_min_i32_e32 v7, v34, v6
	v_max_i32_e32 v6, v32, v35
	v_min_i32_e32 v5, v32, v35
	v_cndmask_b32_e64 v32, 0, v87, s[6:7]
	v_and_b32_e32 v31, v31, v48
	v_bitop3_b32 v31, v31, s35, v32 bitop3:0xc8
	v_cndmask_b32_e64 v32, 0, v86, s[6:7]
	v_and_b32_e32 v30, v30, v48
	v_add_lshl_u32 v30, v30, v32, 8
	v_and_or_b32 v30, v30, s36, v31
	v_cndmask_b32_e64 v31, 0, v84, s[6:7]
	v_and_b32_e32 v29, v29, v48
	v_add_lshl_u32 v29, v29, v31, 16
	v_cndmask_b32_e64 v31, 0, v85, s[6:7]
	v_and_b32_e32 v28, v28, v48
	v_add_lshl_u32 v28, v28, v31, 24
	v_and_b32_e32 v29, 0x7f0000, v29
	v_and_b32_e32 v28, 0x7f000000, v28
	v_or3_b32 v28, v30, v29, v28
	v_cndmask_b32_e64 v29, 0, v83, s[6:7]
	v_and_b32_e32 v27, v27, v48
	v_bitop3_b32 v27, v27, s35, v29 bitop3:0xc8
	v_cndmask_b32_e64 v29, 0, v82, s[6:7]
	v_and_b32_e32 v26, v26, v48
	v_add_lshl_u32 v26, v26, v29, 8
	v_and_or_b32 v26, v26, s36, v27
	v_cndmask_b32_e64 v27, 0, v81, s[6:7]
	v_and_b32_e32 v25, v25, v48
	v_add_lshl_u32 v25, v25, v27, 16
	v_cndmask_b32_e64 v27, 0, v80, s[6:7]
	v_and_b32_e32 v24, v24, v48
	v_add_lshl_u32 v24, v24, v27, 24
	v_and_b32_e32 v25, 0x7f0000, v25
	v_and_b32_e32 v24, 0x7f000000, v24
	v_or3_b32 v29, v26, v25, v24
	v_cndmask_b32_e64 v24, 0, v78, s[6:7]
	v_and_b32_e32 v23, v23, v48
	v_bitop3_b32 v23, v23, s35, v24 bitop3:0xc8
	v_cndmask_b32_e64 v24, 0, v79, s[6:7]
	v_and_b32_e32 v22, v22, v48
	v_add_lshl_u32 v22, v22, v24, 8
	v_and_or_b32 v22, v22, s36, v23
	v_cndmask_b32_e64 v23, 0, v77, s[6:7]
	v_and_b32_e32 v21, v21, v48
	v_add_lshl_u32 v21, v21, v23, 16
	v_cndmask_b32_e64 v23, 0, v76, s[6:7]
	v_and_b32_e32 v20, v20, v48
	v_add_lshl_u32 v20, v20, v23, 24
	v_and_b32_e32 v21, 0x7f0000, v21
	v_and_b32_e32 v20, 0x7f000000, v20
	v_or3_b32 v30, v22, v21, v20
	v_cndmask_b32_e64 v20, 0, v75, s[6:7]
	v_and_b32_e32 v19, v19, v48
	v_bitop3_b32 v19, v19, s35, v20 bitop3:0xc8
	v_cndmask_b32_e64 v20, 0, v74, s[6:7]
	v_and_b32_e32 v18, v18, v48
	v_add_lshl_u32 v18, v18, v20, 8
	v_and_or_b32 v18, v18, s36, v19
	v_cndmask_b32_e64 v19, 0, v73, s[6:7]
	v_and_b32_e32 v17, v17, v48
	v_add_lshl_u32 v17, v17, v19, 16
	v_cndmask_b32_e64 v19, 0, v72, s[6:7]
	v_and_b32_e32 v16, v16, v48
	v_add_lshl_u32 v16, v16, v19, 24
	v_max_i32_e32 v0, v2, v15
	v_and_b32_e32 v17, 0x7f0000, v17
	v_and_b32_e32 v16, 0x7f000000, v16
	v_or3_b32 v31, v18, v17, v16
	v_and_b32_e32 v16, v0, v50
	v_and_b32_e32 v17, v8, v48
	v_or_b32_e32 v18, v17, v16
	v_min_i32_e32 v15, v2, v15
	v_bfe_u32 v18, v18, 4, 4
	v_bitop3_b32 v16, v17, 15, v16 bitop3:0xc8
	v_add_u32_e32 v17, v89, v18
	v_and_b32_e32 v18, v15, v50
	v_and_b32_e32 v19, v7, v48
	v_or_b32_e32 v20, v19, v18
	v_bfe_u32 v20, v20, 4, 4
	v_bitop3_b32 v18, v19, 15, v18 bitop3:0xc8
	v_add_u32_e32 v21, v89, v20
	v_and_b32_e32 v19, v14, v50
	v_and_b32_e32 v20, v6, v48
	v_or_b32_e32 v22, v20, v19
	v_bitop3_b32 v19, v20, 15, v19 bitop3:0xc8
	v_bfe_u32 v22, v22, 4, 4
	v_add_u32_e32 v24, v89, v19
	v_and_b32_e32 v19, v13, v50
	v_and_b32_e32 v20, v5, v48
	v_add_u32_e32 v23, v89, v22
	v_or_b32_e32 v22, v20, v19
	v_bfe_u32 v22, v22, 4, 4
	v_bitop3_b32 v19, v20, 15, v19 bitop3:0xc8
	v_max_i32_e32 v4, v36, v3
	ds_write_b128 v169, v[28:31]
	v_add_u32_e32 v16, v89, v16
	v_add_u32_e32 v25, v89, v22
	v_add_u32_e32 v26, v89, v19
	v_add_u32_e32 v18, v89, v18
	ds_read_u8 v19, v17
	ds_read_u8 v20, v16 offset:16
	ds_read_u8 v21, v21
	ds_read_u8 v22, v18 offset:16
	ds_read_u8 v23, v23
	ds_read_u8 v24, v24 offset:16
	ds_read_u8 v25, v25
	ds_read_u8 v26, v26 offset:16
	v_and_b32_e32 v16, v12, v50
	v_and_b32_e32 v17, v4, v48
	v_or_b32_e32 v18, v17, v16
	v_min_i32_e32 v3, v36, v3
	v_bfe_u32 v18, v18, 4, 4
	v_bitop3_b32 v16, v17, 15, v16 bitop3:0xc8
	v_add_u32_e32 v17, v89, v18
	v_and_b32_e32 v18, v11, v50
	v_and_b32_e32 v27, v3, v48
	v_or_b32_e32 v28, v27, v18
	v_max_i32_e32 v2, v37, v38
	v_bfe_u32 v28, v28, 4, 4
	v_bitop3_b32 v18, v27, 15, v18 bitop3:0xc8
	v_add_u32_e32 v29, v89, v28
	v_and_b32_e32 v27, v10, v50
	v_and_b32_e32 v28, v2, v48
	v_min_i32_e32 v1, v37, v38
	v_or_b32_e32 v30, v28, v27
	v_bitop3_b32 v27, v28, 15, v27 bitop3:0xc8
	v_bfe_u32 v30, v30, 4, 4
	v_add_u32_e32 v32, v89, v27
	v_and_b32_e32 v27, v9, v50
	v_and_b32_e32 v28, v1, v48
	v_add_u32_e32 v31, v89, v30
	v_or_b32_e32 v30, v28, v27
	v_add_u32_e32 v16, v89, v16
	v_add_u32_e32 v18, v89, v18
	v_bfe_u32 v30, v30, 4, 4
	v_bitop3_b32 v27, v28, 15, v27 bitop3:0xc8
	v_add_u32_e32 v33, v89, v30
	v_add_u32_e32 v34, v89, v27
	ds_read_u8 v27, v17
	ds_read_u8 v28, v16 offset:16
	ds_read_u8 v29, v29
	ds_read_u8 v30, v18 offset:16
	ds_read_u8 v31, v31
	ds_read_u8 v16, v32 offset:16
	ds_read_u8 v17, v33
	ds_read_u8 v18, v34 offset:16
	s_and_saveexec_b64 s[8:9], vcc
	s_cbranch_execz .LBB0_630
; __device__ __forceinline__ float fromsort(int b) { return __int_as_float(b ^ ((b >> 31) & 0x7fffffff)); }
; __device__ __forceinline__ int bsel(int m, int a, int b) { return (a & ~m) | (b & m); }
; __device__ __forceinline__ void phase_select(const Params& p, int layer, char* smraw) {
;     ...
;     float g[16]; float gsum = 0.f;
;     const float smax = fromsort(cand[0] & ~255);
; #pragma unroll
;     for (int k = 0; k < 16; ++k) { g[k] = __expf(fromsort(cand[k] & ~255) - smax); gsum += g[k]; }
;     const float ginv = 1.f / gsum;
;     {
;       u32x4 pk;
; #pragma unroll
;       for (int q4 = 0; q4 < 4; ++q4) {
;         unsigned v = 0;
; #pragma unroll
;         for (int m = 0; m < 4; ++m) {
;           int kk = bsel(hmask, lists[q4 * 4 + m], lists[16 + q4 * 4 + m]);
;           v |= (unsigned)(kk & 127) << (8 * m);
;         }
;         pk[q4] = v;
;       }
;       *(u32x4*)(myscr + hf * 16) = pk;
;     }
;     __builtin_amdgcn_fence(__ATOMIC_RELEASE, "wavefront");
;     __builtin_amdgcn_wave_barrier();
;     __builtin_amdgcn_fence(__ATOMIC_ACQUIRE, "wavefront");
;     asm volatile("" ::: "memory");
;     int oi[8]; float ow[8];
; #pragma unroll
;     for (int m = 0; m < 8; ++m) {
;       const int key = bsel(hmask, cand[m], cand[8 + m]);
;       const int i1 = (key >> 4) & 15, j1 = key & 15;
;       const int n1 = myscr[i1], n2 = myscr[16 + j1];
;       oi[m] = n1 * 128 + n2;
;       ow[m] = __int_as_float(bsel(hmask, __float_as_int(g[m]), __float_as_int(g[8 + m]))) * ginv;
;     }
;     asm volatile("" ::: "memory");
;     __builtin_amdgcn_wave_barrier();
;     if (tl < T) {
;       int* di = p.sel_idx + (size_t)t * 128 + hh * 16 + hf * 8;
;       float* dw = p.sel_w + (size_t)t * 128 + hh * 16 + hf * 8;
;       *(u32x4*)di = u32x4{(unsigned)oi[0], (unsigned)oi[1], (unsigned)oi[2], (unsigned)oi[3]};
;       *(u32x4*)(di + 4) = u32x4{(unsigned)oi[4], (unsigned)oi[5], (unsigned)oi[6], (unsigned)oi[7]};
;       *(f32x4*)dw = f32x4{ow[0], ow[1], ow[2], ow[3]};
;       *(f32x4*)(dw + 4) = f32x4{ow[4], ow[5], ow[6], ow[7]};
;     }
	v_ashrrev_i32_e32 v34, 31, v15
	v_and_b32_e32 v15, 0xffffff00, v15
	v_bitop3_b32 v15, v34, v15, s23 bitop3:0x6c
	v_ashrrev_i32_e32 v34, 31, v14
	v_and_b32_e32 v14, 0xffffff00, v14
	v_bitop3_b32 v14, v34, v14, s23 bitop3:0x6c
	v_ashrrev_i32_e32 v34, 31, v13
	v_and_b32_e32 v13, 0xffffff00, v13
	v_bitop3_b32 v13, v34, v13, s23 bitop3:0x6c
	v_ashrrev_i32_e32 v34, 31, v12
	v_and_b32_e32 v12, 0xffffff00, v12
	v_bitop3_b32 v12, v34, v12, s23 bitop3:0x6c
	v_ashrrev_i32_e32 v34, 31, v11
	v_and_b32_e32 v11, 0xffffff00, v11
	v_and_b32_e32 v32, 0xffffff00, v0
	v_bitop3_b32 v11, v34, v11, s23 bitop3:0x6c
	v_ashrrev_i32_e32 v34, 31, v10
	v_and_b32_e32 v10, 0xffffff00, v10
	v_ashrrev_i32_e32 v0, 31, v0
	v_bitop3_b32 v10, v34, v10, s23 bitop3:0x6c
	v_ashrrev_i32_e32 v34, 31, v9
	v_and_b32_e32 v9, 0xffffff00, v9
	v_and_b32_e32 v0, 0x7fffffff, v0
	v_bitop3_b32 v9, v34, v9, s23 bitop3:0x6c
	v_ashrrev_i32_e32 v34, 31, v8
	v_and_b32_e32 v8, 0xffffff00, v8
	v_xor_b32_e32 v0, v0, v32
	v_bitop3_b32 v8, v34, v8, s23 bitop3:0x6c
	v_ashrrev_i32_e32 v34, 31, v7
	v_and_b32_e32 v7, 0xffffff00, v7
	v_sub_f32_e32 v32, v0, v0
	v_bitop3_b32 v7, v34, v7, s23 bitop3:0x6c
	v_ashrrev_i32_e32 v34, 31, v6
	v_and_b32_e32 v6, 0xffffff00, v6
	v_mul_f32_e32 v32, 0x3fb8aa3b, v32
	v_sub_f32_e32 v15, v15, v0
	v_bitop3_b32 v6, v34, v6, s23 bitop3:0x6c
	v_ashrrev_i32_e32 v34, 31, v5
	v_and_b32_e32 v5, 0xffffff00, v5
	v_exp_f32_e32 v32, v32
	v_mul_f32_e32 v15, 0x3fb8aa3b, v15
	v_sub_f32_e32 v14, v14, v0
	v_and_b32_e32 v33, 0xffffff00, v1
	v_bitop3_b32 v5, v34, v5, s23 bitop3:0x6c
	v_ashrrev_i32_e32 v34, 31, v4
	v_and_b32_e32 v4, 0xffffff00, v4
	v_ashrrev_i32_e32 v1, 31, v1
	v_exp_f32_e32 v15, v15
	v_mul_f32_e32 v14, 0x3fb8aa3b, v14
	v_sub_f32_e32 v13, v13, v0
	v_bitop3_b32 v4, v34, v4, s23 bitop3:0x6c
	v_ashrrev_i32_e32 v34, 31, v3
	v_and_b32_e32 v3, 0xffffff00, v3
	v_and_b32_e32 v1, 0x7fffffff, v1
	v_exp_f32_e32 v14, v14
	v_mul_f32_e32 v13, 0x3fb8aa3b, v13
	v_sub_f32_e32 v12, v12, v0
	v_bitop3_b32 v3, v34, v3, s23 bitop3:0x6c
	v_ashrrev_i32_e32 v34, 31, v2
	v_and_b32_e32 v2, 0xffffff00, v2
	v_xor_b32_e32 v1, v1, v33
	v_exp_f32_e32 v33, v13
	v_mul_f32_e32 v12, 0x3fb8aa3b, v12
	v_sub_f32_e32 v11, v11, v0
	v_bitop3_b32 v2, v34, v2, s23 bitop3:0x6c
	v_add_f32_e32 v13, 0, v32
	v_exp_f32_e32 v34, v12
	v_mul_f32_e32 v11, 0x3fb8aa3b, v11
	v_sub_f32_e32 v10, v10, v0
	v_add_f32_e32 v13, v15, v13
	v_exp_f32_e32 v35, v11
	v_mul_f32_e32 v10, 0x3fb8aa3b, v10
	v_sub_f32_e32 v9, v9, v0
	v_add_f32_e32 v13, v14, v13
	v_exp_f32_e32 v36, v10
	v_mul_f32_e32 v9, 0x3fb8aa3b, v9
	v_sub_f32_e32 v8, v8, v0
	v_add_f32_e32 v13, v33, v13
	v_exp_f32_e32 v9, v9
	v_mul_f32_e32 v8, 0x3fb8aa3b, v8
	v_sub_f32_e32 v7, v7, v0
	v_add_f32_e32 v10, v34, v13
	v_exp_f32_e32 v37, v8
	v_mul_f32_e32 v7, 0x3fb8aa3b, v7
	v_sub_f32_e32 v6, v6, v0
	v_add_f32_e32 v10, v35, v10
	v_exp_f32_e32 v38, v7
	v_mul_f32_e32 v6, 0x3fb8aa3b, v6
	v_sub_f32_e32 v5, v5, v0
	v_add_f32_e32 v10, v36, v10
	v_exp_f32_e32 v39, v6
	v_mul_f32_e32 v5, 0x3fb8aa3b, v5
	v_sub_f32_e32 v4, v4, v0
	v_add_f32_e32 v10, v9, v10
	v_exp_f32_e32 v40, v5
	v_mul_f32_e32 v4, 0x3fb8aa3b, v4
	v_sub_f32_e32 v3, v3, v0
	v_add_f32_e32 v5, v37, v10
	v_exp_f32_e32 v41, v4
	v_mul_f32_e32 v3, 0x3fb8aa3b, v3
	v_sub_f32_e32 v2, v2, v0
	v_add_f32_e32 v5, v38, v5
	v_exp_f32_e32 v42, v3
	v_mul_f32_e32 v2, 0x3fb8aa3b, v2
	v_sub_f32_e32 v0, v1, v0
	v_add_f32_e32 v5, v39, v5
	v_exp_f32_e32 v43, v2
	v_mul_f32_e32 v0, 0x3fb8aa3b, v0
	v_add_f32_e32 v5, v40, v5
	v_exp_f32_e32 v44, v0
	v_add_f32_e32 v0, v41, v5
	v_add_f32_e32 v0, v42, v0
	v_add_f32_e32 v0, v43, v0
	v_add_f32_e32 v0, v44, v0
	v_div_scale_f32 v1, s[40:41], v0, v0, 1.0
	v_rcp_f32_e32 v2, v1
	v_lshlrev_b64 v[10:11], 9, v[94:95]
	v_lshl_add_u64 v[12:13], s[52:53], 0, v[10:11]
	s_lshl_b32 s0, s38, 6
	v_fma_f32 v6, -v1, v2, 1.0
	v_fmac_f32_e32 v2, v6, v2
	v_div_scale_f32 v6, vcc, 1.0, v0, 1.0
	v_mul_f32_e32 v7, v6, v2
	v_fma_f32 v8, -v1, v7, v6
	v_fmac_f32_e32 v7, v8, v2
	v_fma_f32 v1, -v1, v7, v6
	s_waitcnt lgkmcnt(14)
	v_and_b32_e32 v19, 0xff, v19
	v_and_b32_e32 v20, 0xff, v20
	s_waitcnt lgkmcnt(13)
	v_and_b32_e32 v21, 0xff, v21
	s_waitcnt lgkmcnt(12)
	v_and_b32_e32 v22, 0xff, v22
	s_waitcnt lgkmcnt(11)
	v_and_b32_e32 v23, 0xff, v23
	s_waitcnt lgkmcnt(10)
	v_and_b32_e32 v24, 0xff, v24
	s_waitcnt lgkmcnt(9)
	v_and_b32_e32 v25, 0xff, v25
	s_waitcnt lgkmcnt(8)
	v_and_b32_e32 v26, 0xff, v26
	s_waitcnt lgkmcnt(7)
	v_and_b32_e32 v27, 0xff, v27
	s_waitcnt lgkmcnt(6)
	v_and_b32_e32 v28, 0xff, v28
	s_waitcnt lgkmcnt(5)
	v_and_b32_e32 v29, 0xff, v29
	s_waitcnt lgkmcnt(4)
	v_and_b32_e32 v30, 0xff, v30
	s_waitcnt lgkmcnt(3)
	v_and_b32_e32 v31, 0xff, v31
	s_waitcnt lgkmcnt(2)
	v_and_b32_e32 v4, 0xff, v16
	s_waitcnt lgkmcnt(1)
	v_and_b32_e32 v3, 0xff, v17
	s_waitcnt lgkmcnt(0)
	v_and_b32_e32 v5, 0xff, v18
	v_div_fmas_f32 v1, v1, v2, v7
	v_lshl_add_u64 v[12:13], v[12:13], 0, s[0:1]
	v_lshlrev_b32_e32 v90, 2, v88
	v_div_fixup_f32 v8, v1, v0, 1.0
	v_lshl_add_u32 v3, v3, 7, v5
	v_lshl_add_u32 v2, v31, 7, v4
	v_lshl_add_u32 v1, v29, 7, v30
	v_lshl_add_u32 v0, v27, 7, v28
	v_lshl_add_u32 v7, v25, 7, v26
	v_lshl_add_u32 v6, v23, 7, v24
	v_lshl_add_u32 v5, v21, 7, v22
	v_lshl_add_u32 v4, v19, 7, v20
	v_lshl_add_u64 v[12:13], v[12:13], 0, v[90:91]
	v_lshl_add_u64 v[10:11], s[54:55], 0, v[10:11]
	global_store_dwordx4 v[12:13], v[4:7], off
	global_store_dwordx4 v[12:13], v[0:3], off offset:16
	v_lshl_add_u64 v[10:11], v[10:11], 0, s[0:1]
	v_lshl_add_u64 v[10:11], v[10:11], 0, v[90:91]
	v_and_b32_e32 v2, v54, v14
	v_and_b32_e32 v3, v55, v33
	v_and_b32_e32 v0, v50, v32
	v_and_b32_e32 v1, v53, v15
	v_and_or_b32 v1, v49, v38, v1
	v_and_or_b32 v0, v48, v37, v0
	v_and_or_b32 v3, v51, v40, v3
	v_and_or_b32 v2, v52, v39, v2
	v_pk_mul_f32 v[2:3], v[8:9], v[2:3] op_sel_hi:[0,1]
	v_pk_mul_f32 v[0:1], v[8:9], v[0:1] op_sel_hi:[0,1]
	global_store_dwordx4 v[10:11], v[0:3], off
	s_nop 1
	v_and_b32_e32 v2, v54, v36
	v_and_b32_e32 v3, v55, v9
	v_and_b32_e32 v0, v50, v34
	v_and_b32_e32 v1, v53, v35
	v_and_or_b32 v1, v49, v42, v1
	v_and_or_b32 v0, v48, v41, v0
	v_and_or_b32 v3, v51, v44, v3
	v_and_or_b32 v2, v52, v43, v2
	v_pk_mul_f32 v[2:3], v[8:9], v[2:3] op_sel_hi:[0,1]
	v_pk_mul_f32 v[0:1], v[8:9], v[0:1] op_sel_hi:[0,1]
	global_store_dwordx4 v[10:11], v[0:3], off offset:16
	s_branch .LBB0_630

; __device__ __forceinline__ int crow(int r, int hf) { return (r & 3) + 8 * (r >> 2) + 4 * hf; }
; __device__ __forceinline__ int tosort(float f) { int b = __float_as_int(f); return b ^ ((b >> 31) & 0x7fffffff); }
; template <int PP>
; __device__ __forceinline__ void select_half(const Params& p, const u16* Subs, int t, int hh, int lc, int hf, int* lists) {
;     ...
;   const u16* qrow = p.qp + (size_t)t * 2048 + hh * 256 + PP * 128 + hf * 8;
; #pragma unroll
;   for (int ks = 0; ks < 8; ++ks) qf[ks] = *(const bf16x8*)(qrow + ks * 16);
;   int keys[64];
; #pragma unroll
;   for (int nb = 0; nb < 4; ++nb) {
;     f32x16 acc;
; #pragma unroll
;     for (int r = 0; r < 16; ++r) acc[r] = 0.f;
; #pragma unroll
;     for (int ks = 0; ks < 8; ++ks) {
;       bf16x8 a = *(const bf16x8*)(Subs + (PP * 128 + nb * 32 + lc) * 136 + ks * 16 + hf * 8);
;       acc = mfma32(a, qf[ks], acc);
;     }
; #pragma unroll
;     for (int r = 0; r < 16; ++r) keys[nb * 16 + r] = (tosort(acc[r]) & ~127) | (nb * 32 + crow(r, hf));
.LBB0_1226:
	s_and_b32 s0, s17, 0xffffff80
	v_add_u32_e32 v0, s0, v98
	v_cmp_gt_i32_e32 vcc, s19, v0
	s_and_b32 s39, s2, 7
	s_lshl_b32 s0, s39, 9
	v_cndmask_b32_e32 v94, v167, v0, vcc
	v_ashrrev_i32_e32 v95, 31, v94
	v_lshlrev_b64 v[0:1], 12, v[94:95]
	v_lshl_add_u64 v[0:1], s[60:61], 0, v[0:1]
	v_lshl_add_u64 v[0:1], v[0:1], 0, s[0:1]
	v_lshl_add_u64 v[96:97], v[0:1], 0, v[92:93]
	global_load_dwordx4 v[60:63], v[96:97], off
	global_load_dwordx4 v[56:59], v[96:97], off offset:32
	global_load_dwordx4 v[84:87], v[96:97], off offset:64
	global_load_dwordx4 v[76:79], v[96:97], off offset:96
	global_load_dwordx4 v[80:83], v[96:97], off offset:128
	ds_read_b128 v[0:3], v168
	ds_read_b128 v[64:67], v168 offset:32
	s_waitcnt vmcnt(4) lgkmcnt(1)
	v_mfma_f32_32x32x16_bf16 v[32:47], v[0:3], v[60:63], 0
	ds_read_b128 v[0:3], v168 offset:8704
	ds_read_b128 v[68:71], v168 offset:8736
	s_waitcnt lgkmcnt(1)
	v_mfma_f32_32x32x16_bf16 v[16:31], v[0:3], v[60:63], 0
	ds_read_b128 v[0:3], v168 offset:17408
	ds_read_b128 v[72:75], v168 offset:17440
	s_waitcnt vmcnt(3)
	v_mfma_f32_32x32x16_bf16 v[32:47], v[64:67], v[56:59], v[32:47]
	s_waitcnt lgkmcnt(2)
	v_mfma_f32_32x32x16_bf16 v[16:31], v[68:71], v[56:59], v[16:31]
	ds_read_b128 v[64:67], v168 offset:64
	ds_read_b128 v[68:71], v168 offset:96
	s_waitcnt lgkmcnt(3)
	v_mfma_f32_32x32x16_bf16 v[0:15], v[0:3], v[60:63], 0
	s_waitcnt lgkmcnt(2)
	v_mfma_f32_32x32x16_bf16 v[0:15], v[72:75], v[56:59], v[0:15]
	s_waitcnt vmcnt(2) lgkmcnt(1)
	v_mfma_f32_32x32x16_bf16 v[32:47], v[64:67], v[84:87], v[32:47]
	ds_read_b128 v[64:67], v168 offset:8768
	ds_read_b128 v[170:173], v168 offset:8800
	s_waitcnt lgkmcnt(1)
	v_mfma_f32_32x32x16_bf16 v[16:31], v[64:67], v[84:87], v[16:31]
	ds_read_b128 v[64:67], v168 offset:17472
	ds_read_b128 v[174:177], v168 offset:17504
	global_load_dwordx4 v[72:75], v[96:97], off offset:160
	s_waitcnt vmcnt(2)
	v_mfma_f32_32x32x16_bf16 v[32:47], v[68:71], v[76:79], v[32:47]
	s_waitcnt lgkmcnt(1)
	v_mfma_f32_32x32x16_bf16 v[0:15], v[64:67], v[84:87], v[0:15]
	v_mfma_f32_32x32x16_bf16 v[16:31], v[170:173], v[76:79], v[16:31]
	ds_read_b128 v[64:67], v168 offset:128
	ds_read_b128 v[170:173], v168 offset:160
	s_waitcnt lgkmcnt(2)
	v_mfma_f32_32x32x16_bf16 v[0:15], v[174:177], v[76:79], v[0:15]
	s_waitcnt vmcnt(1) lgkmcnt(1)
	v_mfma_f32_32x32x16_bf16 v[32:47], v[64:67], v[80:83], v[32:47]
	ds_read_b128 v[64:67], v168 offset:8832
	ds_read_b128 v[178:181], v168 offset:8864
	global_load_dwordx4 v[68:71], v[96:97], off offset:192
	s_waitcnt lgkmcnt(1)
	v_mfma_f32_32x32x16_bf16 v[16:31], v[64:67], v[80:83], v[16:31]
	global_load_dwordx4 v[64:67], v[96:97], off offset:224
	s_waitcnt vmcnt(2)
	v_mfma_f32_32x32x16_bf16 v[32:47], v[170:173], v[72:75], v[32:47]
	s_waitcnt lgkmcnt(0)
	v_mfma_f32_32x32x16_bf16 v[16:31], v[178:181], v[72:75], v[16:31]
	ds_read_b128 v[170:173], v168 offset:192
	ds_read_b128 v[178:181], v168 offset:224
	s_waitcnt vmcnt(1) lgkmcnt(1)
	v_mfma_f32_32x32x16_bf16 v[32:47], v[170:173], v[68:71], v[32:47]
	ds_read_b128 v[170:173], v168 offset:8896
	ds_read_b128 v[182:185], v168 offset:8928
	s_waitcnt lgkmcnt(1)
	v_mfma_f32_32x32x16_bf16 v[16:31], v[170:173], v[68:71], v[16:31]
	s_waitcnt vmcnt(0)
	v_mfma_f32_32x32x16_bf16 v[32:47], v[178:181], v[64:67], v[32:47]
	s_waitcnt lgkmcnt(0)
	v_mfma_f32_32x32x16_bf16 v[16:31], v[182:185], v[64:67], v[16:31]
	s_nop 9
	v_ashrrev_i32_e32 v173, 31, v36
	v_ashrrev_i32_e32 v178, 31, v37
	v_and_b32_e32 v36, 0xffffff80, v36
	v_and_b32_e32 v37, 0xffffff80, v37
	v_ashrrev_i32_e32 v185, 31, v44
	v_and_b32_e32 v173, 0x7fffff80, v173
	v_and_b32_e32 v178, 0x7fffff80, v178
	v_ashrrev_i32_e32 v190, 31, v16
	v_ashrrev_i32_e32 v192, 31, v17
	v_and_b32_e32 v16, 0xffffff80, v16
	v_and_b32_e32 v17, 0xffffff80, v17
	v_ashrrev_i32_e32 v199, 31, v24
	v_and_b32_e32 v190, 0x7fffff80, v190
	v_and_b32_e32 v192, 0x7fffff80, v192
	v_ashrrev_i32_e32 v179, 31, v38
	v_ashrrev_i32_e32 v180, 31, v39
	v_ashrrev_i32_e32 v181, 31, v40
	v_and_b32_e32 v44, 0xffffff80, v44
	v_ashrrev_i32_e32 v193, 31, v18
	v_ashrrev_i32_e32 v194, 31, v19
	v_ashrrev_i32_e32 v195, 31, v20
	v_and_b32_e32 v185, 0x7fffff80, v185
	v_bitop3_b32 v36, v173, v105, v36 bitop3:0xde
	v_bitop3_b32 v37, v178, v106, v37 bitop3:0xde
	v_bitop3_b32 v173, v190, v117, v16 bitop3:0xde
	v_bitop3_b32 v178, v192, v118, v17 bitop3:0xde
	v_and_b32_e32 v16, 0x7fffff80, v199
	v_and_b32_e32 v17, 0xffffff80, v24
	v_and_b32_e32 v38, 0xffffff80, v38
	v_and_b32_e32 v39, 0xffffff80, v39
	v_and_b32_e32 v40, 0xffffff80, v40
	v_and_b32_e32 v18, 0xffffff80, v18
	v_and_b32_e32 v19, 0xffffff80, v19
	v_and_b32_e32 v20, 0xffffff80, v20
	v_and_b32_e32 v179, 0x7fffff80, v179
	v_and_b32_e32 v180, 0x7fffff80, v180
	v_and_b32_e32 v181, 0x7fffff80, v181
	v_and_b32_e32 v193, 0x7fffff80, v193
	v_and_b32_e32 v194, 0x7fffff80, v194
	v_and_b32_e32 v195, 0x7fffff80, v195
	v_bitop3_b32 v44, v185, v113, v44 bitop3:0xde
	v_bitop3_b32 v185, v16, v125, v17 bitop3:0xde
	v_ashrrev_i32_e32 v16, 31, v25
	v_bitop3_b32 v38, v179, v107, v38 bitop3:0xde
	v_bitop3_b32 v39, v180, v108, v39 bitop3:0xde
	v_bitop3_b32 v40, v181, v109, v40 bitop3:0xde
	v_bitop3_b32 v179, v193, v119, v18 bitop3:0xde
	v_bitop3_b32 v180, v194, v120, v19 bitop3:0xde
	v_bitop3_b32 v181, v195, v121, v20 bitop3:0xde
	v_and_b32_e32 v20, 0x7fffff80, v16
	ds_read_b128 v[16:19], v168 offset:17536
	v_ashrrev_i32_e32 v182, 31, v41
	v_ashrrev_i32_e32 v196, 31, v21
	v_and_b32_e32 v41, 0xffffff80, v41
	v_and_b32_e32 v21, 0xffffff80, v21
	v_and_b32_e32 v182, 0x7fffff80, v182
	v_and_b32_e32 v196, 0x7fffff80, v196
	v_bitop3_b32 v41, v182, v110, v41 bitop3:0xde
	v_bitop3_b32 v182, v196, v122, v21 bitop3:0xde
	v_and_b32_e32 v21, 0xffffff80, v25
	v_ashrrev_i32_e32 v183, 31, v42
	v_ashrrev_i32_e32 v184, 31, v43
	v_ashrrev_i32_e32 v197, 31, v22
	v_ashrrev_i32_e32 v198, 31, v23
	v_bitop3_b32 v174, v20, v126, v21 bitop3:0xde
	v_ashrrev_i32_e32 v20, 31, v26
	v_and_b32_e32 v42, 0xffffff80, v42
	v_and_b32_e32 v43, 0xffffff80, v43
	v_and_b32_e32 v22, 0xffffff80, v22
	v_and_b32_e32 v23, 0xffffff80, v23
	v_and_b32_e32 v183, 0x7fffff80, v183
	v_and_b32_e32 v184, 0x7fffff80, v184
	v_and_b32_e32 v197, 0x7fffff80, v197
	v_and_b32_e32 v198, 0x7fffff80, v198
	v_and_b32_e32 v20, 0x7fffff80, v20
	v_and_b32_e32 v21, 0xffffff80, v26
	v_bitop3_b32 v42, v183, v111, v42 bitop3:0xde
	v_bitop3_b32 v43, v184, v112, v43 bitop3:0xde
	v_bitop3_b32 v183, v197, v123, v22 bitop3:0xde
	v_bitop3_b32 v184, v198, v124, v23 bitop3:0xde
	v_bitop3_b32 v175, v20, v127, v21 bitop3:0xde
	ds_read_b128 v[20:23], v168 offset:17568
	s_waitcnt lgkmcnt(1)
; __device__ __forceinline__ int crow(int r, int hf) { return (r & 3) + 8 * (r >> 2) + 4 * hf; }
; __device__ __forceinline__ int tosort(float f) { int b = __float_as_int(f); return b ^ ((b >> 31) & 0x7fffffff); }
; template <int PP>
; __device__ __forceinline__ void select_half(const Params& p, const u16* Subs, int t, int hh, int lc, int hf, int* lists) {
;     ...
;   for (int nb = 0; nb < 4; ++nb) {
;     f32x16 acc;
; #pragma unroll
;     for (int r = 0; r < 16; ++r) acc[r] = 0.f;
; #pragma unroll
;     for (int ks = 0; ks < 8; ++ks) {
;       bf16x8 a = *(const bf16x8*)(Subs + (PP * 128 + nb * 32 + lc) * 136 + ks * 16 + hf * 8);
;       acc = mfma32(a, qf[ks], acc);
;     }
; #pragma unroll
;     for (int r = 0; r < 16; ++r) keys[nb * 16 + r] = (tosort(acc[r]) & ~127) | (nb * 32 + crow(r, hf));
	v_mfma_f32_32x32x16_bf16 v[0:15], v[16:19], v[80:83], v[0:15]
	v_ashrrev_i32_e32 v24, 31, v27
	v_and_b32_e32 v16, 0x7fffff80, v24
	v_and_b32_e32 v17, 0xffffff80, v27
	v_bitop3_b32 v176, v16, v128, v17 bitop3:0xde
	v_ashrrev_i32_e32 v16, 31, v28
	v_and_b32_e32 v24, 0x7fffff80, v16
	ds_read_b128 v[16:19], v168 offset:17600
	s_waitcnt lgkmcnt(1)
	v_mfma_f32_32x32x16_bf16 v[0:15], v[20:23], v[72:75], v[0:15]
	v_ashrrev_i32_e32 v186, 31, v45
	v_ashrrev_i32_e32 v20, 31, v29
	v_and_b32_e32 v45, 0xffffff80, v45
	v_and_b32_e32 v186, 0x7fffff80, v186
	v_and_b32_e32 v20, 0x7fffff80, v20
	v_and_b32_e32 v21, 0xffffff80, v29
	v_bitop3_b32 v45, v186, v114, v45 bitop3:0xde
	v_bitop3_b32 v186, v20, v130, v21 bitop3:0xde
	ds_read_b128 v[20:23], v168 offset:17632
	s_waitcnt lgkmcnt(1)
	v_mfma_f32_32x32x16_bf16 v[0:15], v[16:19], v[68:71], v[0:15]
	v_and_b32_e32 v25, 0xffffff80, v28
	v_ashrrev_i32_e32 v187, 31, v46
	v_bitop3_b32 v177, v24, v129, v25 bitop3:0xde
	v_ashrrev_i32_e32 v24, 31, v30
	v_and_b32_e32 v46, 0xffffff80, v46
	v_and_b32_e32 v187, 0x7fffff80, v187
	v_and_b32_e32 v16, 0x7fffff80, v24
	s_waitcnt lgkmcnt(0)
	v_mfma_f32_32x32x16_bf16 v[0:15], v[20:23], v[64:67], v[0:15]
	v_and_b32_e32 v17, 0xffffff80, v30
	v_ashrrev_i32_e32 v188, 31, v47
	v_bitop3_b32 v46, v187, v115, v46 bitop3:0xde
	v_bitop3_b32 v187, v16, v131, v17 bitop3:0xde
	v_ashrrev_i32_e32 v16, 31, v31
	v_and_b32_e32 v47, 0xffffff80, v47
	v_and_b32_e32 v188, 0x7fffff80, v188
	v_and_b32_e32 v16, 0x7fffff80, v16
	v_and_b32_e32 v17, 0xffffff80, v31
	v_bitop3_b32 v47, v188, v116, v47 bitop3:0xde
	v_bitop3_b32 v188, v16, v132, v17 bitop3:0xde
	s_nop 0
	v_ashrrev_i32_e32 v16, 31, v0
	v_and_b32_e32 v16, 0x7fffff80, v16
	v_and_b32_e32 v0, 0xffffff80, v0
	v_bitop3_b32 v190, v16, v133, v0 bitop3:0xde
	v_ashrrev_i32_e32 v0, 31, v1
	ds_read_b128 v[16:19], v168 offset:26112
	v_and_b32_e32 v0, 0x7fffff80, v0
	v_and_b32_e32 v1, 0xffffff80, v1
	v_bitop3_b32 v192, v0, v134, v1 bitop3:0xde
	v_ashrrev_i32_e32 v0, 31, v2
	v_and_b32_e32 v0, 0x7fffff80, v0
	v_and_b32_e32 v1, 0xffffff80, v2
	v_bitop3_b32 v193, v0, v135, v1 bitop3:0xde
	v_ashrrev_i32_e32 v0, 31, v3
	v_and_b32_e32 v0, 0x7fffff80, v0
	v_and_b32_e32 v1, 0xffffff80, v3
	v_bitop3_b32 v194, v0, v136, v1 bitop3:0xde
	v_ashrrev_i32_e32 v0, 31, v4
	v_and_b32_e32 v0, 0x7fffff80, v0
	v_and_b32_e32 v1, 0xffffff80, v4
	v_bitop3_b32 v195, v0, v137, v1 bitop3:0xde
	ds_read_b128 v[0:3], v168 offset:26144
	s_waitcnt lgkmcnt(1)
	v_mfma_f32_32x32x16_bf16 v[16:31], v[16:19], v[60:63], 0
	v_ashrrev_i32_e32 v90, 31, v32
	v_ashrrev_i32_e32 v170, 31, v33
	v_ashrrev_i32_e32 v171, 31, v34
	v_ashrrev_i32_e32 v172, 31, v35
	v_and_b32_e32 v32, 0xffffff80, v32
	v_and_b32_e32 v33, 0xffffff80, v33
	v_and_b32_e32 v34, 0xffffff80, v34
	v_and_b32_e32 v35, 0xffffff80, v35
	v_and_b32_e32 v90, 0x7fffff80, v90
	v_and_b32_e32 v170, 0x7fffff80, v170
	v_and_b32_e32 v171, 0x7fffff80, v171
	v_and_b32_e32 v172, 0x7fffff80, v172
	v_bitop3_b32 v90, v90, v99, v32 bitop3:0xde
	v_bitop3_b32 v170, v170, v102, v33 bitop3:0xde
	v_bitop3_b32 v171, v171, v103, v34 bitop3:0xde
	v_bitop3_b32 v172, v172, v104, v35 bitop3:0xde
	ds_read_b128 v[32:35], v168 offset:26176
	s_waitcnt lgkmcnt(1)
	v_mfma_f32_32x32x16_bf16 v[16:31], v[0:3], v[56:59], v[16:31]
	v_ashrrev_i32_e32 v0, 31, v7
	v_and_b32_e32 v0, 0x7fffff80, v0
	v_and_b32_e32 v1, 0xffffff80, v7
	v_bitop3_b32 v57, v0, v140, v1 bitop3:0xde
	ds_read_b128 v[0:3], v168 offset:26208
	v_ashrrev_i32_e32 v4, 31, v5
	v_and_b32_e32 v4, 0x7fffff80, v4
	s_waitcnt lgkmcnt(1)
	v_mfma_f32_32x32x16_bf16 v[16:31], v[32:35], v[84:87], v[16:31]
	v_and_b32_e32 v5, 0xffffff80, v5
	v_bitop3_b32 v60, v4, v138, v5 bitop3:0xde
	v_ashrrev_i32_e32 v4, 31, v6
	v_and_b32_e32 v4, 0x7fffff80, v4
	v_and_b32_e32 v5, 0xffffff80, v6
	v_bitop3_b32 v56, v4, v139, v5 bitop3:0xde
	v_ashrrev_i32_e32 v4, 31, v8
	v_and_b32_e32 v4, 0x7fffff80, v4
	v_and_b32_e32 v5, 0xffffff80, v8
	v_bitop3_b32 v8, v4, v141, v5 bitop3:0xde
	v_ashrrev_i32_e32 v4, 31, v9
	v_and_b32_e32 v32, 0x7fffff80, v4
	ds_read_b128 v[4:7], v168 offset:26240
	s_waitcnt lgkmcnt(1)
	v_mfma_f32_32x32x16_bf16 v[16:31], v[0:3], v[76:79], v[16:31]
	v_ashrrev_i32_e32 v0, 31, v10
	v_and_b32_e32 v0, 0x7fffff80, v0
	v_and_b32_e32 v1, 0xffffff80, v10
	v_bitop3_b32 v10, v0, v143, v1 bitop3:0xde
	ds_read_b128 v[0:3], v168 offset:26272
	v_and_b32_e32 v9, 0xffffff80, v9
	v_bitop3_b32 v9, v32, v142, v9 bitop3:0xde
	s_waitcnt lgkmcnt(1)
	v_mfma_f32_32x32x16_bf16 v[16:31], v[4:7], v[80:83], v[16:31]
	v_ashrrev_i32_e32 v32, 31, v11
	v_and_b32_e32 v4, 0x7fffff80, v32
	v_and_b32_e32 v5, 0xffffff80, v11
	v_bitop3_b32 v11, v4, v144, v5 bitop3:0xde
	v_ashrrev_i32_e32 v4, 31, v12
	v_and_b32_e32 v32, 0x7fffff80, v4
	ds_read_b128 v[4:7], v168 offset:26304
	s_waitcnt lgkmcnt(1)
	v_mfma_f32_32x32x16_bf16 v[16:31], v[0:3], v[72:75], v[16:31]
	v_ashrrev_i32_e32 v0, 31, v13
	v_and_b32_e32 v0, 0x7fffff80, v0
	v_and_b32_e32 v1, 0xffffff80, v13
	v_bitop3_b32 v13, v0, v146, v1 bitop3:0xde
	ds_read_b128 v[0:3], v168 offset:26336
	v_and_b32_e32 v12, 0xffffff80, v12
	v_bitop3_b32 v12, v32, v145, v12 bitop3:0xde
	s_waitcnt lgkmcnt(1)
	v_mfma_f32_32x32x16_bf16 v[16:31], v[4:7], v[68:71], v[16:31]
	v_ashrrev_i32_e32 v32, 31, v14
	v_and_b32_e32 v4, 0x7fffff80, v32
	v_and_b32_e32 v5, 0xffffff80, v14
	v_bitop3_b32 v4, v4, v147, v5 bitop3:0xde
	v_ashrrev_i32_e32 v5, 31, v15
	v_and_b32_e32 v5, 0x7fffff80, v5
	v_and_b32_e32 v6, 0xffffff80, v15
	s_waitcnt lgkmcnt(0)
; __device__ __forceinline__ int crow(int r, int hf) { return (r & 3) + 8 * (r >> 2) + 4 * hf; }
; __device__ __forceinline__ int tosort(float f) { int b = __float_as_int(f); return b ^ ((b >> 31) & 0x7fffffff); }
; template <int PP>
; __device__ __forceinline__ void select_half(const Params& p, const u16* Subs, int t, int hh, int lc, int hf, int* lists) {
;     ...
;     for (int ks = 0; ks < 8; ++ks) {
;       bf16x8 a = *(const bf16x8*)(Subs + (PP * 128 + nb * 32 + lc) * 136 + ks * 16 + hf * 8);
;       acc = mfma32(a, qf[ks], acc);
;     }
; #pragma unroll
;     for (int r = 0; r < 16; ++r) keys[nb * 16 + r] = (tosort(acc[r]) & ~127) | (nb * 32 + crow(r, hf));
;   }
;   sort16_desc<0>(keys); sort16_desc<16>(keys); sort16_desc<32>(keys); sort16_desc<48>(keys);
	v_mfma_f32_32x32x16_bf16 v[16:31], v[0:3], v[64:67], v[16:31]
	v_bitop3_b32 v5, v5, v148, v6 bitop3:0xde
	v_max_i32_e32 v32, v40, v41
	v_min_i32_e32 v33, v40, v41
	v_max_i32_e32 v34, v43, v42
	v_min_i32_e32 v35, v43, v42
	v_max_i32_e32 v58, v173, v178
	v_min_i32_e32 v59, v173, v178
	s_nop 4
	v_ashrrev_i32_e32 v0, 31, v16
	v_and_b32_e32 v0, 0x7fffff80, v0
	v_and_b32_e32 v1, 0xffffff80, v16
	v_bitop3_b32 v0, v0, v149, v1 bitop3:0xde
	v_ashrrev_i32_e32 v1, 31, v17
	v_and_b32_e32 v1, 0x7fffff80, v1
	v_and_b32_e32 v2, 0xffffff80, v17
	v_bitop3_b32 v1, v1, v150, v2 bitop3:0xde
	v_ashrrev_i32_e32 v2, 31, v18
	v_and_b32_e32 v2, 0x7fffff80, v2
	v_and_b32_e32 v3, 0xffffff80, v18
	v_bitop3_b32 v2, v2, v151, v3 bitop3:0xde
	v_ashrrev_i32_e32 v3, 31, v19
	v_and_b32_e32 v3, 0x7fffff80, v3
	v_and_b32_e32 v6, 0xffffff80, v19
	v_bitop3_b32 v3, v3, v152, v6 bitop3:0xde
	v_ashrrev_i32_e32 v6, 31, v20
	v_and_b32_e32 v6, 0x7fffff80, v6
	v_and_b32_e32 v7, 0xffffff80, v20
	v_bitop3_b32 v6, v6, v153, v7 bitop3:0xde
	v_ashrrev_i32_e32 v7, 31, v21
	v_and_b32_e32 v7, 0x7fffff80, v7
	v_and_b32_e32 v14, 0xffffff80, v21
	v_bitop3_b32 v7, v7, v154, v14 bitop3:0xde
	v_ashrrev_i32_e32 v14, 31, v22
	v_and_b32_e32 v14, 0x7fffff80, v14
	v_and_b32_e32 v15, 0xffffff80, v22
	v_bitop3_b32 v14, v14, v155, v15 bitop3:0xde
	v_ashrrev_i32_e32 v15, 31, v23
	v_and_b32_e32 v15, 0x7fffff80, v15
	v_and_b32_e32 v16, 0xffffff80, v23
	v_bitop3_b32 v15, v15, v156, v16 bitop3:0xde
	v_ashrrev_i32_e32 v16, 31, v24
	v_and_b32_e32 v16, 0x7fffff80, v16
	v_and_b32_e32 v17, 0xffffff80, v24
	v_bitop3_b32 v16, v16, v157, v17 bitop3:0xde
	v_ashrrev_i32_e32 v17, 31, v25
	v_and_b32_e32 v17, 0x7fffff80, v17
	v_and_b32_e32 v18, 0xffffff80, v25
	v_bitop3_b32 v17, v17, v158, v18 bitop3:0xde
	v_ashrrev_i32_e32 v18, 31, v26
	v_and_b32_e32 v18, 0x7fffff80, v18
	v_and_b32_e32 v19, 0xffffff80, v26
	v_bitop3_b32 v18, v18, v159, v19 bitop3:0xde
	v_ashrrev_i32_e32 v19, 31, v27
	v_and_b32_e32 v19, 0x7fffff80, v19
	v_and_b32_e32 v20, 0xffffff80, v27
	v_bitop3_b32 v19, v19, v160, v20 bitop3:0xde
	v_ashrrev_i32_e32 v20, 31, v28
	v_and_b32_e32 v20, 0x7fffff80, v20
	v_and_b32_e32 v21, 0xffffff80, v28
	v_bitop3_b32 v20, v20, v161, v21 bitop3:0xde
	v_ashrrev_i32_e32 v21, 31, v29
	v_and_b32_e32 v21, 0x7fffff80, v21
	v_and_b32_e32 v22, 0xffffff80, v29
	v_bitop3_b32 v21, v21, v162, v22 bitop3:0xde
	v_ashrrev_i32_e32 v22, 31, v30
	v_and_b32_e32 v22, 0x7fffff80, v22
	v_and_b32_e32 v23, 0xffffff80, v30
	v_bitop3_b32 v22, v22, v163, v23 bitop3:0xde
	v_ashrrev_i32_e32 v23, 31, v31
	v_and_b32_e32 v23, 0x7fffff80, v23
	v_and_b32_e32 v24, 0xffffff80, v31
	v_bitop3_b32 v23, v23, v164, v24 bitop3:0xde
	v_max_i32_e32 v24, v90, v170
	v_min_i32_e32 v25, v90, v170
	v_max_i32_e32 v26, v172, v171
	v_min_i32_e32 v27, v172, v171
	v_max_i32_e32 v28, v36, v37
	v_min_i32_e32 v29, v36, v37
	v_max_i32_e32 v30, v39, v38
	v_min_i32_e32 v31, v39, v38
	v_max_i32_e32 v36, v44, v45
	v_min_i32_e32 v37, v44, v45
	v_max_i32_e32 v38, v47, v46
	v_min_i32_e32 v39, v47, v46
	v_max_i32_e32 v61, v180, v179
	v_min_i32_e32 v62, v180, v179
	v_max_i32_e32 v63, v181, v182
	v_min_i32_e32 v64, v181, v182
	v_max_i32_e32 v65, v184, v183
	v_min_i32_e32 v66, v184, v183
	v_max_i32_e32 v67, v185, v174
	v_min_i32_e32 v68, v185, v174
	v_max_i32_e32 v69, v176, v175
	v_min_i32_e32 v70, v176, v175
	v_max_i32_e32 v71, v177, v186
	v_min_i32_e32 v72, v177, v186
	v_max_i32_e32 v73, v188, v187
	v_min_i32_e32 v74, v188, v187
	v_max_i32_e32 v40, v24, v27
	v_min_i32_e32 v24, v24, v27
	v_max_i32_e32 v27, v25, v26
	v_min_i32_e32 v25, v25, v26
	v_max_i32_e32 v26, v31, v28
	v_min_i32_e32 v28, v31, v28
	v_max_i32_e32 v31, v30, v29
	v_min_i32_e32 v29, v30, v29
	v_max_i32_e32 v30, v32, v35
	v_min_i32_e32 v32, v32, v35
	v_max_i32_e32 v35, v33, v34
	v_min_i32_e32 v33, v33, v34
	v_max_i32_e32 v34, v39, v36
	v_min_i32_e32 v36, v39, v36
	v_max_i32_e32 v39, v38, v37
	v_min_i32_e32 v37, v38, v37
	v_max_i32_e32 v75, v58, v62
	v_min_i32_e32 v58, v58, v62
	v_max_i32_e32 v62, v59, v61
	v_min_i32_e32 v59, v59, v61
	v_max_i32_e32 v61, v66, v63
	v_min_i32_e32 v63, v66, v63
	v_max_i32_e32 v66, v65, v64
	v_min_i32_e32 v64, v65, v64
	v_max_i32_e32 v65, v67, v70
	v_min_i32_e32 v67, v67, v70
	v_max_i32_e32 v70, v68, v69
	v_min_i32_e32 v68, v68, v69
	v_max_i32_e32 v69, v74, v71
	v_min_i32_e32 v71, v74, v71
	v_max_i32_e32 v74, v73, v72
	v_min_i32_e32 v72, v73, v72
	v_max_i32_e32 v38, v40, v27
	v_min_i32_e32 v27, v40, v27
	v_max_i32_e32 v40, v24, v25
	v_min_i32_e32 v24, v24, v25
	v_max_i32_e32 v25, v29, v28
	v_min_i32_e32 v28, v29, v28
	v_max_i32_e32 v29, v31, v26
	v_min_i32_e32 v26, v31, v26
	v_max_i32_e32 v31, v30, v35
	v_min_i32_e32 v30, v30, v35
	v_max_i32_e32 v35, v32, v33
	v_min_i32_e32 v32, v32, v33
	v_max_i32_e32 v33, v37, v36
	v_min_i32_e32 v36, v37, v36
	v_max_i32_e32 v37, v39, v34
	v_min_i32_e32 v34, v39, v34
	v_max_i32_e32 v73, v75, v62
	v_min_i32_e32 v62, v75, v62
	v_max_i32_e32 v75, v58, v59
	v_min_i32_e32 v58, v58, v59
	v_max_i32_e32 v59, v64, v63
	v_min_i32_e32 v63, v64, v63
	v_max_i32_e32 v64, v66, v61
	v_min_i32_e32 v61, v66, v61
	v_max_i32_e32 v66, v65, v70
	v_min_i32_e32 v65, v65, v70
	v_max_i32_e32 v70, v67, v68
	v_min_i32_e32 v67, v67, v68
	v_max_i32_e32 v68, v72, v71
	v_min_i32_e32 v71, v72, v71
	v_max_i32_e32 v72, v74, v69
	v_min_i32_e32 v69, v74, v69
	v_max_i32_e32 v39, v38, v28
	v_min_i32_e32 v28, v38, v28
	v_max_i32_e32 v38, v27, v25
	v_min_i32_e32 v25, v27, v25
	v_max_i32_e32 v27, v40, v26
	v_min_i32_e32 v26, v40, v26
	v_max_i32_e32 v40, v24, v29
	v_min_i32_e32 v24, v24, v29
	v_max_i32_e32 v29, v36, v31
	v_min_i32_e32 v31, v36, v31
	v_max_i32_e32 v36, v33, v30
	v_min_i32_e32 v30, v33, v30
; template <int OFF>
; __device__ __forceinline__ void sort16_desc(int* a) {
; #pragma unroll
;   for (int ks = 1; ks <= 4; ++ks) {
; #pragma unroll
;     ...
; #pragma unroll
;       for (int i = 0; i < 16; ++i) {
;         const int k = 1 << ks, j = 1 << js;
;         const int l2 = i ^ j;
;         if (l2 > i) { if ((i & k) == 0) cas_desc(a[OFF + i], a[OFF + l2]); else cas_desc(a[OFF + l2], a[OFF + i]); }
;       }
;     }
;   }
; }
	v_max_i32_e32 v33, v34, v35
	v_min_i32_e32 v34, v34, v35
	v_max_i32_e32 v35, v37, v32
	v_min_i32_e32 v32, v37, v32
	v_max_i32_e32 v74, v73, v63
	v_min_i32_e32 v63, v73, v63
	v_max_i32_e32 v73, v62, v59
	v_min_i32_e32 v59, v62, v59
	v_max_i32_e32 v62, v75, v61
	v_min_i32_e32 v61, v75, v61
	v_max_i32_e32 v75, v58, v64
	v_min_i32_e32 v58, v58, v64
	v_max_i32_e32 v64, v71, v66
	v_min_i32_e32 v66, v71, v66
	v_max_i32_e32 v71, v68, v65
	v_min_i32_e32 v65, v68, v65
	v_max_i32_e32 v68, v69, v70
	v_min_i32_e32 v69, v69, v70
	v_max_i32_e32 v70, v72, v67
	v_min_i32_e32 v67, v72, v67
	v_max_i32_e32 v37, v39, v27
	v_min_i32_e32 v27, v39, v27
	v_max_i32_e32 v39, v38, v40
	v_min_i32_e32 v38, v38, v40
	v_max_i32_e32 v40, v28, v26
	v_min_i32_e32 v26, v28, v26
	v_max_i32_e32 v28, v25, v24
	v_min_i32_e32 v24, v25, v24
	v_max_i32_e32 v25, v34, v31
	v_min_i32_e32 v31, v34, v31
	v_max_i32_e32 v34, v32, v30
	v_min_i32_e32 v30, v32, v30
	v_max_i32_e32 v32, v33, v29
	v_min_i32_e32 v29, v33, v29
	v_max_i32_e32 v33, v35, v36
	v_min_i32_e32 v35, v35, v36
	v_max_i32_e32 v72, v74, v62
	v_min_i32_e32 v62, v74, v62
	v_max_i32_e32 v74, v73, v75
	v_min_i32_e32 v73, v73, v75
	v_max_i32_e32 v75, v63, v61
	v_min_i32_e32 v61, v63, v61
	v_max_i32_e32 v63, v59, v58
	v_min_i32_e32 v58, v59, v58
	v_max_i32_e32 v59, v69, v66
	v_min_i32_e32 v66, v69, v66
	v_max_i32_e32 v69, v67, v65
	v_min_i32_e32 v65, v67, v65
	v_max_i32_e32 v67, v68, v64
	v_min_i32_e32 v64, v68, v64
	v_max_i32_e32 v68, v70, v71
	v_min_i32_e32 v70, v70, v71
	v_max_i32_e32 v36, v37, v39
	v_min_i32_e32 v37, v37, v39
	v_max_i32_e32 v39, v27, v38
	v_min_i32_e32 v27, v27, v38
	v_max_i32_e32 v38, v40, v28
	v_min_i32_e32 v28, v40, v28
	v_max_i32_e32 v40, v26, v24
	v_min_i32_e32 v24, v26, v24
	v_max_i32_e32 v26, v30, v31
	v_min_i32_e32 v30, v30, v31
	v_max_i32_e32 v31, v34, v25
	v_min_i32_e32 v25, v34, v25
	v_max_i32_e32 v34, v35, v29
	v_min_i32_e32 v29, v35, v29
	v_max_i32_e32 v35, v33, v32
	v_min_i32_e32 v32, v33, v32
	v_max_i32_e32 v71, v72, v74
	v_min_i32_e32 v72, v72, v74
	v_max_i32_e32 v74, v62, v73
	v_min_i32_e32 v62, v62, v73
	v_max_i32_e32 v73, v75, v63
	v_min_i32_e32 v63, v75, v63
	v_max_i32_e32 v75, v61, v58
	v_min_i32_e32 v58, v61, v58
	v_max_i32_e32 v61, v65, v66
	v_min_i32_e32 v65, v65, v66
	v_max_i32_e32 v66, v69, v59
	v_min_i32_e32 v59, v69, v59
	v_max_i32_e32 v69, v70, v64
	v_min_i32_e32 v64, v70, v64
	v_max_i32_e32 v70, v68, v67
	v_min_i32_e32 v67, v68, v67
	v_max_i32_e32 v33, v36, v30
	v_min_i32_e32 v30, v36, v30
	v_max_i32_e32 v36, v37, v26
	v_min_i32_e32 v26, v37, v26
	v_max_i32_e32 v37, v39, v25
	v_min_i32_e32 v25, v39, v25
	v_max_i32_e32 v39, v27, v31
	v_min_i32_e32 v27, v27, v31
	v_max_i32_e32 v31, v38, v29
	v_min_i32_e32 v29, v38, v29
	v_max_i32_e32 v38, v28, v34
	v_min_i32_e32 v28, v28, v34
	v_max_i32_e32 v34, v40, v32
	v_min_i32_e32 v32, v40, v32
	v_max_i32_e32 v40, v24, v35
	v_min_i32_e32 v24, v24, v35
	v_max_i32_e32 v68, v71, v65
	v_min_i32_e32 v65, v71, v65
	v_max_i32_e32 v71, v72, v61
	v_min_i32_e32 v61, v72, v61
	v_max_i32_e32 v72, v74, v59
	v_min_i32_e32 v59, v74, v59
	v_max_i32_e32 v74, v62, v66
	v_min_i32_e32 v62, v62, v66
	v_max_i32_e32 v66, v73, v64
	v_min_i32_e32 v64, v73, v64
	v_max_i32_e32 v73, v63, v69
	v_min_i32_e32 v63, v63, v69
	v_max_i32_e32 v69, v75, v67
	v_min_i32_e32 v67, v75, v67
	v_max_i32_e32 v75, v58, v70
	v_min_i32_e32 v58, v58, v70
	v_max_i32_e32 v35, v33, v31
	v_min_i32_e32 v31, v33, v31
	v_max_i32_e32 v33, v36, v38
	v_min_i32_e32 v36, v36, v38
	v_max_i32_e32 v38, v37, v34
	v_min_i32_e32 v34, v37, v34
	v_max_i32_e32 v37, v39, v40
	v_min_i32_e32 v39, v39, v40
	v_max_i32_e32 v40, v30, v29
	v_min_i32_e32 v29, v30, v29
	v_max_i32_e32 v30, v26, v28
	v_min_i32_e32 v26, v26, v28
	v_max_i32_e32 v28, v25, v32
	v_min_i32_e32 v25, v25, v32
	v_max_i32_e32 v32, v27, v24
	v_min_i32_e32 v24, v27, v24
	v_max_i32_e32 v70, v68, v66
	v_min_i32_e32 v66, v68, v66
	v_max_i32_e32 v68, v71, v73
	v_min_i32_e32 v71, v71, v73
	v_max_i32_e32 v73, v72, v69
	v_min_i32_e32 v69, v72, v69
	v_max_i32_e32 v72, v74, v75
	v_min_i32_e32 v74, v74, v75
	v_max_i32_e32 v75, v65, v64
	v_min_i32_e32 v64, v65, v64
	v_max_i32_e32 v65, v61, v63
	v_min_i32_e32 v61, v61, v63
	v_max_i32_e32 v63, v59, v67
	v_min_i32_e32 v59, v59, v67
	v_max_i32_e32 v67, v62, v58
	v_min_i32_e32 v58, v62, v58
	v_max_i32_e32 v27, v35, v38
	v_min_i32_e32 v35, v35, v38
	v_max_i32_e32 v38, v33, v37
	v_min_i32_e32 v33, v33, v37
	v_max_i32_e32 v37, v31, v34
	v_min_i32_e32 v31, v31, v34
	v_max_i32_e32 v34, v36, v39
	v_min_i32_e32 v36, v36, v39
	v_max_i32_e32 v39, v40, v28
	v_min_i32_e32 v28, v40, v28
	v_max_i32_e32 v40, v30, v32
	v_min_i32_e32 v30, v30, v32
	v_max_i32_e32 v32, v29, v25
	v_min_i32_e32 v25, v29, v25
	v_max_i32_e32 v29, v26, v24
	v_max_i32_e32 v62, v70, v73
	v_min_i32_e32 v70, v70, v73
	v_max_i32_e32 v73, v68, v72
	v_min_i32_e32 v68, v68, v72
	v_max_i32_e32 v72, v66, v69
	v_min_i32_e32 v66, v66, v69
	v_max_i32_e32 v69, v71, v74
	v_min_i32_e32 v71, v71, v74
	v_max_i32_e32 v74, v75, v63
	v_min_i32_e32 v63, v75, v63
	v_max_i32_e32 v75, v65, v67
	v_min_i32_e32 v65, v65, v67
	v_max_i32_e32 v67, v64, v59
	v_min_i32_e32 v59, v64, v59
	v_max_i32_e32 v64, v61, v58
	v_min_i32_e32 v58, v61, v58
	v_min_i32_e32 v44, v39, v40
	v_min_i32_e32 v45, v28, v30
	v_min_i32_e32 v46, v32, v29
	v_min_i32_e32 v76, v70, v68
	v_min_i32_e32 v77, v72, v69
	v_min_i32_e32 v78, v66, v71
	v_min_i32_e32 v82, v59, v58
	v_min_i32_e32 v24, v26, v24
	v_min_i32_e32 v26, v27, v38
	v_max3_i32 v27, v27, v38, v82
	v_max3_i32 v38, v39, v40, v78
	v_max3_i32 v39, v44, v66, v71
	v_max3_i32 v28, v28, v30, v77
	v_max3_i32 v30, v45, v72, v69
	v_max3_i32 v29, v32, v29, v76
; template <int OFF>
; __device__ __forceinline__ void sort16_desc(int* a) {
; #pragma unroll
;   for (int ks = 1; ks <= 4; ++ks) {
; #pragma unroll
;     ...
; #pragma unroll
;       for (int i = 0; i < 16; ++i) {
;         const int k = 1 << ks, j = 1 << js;
;         const int l2 = i ^ j;
;         if (l2 > i) { if ((i & k) == 0) cas_desc(a[OFF + i], a[OFF + l2]); else cas_desc(a[OFF + l2], a[OFF + i]); }
;       }
;     }
;   }
; }
; template <int PP>
; __device__ __forceinline__ void select_half(const Params& p, const u16* Subs, int t, int hh, int lc, int hf, int* lists) {
;     ...
;   const u16* qrow = p.qp + (size_t)t * 2048 + hh * 256 + PP * 128 + hf * 8;
; #pragma unroll
;   for (int ks = 0; ks < 8; ++ks) qf[ks] = *(const bf16x8*)(qrow + ks * 16);
	v_max3_i32 v32, v46, v70, v68
	global_load_dwordx4 v[68:71], v[96:97], off offset:256
	v_max_i32_e32 v177, v0, v1
	v_min_i32_e32 v0, v0, v1
	v_max_i32_e32 v1, v3, v2
	v_min_i32_e32 v2, v3, v2
	v_max_i32_e32 v3, v6, v7
	v_min_i32_e32 v6, v6, v7
	v_max_i32_e32 v7, v15, v14
	v_min_i32_e32 v14, v15, v14
	v_max_i32_e32 v15, v16, v17
	v_min_i32_e32 v16, v16, v17
	v_max_i32_e32 v17, v19, v18
	v_min_i32_e32 v18, v19, v18
	v_max_i32_e32 v19, v20, v21
	v_min_i32_e32 v20, v20, v21
	v_max_i32_e32 v21, v23, v22
	v_min_i32_e32 v22, v23, v22
	v_min_i32_e32 v41, v35, v33
	v_min_i32_e32 v42, v37, v34
	v_min_i32_e32 v80, v63, v65
	v_min_i32_e32 v81, v67, v64
	v_max_i32_e32 v83, v190, v192
	v_min_i32_e32 v84, v190, v192
	v_max_i32_e32 v85, v194, v193
	v_min_i32_e32 v86, v194, v193
	v_max_i32_e32 v87, v195, v60
	v_min_i32_e32 v60, v195, v60
	v_max_i32_e32 v90, v57, v56
	v_min_i32_e32 v56, v57, v56
	v_max_i32_e32 v57, v8, v9
	v_min_i32_e32 v8, v8, v9
	v_max_i32_e32 v9, v11, v10
	v_min_i32_e32 v10, v11, v10
	v_max_i32_e32 v11, v12, v13
	v_min_i32_e32 v12, v12, v13
	v_max_i32_e32 v13, v5, v4
	v_min_i32_e32 v4, v5, v4
	v_max_i32_e32 v23, v177, v2
	v_min_i32_e32 v2, v177, v2
	v_max_i32_e32 v177, v0, v1
	v_min_i32_e32 v0, v0, v1
	v_max_i32_e32 v1, v14, v3
	v_min_i32_e32 v3, v14, v3
	v_max_i32_e32 v14, v7, v6
	v_min_i32_e32 v6, v7, v6
	v_max_i32_e32 v7, v15, v18
	v_min_i32_e32 v15, v15, v18
	v_max_i32_e32 v18, v16, v17
	v_min_i32_e32 v16, v16, v17
	v_max_i32_e32 v17, v22, v19
	v_min_i32_e32 v19, v22, v19
	v_max_i32_e32 v22, v21, v20
	v_min_i32_e32 v20, v21, v20
	v_max_i32_e32 v5, v83, v86
	v_min_i32_e32 v83, v83, v86
	v_max_i32_e32 v86, v84, v85
	v_min_i32_e32 v84, v84, v85
	v_max_i32_e32 v85, v56, v87
	v_min_i32_e32 v56, v56, v87
	v_max_i32_e32 v87, v90, v60
	v_min_i32_e32 v60, v90, v60
	v_max_i32_e32 v90, v57, v10
	v_min_i32_e32 v10, v57, v10
	v_max_i32_e32 v57, v8, v9
	v_min_i32_e32 v8, v8, v9
	v_max_i32_e32 v9, v4, v11
	v_min_i32_e32 v4, v4, v11
	v_max_i32_e32 v11, v13, v12
	v_min_i32_e32 v12, v13, v12
	v_max_i32_e32 v21, v23, v177
	v_min_i32_e32 v23, v23, v177
	v_max_i32_e32 v177, v2, v0
	v_min_i32_e32 v0, v2, v0
	v_max_i32_e32 v2, v6, v3
	v_min_i32_e32 v3, v6, v3
	v_max_i32_e32 v6, v14, v1
	v_min_i32_e32 v1, v14, v1
	v_max_i32_e32 v14, v7, v18
	v_min_i32_e32 v7, v7, v18
	v_max_i32_e32 v18, v15, v16
	v_min_i32_e32 v15, v15, v16
	v_max_i32_e32 v16, v20, v19
	v_min_i32_e32 v19, v20, v19
	v_max_i32_e32 v20, v22, v17
	v_min_i32_e32 v17, v22, v17
	v_max3_i32 v33, v35, v33, v81
	v_max3_i32 v35, v41, v67, v64
	v_max3_i32 v34, v37, v34, v80
	v_max3_i32 v37, v42, v63, v65
	global_load_dwordx4 v[64:67], v[96:97], off offset:288
	v_max_i32_e32 v13, v5, v86
	v_min_i32_e32 v5, v5, v86
	v_max_i32_e32 v86, v83, v84
	v_min_i32_e32 v83, v83, v84
	v_max_i32_e32 v84, v60, v56
	v_min_i32_e32 v56, v60, v56
	v_max_i32_e32 v60, v87, v85
	v_min_i32_e32 v85, v87, v85
	v_max_i32_e32 v87, v90, v57
	v_min_i32_e32 v57, v90, v57
	v_max_i32_e32 v90, v10, v8
	v_min_i32_e32 v8, v10, v8
	v_max_i32_e32 v10, v12, v4
	v_min_i32_e32 v4, v12, v4
	v_max_i32_e32 v12, v11, v9
	v_min_i32_e32 v9, v11, v9
	v_max_i32_e32 v22, v21, v3
	v_min_i32_e32 v3, v21, v3
	v_max_i32_e32 v21, v23, v2
	v_min_i32_e32 v2, v23, v2
	v_max_i32_e32 v23, v177, v1
	v_min_i32_e32 v1, v177, v1
	v_max_i32_e32 v177, v0, v6
	v_min_i32_e32 v0, v0, v6
	v_max_i32_e32 v6, v19, v14
	v_min_i32_e32 v14, v19, v14
	v_max_i32_e32 v19, v16, v7
	v_min_i32_e32 v7, v16, v7
	v_max_i32_e32 v16, v17, v18
	v_min_i32_e32 v17, v17, v18
	v_max_i32_e32 v18, v20, v15
	v_min_i32_e32 v15, v20, v15
	v_max_i32_e32 v11, v13, v56
	v_min_i32_e32 v13, v13, v56
	v_max_i32_e32 v56, v5, v84
	v_min_i32_e32 v5, v5, v84
	v_max_i32_e32 v84, v86, v85
	v_min_i32_e32 v85, v86, v85
	v_max_i32_e32 v86, v83, v60
	v_min_i32_e32 v60, v83, v60
	v_max_i32_e32 v83, v4, v87
	v_min_i32_e32 v4, v4, v87
	v_max_i32_e32 v87, v10, v57
	v_min_i32_e32 v10, v10, v57
	v_max_i32_e32 v57, v9, v90
	v_min_i32_e32 v9, v9, v90
	v_max_i32_e32 v90, v12, v8
	v_min_i32_e32 v8, v12, v8
	v_max_i32_e32 v20, v22, v23
	v_min_i32_e32 v22, v22, v23
	v_max_i32_e32 v23, v21, v177
	v_min_i32_e32 v21, v21, v177
	v_max_i32_e32 v177, v3, v1
	v_min_i32_e32 v1, v3, v1
	v_max_i32_e32 v3, v2, v0
	v_min_i32_e32 v0, v2, v0
	v_max_i32_e32 v2, v17, v14
	v_min_i32_e32 v14, v17, v14
	v_max_i32_e32 v17, v15, v7
	v_min_i32_e32 v7, v15, v7
	v_max_i32_e32 v15, v16, v6
	v_min_i32_e32 v6, v16, v6
	v_max_i32_e32 v16, v18, v19
	v_min_i32_e32 v18, v18, v19
	v_max_i32_e32 v12, v11, v84
	v_min_i32_e32 v11, v11, v84
	v_max_i32_e32 v84, v56, v86
	v_min_i32_e32 v56, v56, v86
	v_max_i32_e32 v86, v13, v85
	v_min_i32_e32 v13, v13, v85
	v_max_i32_e32 v85, v5, v60
	v_min_i32_e32 v5, v5, v60
	v_max_i32_e32 v60, v9, v4
	v_min_i32_e32 v4, v9, v4
	v_max_i32_e32 v9, v8, v10
	v_min_i32_e32 v8, v8, v10
	v_max_i32_e32 v10, v57, v83
	v_min_i32_e32 v57, v57, v83
	v_max_i32_e32 v83, v90, v87
	v_min_i32_e32 v87, v90, v87
	v_max_i32_e32 v19, v20, v23
	v_min_i32_e32 v20, v20, v23
	v_max_i32_e32 v23, v22, v21
	v_min_i32_e32 v21, v22, v21
	v_max_i32_e32 v22, v177, v3
	v_min_i32_e32 v3, v177, v3
	v_max_i32_e32 v177, v1, v0
	v_min_i32_e32 v0, v1, v0
	v_max_i32_e32 v1, v7, v14
	v_min_i32_e32 v7, v7, v14
	v_max_i32_e32 v14, v17, v2
	v_min_i32_e32 v2, v17, v2
	v_max_i32_e32 v17, v18, v6
	v_min_i32_e32 v6, v18, v6
	v_max_i32_e32 v18, v16, v15
	v_min_i32_e32 v15, v16, v15
	v_max_i32_e32 v90, v12, v84
	v_min_i32_e32 v12, v12, v84
	v_max_i32_e32 v84, v11, v56
	v_min_i32_e32 v11, v11, v56
	v_max_i32_e32 v56, v86, v85
	v_min_i32_e32 v85, v86, v85
	v_max_i32_e32 v86, v13, v5
	v_min_i32_e32 v5, v13, v5
	v_max_i32_e32 v13, v8, v4
	v_min_i32_e32 v4, v8, v4
; template <int OFF>
; __device__ __forceinline__ void sort16_desc(int* a) {
; #pragma unroll
;   for (int ks = 1; ks <= 4; ++ks) {
; #pragma unroll
;     ...
; #pragma unroll
;       for (int i = 0; i < 16; ++i) {
;         const int k = 1 << ks, j = 1 << js;
;         const int l2 = i ^ j;
;         if (l2 > i) { if ((i & k) == 0) cas_desc(a[OFF + i], a[OFF + l2]); else cas_desc(a[OFF + l2], a[OFF + i]); }
;       }
;     }
;   }
; }
; template <int OA, int OB>
; __device__ __forceinline__ void merge16(int* a, const int* b) {
; #pragma unroll
;   for (int i = 0; i < 16; ++i) a[OA + i] = max(a[OA + i], b[OB + 15 - i]);
; #pragma unroll
;     ...
; #pragma unroll
;     for (int i = 0; i < 16; ++i) {
;       const int j = 1 << js; const int l2 = i ^ j;
;       if (l2 > i) cas_desc(a[OA + i], a[OA + l2]);
;     }
;   }
; }
	v_max_i32_e32 v8, v9, v60
	v_min_i32_e32 v9, v9, v60
	v_max_i32_e32 v60, v87, v57
	v_min_i32_e32 v57, v87, v57
	v_max_i32_e32 v87, v83, v10
	v_min_i32_e32 v10, v83, v10
	v_max_i32_e32 v16, v19, v7
	v_min_i32_e32 v7, v19, v7
	v_max_i32_e32 v19, v20, v1
	v_min_i32_e32 v1, v20, v1
	v_max_i32_e32 v20, v23, v2
	v_min_i32_e32 v2, v23, v2
	v_max_i32_e32 v23, v21, v14
	v_min_i32_e32 v14, v21, v14
	v_max_i32_e32 v21, v22, v6
	v_min_i32_e32 v6, v22, v6
	v_max_i32_e32 v22, v3, v17
	v_min_i32_e32 v3, v3, v17
	v_max_i32_e32 v17, v177, v15
	v_min_i32_e32 v15, v177, v15
	v_max_i32_e32 v177, v0, v18
	v_max_i32_e32 v83, v90, v4
	v_min_i32_e32 v4, v90, v4
	v_max_i32_e32 v90, v12, v13
	v_min_i32_e32 v12, v12, v13
	v_max_i32_e32 v13, v84, v9
	v_min_i32_e32 v9, v84, v9
	v_max_i32_e32 v84, v11, v8
	v_min_i32_e32 v8, v11, v8
	v_max_i32_e32 v11, v56, v57
	v_min_i32_e32 v56, v56, v57
	v_max_i32_e32 v57, v85, v60
	v_min_i32_e32 v60, v85, v60
	v_max_i32_e32 v85, v86, v10
	v_min_i32_e32 v10, v86, v10
	v_max_i32_e32 v86, v5, v87
	v_min_i32_e32 v5, v5, v87
	v_min_i32_e32 v0, v0, v18
	v_max_i32_e32 v18, v16, v21
	v_min_i32_e32 v16, v16, v21
	v_max_i32_e32 v21, v19, v22
	v_min_i32_e32 v19, v19, v22
	v_max_i32_e32 v22, v20, v17
	v_min_i32_e32 v17, v20, v17
	v_max_i32_e32 v20, v23, v177
	v_min_i32_e32 v23, v23, v177
	v_max_i32_e32 v87, v83, v11
	v_min_i32_e32 v11, v83, v11
	v_max_i32_e32 v83, v90, v57
	v_min_i32_e32 v57, v90, v57
	v_max_i32_e32 v90, v13, v85
	v_min_i32_e32 v13, v13, v85
	v_max_i32_e32 v85, v84, v86
	v_min_i32_e32 v84, v84, v86
	v_max_i32_e32 v86, v4, v56
	v_min_i32_e32 v4, v4, v56
	v_max_i32_e32 v56, v12, v60
	v_min_i32_e32 v12, v12, v60
	v_max_i32_e32 v60, v9, v10
	v_min_i32_e32 v9, v9, v10
	v_max_i32_e32 v10, v8, v5
	v_max_i32_e32 v177, v7, v6
	v_min_i32_e32 v6, v7, v6
	v_max_i32_e32 v7, v1, v3
	v_min_i32_e32 v1, v1, v3
	v_max_i32_e32 v3, v2, v15
	v_min_i32_e32 v2, v2, v15
	v_max_i32_e32 v15, v14, v0
	v_min_i32_e32 v0, v14, v0
	v_max_i32_e32 v14, v18, v22
	v_min_i32_e32 v18, v18, v22
	v_max_i32_e32 v22, v21, v20
	v_min_i32_e32 v20, v21, v20
	v_max_i32_e32 v21, v16, v17
	v_min_i32_e32 v16, v16, v17
	v_max_i32_e32 v17, v19, v23
	v_min_i32_e32 v47, v25, v24
	v_min_i32_e32 v61, v62, v73
	v_min_i32_e32 v5, v8, v5
	v_max_i32_e32 v8, v87, v90
	v_min_i32_e32 v87, v87, v90
	v_max_i32_e32 v90, v83, v85
	v_min_i32_e32 v83, v83, v85
	v_max_i32_e32 v85, v11, v13
	v_min_i32_e32 v11, v11, v13
	v_max_i32_e32 v13, v57, v84
	v_min_i32_e32 v57, v57, v84
	v_max_i32_e32 v84, v86, v60
	v_min_i32_e32 v60, v86, v60
	v_max_i32_e32 v86, v56, v10
	v_min_i32_e32 v10, v56, v10
	v_min_i32_e32 v179, v21, v17
	v_min_i32_e32 v174, v60, v10
	v_max3_i32 v24, v25, v24, v61
	v_max3_i32 v25, v47, v62, v73
	v_max3_i32 v10, v60, v10, v179
	global_load_dwordx4 v[60:63], v[96:97], off offset:320
	v_min_i32_e32 v19, v19, v23
	v_max_i32_e32 v23, v177, v3
	v_min_i32_e32 v3, v177, v3
	v_max_i32_e32 v177, v7, v15
	v_max_i32_e32 v56, v4, v9
	v_min_i32_e32 v4, v4, v9
	v_max_i32_e32 v9, v12, v5
	v_min_i32_e32 v171, v85, v13
	v_min_i32_e32 v7, v7, v15
	v_min_i32_e32 v178, v18, v20
	v_min_i32_e32 v181, v23, v177
	v_min_i32_e32 v172, v11, v57
	v_min_i32_e32 v175, v56, v9
	v_min_i32_e32 v182, v3, v7
	v_max3_i32 v26, v26, v59, v58
	v_max3_i32 v3, v171, v3, v7
	v_max3_i32 v7, v11, v57, v181
	v_max3_i32 v9, v56, v9, v178
	global_load_dwordx4 v[56:59], v[96:97], off offset:352
	v_min_i32_e32 v43, v31, v36
	v_min_i32_e32 v79, v74, v75
	v_min_i32_e32 v5, v12, v5
	v_max_i32_e32 v15, v6, v2
	v_min_i32_e32 v2, v6, v2
	v_max_i32_e32 v6, v1, v0
	v_min_i32_e32 v0, v1, v0
	v_min_i32_e32 v12, v8, v90
	v_min_i32_e32 v170, v87, v83
	v_min_i32_e32 v173, v84, v86
	v_min_i32_e32 v176, v4, v5
	v_min_i32_e32 v1, v14, v22
	v_min_i32_e32 v180, v16, v19
	v_min_i32_e32 v183, v15, v6
	v_min_i32_e32 v184, v2, v0
	v_max3_i32 v31, v31, v36, v79
	v_max3_i32 v36, v43, v74, v75
	v_max_i32_e32 v40, v27, v38
	v_min_i32_e32 v27, v27, v38
	v_max_i32_e32 v38, v26, v39
	v_min_i32_e32 v26, v26, v39
	v_max_i32_e32 v39, v33, v28
	v_min_i32_e32 v28, v33, v28
	v_max_i32_e32 v33, v35, v30
	v_min_i32_e32 v30, v35, v30
	v_max_i32_e32 v35, v34, v29
	v_min_i32_e32 v29, v34, v29
	v_max_i32_e32 v34, v37, v32
	v_min_i32_e32 v32, v37, v32
	v_max_i32_e32 v37, v31, v24
	v_min_i32_e32 v24, v31, v24
	v_max_i32_e32 v31, v36, v25
	v_min_i32_e32 v25, v36, v25
	v_max3_i32 v8, v8, v90, v184
	v_max3_i32 v0, v12, v2, v0
	v_max3_i32 v2, v87, v83, v183
	v_max3_i32 v6, v170, v15, v6
	v_max3_i32 v12, v85, v13, v182
	v_max3_i32 v11, v172, v23, v177
	v_max3_i32 v13, v84, v86, v180
	v_max3_i32 v15, v173, v16, v19
	v_max3_i32 v16, v174, v21, v17
	v_max3_i32 v17, v175, v18, v20
	v_max3_i32 v1, v4, v5, v1
	v_max3_i32 v4, v176, v14, v22
	v_max_i32_e32 v36, v40, v35
	v_min_i32_e32 v35, v40, v35
	v_max_i32_e32 v40, v38, v34
	v_min_i32_e32 v34, v38, v34
	v_max_i32_e32 v38, v39, v37
	v_min_i32_e32 v37, v39, v37
	v_max_i32_e32 v39, v33, v31
	v_min_i32_e32 v31, v33, v31
	v_max_i32_e32 v33, v27, v29
	v_min_i32_e32 v27, v27, v29
	v_max_i32_e32 v29, v26, v32
	v_min_i32_e32 v26, v26, v32
	v_max_i32_e32 v32, v28, v24
	v_min_i32_e32 v24, v28, v24
	v_max_i32_e32 v28, v30, v25
	v_min_i32_e32 v25, v30, v25
	v_max_i32_e32 v5, v8, v13
	v_min_i32_e32 v8, v8, v13
	v_max_i32_e32 v13, v0, v15
	v_min_i32_e32 v0, v0, v15
	v_max_i32_e32 v14, v2, v10
	v_min_i32_e32 v2, v2, v10
	v_max_i32_e32 v10, v6, v16
	v_min_i32_e32 v6, v6, v16
	v_max_i32_e32 v15, v12, v9
	v_min_i32_e32 v9, v12, v9
	v_max_i32_e32 v12, v3, v17
	v_max_i32_e32 v16, v7, v1
	v_min_i32_e32 v1, v7, v1
	v_max_i32_e32 v7, v11, v4
	v_max_i32_e32 v30, v36, v38
	v_min_i32_e32 v36, v36, v38
	v_max_i32_e32 v38, v40, v39
	v_min_i32_e32 v39, v40, v39
; template <int PP>
; __device__ __forceinline__ void select_half(const Params& p, const u16* Subs, int t, int hh, int lc, int hf, int* lists) {
;     ...
;   const u16* qrow = p.qp + (size_t)t * 2048 + hh * 256 + PP * 128 + hf * 8;
; #pragma unroll
;   for (int ks = 0; ks < 8; ++ks) qf[ks] = *(const bf16x8*)(qrow + ks * 16);
;   int keys[64];
; #pragma unroll
;   for (int nb = 0; nb < 4; ++nb) {
;     f32x16 acc;
; #pragma unroll
;     for (int r = 0; r < 16; ++r) acc[r] = 0.f;
; #pragma unroll
;     for (int ks = 0; ks < 8; ++ks) {
;       bf16x8 a = *(const bf16x8*)(Subs + (PP * 128 + nb * 32 + lc) * 136 + ks * 16 + hf * 8);
;       acc = mfma32(a, qf[ks], acc);
;     ...
;   sort16_desc<0>(keys); sort16_desc<16>(keys); sort16_desc<32>(keys); sort16_desc<48>(keys);
;   merge16<0, 16>(keys, keys); merge16<32, 48>(keys, keys); merge16<0, 32>(keys, keys);
;   int other[16];
; #pragma unroll
;   for (int i = 0; i < 16; ++i) other[i] = __shfl_xor(keys[i], 32);
;   merge16<0, 0>(keys, other);
	v_max_i32_e32 v40, v35, v37
	v_min_i32_e32 v35, v35, v37
	v_max_i32_e32 v37, v34, v31
	v_min_i32_e32 v31, v34, v31
	v_max_i32_e32 v34, v33, v32
	v_min_i32_e32 v32, v33, v32
	v_max_i32_e32 v33, v29, v28
	v_min_i32_e32 v28, v29, v28
	v_max_i32_e32 v29, v27, v24
	v_min_i32_e32 v24, v27, v24
	v_max_i32_e32 v27, v26, v25
	v_min_i32_e32 v25, v26, v25
	v_min_i32_e32 v3, v3, v17
	v_min_i32_e32 v4, v11, v4
	v_max_i32_e32 v11, v5, v15
	v_min_i32_e32 v5, v5, v15
	v_max_i32_e32 v15, v13, v12
	v_min_i32_e32 v12, v13, v12
	v_max_i32_e32 v13, v14, v16
	v_min_i32_e32 v14, v14, v16
	v_max_i32_e32 v16, v10, v7
	v_min_i32_e32 v7, v10, v7
	v_min_i32_e32 v44, v34, v33
	v_min_i32_e32 v45, v32, v28
	v_min_i32_e32 v46, v29, v27
	v_min_i32_e32 v47, v24, v25
	v_max_i32_e32 v10, v8, v9
	v_min_i32_e32 v8, v8, v9
	v_max_i32_e32 v9, v0, v3
	v_min_i32_e32 v0, v0, v3
	v_max_i32_e32 v3, v2, v1
	v_min_i32_e32 v1, v2, v1
	v_max_i32_e32 v2, v6, v4
	v_min_i32_e32 v4, v6, v4
	v_max_i32_e32 v6, v11, v13
	v_min_i32_e32 v11, v11, v13
	v_max_i32_e32 v13, v15, v16
	v_min_i32_e32 v15, v15, v16
	v_max_i32_e32 v16, v5, v14
	v_min_i32_e32 v5, v5, v14
	v_max_i32_e32 v14, v12, v7
	v_min_i32_e32 v7, v12, v7
	v_max_i32_e32 v12, v10, v3
	v_min_i32_e32 v3, v10, v3
	v_max_i32_e32 v10, v9, v2
	v_min_i32_e32 v2, v9, v2
	v_max_i32_e32 v9, v8, v1
	v_min_i32_e32 v1, v8, v1
	v_max_i32_e32 v8, v0, v4
	v_min_i32_e32 v0, v0, v4
	v_min_i32_e32 v4, v6, v13
	v_min_i32_e32 v17, v11, v15
	v_min_i32_e32 v18, v16, v14
	v_min_i32_e32 v19, v5, v7
	v_max3_i32 v5, v44, v5, v7
	v_max3_i32 v14, v45, v16, v14
	v_max3_i32 v11, v46, v11, v15
	v_max3_i32 v6, v47, v6, v13
	global_load_dwordx4 v[44:47], v[96:97], off offset:384
	v_min_i32_e32 v41, v36, v39
	v_min_i32_e32 v42, v40, v37
	v_min_i32_e32 v43, v35, v31
	v_min_i32_e32 v21, v3, v2
	v_min_i32_e32 v20, v12, v10
	v_min_i32_e32 v22, v9, v8
	v_max3_i32 v8, v41, v9, v8
	v_max3_i32 v9, v40, v37, v21
	v_max3_i32 v2, v42, v3, v2
	v_max3_i32 v10, v43, v12, v10
	global_load_dwordx4 v[40:43], v[96:97], off offset:416
	v_min_i32_e32 v26, v30, v38
	v_min_i32_e32 v23, v1, v0
	v_max3_i32 v23, v30, v38, v23
	v_max3_i32 v0, v26, v1, v0
	v_max3_i32 v1, v36, v39, v22
	global_load_dwordx4 v[36:39], v[96:97], off offset:448
	v_max3_i32 v3, v35, v31, v20
	v_max3_i32 v12, v34, v33, v19
	v_max3_i32 v7, v32, v28, v18
	global_load_dwordx4 v[32:35], v[96:97], off offset:480
	v_max3_i32 v16, v29, v27, v17
	v_max3_i32 v4, v24, v25, v4
	v_max_i32_e32 v13, v23, v12
	v_min_i32_e32 v12, v23, v12
	v_max_i32_e32 v15, v0, v5
	v_min_i32_e32 v0, v0, v5
	v_max_i32_e32 v5, v1, v7
	v_min_i32_e32 v1, v1, v7
	v_max_i32_e32 v7, v8, v14
	v_min_i32_e32 v8, v8, v14
	v_max_i32_e32 v14, v9, v16
	v_min_i32_e32 v9, v9, v16
	v_max_i32_e32 v16, v2, v11
	v_min_i32_e32 v2, v2, v11
	v_max_i32_e32 v11, v3, v4
	v_min_i32_e32 v3, v3, v4
	v_max_i32_e32 v4, v10, v6
	v_min_i32_e32 v6, v10, v6
	v_max_i32_e32 v10, v13, v14
	v_min_i32_e32 v13, v13, v14
	v_max_i32_e32 v14, v15, v16
	v_min_i32_e32 v15, v15, v16
	v_max_i32_e32 v16, v5, v11
	v_min_i32_e32 v5, v5, v11
	v_max_i32_e32 v11, v7, v4
	v_min_i32_e32 v4, v7, v4
	v_max_i32_e32 v7, v12, v9
	v_min_i32_e32 v9, v12, v9
	v_max_i32_e32 v12, v0, v2
	v_min_i32_e32 v0, v0, v2
	v_max_i32_e32 v2, v1, v3
	v_min_i32_e32 v1, v1, v3
	v_max_i32_e32 v3, v8, v6
	v_min_i32_e32 v6, v8, v6
	v_max_i32_e32 v8, v10, v16
	v_min_i32_e32 v10, v10, v16
	v_max_i32_e32 v16, v14, v11
	v_min_i32_e32 v11, v14, v11
	v_max_i32_e32 v14, v13, v5
	v_min_i32_e32 v5, v13, v5
	v_max_i32_e32 v13, v15, v4
	v_min_i32_e32 v4, v15, v4
	v_max_i32_e32 v15, v7, v2
	v_min_i32_e32 v2, v7, v2
	v_max_i32_e32 v7, v12, v3
	v_min_i32_e32 v3, v12, v3
	v_max_i32_e32 v12, v9, v1
	v_min_i32_e32 v1, v9, v1
	v_max_i32_e32 v9, v0, v6
	v_min_i32_e32 v0, v0, v6
	v_max_i32_e32 v6, v8, v16
	v_min_i32_e32 v8, v8, v16
	v_max_i32_e32 v16, v10, v11
	v_min_i32_e32 v10, v10, v11
	v_max_i32_e32 v11, v14, v13
	v_min_i32_e32 v13, v14, v13
	v_max_i32_e32 v14, v5, v4
	v_min_i32_e32 v4, v5, v4
	v_max_i32_e32 v5, v15, v7
	v_min_i32_e32 v7, v15, v7
	v_max_i32_e32 v15, v2, v3
	v_min_i32_e32 v2, v2, v3
	v_max_i32_e32 v3, v12, v9
	v_min_i32_e32 v9, v12, v9
	v_max_i32_e32 v12, v1, v0
	v_min_i32_e32 v0, v1, v0
	ds_bpermute_b32 v19, v100, v10
	ds_bpermute_b32 v20, v100, v11
	ds_bpermute_b32 v23, v100, v4
	ds_bpermute_b32 v27, v100, v0
	ds_bpermute_b32 v29, v100, v2
	ds_bpermute_b32 v31, v100, v3
	ds_bpermute_b32 v1, v100, v6
	ds_bpermute_b32 v17, v100, v8
	ds_bpermute_b32 v18, v100, v16
	ds_bpermute_b32 v22, v100, v14
	ds_bpermute_b32 v26, v100, v15
	ds_bpermute_b32 v24, v100, v5
	s_waitcnt lgkmcnt(8)
	v_max_i32_e32 v6, v6, v27
	s_waitcnt lgkmcnt(6)
	v_max_i32_e32 v10, v10, v31
	v_max_i32_e32 v11, v11, v29
	v_max_i32_e32 v5, v5, v23
	v_max_i32_e32 v2, v2, v20
	v_max_i32_e32 v3, v3, v19
	ds_bpermute_b32 v21, v100, v13
	ds_bpermute_b32 v25, v100, v7
	ds_bpermute_b32 v28, v100, v12
	ds_bpermute_b32 v30, v100, v9
	s_waitcnt lgkmcnt(5)
	v_max_i32_e32 v13, v13, v26
	v_max_i32_e32 v7, v7, v22
	v_max_i32_e32 v9, v9, v18
	v_max_i32_e32 v12, v12, v17
	v_max_i32_e32 v17, v0, v1
	v_max_i32_e32 v18, v6, v5
	v_min_i32_e32 v20, v6, v5
	v_max_i32_e32 v22, v10, v2
	v_min_i32_e32 v26, v10, v2
	v_max_i32_e32 v6, v11, v3
	v_min_i32_e32 v23, v11, v3
	ds_read_b128 v[0:3], v101 offset:34816
	s_waitcnt lgkmcnt(2)
	v_max_i32_e32 v8, v8, v28
	s_waitcnt lgkmcnt(1)
	v_max_i32_e32 v16, v16, v30
	v_max_i32_e32 v4, v4, v24
	v_max_i32_e32 v15, v15, v21
	v_max_i32_e32 v14, v14, v25
	v_max_i32_e32 v5, v8, v7
	v_min_i32_e32 v24, v8, v7
	v_max_i32_e32 v21, v16, v15
	v_min_i32_e32 v25, v16, v15
	v_max_i32_e32 v7, v13, v9
	v_max_i32_e32 v30, v4, v17
	v_min_i32_e32 v31, v4, v17
	v_max_i32_e32 v72, v18, v6
	v_min_i32_e32 v73, v18, v6
	ds_read_b128 v[16:19], v101 offset:34848
	v_min_i32_e32 v27, v13, v9
	v_max_i32_e32 v28, v14, v12
	v_min_i32_e32 v29, v14, v12
	v_max_i32_e32 v74, v5, v7
	v_min_i32_e32 v75, v5, v7
	s_waitcnt vmcnt(7) lgkmcnt(1)
; __device__ __forceinline__ int crow(int r, int hf) { return (r & 3) + 8 * (r >> 2) + 4 * hf; }
; __device__ __forceinline__ int tosort(float f) { int b = __float_as_int(f); return b ^ ((b >> 31) & 0x7fffffff); }
; template <int PP>
; __device__ __forceinline__ void select_half(const Params& p, const u16* Subs, int t, int hh, int lc, int hf, int* lists) {
;     ...
;   for (int nb = 0; nb < 4; ++nb) {
;     f32x16 acc;
; #pragma unroll
;     for (int r = 0; r < 16; ++r) acc[r] = 0.f;
; #pragma unroll
;     for (int ks = 0; ks < 8; ++ks) {
;       bf16x8 a = *(const bf16x8*)(Subs + (PP * 128 + nb * 32 + lc) * 136 + ks * 16 + hf * 8);
;       acc = mfma32(a, qf[ks], acc);
;     }
; #pragma unroll
;     for (int r = 0; r < 16; ++r) keys[nb * 16 + r] = (tosort(acc[r]) & ~127) | (nb * 32 + crow(r, hf));
;   }
;   sort16_desc<0>(keys); sort16_desc<16>(keys); sort16_desc<32>(keys); sort16_desc<48>(keys);
;   merge16<0, 16>(keys, keys); merge16<32, 48>(keys, keys); merge16<0, 32>(keys, keys);
;   int other[16];
; #pragma unroll
;   for (int i = 0; i < 16; ++i) other[i] = __shfl_xor(keys[i], 32);
;   merge16<0, 0>(keys, other);
; #pragma unroll
;   for (int i = 0; i < 16; ++i) lists[PP * 16 + i] = keys[i];
	v_mfma_f32_32x32x16_bf16 v[0:15], v[0:3], v[68:71], 0
	v_max_i32_e32 v76, v21, v28
	v_min_i32_e32 v28, v21, v28
	v_max_i32_e32 v77, v22, v30
	v_min_i32_e32 v30, v22, v30
	v_max_i32_e32 v78, v20, v23
	v_min_i32_e32 v79, v20, v23
	ds_read_b128 v[20:23], v101 offset:34880
	s_waitcnt vmcnt(6) lgkmcnt(1)
	v_mfma_f32_32x32x16_bf16 v[0:15], v[16:19], v[64:67], v[0:15]
	ds_read_b128 v[16:19], v101 offset:34912
	v_max_i32_e32 v80, v24, v27
	v_min_i32_e32 v24, v24, v27
	v_max_i32_e32 v27, v25, v29
	v_min_i32_e32 v25, v25, v29
	v_max_i32_e32 v29, v26, v31
	v_min_i32_e32 v26, v26, v31
	s_waitcnt vmcnt(5) lgkmcnt(1)
	v_mfma_f32_32x32x16_bf16 v[0:15], v[20:23], v[60:63], v[0:15]
	ds_read_b128 v[20:23], v101 offset:34944
	v_max_i32_e32 v31, v72, v76
	v_min_i32_e32 v72, v72, v76
	v_max_i32_e32 v76, v74, v77
	v_min_i32_e32 v74, v74, v77
	v_max_i32_e32 v77, v73, v28
	v_min_i32_e32 v28, v73, v28
	s_waitcnt vmcnt(4) lgkmcnt(1)
	v_mfma_f32_32x32x16_bf16 v[0:15], v[16:19], v[56:59], v[0:15]
	ds_read_b128 v[16:19], v101 offset:34976
	v_max_i32_e32 v73, v75, v30
	v_min_i32_e32 v30, v75, v30
	v_max_i32_e32 v75, v78, v27
	v_max_i32_e32 v90, v80, v29
	v_min_i32_e32 v27, v78, v27
	v_max_i32_e32 v96, v79, v25
	s_waitcnt vmcnt(3) lgkmcnt(1)
	v_mfma_f32_32x32x16_bf16 v[0:15], v[20:23], v[44:47], v[0:15]
	ds_read_b128 v[20:23], v101 offset:35008
	v_min_i32_e32 v25, v79, v25
	v_max_i32_e32 v78, v75, v90
	v_min_i32_e32 v79, v75, v90
	v_max_i32_e32 v97, v24, v26
	v_max_i32_e32 v84, v72, v74
	v_min_i32_e32 v85, v72, v74
	s_waitcnt vmcnt(2) lgkmcnt(1)
	v_mfma_f32_32x32x16_bf16 v[0:15], v[16:19], v[40:43], v[0:15]
	ds_read_b128 v[16:19], v101 offset:35040
	v_max_i32_e32 v75, v96, v97
	v_min_i32_e32 v74, v96, v97
	v_min_i32_e32 v29, v80, v29
	v_min_i32_e32 v24, v24, v26
	v_max_i32_e32 v87, v31, v76
	v_min_i32_e32 v86, v31, v76
	s_waitcnt vmcnt(1) lgkmcnt(1)
	v_mfma_f32_32x32x16_bf16 v[0:15], v[20:23], v[36:39], v[0:15]
	v_max_i32_e32 v83, v77, v73
	v_min_i32_e32 v82, v77, v73
	v_max_i32_e32 v81, v28, v30
	v_min_i32_e32 v80, v28, v30
	v_max_i32_e32 v77, v27, v29
	v_min_i32_e32 v76, v27, v29
	v_max_i32_e32 v73, v25, v24
	s_waitcnt vmcnt(0) lgkmcnt(0)
	v_mfma_f32_32x32x16_bf16 v[0:15], v[16:19], v[32:35], v[0:15]
	v_min_i32_e32 v72, v25, v24
	ds_read_b128 v[170:173], v101 offset:43584
	s_nop 9
	v_ashrrev_i32_e32 v16, 31, v0
	v_and_b32_e32 v16, 0x7fffff80, v16
	v_and_b32_e32 v0, 0xffffff80, v0
	v_bitop3_b32 v90, v16, v99, v0 bitop3:0xde
	v_ashrrev_i32_e32 v0, 31, v1
	ds_read_b128 v[16:19], v101 offset:43520
	v_and_b32_e32 v0, 0x7fffff80, v0
	v_and_b32_e32 v1, 0xffffff80, v1
	v_bitop3_b32 v96, v0, v102, v1 bitop3:0xde
	v_ashrrev_i32_e32 v0, 31, v2
	v_and_b32_e32 v0, 0x7fffff80, v0
	v_and_b32_e32 v1, 0xffffff80, v2
	v_bitop3_b32 v97, v0, v103, v1 bitop3:0xde
	v_ashrrev_i32_e32 v0, 31, v3
	v_and_b32_e32 v0, 0x7fffff80, v0
	v_and_b32_e32 v1, 0xffffff80, v3
	v_bitop3_b32 v174, v0, v104, v1 bitop3:0xde
	v_ashrrev_i32_e32 v0, 31, v4
	v_and_b32_e32 v0, 0x7fffff80, v0
	v_and_b32_e32 v1, 0xffffff80, v4
	v_bitop3_b32 v175, v0, v105, v1 bitop3:0xde
	ds_read_b128 v[0:3], v101 offset:43552
	s_waitcnt lgkmcnt(1)
	v_mfma_f32_32x32x16_bf16 v[16:31], v[16:19], v[68:71], 0
	v_ashrrev_i32_e32 v4, 31, v5
	v_and_b32_e32 v4, 0x7fffff80, v4
	v_and_b32_e32 v5, 0xffffff80, v5
	v_bitop3_b32 v176, v4, v106, v5 bitop3:0xde
	v_ashrrev_i32_e32 v4, 31, v6
	v_and_b32_e32 v4, 0x7fffff80, v4
	v_and_b32_e32 v5, 0xffffff80, v6
	s_waitcnt lgkmcnt(0)
	v_mfma_f32_32x32x16_bf16 v[16:31], v[0:3], v[64:67], v[16:31]
	v_ashrrev_i32_e32 v0, 31, v7
	v_and_b32_e32 v0, 0x7fffff80, v0
	v_and_b32_e32 v1, 0xffffff80, v7
	v_bitop3_b32 v178, v0, v108, v1 bitop3:0xde
	ds_read_b128 v[0:3], v101 offset:43616
	v_bitop3_b32 v177, v4, v107, v5 bitop3:0xde
	v_ashrrev_i32_e32 v4, 31, v8
	v_mfma_f32_32x32x16_bf16 v[16:31], v[170:173], v[60:63], v[16:31]
	v_and_b32_e32 v4, 0x7fffff80, v4
	v_and_b32_e32 v5, 0xffffff80, v8
	v_bitop3_b32 v179, v4, v109, v5 bitop3:0xde
	v_ashrrev_i32_e32 v4, 31, v9
	v_and_b32_e32 v8, 0x7fffff80, v4
	ds_read_b128 v[4:7], v101 offset:43648
	v_and_b32_e32 v9, 0xffffff80, v9
	s_waitcnt lgkmcnt(1)
	v_mfma_f32_32x32x16_bf16 v[16:31], v[0:3], v[56:59], v[16:31]
	v_ashrrev_i32_e32 v0, 31, v10
	v_and_b32_e32 v0, 0x7fffff80, v0
	v_and_b32_e32 v1, 0xffffff80, v10
	v_bitop3_b32 v181, v0, v111, v1 bitop3:0xde
	ds_read_b128 v[0:3], v101 offset:43680
	v_bitop3_b32 v180, v8, v110, v9 bitop3:0xde
	v_ashrrev_i32_e32 v8, 31, v11
	s_waitcnt lgkmcnt(1)
	v_mfma_f32_32x32x16_bf16 v[16:31], v[4:7], v[44:47], v[16:31]
	v_and_b32_e32 v4, 0x7fffff80, v8
	v_and_b32_e32 v5, 0xffffff80, v11
	v_bitop3_b32 v182, v4, v112, v5 bitop3:0xde
	v_ashrrev_i32_e32 v4, 31, v12
	v_and_b32_e32 v8, 0x7fffff80, v4
	ds_read_b128 v[4:7], v101 offset:43712
	v_and_b32_e32 v9, 0xffffff80, v12
	s_waitcnt lgkmcnt(1)
	v_mfma_f32_32x32x16_bf16 v[16:31], v[0:3], v[40:43], v[16:31]
	v_ashrrev_i32_e32 v0, 31, v13
	v_and_b32_e32 v0, 0x7fffff80, v0
	v_and_b32_e32 v1, 0xffffff80, v13
	v_bitop3_b32 v184, v0, v114, v1 bitop3:0xde
	ds_read_b128 v[0:3], v101 offset:43744
	v_bitop3_b32 v183, v8, v113, v9 bitop3:0xde
	v_ashrrev_i32_e32 v8, 31, v14
	s_waitcnt lgkmcnt(1)
	v_mfma_f32_32x32x16_bf16 v[16:31], v[4:7], v[36:39], v[16:31]
	v_and_b32_e32 v4, 0x7fffff80, v8
	v_and_b32_e32 v5, 0xffffff80, v14
	v_bitop3_b32 v185, v4, v115, v5 bitop3:0xde
	v_ashrrev_i32_e32 v4, 31, v15
	v_and_b32_e32 v4, 0x7fffff80, v4
	v_and_b32_e32 v5, 0xffffff80, v15
	v_bitop3_b32 v186, v4, v116, v5 bitop3:0xde
	s_waitcnt lgkmcnt(0)
; __device__ __forceinline__ int crow(int r, int hf) { return (r & 3) + 8 * (r >> 2) + 4 * hf; }
; __device__ __forceinline__ int tosort(float f) { int b = __float_as_int(f); return b ^ ((b >> 31) & 0x7fffffff); }
; template <int PP>
; __device__ __forceinline__ void select_half(const Params& p, const u16* Subs, int t, int hh, int lc, int hf, int* lists) {
;     ...
;   for (int nb = 0; nb < 4; ++nb) {
;     f32x16 acc;
; #pragma unroll
;     for (int r = 0; r < 16; ++r) acc[r] = 0.f;
; #pragma unroll
;     for (int ks = 0; ks < 8; ++ks) {
;       bf16x8 a = *(const bf16x8*)(Subs + (PP * 128 + nb * 32 + lc) * 136 + ks * 16 + hf * 8);
;       acc = mfma32(a, qf[ks], acc);
;     }
; #pragma unroll
;     for (int r = 0; r < 16; ++r) keys[nb * 16 + r] = (tosort(acc[r]) & ~127) | (nb * 32 + crow(r, hf));
	v_mfma_f32_32x32x16_bf16 v[16:31], v[0:3], v[32:35], v[16:31]
	ds_read_b128 v[170:173], v101 offset:52288
	s_nop 10
	v_ashrrev_i32_e32 v0, 31, v16
	v_and_b32_e32 v0, 0x7fffff80, v0
	v_and_b32_e32 v1, 0xffffff80, v16
	v_bitop3_b32 v187, v0, v117, v1 bitop3:0xde
	v_ashrrev_i32_e32 v0, 31, v17
	v_and_b32_e32 v0, 0x7fffff80, v0
	v_and_b32_e32 v1, 0xffffff80, v17
	v_bitop3_b32 v188, v0, v118, v1 bitop3:0xde
	v_ashrrev_i32_e32 v0, 31, v18
	v_and_b32_e32 v0, 0x7fffff80, v0
	v_and_b32_e32 v1, 0xffffff80, v18
	v_bitop3_b32 v190, v0, v119, v1 bitop3:0xde
	v_ashrrev_i32_e32 v0, 31, v19
	v_and_b32_e32 v4, 0x7fffff80, v0
	ds_read_b128 v[0:3], v101 offset:52224
	v_and_b32_e32 v5, 0xffffff80, v19
	v_bitop3_b32 v192, v4, v120, v5 bitop3:0xde
	v_ashrrev_i32_e32 v4, 31, v20
	v_and_b32_e32 v4, 0x7fffff80, v4
	v_and_b32_e32 v5, 0xffffff80, v20
	ds_read_b128 v[16:19], v101 offset:52256
	v_bitop3_b32 v193, v4, v121, v5 bitop3:0xde
	s_waitcnt lgkmcnt(1)
	v_mfma_f32_32x32x16_bf16 v[0:15], v[0:3], v[68:71], 0
	v_ashrrev_i32_e32 v20, 31, v21
	v_and_b32_e32 v20, 0x7fffff80, v20
	v_and_b32_e32 v21, 0xffffff80, v21
	v_bitop3_b32 v194, v20, v122, v21 bitop3:0xde
	v_ashrrev_i32_e32 v20, 31, v22
	v_and_b32_e32 v20, 0x7fffff80, v20
	v_and_b32_e32 v21, 0xffffff80, v22
	s_waitcnt lgkmcnt(0)
	v_mfma_f32_32x32x16_bf16 v[0:15], v[16:19], v[64:67], v[0:15]
	v_ashrrev_i32_e32 v16, 31, v23
	v_and_b32_e32 v16, 0x7fffff80, v16
	v_and_b32_e32 v17, 0xffffff80, v23
	v_bitop3_b32 v196, v16, v124, v17 bitop3:0xde
	ds_read_b128 v[16:19], v101 offset:52320
	v_bitop3_b32 v195, v20, v123, v21 bitop3:0xde
	v_ashrrev_i32_e32 v20, 31, v24
	v_mfma_f32_32x32x16_bf16 v[0:15], v[170:173], v[60:63], v[0:15]
	v_and_b32_e32 v20, 0x7fffff80, v20
	v_and_b32_e32 v21, 0xffffff80, v24
	v_bitop3_b32 v170, v20, v125, v21 bitop3:0xde
	v_ashrrev_i32_e32 v20, 31, v25
	v_and_b32_e32 v24, 0x7fffff80, v20
	ds_read_b128 v[20:23], v101 offset:52352
	v_and_b32_e32 v25, 0xffffff80, v25
	s_waitcnt lgkmcnt(1)
	v_mfma_f32_32x32x16_bf16 v[0:15], v[16:19], v[56:59], v[0:15]
	v_ashrrev_i32_e32 v16, 31, v26
	v_and_b32_e32 v16, 0x7fffff80, v16
	v_and_b32_e32 v17, 0xffffff80, v26
	v_bitop3_b32 v172, v16, v127, v17 bitop3:0xde
	ds_read_b128 v[16:19], v101 offset:52384
	v_bitop3_b32 v171, v24, v126, v25 bitop3:0xde
	v_ashrrev_i32_e32 v24, 31, v27
	s_waitcnt lgkmcnt(1)
	v_mfma_f32_32x32x16_bf16 v[0:15], v[20:23], v[44:47], v[0:15]
	v_and_b32_e32 v20, 0x7fffff80, v24
	v_and_b32_e32 v21, 0xffffff80, v27
	v_bitop3_b32 v173, v20, v128, v21 bitop3:0xde
	v_ashrrev_i32_e32 v20, 31, v28
	v_and_b32_e32 v24, 0x7fffff80, v20
	ds_read_b128 v[20:23], v101 offset:52416
	v_and_b32_e32 v25, 0xffffff80, v28
	s_waitcnt lgkmcnt(1)
	v_mfma_f32_32x32x16_bf16 v[0:15], v[16:19], v[40:43], v[0:15]
	v_ashrrev_i32_e32 v16, 31, v29
	v_and_b32_e32 v16, 0x7fffff80, v16
	v_and_b32_e32 v17, 0xffffff80, v29
	v_bitop3_b32 v198, v16, v130, v17 bitop3:0xde
	ds_read_b128 v[16:19], v101 offset:52448
	v_bitop3_b32 v197, v24, v129, v25 bitop3:0xde
	v_ashrrev_i32_e32 v24, 31, v30
	s_waitcnt lgkmcnt(1)
	v_mfma_f32_32x32x16_bf16 v[0:15], v[20:23], v[36:39], v[0:15]
	v_and_b32_e32 v20, 0x7fffff80, v24
	v_and_b32_e32 v21, 0xffffff80, v30
	v_bitop3_b32 v199, v20, v131, v21 bitop3:0xde
	v_ashrrev_i32_e32 v20, 31, v31
	v_and_b32_e32 v20, 0x7fffff80, v20
	v_and_b32_e32 v21, 0xffffff80, v31
	v_bitop3_b32 v200, v20, v132, v21 bitop3:0xde
	s_waitcnt lgkmcnt(0)
	v_mfma_f32_32x32x16_bf16 v[0:15], v[16:19], v[32:35], v[0:15]
	s_nop 11
	v_ashrrev_i32_e32 v16, 31, v0
	v_and_b32_e32 v16, 0x7fffff80, v16
	v_and_b32_e32 v0, 0xffffff80, v0
	v_bitop3_b32 v201, v16, v133, v0 bitop3:0xde
	v_ashrrev_i32_e32 v0, 31, v1
	ds_read_b128 v[16:19], v101 offset:60928
	v_and_b32_e32 v0, 0x7fffff80, v0
	v_and_b32_e32 v1, 0xffffff80, v1
	v_bitop3_b32 v202, v0, v134, v1 bitop3:0xde
	v_ashrrev_i32_e32 v0, 31, v2
	v_and_b32_e32 v0, 0x7fffff80, v0
	v_and_b32_e32 v1, 0xffffff80, v2
	v_bitop3_b32 v203, v0, v135, v1 bitop3:0xde
	v_ashrrev_i32_e32 v0, 31, v3
	v_and_b32_e32 v0, 0x7fffff80, v0
	v_and_b32_e32 v1, 0xffffff80, v3
	v_bitop3_b32 v204, v0, v136, v1 bitop3:0xde
	v_ashrrev_i32_e32 v0, 31, v4
	v_and_b32_e32 v0, 0x7fffff80, v0
	v_and_b32_e32 v1, 0xffffff80, v4
	v_bitop3_b32 v205, v0, v137, v1 bitop3:0xde
	ds_read_b128 v[0:3], v101 offset:60960
	s_waitcnt lgkmcnt(1)
	v_mfma_f32_32x32x16_bf16 v[16:31], v[16:19], v[68:71], 0
	ds_read_b128 v[68:71], v101 offset:60992
	v_ashrrev_i32_e32 v4, 31, v5
	v_and_b32_e32 v4, 0x7fffff80, v4
	v_and_b32_e32 v5, 0xffffff80, v5
	v_bitop3_b32 v206, v4, v138, v5 bitop3:0xde
	v_ashrrev_i32_e32 v4, 31, v6
	v_and_b32_e32 v4, 0x7fffff80, v4
	s_waitcnt lgkmcnt(1)
	v_mfma_f32_32x32x16_bf16 v[16:31], v[0:3], v[64:67], v[16:31]
	v_ashrrev_i32_e32 v0, 31, v7
	v_and_b32_e32 v0, 0x7fffff80, v0
	v_and_b32_e32 v1, 0xffffff80, v7
	v_bitop3_b32 v65, v0, v140, v1 bitop3:0xde
	ds_read_b128 v[0:3], v101 offset:61024
	v_and_b32_e32 v5, 0xffffff80, v6
	v_bitop3_b32 v64, v4, v139, v5 bitop3:0xde
	s_waitcnt lgkmcnt(1)
	v_mfma_f32_32x32x16_bf16 v[16:31], v[68:71], v[60:63], v[16:31]
	v_ashrrev_i32_e32 v4, 31, v8
	v_and_b32_e32 v4, 0x7fffff80, v4
	v_and_b32_e32 v5, 0xffffff80, v8
	v_bitop3_b32 v8, v4, v141, v5 bitop3:0xde
	v_ashrrev_i32_e32 v4, 31, v9
	v_and_b32_e32 v60, 0x7fffff80, v4
	ds_read_b128 v[4:7], v101 offset:61056
	s_waitcnt lgkmcnt(1)
	v_mfma_f32_32x32x16_bf16 v[16:31], v[0:3], v[56:59], v[16:31]
	v_ashrrev_i32_e32 v0, 31, v10
	v_and_b32_e32 v0, 0x7fffff80, v0
	v_and_b32_e32 v1, 0xffffff80, v10
	v_bitop3_b32 v10, v0, v143, v1 bitop3:0xde
	ds_read_b128 v[0:3], v101 offset:61088
	v_ashrrev_i32_e32 v56, 31, v11
	v_and_b32_e32 v9, 0xffffff80, v9
	s_waitcnt lgkmcnt(1)
; __device__ __forceinline__ int crow(int r, int hf) { return (r & 3) + 8 * (r >> 2) + 4 * hf; }
; __device__ __forceinline__ int tosort(float f) { int b = __float_as_int(f); return b ^ ((b >> 31) & 0x7fffffff); }
; template <int PP>
; __device__ __forceinline__ void select_half(const Params& p, const u16* Subs, int t, int hh, int lc, int hf, int* lists) {
;     ...
;     for (int ks = 0; ks < 8; ++ks) {
;       bf16x8 a = *(const bf16x8*)(Subs + (PP * 128 + nb * 32 + lc) * 136 + ks * 16 + hf * 8);
;       acc = mfma32(a, qf[ks], acc);
;     }
; #pragma unroll
;     for (int r = 0; r < 16; ++r) keys[nb * 16 + r] = (tosort(acc[r]) & ~127) | (nb * 32 + crow(r, hf));
;   }
;   sort16_desc<0>(keys); sort16_desc<16>(keys); sort16_desc<32>(keys); sort16_desc<48>(keys);
	v_mfma_f32_32x32x16_bf16 v[16:31], v[4:7], v[44:47], v[16:31]
	v_and_b32_e32 v4, 0x7fffff80, v56
	v_and_b32_e32 v5, 0xffffff80, v11
	v_bitop3_b32 v11, v4, v144, v5 bitop3:0xde
	v_ashrrev_i32_e32 v4, 31, v12
	v_and_b32_e32 v44, 0x7fffff80, v4
	ds_read_b128 v[4:7], v101 offset:61120
	v_and_b32_e32 v12, 0xffffff80, v12
	s_waitcnt lgkmcnt(1)
	v_mfma_f32_32x32x16_bf16 v[16:31], v[0:3], v[40:43], v[16:31]
	v_ashrrev_i32_e32 v0, 31, v13
	v_and_b32_e32 v0, 0x7fffff80, v0
	v_and_b32_e32 v1, 0xffffff80, v13
	v_bitop3_b32 v13, v0, v146, v1 bitop3:0xde
	ds_read_b128 v[0:3], v101 offset:61152
	v_ashrrev_i32_e32 v40, 31, v14
	v_bitop3_b32 v9, v60, v142, v9 bitop3:0xde
	s_waitcnt lgkmcnt(1)
	v_mfma_f32_32x32x16_bf16 v[16:31], v[4:7], v[36:39], v[16:31]
	v_and_b32_e32 v4, 0x7fffff80, v40
	v_and_b32_e32 v5, 0xffffff80, v14
	v_bitop3_b32 v4, v4, v147, v5 bitop3:0xde
	v_ashrrev_i32_e32 v5, 31, v15
	v_and_b32_e32 v5, 0x7fffff80, v5
	v_and_b32_e32 v6, 0xffffff80, v15
	v_bitop3_b32 v5, v5, v148, v6 bitop3:0xde
	s_waitcnt lgkmcnt(0)
	v_mfma_f32_32x32x16_bf16 v[16:31], v[0:3], v[32:35], v[16:31]
	v_bitop3_b32 v12, v44, v145, v12 bitop3:0xde
	v_max_i32_e32 v32, v179, v180
	v_min_i32_e32 v33, v179, v180
	v_max_i32_e32 v34, v182, v181
	v_min_i32_e32 v35, v182, v181
	v_max_i32_e32 v36, v183, v184
	v_min_i32_e32 v37, v183, v184
	s_nop 4
	v_ashrrev_i32_e32 v0, 31, v16
	v_and_b32_e32 v0, 0x7fffff80, v0
	v_and_b32_e32 v1, 0xffffff80, v16
	v_bitop3_b32 v0, v0, v149, v1 bitop3:0xde
	v_ashrrev_i32_e32 v1, 31, v17
	v_and_b32_e32 v1, 0x7fffff80, v1
	v_and_b32_e32 v2, 0xffffff80, v17
	v_bitop3_b32 v1, v1, v150, v2 bitop3:0xde
	v_ashrrev_i32_e32 v2, 31, v18
	v_and_b32_e32 v2, 0x7fffff80, v2
	v_and_b32_e32 v3, 0xffffff80, v18
	v_bitop3_b32 v2, v2, v151, v3 bitop3:0xde
	v_ashrrev_i32_e32 v3, 31, v19
	v_and_b32_e32 v3, 0x7fffff80, v3
	v_and_b32_e32 v6, 0xffffff80, v19
	v_bitop3_b32 v3, v3, v152, v6 bitop3:0xde
	v_ashrrev_i32_e32 v6, 31, v20
	v_and_b32_e32 v6, 0x7fffff80, v6
	v_and_b32_e32 v7, 0xffffff80, v20
	v_bitop3_b32 v6, v6, v153, v7 bitop3:0xde
	v_ashrrev_i32_e32 v7, 31, v21
	v_and_b32_e32 v7, 0x7fffff80, v7
	v_and_b32_e32 v14, 0xffffff80, v21
	v_bitop3_b32 v7, v7, v154, v14 bitop3:0xde
	v_ashrrev_i32_e32 v14, 31, v22
	v_and_b32_e32 v14, 0x7fffff80, v14
	v_and_b32_e32 v15, 0xffffff80, v22
	v_bitop3_b32 v14, v14, v155, v15 bitop3:0xde
	v_ashrrev_i32_e32 v15, 31, v23
	v_and_b32_e32 v15, 0x7fffff80, v15
	v_and_b32_e32 v16, 0xffffff80, v23
	v_bitop3_b32 v15, v15, v156, v16 bitop3:0xde
	v_ashrrev_i32_e32 v16, 31, v24
	v_and_b32_e32 v16, 0x7fffff80, v16
	v_and_b32_e32 v17, 0xffffff80, v24
	v_bitop3_b32 v16, v16, v157, v17 bitop3:0xde
	v_ashrrev_i32_e32 v17, 31, v25
	v_and_b32_e32 v17, 0x7fffff80, v17
	v_and_b32_e32 v18, 0xffffff80, v25
	v_bitop3_b32 v17, v17, v158, v18 bitop3:0xde
	v_ashrrev_i32_e32 v18, 31, v26
	v_and_b32_e32 v18, 0x7fffff80, v18
	v_and_b32_e32 v19, 0xffffff80, v26
	v_bitop3_b32 v18, v18, v159, v19 bitop3:0xde
	v_ashrrev_i32_e32 v19, 31, v27
	v_and_b32_e32 v19, 0x7fffff80, v19
	v_and_b32_e32 v20, 0xffffff80, v27
	v_bitop3_b32 v19, v19, v160, v20 bitop3:0xde
	v_ashrrev_i32_e32 v20, 31, v28
	v_and_b32_e32 v20, 0x7fffff80, v20
	v_and_b32_e32 v21, 0xffffff80, v28
	v_bitop3_b32 v20, v20, v161, v21 bitop3:0xde
	v_ashrrev_i32_e32 v21, 31, v29
	v_and_b32_e32 v21, 0x7fffff80, v21
	v_and_b32_e32 v22, 0xffffff80, v29
	v_bitop3_b32 v21, v21, v162, v22 bitop3:0xde
	v_ashrrev_i32_e32 v22, 31, v30
	v_and_b32_e32 v22, 0x7fffff80, v22
	v_and_b32_e32 v23, 0xffffff80, v30
	v_bitop3_b32 v22, v22, v163, v23 bitop3:0xde
	v_ashrrev_i32_e32 v23, 31, v31
	v_and_b32_e32 v23, 0x7fffff80, v23
	v_and_b32_e32 v24, 0xffffff80, v31
	v_bitop3_b32 v23, v23, v164, v24 bitop3:0xde
	v_max_i32_e32 v24, v90, v96
	v_min_i32_e32 v25, v90, v96
	v_max_i32_e32 v26, v174, v97
	v_min_i32_e32 v27, v174, v97
	v_max_i32_e32 v28, v175, v176
	v_min_i32_e32 v29, v175, v176
	v_max_i32_e32 v30, v178, v177
	v_min_i32_e32 v31, v178, v177
	v_max_i32_e32 v38, v186, v185
	v_min_i32_e32 v39, v186, v185
	v_max_i32_e32 v56, v187, v188
	v_min_i32_e32 v57, v187, v188
	v_max_i32_e32 v58, v192, v190
	v_min_i32_e32 v59, v192, v190
	v_max_i32_e32 v60, v193, v194
	v_min_i32_e32 v61, v193, v194
	v_max_i32_e32 v62, v196, v195
	v_min_i32_e32 v63, v196, v195
	v_max_i32_e32 v66, v170, v171
	v_min_i32_e32 v67, v170, v171
	v_max_i32_e32 v68, v173, v172
	v_min_i32_e32 v69, v173, v172
	v_max_i32_e32 v70, v197, v198
	v_min_i32_e32 v71, v197, v198
	v_max_i32_e32 v90, v200, v199
	v_min_i32_e32 v96, v200, v199
	v_max_i32_e32 v177, v201, v202
	v_min_i32_e32 v178, v201, v202
	v_max_i32_e32 v179, v204, v203
	v_min_i32_e32 v180, v204, v203
	v_max_i32_e32 v181, v205, v206
	v_min_i32_e32 v182, v205, v206
	v_max_i32_e32 v183, v65, v64
	v_min_i32_e32 v64, v65, v64
	v_max_i32_e32 v65, v8, v9
	v_min_i32_e32 v8, v8, v9
	v_max_i32_e32 v9, v11, v10
	v_min_i32_e32 v10, v11, v10
	v_max_i32_e32 v11, v12, v13
	v_min_i32_e32 v12, v12, v13
	v_max_i32_e32 v13, v5, v4
	v_min_i32_e32 v4, v5, v4
	v_max_i32_e32 v193, v0, v1
	v_min_i32_e32 v0, v0, v1
	v_max_i32_e32 v1, v3, v2
	v_min_i32_e32 v2, v3, v2
	v_max_i32_e32 v3, v6, v7
	v_min_i32_e32 v6, v6, v7
	v_max_i32_e32 v7, v15, v14
	v_min_i32_e32 v14, v15, v14
	v_max_i32_e32 v15, v16, v17
	v_min_i32_e32 v16, v16, v17
	v_max_i32_e32 v17, v19, v18
	v_min_i32_e32 v18, v19, v18
	v_max_i32_e32 v19, v20, v21
	v_min_i32_e32 v20, v20, v21
	v_max_i32_e32 v21, v23, v22
	v_min_i32_e32 v22, v23, v22
	v_max_i32_e32 v40, v24, v27
	v_min_i32_e32 v24, v24, v27
	v_max_i32_e32 v27, v25, v26
	v_min_i32_e32 v25, v25, v26
	v_max_i32_e32 v26, v31, v28
	v_min_i32_e32 v28, v31, v28
	v_max_i32_e32 v31, v30, v29
	v_min_i32_e32 v29, v30, v29
; template <int OFF>
; __device__ __forceinline__ void sort16_desc(int* a) {
; #pragma unroll
;   for (int ks = 1; ks <= 4; ++ks) {
; #pragma unroll
;     ...
; #pragma unroll
;       for (int i = 0; i < 16; ++i) {
;         const int k = 1 << ks, j = 1 << js;
;         const int l2 = i ^ j;
;         if (l2 > i) { if ((i & k) == 0) cas_desc(a[OFF + i], a[OFF + l2]); else cas_desc(a[OFF + l2], a[OFF + i]); }
;       }
;     }
;   }
; }
	v_max_i32_e32 v30, v32, v35
	v_min_i32_e32 v32, v32, v35
	v_max_i32_e32 v35, v33, v34
	v_min_i32_e32 v33, v33, v34
	v_max_i32_e32 v34, v39, v36
	v_min_i32_e32 v36, v39, v36
	v_max_i32_e32 v39, v38, v37
	v_min_i32_e32 v37, v38, v37
	v_max_i32_e32 v97, v56, v59
	v_min_i32_e32 v56, v56, v59
	v_max_i32_e32 v59, v57, v58
	v_min_i32_e32 v57, v57, v58
	v_max_i32_e32 v58, v63, v60
	v_min_i32_e32 v60, v63, v60
	v_max_i32_e32 v63, v62, v61
	v_min_i32_e32 v61, v62, v61
	v_max_i32_e32 v62, v66, v69
	v_min_i32_e32 v66, v66, v69
	v_max_i32_e32 v69, v67, v68
	v_min_i32_e32 v67, v67, v68
	v_max_i32_e32 v68, v96, v70
	v_min_i32_e32 v70, v96, v70
	v_max_i32_e32 v96, v90, v71
	v_min_i32_e32 v71, v90, v71
	v_max_i32_e32 v5, v177, v180
	v_min_i32_e32 v177, v177, v180
	v_max_i32_e32 v180, v178, v179
	v_min_i32_e32 v178, v178, v179
	v_max_i32_e32 v179, v64, v181
	v_min_i32_e32 v64, v64, v181
	v_max_i32_e32 v181, v183, v182
	v_min_i32_e32 v182, v183, v182
	v_max_i32_e32 v183, v65, v10
	v_min_i32_e32 v10, v65, v10
	v_max_i32_e32 v65, v8, v9
	v_min_i32_e32 v8, v8, v9
	v_max_i32_e32 v9, v4, v11
	v_min_i32_e32 v4, v4, v11
	v_max_i32_e32 v11, v13, v12
	v_min_i32_e32 v12, v13, v12
	v_max_i32_e32 v23, v193, v2
	v_min_i32_e32 v2, v193, v2
	v_max_i32_e32 v193, v0, v1
	v_min_i32_e32 v0, v0, v1
	v_max_i32_e32 v1, v14, v3
	v_min_i32_e32 v3, v14, v3
	v_max_i32_e32 v14, v7, v6
	v_min_i32_e32 v6, v7, v6
	v_max_i32_e32 v7, v15, v18
	v_min_i32_e32 v15, v15, v18
	v_max_i32_e32 v18, v16, v17
	v_min_i32_e32 v16, v16, v17
	v_max_i32_e32 v17, v22, v19
	v_min_i32_e32 v19, v22, v19
	v_max_i32_e32 v22, v21, v20
	v_min_i32_e32 v20, v21, v20
	v_max_i32_e32 v38, v40, v27
	v_min_i32_e32 v27, v40, v27
	v_max_i32_e32 v40, v24, v25
	v_min_i32_e32 v24, v24, v25
	v_max_i32_e32 v25, v29, v28
	v_min_i32_e32 v28, v29, v28
	v_max_i32_e32 v29, v31, v26
	v_min_i32_e32 v26, v31, v26
	v_max_i32_e32 v31, v30, v35
	v_min_i32_e32 v30, v30, v35
	v_max_i32_e32 v35, v32, v33
	v_min_i32_e32 v32, v32, v33
	v_max_i32_e32 v33, v37, v36
	v_min_i32_e32 v36, v37, v36
	v_max_i32_e32 v37, v39, v34
	v_min_i32_e32 v34, v39, v34
	v_max_i32_e32 v90, v97, v59
	v_min_i32_e32 v59, v97, v59
	v_max_i32_e32 v97, v56, v57
	v_min_i32_e32 v56, v56, v57
	v_max_i32_e32 v57, v61, v60
	v_min_i32_e32 v60, v61, v60
	v_max_i32_e32 v61, v63, v58
	v_min_i32_e32 v58, v63, v58
	v_max_i32_e32 v63, v62, v69
	v_min_i32_e32 v62, v62, v69
	v_max_i32_e32 v69, v66, v67
	v_min_i32_e32 v66, v66, v67
	v_max_i32_e32 v67, v71, v70
	v_min_i32_e32 v70, v71, v70
	v_max_i32_e32 v71, v96, v68
	v_min_i32_e32 v68, v96, v68
	v_max_i32_e32 v13, v5, v180
	v_min_i32_e32 v5, v5, v180
	v_max_i32_e32 v180, v177, v178
	v_min_i32_e32 v177, v177, v178
	v_max_i32_e32 v178, v182, v64
	v_min_i32_e32 v64, v182, v64
	v_max_i32_e32 v182, v181, v179
	v_min_i32_e32 v179, v181, v179
	v_max_i32_e32 v181, v183, v65
	v_min_i32_e32 v65, v183, v65
	v_max_i32_e32 v183, v10, v8
	v_min_i32_e32 v8, v10, v8
	v_max_i32_e32 v10, v12, v4
	v_min_i32_e32 v4, v12, v4
	v_max_i32_e32 v12, v11, v9
	v_min_i32_e32 v9, v11, v9
	v_max_i32_e32 v21, v23, v193
	v_min_i32_e32 v23, v23, v193
	v_max_i32_e32 v193, v2, v0
	v_min_i32_e32 v0, v2, v0
	v_max_i32_e32 v2, v6, v3
	v_min_i32_e32 v3, v6, v3
	v_max_i32_e32 v6, v14, v1
	v_min_i32_e32 v1, v14, v1
	v_max_i32_e32 v14, v7, v18
	v_min_i32_e32 v7, v7, v18
	v_max_i32_e32 v18, v15, v16
	v_min_i32_e32 v15, v15, v16
	v_max_i32_e32 v16, v20, v19
	v_min_i32_e32 v19, v20, v19
	v_max_i32_e32 v20, v22, v17
	v_min_i32_e32 v17, v22, v17
	v_max_i32_e32 v39, v38, v28
	v_min_i32_e32 v28, v38, v28
	v_max_i32_e32 v38, v27, v25
	v_min_i32_e32 v25, v27, v25
	v_max_i32_e32 v27, v40, v26
	v_min_i32_e32 v26, v40, v26
	v_max_i32_e32 v40, v24, v29
	v_min_i32_e32 v24, v24, v29
	v_max_i32_e32 v29, v36, v31
	v_min_i32_e32 v31, v36, v31
	v_max_i32_e32 v36, v33, v30
	v_min_i32_e32 v30, v33, v30
	v_max_i32_e32 v33, v34, v35
	v_min_i32_e32 v34, v34, v35
	v_max_i32_e32 v35, v37, v32
	v_min_i32_e32 v32, v37, v32
	v_max_i32_e32 v96, v90, v60
	v_min_i32_e32 v60, v90, v60
	v_max_i32_e32 v90, v59, v57
	v_min_i32_e32 v57, v59, v57
	v_max_i32_e32 v59, v97, v58
	v_min_i32_e32 v58, v97, v58
	v_max_i32_e32 v97, v56, v61
	v_min_i32_e32 v56, v56, v61
	v_max_i32_e32 v61, v70, v63
	v_min_i32_e32 v63, v70, v63
	v_max_i32_e32 v70, v67, v62
	v_min_i32_e32 v62, v67, v62
	v_max_i32_e32 v67, v68, v69
	v_min_i32_e32 v68, v68, v69
	v_max_i32_e32 v69, v71, v66
	v_min_i32_e32 v66, v71, v66
	v_max_i32_e32 v11, v13, v64
	v_min_i32_e32 v13, v13, v64
	v_max_i32_e32 v64, v5, v178
	v_min_i32_e32 v5, v5, v178
	v_max_i32_e32 v178, v180, v179
	v_min_i32_e32 v179, v180, v179
	v_max_i32_e32 v180, v177, v182
	v_min_i32_e32 v177, v177, v182
	v_max_i32_e32 v182, v4, v181
	v_min_i32_e32 v4, v4, v181
	v_max_i32_e32 v181, v10, v65
	v_min_i32_e32 v10, v10, v65
	v_max_i32_e32 v65, v9, v183
	v_min_i32_e32 v9, v9, v183
	v_max_i32_e32 v183, v12, v8
	v_min_i32_e32 v8, v12, v8
	v_max_i32_e32 v22, v21, v3
	v_min_i32_e32 v3, v21, v3
	v_max_i32_e32 v21, v23, v2
	v_min_i32_e32 v2, v23, v2
	v_max_i32_e32 v23, v193, v1
	v_min_i32_e32 v1, v193, v1
	v_max_i32_e32 v193, v0, v6
	v_min_i32_e32 v0, v0, v6
	v_max_i32_e32 v6, v19, v14
	v_min_i32_e32 v14, v19, v14
	v_max_i32_e32 v19, v16, v7
	v_min_i32_e32 v7, v16, v7
	v_max_i32_e32 v16, v17, v18
	v_min_i32_e32 v17, v17, v18
	v_max_i32_e32 v18, v20, v15
	v_min_i32_e32 v15, v20, v15
	v_max_i32_e32 v37, v39, v27
	v_min_i32_e32 v27, v39, v27
	v_max_i32_e32 v39, v38, v40
	v_min_i32_e32 v38, v38, v40
	v_max_i32_e32 v40, v28, v26
	v_min_i32_e32 v26, v28, v26
	v_max_i32_e32 v28, v25, v24
	v_min_i32_e32 v24, v25, v24
	v_max_i32_e32 v25, v34, v31
	v_min_i32_e32 v31, v34, v31
	v_max_i32_e32 v34, v32, v30
; template <int OFF>
; __device__ __forceinline__ void sort16_desc(int* a) {
; #pragma unroll
;   for (int ks = 1; ks <= 4; ++ks) {
; #pragma unroll
;     ...
; #pragma unroll
;       for (int i = 0; i < 16; ++i) {
;         const int k = 1 << ks, j = 1 << js;
;         const int l2 = i ^ j;
;         if (l2 > i) { if ((i & k) == 0) cas_desc(a[OFF + i], a[OFF + l2]); else cas_desc(a[OFF + l2], a[OFF + i]); }
;       }
;     }
;   }
; }
	v_min_i32_e32 v30, v32, v30
	v_max_i32_e32 v32, v33, v29
	v_min_i32_e32 v29, v33, v29
	v_max_i32_e32 v33, v35, v36
	v_min_i32_e32 v35, v35, v36
	v_max_i32_e32 v71, v96, v59
	v_min_i32_e32 v59, v96, v59
	v_max_i32_e32 v96, v90, v97
	v_min_i32_e32 v90, v90, v97
	v_max_i32_e32 v97, v60, v58
	v_min_i32_e32 v58, v60, v58
	v_max_i32_e32 v60, v57, v56
	v_min_i32_e32 v56, v57, v56
	v_max_i32_e32 v57, v68, v63
	v_min_i32_e32 v63, v68, v63
	v_max_i32_e32 v68, v66, v62
	v_min_i32_e32 v62, v66, v62
	v_max_i32_e32 v66, v67, v61
	v_min_i32_e32 v61, v67, v61
	v_max_i32_e32 v67, v69, v70
	v_min_i32_e32 v69, v69, v70
	v_max_i32_e32 v12, v11, v178
	v_min_i32_e32 v11, v11, v178
	v_max_i32_e32 v178, v64, v180
	v_min_i32_e32 v64, v64, v180
	v_max_i32_e32 v180, v13, v179
	v_min_i32_e32 v13, v13, v179
	v_max_i32_e32 v179, v5, v177
	v_min_i32_e32 v5, v5, v177
	v_max_i32_e32 v177, v9, v4
	v_min_i32_e32 v4, v9, v4
	v_max_i32_e32 v9, v8, v10
	v_min_i32_e32 v8, v8, v10
	v_max_i32_e32 v10, v65, v182
	v_min_i32_e32 v65, v65, v182
	v_max_i32_e32 v182, v183, v181
	v_min_i32_e32 v181, v183, v181
	v_max_i32_e32 v20, v22, v23
	v_min_i32_e32 v22, v22, v23
	v_max_i32_e32 v23, v21, v193
	v_min_i32_e32 v21, v21, v193
	v_max_i32_e32 v193, v3, v1
	v_min_i32_e32 v1, v3, v1
	v_max_i32_e32 v3, v2, v0
	v_min_i32_e32 v0, v2, v0
	v_max_i32_e32 v2, v17, v14
	v_min_i32_e32 v14, v17, v14
	v_max_i32_e32 v17, v15, v7
	v_min_i32_e32 v7, v15, v7
	v_max_i32_e32 v15, v16, v6
	v_min_i32_e32 v6, v16, v6
	v_max_i32_e32 v16, v18, v19
	v_min_i32_e32 v18, v18, v19
	v_max_i32_e32 v36, v37, v39
	v_min_i32_e32 v37, v37, v39
	v_max_i32_e32 v39, v27, v38
	v_min_i32_e32 v27, v27, v38
	v_max_i32_e32 v38, v40, v28
	v_min_i32_e32 v28, v40, v28
	v_max_i32_e32 v40, v26, v24
	v_min_i32_e32 v24, v26, v24
	v_max_i32_e32 v26, v30, v31
	v_min_i32_e32 v30, v30, v31
	v_max_i32_e32 v31, v34, v25
	v_min_i32_e32 v25, v34, v25
	v_max_i32_e32 v34, v35, v29
	v_min_i32_e32 v29, v35, v29
	v_max_i32_e32 v35, v33, v32
	v_min_i32_e32 v32, v33, v32
	v_max_i32_e32 v70, v71, v96
	v_min_i32_e32 v71, v71, v96
	v_max_i32_e32 v96, v59, v90
	v_min_i32_e32 v59, v59, v90
	v_max_i32_e32 v90, v97, v60
	v_min_i32_e32 v60, v97, v60
	v_max_i32_e32 v97, v58, v56
	v_min_i32_e32 v56, v58, v56
	v_max_i32_e32 v58, v62, v63
	v_min_i32_e32 v62, v62, v63
	v_max_i32_e32 v63, v68, v57
	v_min_i32_e32 v57, v68, v57
	v_max_i32_e32 v68, v69, v61
	v_min_i32_e32 v61, v69, v61
	v_max_i32_e32 v69, v67, v66
	v_min_i32_e32 v66, v67, v66
	v_max_i32_e32 v183, v12, v178
	v_min_i32_e32 v12, v12, v178
	v_max_i32_e32 v178, v11, v64
	v_min_i32_e32 v11, v11, v64
	v_max_i32_e32 v64, v180, v179
	v_min_i32_e32 v179, v180, v179
	v_max_i32_e32 v180, v13, v5
	v_min_i32_e32 v5, v13, v5
	v_max_i32_e32 v13, v8, v4
	v_min_i32_e32 v4, v8, v4
	v_max_i32_e32 v8, v9, v177
	v_min_i32_e32 v9, v9, v177
	v_max_i32_e32 v177, v181, v65
	v_min_i32_e32 v65, v181, v65
	v_max_i32_e32 v181, v182, v10
	v_min_i32_e32 v10, v182, v10
	v_max_i32_e32 v19, v20, v23
	v_min_i32_e32 v20, v20, v23
	v_max_i32_e32 v23, v22, v21
	v_min_i32_e32 v21, v22, v21
	v_max_i32_e32 v22, v193, v3
	v_min_i32_e32 v3, v193, v3
	v_max_i32_e32 v193, v1, v0
	v_min_i32_e32 v0, v1, v0
	v_max_i32_e32 v1, v7, v14
	v_min_i32_e32 v7, v7, v14
	v_max_i32_e32 v14, v17, v2
	v_min_i32_e32 v2, v17, v2
	v_max_i32_e32 v17, v18, v6
	v_min_i32_e32 v6, v18, v6
	v_max_i32_e32 v18, v16, v15
	v_min_i32_e32 v15, v16, v15
	v_max_i32_e32 v33, v36, v30
	v_min_i32_e32 v30, v36, v30
	v_max_i32_e32 v36, v37, v26
	v_min_i32_e32 v26, v37, v26
	v_max_i32_e32 v37, v39, v25
	v_min_i32_e32 v25, v39, v25
	v_max_i32_e32 v39, v27, v31
	v_min_i32_e32 v27, v27, v31
	v_max_i32_e32 v31, v38, v29
	v_min_i32_e32 v29, v38, v29
	v_max_i32_e32 v38, v28, v34
	v_min_i32_e32 v28, v28, v34
	v_max_i32_e32 v34, v40, v32
	v_min_i32_e32 v32, v40, v32
	v_max_i32_e32 v40, v24, v35
	v_min_i32_e32 v24, v24, v35
	v_max_i32_e32 v67, v70, v62
	v_min_i32_e32 v62, v70, v62
	v_max_i32_e32 v70, v71, v58
	v_min_i32_e32 v58, v71, v58
	v_max_i32_e32 v71, v96, v57
	v_min_i32_e32 v57, v96, v57
	v_max_i32_e32 v96, v59, v63
	v_min_i32_e32 v59, v59, v63
	v_max_i32_e32 v63, v90, v61
	v_min_i32_e32 v61, v90, v61
	v_max_i32_e32 v90, v60, v68
	v_min_i32_e32 v60, v60, v68
	v_max_i32_e32 v68, v97, v66
	v_min_i32_e32 v66, v97, v66
	v_max_i32_e32 v97, v56, v69
	v_min_i32_e32 v56, v56, v69
	v_max_i32_e32 v182, v183, v4
	v_min_i32_e32 v4, v183, v4
	v_max_i32_e32 v183, v12, v13
	v_min_i32_e32 v12, v12, v13
	v_max_i32_e32 v13, v178, v9
	v_min_i32_e32 v9, v178, v9
	v_max_i32_e32 v178, v11, v8
	v_min_i32_e32 v8, v11, v8
	v_max_i32_e32 v11, v64, v65
	v_min_i32_e32 v64, v64, v65
	v_max_i32_e32 v65, v179, v177
	v_min_i32_e32 v177, v179, v177
	v_max_i32_e32 v179, v180, v10
	v_min_i32_e32 v10, v180, v10
	v_max_i32_e32 v180, v5, v181
	v_min_i32_e32 v5, v5, v181
	v_max_i32_e32 v16, v19, v7
	v_min_i32_e32 v7, v19, v7
	v_max_i32_e32 v19, v20, v1
	v_min_i32_e32 v1, v20, v1
	v_max_i32_e32 v20, v23, v2
	v_min_i32_e32 v2, v23, v2
	v_max_i32_e32 v23, v21, v14
	v_min_i32_e32 v14, v21, v14
	v_max_i32_e32 v21, v22, v6
	v_min_i32_e32 v6, v22, v6
	v_max_i32_e32 v22, v3, v17
	v_min_i32_e32 v3, v3, v17
	v_max_i32_e32 v17, v193, v15
	v_min_i32_e32 v15, v193, v15
	v_max_i32_e32 v193, v0, v18
	v_min_i32_e32 v0, v0, v18
	v_max_i32_e32 v35, v33, v31
	v_min_i32_e32 v31, v33, v31
	v_max_i32_e32 v33, v36, v38
	v_min_i32_e32 v36, v36, v38
	v_max_i32_e32 v38, v37, v34
	v_min_i32_e32 v34, v37, v34
	v_max_i32_e32 v37, v39, v40
	v_min_i32_e32 v39, v39, v40
	v_max_i32_e32 v40, v30, v29
	v_min_i32_e32 v29, v30, v29
	v_max_i32_e32 v30, v26, v28
	v_min_i32_e32 v26, v26, v28
	v_max_i32_e32 v28, v25, v32
	v_min_i32_e32 v25, v25, v32
; template <int OFF>
; __device__ __forceinline__ void sort16_desc(int* a) {
; #pragma unroll
;   for (int ks = 1; ks <= 4; ++ks) {
; #pragma unroll
;     ...
; #pragma unroll
;       for (int i = 0; i < 16; ++i) {
;         const int k = 1 << ks, j = 1 << js;
;         const int l2 = i ^ j;
;         if (l2 > i) { if ((i & k) == 0) cas_desc(a[OFF + i], a[OFF + l2]); else cas_desc(a[OFF + l2], a[OFF + i]); }
;       }
;     }
;   }
; }
; template <int OA, int OB>
; __device__ __forceinline__ void merge16(int* a, const int* b) {
; #pragma unroll
;   for (int i = 0; i < 16; ++i) a[OA + i] = max(a[OA + i], b[OB + 15 - i]);
; #pragma unroll
;     ...
; #pragma unroll
;     for (int i = 0; i < 16; ++i) {
;       const int j = 1 << js; const int l2 = i ^ j;
;       if (l2 > i) cas_desc(a[OA + i], a[OA + l2]);
;     }
;   }
; }
	v_max_i32_e32 v32, v27, v24
	v_min_i32_e32 v24, v27, v24
	v_max_i32_e32 v69, v67, v63
	v_min_i32_e32 v63, v67, v63
	v_max_i32_e32 v67, v70, v90
	v_min_i32_e32 v70, v70, v90
	v_max_i32_e32 v90, v71, v68
	v_min_i32_e32 v68, v71, v68
	v_max_i32_e32 v71, v96, v97
	v_min_i32_e32 v96, v96, v97
	v_max_i32_e32 v97, v62, v61
	v_min_i32_e32 v61, v62, v61
	v_max_i32_e32 v62, v58, v60
	v_min_i32_e32 v58, v58, v60
	v_max_i32_e32 v60, v57, v66
	v_min_i32_e32 v57, v57, v66
	v_max_i32_e32 v66, v59, v56
	v_min_i32_e32 v56, v59, v56
	v_max_i32_e32 v181, v182, v11
	v_min_i32_e32 v11, v182, v11
	v_max_i32_e32 v182, v183, v65
	v_min_i32_e32 v65, v183, v65
	v_max_i32_e32 v183, v13, v179
	v_min_i32_e32 v13, v13, v179
	v_max_i32_e32 v179, v178, v180
	v_min_i32_e32 v178, v178, v180
	v_max_i32_e32 v180, v4, v64
	v_min_i32_e32 v4, v4, v64
	v_max_i32_e32 v64, v12, v177
	v_min_i32_e32 v12, v12, v177
	v_max_i32_e32 v177, v9, v10
	v_min_i32_e32 v9, v9, v10
	v_max_i32_e32 v10, v8, v5
	v_min_i32_e32 v5, v8, v5
	v_max_i32_e32 v18, v16, v21
	v_min_i32_e32 v16, v16, v21
	v_max_i32_e32 v21, v19, v22
	v_min_i32_e32 v19, v19, v22
	v_max_i32_e32 v22, v20, v17
	v_min_i32_e32 v17, v20, v17
	v_max_i32_e32 v20, v23, v193
	v_min_i32_e32 v23, v23, v193
	v_max_i32_e32 v193, v7, v6
	v_min_i32_e32 v6, v7, v6
	v_max_i32_e32 v7, v1, v3
	v_min_i32_e32 v1, v1, v3
	v_max_i32_e32 v3, v2, v15
	v_min_i32_e32 v2, v2, v15
	v_max_i32_e32 v15, v14, v0
	v_min_i32_e32 v0, v14, v0
	v_max_i32_e32 v27, v35, v38
	v_min_i32_e32 v35, v35, v38
	v_max_i32_e32 v38, v33, v37
	v_min_i32_e32 v33, v33, v37
	v_max_i32_e32 v37, v31, v34
	v_min_i32_e32 v31, v31, v34
	v_max_i32_e32 v34, v36, v39
	v_min_i32_e32 v36, v36, v39
	v_max_i32_e32 v39, v40, v28
	v_min_i32_e32 v28, v40, v28
	v_max_i32_e32 v40, v30, v32
	v_min_i32_e32 v30, v30, v32
	v_max_i32_e32 v32, v29, v25
	v_min_i32_e32 v25, v29, v25
	v_max_i32_e32 v29, v26, v24
	v_min_i32_e32 v24, v26, v24
	v_max_i32_e32 v59, v69, v90
	v_min_i32_e32 v69, v69, v90
	v_max_i32_e32 v90, v67, v71
	v_min_i32_e32 v67, v67, v71
	v_max_i32_e32 v71, v63, v68
	v_min_i32_e32 v63, v63, v68
	v_max_i32_e32 v68, v70, v96
	v_min_i32_e32 v70, v70, v96
	v_max_i32_e32 v96, v97, v60
	v_min_i32_e32 v60, v97, v60
	v_max_i32_e32 v97, v62, v66
	v_min_i32_e32 v62, v62, v66
	v_max_i32_e32 v66, v61, v57
	v_min_i32_e32 v57, v61, v57
	v_max_i32_e32 v61, v58, v56
	v_min_i32_e32 v56, v58, v56
	v_max_i32_e32 v8, v181, v183
	v_min_i32_e32 v181, v181, v183
	v_max_i32_e32 v183, v182, v179
	v_min_i32_e32 v179, v182, v179
	v_max_i32_e32 v182, v11, v13
	v_min_i32_e32 v11, v11, v13
	v_max_i32_e32 v13, v65, v178
	v_min_i32_e32 v65, v65, v178
	v_max_i32_e32 v178, v180, v177
	v_min_i32_e32 v177, v180, v177
	v_max_i32_e32 v180, v64, v10
	v_min_i32_e32 v10, v64, v10
	v_max_i32_e32 v64, v4, v9
	v_min_i32_e32 v4, v4, v9
	v_max_i32_e32 v9, v12, v5
	v_min_i32_e32 v5, v12, v5
	v_max_i32_e32 v14, v18, v22
	v_min_i32_e32 v18, v18, v22
	v_max_i32_e32 v22, v21, v20
	v_min_i32_e32 v20, v21, v20
	v_max_i32_e32 v21, v16, v17
	v_min_i32_e32 v16, v16, v17
	v_max_i32_e32 v17, v19, v23
	v_min_i32_e32 v19, v19, v23
	v_max_i32_e32 v23, v193, v3
	v_min_i32_e32 v3, v193, v3
	v_max_i32_e32 v193, v7, v15
	v_min_i32_e32 v7, v7, v15
	v_max_i32_e32 v15, v6, v2
	v_min_i32_e32 v2, v6, v2
	v_max_i32_e32 v6, v1, v0
	v_min_i32_e32 v0, v1, v0
	v_min_i32_e32 v26, v27, v38
	v_min_i32_e32 v41, v35, v33
	v_min_i32_e32 v42, v37, v34
	v_min_i32_e32 v43, v31, v36
	v_min_i32_e32 v44, v39, v40
	v_min_i32_e32 v45, v28, v30
	v_min_i32_e32 v46, v32, v29
	v_min_i32_e32 v47, v25, v24
	v_min_i32_e32 v58, v59, v90
	v_min_i32_e32 v170, v69, v67
	v_min_i32_e32 v171, v71, v68
	v_min_i32_e32 v172, v63, v70
	v_min_i32_e32 v173, v96, v97
	v_min_i32_e32 v174, v60, v62
	v_min_i32_e32 v175, v66, v61
	v_min_i32_e32 v176, v57, v56
	v_min_i32_e32 v12, v8, v183
	v_min_i32_e32 v184, v181, v179
	v_min_i32_e32 v185, v182, v13
	v_min_i32_e32 v186, v11, v65
	v_min_i32_e32 v187, v178, v180
	v_min_i32_e32 v188, v177, v10
	v_min_i32_e32 v190, v64, v9
	v_min_i32_e32 v192, v4, v5
	v_min_i32_e32 v1, v14, v22
	v_min_i32_e32 v194, v18, v20
	v_min_i32_e32 v195, v21, v17
	v_min_i32_e32 v196, v16, v19
	v_min_i32_e32 v197, v23, v193
	v_min_i32_e32 v198, v3, v7
	v_min_i32_e32 v199, v15, v6
	v_min_i32_e32 v200, v2, v0
	v_max3_i32 v27, v27, v38, v176
	v_max3_i32 v26, v26, v57, v56
	v_max3_i32 v33, v35, v33, v175
	v_max3_i32 v35, v41, v66, v61
	v_max3_i32 v34, v37, v34, v174
	v_max3_i32 v37, v42, v60, v62
	v_max3_i32 v31, v31, v36, v173
	v_max3_i32 v36, v43, v96, v97
	v_max3_i32 v38, v39, v40, v172
	v_max3_i32 v39, v44, v63, v70
	v_max3_i32 v28, v28, v30, v171
	v_max3_i32 v30, v45, v71, v68
	v_max3_i32 v29, v32, v29, v170
	v_max3_i32 v32, v46, v69, v67
	v_max3_i32 v24, v25, v24, v58
	v_max3_i32 v25, v47, v59, v90
	v_max3_i32 v8, v8, v183, v200
	v_max3_i32 v0, v12, v2, v0
	v_max3_i32 v2, v181, v179, v199
	v_max3_i32 v6, v184, v15, v6
	v_max3_i32 v12, v182, v13, v198
	v_max3_i32 v3, v185, v3, v7
	v_max3_i32 v7, v11, v65, v197
	v_max3_i32 v11, v186, v23, v193
	v_max3_i32 v13, v178, v180, v196
	v_max3_i32 v15, v187, v16, v19
	v_max3_i32 v10, v177, v10, v195
	v_max3_i32 v16, v188, v21, v17
	v_max3_i32 v9, v64, v9, v194
	v_max3_i32 v17, v190, v18, v20
	v_max3_i32 v1, v4, v5, v1
	v_max3_i32 v4, v192, v14, v22
	v_max_i32_e32 v40, v27, v38
	v_min_i32_e32 v27, v27, v38
	v_max_i32_e32 v38, v26, v39
	v_min_i32_e32 v26, v26, v39
	v_max_i32_e32 v39, v33, v28
	v_min_i32_e32 v28, v33, v28
	v_max_i32_e32 v33, v35, v30
	v_min_i32_e32 v30, v35, v30
	v_max_i32_e32 v35, v34, v29
	v_min_i32_e32 v29, v34, v29
	v_max_i32_e32 v34, v37, v32
	v_min_i32_e32 v32, v37, v32
	v_max_i32_e32 v37, v31, v24
	v_min_i32_e32 v24, v31, v24
; __device__ __forceinline__ int crow(int r, int hf) { return (r & 3) + 8 * (r >> 2) + 4 * hf; }
; __device__ __forceinline__ int tosort(float f) { int b = __float_as_int(f); return b ^ ((b >> 31) & 0x7fffffff); }
; template <int OA, int OB>
; __device__ __forceinline__ void merge16(int* a, const int* b) {
; #pragma unroll
;   for (int i = 0; i < 16; ++i) a[OA + i] = max(a[OA + i], b[OB + 15 - i]);
; #pragma unroll
;     ...
; #pragma unroll
;     for (int i = 0; i < 16; ++i) {
;       const int j = 1 << js; const int l2 = i ^ j;
;       if (l2 > i) cas_desc(a[OA + i], a[OA + l2]);
;     }
;   }
; }
; template <int PP>
; __device__ __forceinline__ void select_half(const Params& p, const u16* Subs, int t, int hh, int lc, int hf, int* lists) {
;   bf16x8 qf[8];
;   const u16* qrow = p.qp + (size_t)t * 2048 + hh * 256 + PP * 128 + hf * 8;
; #pragma unroll
;   for (int ks = 0; ks < 8; ++ks) qf[ks] = *(const bf16x8*)(qrow + ks * 16);
;   int keys[64];
; #pragma unroll
;   for (int nb = 0; nb < 4; ++nb) {
;     f32x16 acc;
; #pragma unroll
;     for (int r = 0; r < 16; ++r) acc[r] = 0.f;
; #pragma unroll
;     for (int ks = 0; ks < 8; ++ks) {
;       bf16x8 a = *(const bf16x8*)(Subs + (PP * 128 + nb * 32 + lc) * 136 + ks * 16 + hf * 8);
;       acc = mfma32(a, qf[ks], acc);
;     }
; #pragma unroll
;     for (int r = 0; r < 16; ++r) keys[nb * 16 + r] = (tosort(acc[r]) & ~127) | (nb * 32 + crow(r, hf));
;   }
;   sort16_desc<0>(keys); sort16_desc<16>(keys); sort16_desc<32>(keys); sort16_desc<48>(keys);
;   merge16<0, 16>(keys, keys); merge16<32, 48>(keys, keys); merge16<0, 32>(keys, keys);
;   int other[16];
; #pragma unroll
;   for (int i = 0; i < 16; ++i) other[i] = __shfl_xor(keys[i], 32);
;   merge16<0, 0>(keys, other);
	v_max_i32_e32 v31, v36, v25
	v_min_i32_e32 v25, v36, v25
	v_max_i32_e32 v5, v8, v13
	v_min_i32_e32 v8, v8, v13
	v_max_i32_e32 v13, v0, v15
	v_min_i32_e32 v0, v0, v15
	v_max_i32_e32 v14, v2, v10
	v_min_i32_e32 v2, v2, v10
	v_max_i32_e32 v10, v6, v16
	v_min_i32_e32 v6, v6, v16
	v_max_i32_e32 v15, v12, v9
	v_min_i32_e32 v9, v12, v9
	v_max_i32_e32 v12, v3, v17
	v_min_i32_e32 v3, v3, v17
	v_max_i32_e32 v16, v7, v1
	v_min_i32_e32 v1, v7, v1
	v_max_i32_e32 v7, v11, v4
	v_min_i32_e32 v4, v11, v4
	v_max_i32_e32 v36, v40, v35
	v_min_i32_e32 v35, v40, v35
	v_max_i32_e32 v40, v38, v34
	v_min_i32_e32 v34, v38, v34
	v_max_i32_e32 v38, v39, v37
	v_min_i32_e32 v37, v39, v37
	v_max_i32_e32 v39, v33, v31
	v_min_i32_e32 v31, v33, v31
	v_max_i32_e32 v33, v27, v29
	v_min_i32_e32 v27, v27, v29
	v_max_i32_e32 v29, v26, v32
	v_min_i32_e32 v26, v26, v32
	v_max_i32_e32 v32, v28, v24
	v_min_i32_e32 v24, v28, v24
	v_max_i32_e32 v28, v30, v25
	v_min_i32_e32 v25, v30, v25
	v_max_i32_e32 v11, v5, v15
	v_min_i32_e32 v5, v5, v15
	v_max_i32_e32 v15, v13, v12
	v_min_i32_e32 v12, v13, v12
	v_max_i32_e32 v13, v14, v16
	v_min_i32_e32 v14, v14, v16
	v_max_i32_e32 v16, v10, v7
	v_min_i32_e32 v7, v10, v7
	v_max_i32_e32 v10, v8, v9
	v_min_i32_e32 v8, v8, v9
	v_max_i32_e32 v9, v0, v3
	v_min_i32_e32 v0, v0, v3
	v_max_i32_e32 v3, v2, v1
	v_min_i32_e32 v1, v2, v1
	v_max_i32_e32 v2, v6, v4
	v_min_i32_e32 v4, v6, v4
	v_max_i32_e32 v30, v36, v38
	v_min_i32_e32 v36, v36, v38
	v_max_i32_e32 v38, v40, v39
	v_min_i32_e32 v39, v40, v39
	v_max_i32_e32 v40, v35, v37
	v_min_i32_e32 v35, v35, v37
	v_max_i32_e32 v37, v34, v31
	v_min_i32_e32 v31, v34, v31
	v_max_i32_e32 v34, v33, v32
	v_min_i32_e32 v32, v33, v32
	v_max_i32_e32 v33, v29, v28
	v_min_i32_e32 v28, v29, v28
	v_max_i32_e32 v29, v27, v24
	v_min_i32_e32 v24, v27, v24
	v_max_i32_e32 v27, v26, v25
	v_min_i32_e32 v25, v26, v25
	v_max_i32_e32 v6, v11, v13
	v_min_i32_e32 v11, v11, v13
	v_max_i32_e32 v13, v15, v16
	v_min_i32_e32 v15, v15, v16
	v_max_i32_e32 v16, v5, v14
	v_min_i32_e32 v5, v5, v14
	v_max_i32_e32 v14, v12, v7
	v_min_i32_e32 v7, v12, v7
	v_max_i32_e32 v12, v10, v3
	v_min_i32_e32 v3, v10, v3
	v_max_i32_e32 v10, v9, v2
	v_min_i32_e32 v2, v9, v2
	v_max_i32_e32 v9, v8, v1
	v_min_i32_e32 v1, v8, v1
	v_max_i32_e32 v8, v0, v4
	v_min_i32_e32 v0, v0, v4
	v_min_i32_e32 v26, v30, v38
	v_min_i32_e32 v41, v36, v39
	v_min_i32_e32 v42, v40, v37
	v_min_i32_e32 v43, v35, v31
	v_min_i32_e32 v44, v34, v33
	v_min_i32_e32 v45, v32, v28
	v_min_i32_e32 v46, v29, v27
	v_min_i32_e32 v47, v24, v25
	v_min_i32_e32 v4, v6, v13
	v_min_i32_e32 v17, v11, v15
	v_min_i32_e32 v18, v16, v14
	v_min_i32_e32 v19, v5, v7
	v_min_i32_e32 v20, v12, v10
	v_min_i32_e32 v21, v3, v2
	v_min_i32_e32 v22, v9, v8
	v_min_i32_e32 v23, v1, v0
	v_max3_i32 v23, v30, v38, v23
	v_max3_i32 v0, v26, v1, v0
	v_max3_i32 v1, v36, v39, v22
	v_max3_i32 v8, v41, v9, v8
	v_max3_i32 v9, v40, v37, v21
	v_max3_i32 v2, v42, v3, v2
	v_max3_i32 v3, v35, v31, v20
	v_max3_i32 v10, v43, v12, v10
	v_max3_i32 v12, v34, v33, v19
	v_max3_i32 v5, v44, v5, v7
	v_max3_i32 v7, v32, v28, v18
	v_max3_i32 v14, v45, v16, v14
	v_max3_i32 v16, v29, v27, v17
	v_max3_i32 v11, v46, v11, v15
	v_max3_i32 v4, v24, v25, v4
	v_max3_i32 v6, v47, v6, v13
	v_max_i32_e32 v13, v23, v12
	v_min_i32_e32 v12, v23, v12
	v_max_i32_e32 v15, v0, v5
	v_min_i32_e32 v0, v0, v5
	v_max_i32_e32 v5, v1, v7
	v_min_i32_e32 v1, v1, v7
	v_max_i32_e32 v7, v8, v14
	v_min_i32_e32 v8, v8, v14
	v_max_i32_e32 v14, v9, v16
	v_min_i32_e32 v9, v9, v16
	v_max_i32_e32 v16, v2, v11
	v_min_i32_e32 v2, v2, v11
	v_max_i32_e32 v11, v3, v4
	v_min_i32_e32 v3, v3, v4
	v_max_i32_e32 v4, v10, v6
	v_min_i32_e32 v6, v10, v6
	v_max_i32_e32 v10, v13, v14
	v_min_i32_e32 v13, v13, v14
	v_max_i32_e32 v14, v15, v16
	v_min_i32_e32 v15, v15, v16
	v_max_i32_e32 v16, v5, v11
	v_min_i32_e32 v5, v5, v11
	v_max_i32_e32 v11, v7, v4
	v_min_i32_e32 v4, v7, v4
	v_max_i32_e32 v7, v12, v9
	v_min_i32_e32 v9, v12, v9
	v_max_i32_e32 v12, v0, v2
	v_min_i32_e32 v0, v0, v2
	v_max_i32_e32 v2, v1, v3
	v_min_i32_e32 v1, v1, v3
	v_max_i32_e32 v3, v8, v6
	v_min_i32_e32 v6, v8, v6
	v_max_i32_e32 v8, v10, v16
	v_min_i32_e32 v10, v10, v16
	v_max_i32_e32 v16, v14, v11
	v_min_i32_e32 v11, v14, v11
	v_max_i32_e32 v14, v13, v5
	v_min_i32_e32 v5, v13, v5
	v_max_i32_e32 v13, v15, v4
	v_min_i32_e32 v4, v15, v4
	v_max_i32_e32 v15, v7, v2
	v_min_i32_e32 v2, v7, v2
	v_max_i32_e32 v7, v12, v3
	v_min_i32_e32 v3, v12, v3
	v_max_i32_e32 v12, v9, v1
	v_min_i32_e32 v1, v9, v1
	v_max_i32_e32 v9, v0, v6
	v_min_i32_e32 v0, v0, v6
	v_max_i32_e32 v6, v8, v16
	v_min_i32_e32 v8, v8, v16
	v_max_i32_e32 v16, v10, v11
	v_min_i32_e32 v10, v10, v11
	v_max_i32_e32 v11, v14, v13
	v_min_i32_e32 v13, v14, v13
	v_max_i32_e32 v14, v5, v4
	v_min_i32_e32 v4, v5, v4
	v_max_i32_e32 v5, v15, v7
	v_min_i32_e32 v7, v15, v7
	v_max_i32_e32 v15, v2, v3
	v_min_i32_e32 v2, v2, v3
	v_max_i32_e32 v3, v12, v9
	v_min_i32_e32 v9, v12, v9
	v_max_i32_e32 v12, v1, v0
	v_min_i32_e32 v0, v1, v0
	ds_bpermute_b32 v1, v100, v6
	ds_bpermute_b32 v17, v100, v8
	ds_bpermute_b32 v18, v100, v16
	ds_bpermute_b32 v19, v100, v10
	ds_bpermute_b32 v20, v100, v11
	ds_bpermute_b32 v21, v100, v13
	ds_bpermute_b32 v22, v100, v14
	ds_bpermute_b32 v23, v100, v4
	ds_bpermute_b32 v24, v100, v5
	ds_bpermute_b32 v25, v100, v7
	ds_bpermute_b32 v26, v100, v15
	ds_bpermute_b32 v27, v100, v0
	ds_bpermute_b32 v28, v100, v12
	ds_bpermute_b32 v29, v100, v9
	ds_bpermute_b32 v30, v100, v3
	ds_bpermute_b32 v31, v100, v2
	s_waitcnt lgkmcnt(4)
	v_max_i32_e32 v6, v6, v27
	s_waitcnt lgkmcnt(3)
	v_max_i32_e32 v8, v8, v28
	s_waitcnt lgkmcnt(2)
	v_max_i32_e32 v16, v16, v29
	s_waitcnt lgkmcnt(1)
; __device__ __forceinline__ int tosort(float f) { int b = __float_as_int(f); return b ^ ((b >> 31) & 0x7fffffff); }
; __device__ __forceinline__ float fromsort(int b) { return __int_as_float(b ^ ((b >> 31) & 0x7fffffff)); }
; __device__ __forceinline__ int bsel(int m, int a, int b) { return (a & ~m) | (b & m); }
; template <int PP>
; __device__ __forceinline__ void select_half(const Params& p, const u16* Subs, int t, int hh, int lc, int hf, int* lists) {
;     ...
;   sort16_desc<0>(keys); sort16_desc<16>(keys); sort16_desc<32>(keys); sort16_desc<48>(keys);
;   merge16<0, 16>(keys, keys); merge16<32, 48>(keys, keys); merge16<0, 32>(keys, keys);
;   int other[16];
; #pragma unroll
;   for (int i = 0; i < 16; ++i) other[i] = __shfl_xor(keys[i], 32);
;   merge16<0, 0>(keys, other);
; #pragma unroll
;   for (int i = 0; i < 16; ++i) lists[PP * 16 + i] = keys[i];
; __device__ __forceinline__ void phase_select(const Params& p, int layer, char* smraw) {
;     ...
;     for (int i = 0; i < 16; ++i) { f1[i] = fromsort(lists[i] & ~127); f2[i] = fromsort(lists[16 + i] & ~127); }
;     int cand[32];
; #pragma unroll
;     for (int c = 0; c < 32; ++c) {
;       constexpr int IMIN = (int)0x80000000;
;       const int ia = candA_i(c), ja = candA_j(c), ib = candB_i(c), jb = candB_j(c);
;       int ka = IMIN, kb2 = IMIN;
;       if (ia >= 0) ka = (tosort(f1[ia >= 0 ? ia : 0] + f2[ja]) & ~255) | (ia << 4) | ja;
;       if (ib >= 0) kb2 = (tosort(f1[ib >= 0 ? ib : 0] + f2[jb]) & ~255) | (ib << 4) | jb;
;       cand[c] = bsel(hmask, ka, kb2);
	v_max_i32_e32 v10, v10, v30
	s_waitcnt lgkmcnt(0)
	v_max_i32_e32 v11, v11, v31
	v_max_i32_e32 v13, v13, v26
	v_max_i32_e32 v14, v14, v25
	v_max_i32_e32 v4, v4, v24
	v_max_i32_e32 v5, v5, v23
	v_max_i32_e32 v7, v7, v22
	v_max_i32_e32 v15, v15, v21
	v_max_i32_e32 v2, v2, v20
	v_max_i32_e32 v3, v3, v19
	v_max_i32_e32 v9, v9, v18
	v_max_i32_e32 v12, v12, v17
	v_max_i32_e32 v0, v0, v1
	v_max_i32_e32 v1, v6, v5
	v_min_i32_e32 v5, v6, v5
	v_max_i32_e32 v6, v8, v7
	v_min_i32_e32 v7, v8, v7
	v_max_i32_e32 v8, v16, v15
	v_min_i32_e32 v15, v16, v15
	v_max_i32_e32 v16, v10, v2
	v_min_i32_e32 v2, v10, v2
	v_max_i32_e32 v10, v11, v3
	v_min_i32_e32 v3, v11, v3
	v_max_i32_e32 v11, v13, v9
	v_min_i32_e32 v9, v13, v9
	v_max_i32_e32 v13, v14, v12
	v_min_i32_e32 v12, v14, v12
	v_max_i32_e32 v14, v4, v0
	v_min_i32_e32 v0, v4, v0
	v_max_i32_e32 v4, v1, v10
	v_min_i32_e32 v1, v1, v10
	v_max_i32_e32 v10, v6, v11
	v_min_i32_e32 v6, v6, v11
	v_max_i32_e32 v11, v8, v13
	v_min_i32_e32 v8, v8, v13
	v_max_i32_e32 v13, v16, v14
	v_min_i32_e32 v14, v16, v14
	v_max_i32_e32 v16, v5, v3
	v_min_i32_e32 v3, v5, v3
	v_max_i32_e32 v5, v7, v9
	v_min_i32_e32 v7, v7, v9
	v_max_i32_e32 v9, v15, v12
	v_min_i32_e32 v12, v15, v12
	v_max_i32_e32 v15, v2, v0
	v_min_i32_e32 v0, v2, v0
	v_max_i32_e32 v2, v4, v11
	v_min_i32_e32 v4, v4, v11
	v_max_i32_e32 v11, v10, v13
	v_min_i32_e32 v10, v10, v13
	v_max_i32_e32 v13, v1, v8
	v_min_i32_e32 v1, v1, v8
	v_max_i32_e32 v8, v6, v14
	v_min_i32_e32 v6, v6, v14
	v_max_i32_e32 v14, v16, v9
	v_min_i32_e32 v9, v16, v9
	v_max_i32_e32 v16, v5, v15
	v_min_i32_e32 v5, v5, v15
	v_max_i32_e32 v15, v3, v12
	v_min_i32_e32 v3, v3, v12
	v_max_i32_e32 v12, v7, v0
	v_min_i32_e32 v0, v7, v0
	v_max_i32_e32 v29, v4, v10
	v_max_i32_e32 v23, v14, v16
	v_min_i32_e32 v22, v14, v16
	v_max_i32_e32 v17, v3, v0
	v_min_i32_e32 v16, v3, v0
	v_ashrrev_i32_e32 v3, 31, v85
	v_max_i32_e32 v31, v2, v11
	v_min_i32_e32 v30, v2, v11
	v_max_i32_e32 v25, v1, v6
	v_min_i32_e32 v24, v1, v6
	v_and_b32_e32 v1, 0xffffff80, v85
	v_ashrrev_i32_e32 v2, 31, v29
	v_and_b32_e32 v3, 0x7fffffff, v3
	v_min_i32_e32 v28, v4, v10
	v_max_i32_e32 v27, v13, v8
	v_min_i32_e32 v26, v13, v8
	v_and_b32_e32 v0, 0xffffff80, v29
	v_and_b32_e32 v2, 0x7fffffff, v2
	v_xor_b32_e32 v8, v3, v1
	v_ashrrev_i32_e32 v3, 31, v84
	v_xor_b32_e32 v4, v2, v0
	v_and_b32_e32 v1, 0xffffff80, v84
	v_ashrrev_i32_e32 v2, 31, v28
	v_and_b32_e32 v3, 0x7fffffff, v3
	v_and_b32_e32 v0, 0xffffff80, v28
	v_and_b32_e32 v2, 0x7fffffff, v2
	v_xor_b32_e32 v10, v3, v1
	v_ashrrev_i32_e32 v1, 31, v30
	v_ashrrev_i32_e32 v3, 31, v81
	v_xor_b32_e32 v11, v2, v0
	v_and_b32_e32 v0, 0xffffff80, v30
	v_and_b32_e32 v2, 0xffffff80, v81
	v_and_b32_e32 v1, 0x7fffffff, v1
	v_and_b32_e32 v3, 0x7fffffff, v3
	v_ashrrev_i32_e32 v6, 31, v86
	v_max_i32_e32 v21, v9, v5
	v_min_i32_e32 v20, v9, v5
	v_xor_b32_e32 v1, v1, v0
	v_xor_b32_e32 v0, v3, v2
	v_and_b32_e32 v3, 0xffffff80, v86
	v_ashrrev_i32_e32 v5, 31, v25
	v_and_b32_e32 v6, 0x7fffffff, v6
	v_and_b32_e32 v2, 0xffffff80, v25
	v_and_b32_e32 v5, 0x7fffffff, v5
	v_xor_b32_e32 v32, v6, v3
	v_ashrrev_i32_e32 v3, 31, v31
	v_ashrrev_i32_e32 v6, 31, v80
	v_xor_b32_e32 v33, v5, v2
	v_and_b32_e32 v2, 0xffffff80, v31
	v_and_b32_e32 v5, 0xffffff80, v80
	v_and_b32_e32 v3, 0x7fffffff, v3
	v_and_b32_e32 v6, 0x7fffffff, v6
	v_xor_b32_e32 v3, v3, v2
	v_xor_b32_e32 v2, v6, v5
	v_and_b32_e32 v5, 0xffffff80, v78
	v_ashrrev_i32_e32 v6, 31, v78
	v_max_i32_e32 v19, v15, v12
	v_min_i32_e32 v18, v15, v12
	v_bitop3_b32 v12, v6, v5, s20 bitop3:0x6c
	v_and_b32_e32 v5, 0xffffff80, v79
	v_ashrrev_i32_e32 v6, 31, v79
	v_bitop3_b32 v15, v6, v5, s20 bitop3:0x6c
	v_and_b32_e32 v5, 0xffffff80, v22
	v_ashrrev_i32_e32 v6, 31, v22
	v_bitop3_b32 v34, v6, v5, s20 bitop3:0x6c
	v_and_b32_e32 v5, 0xffffff80, v77
	v_ashrrev_i32_e32 v6, 31, v77
	v_bitop3_b32 v13, v6, v5, s20 bitop3:0x6c
	v_and_b32_e32 v5, 0xffffff80, v21
	v_ashrrev_i32_e32 v6, 31, v21
	v_bitop3_b32 v36, v6, v5, s20 bitop3:0x6c
	v_and_b32_e32 v5, 0xffffff80, v20
	v_ashrrev_i32_e32 v6, 31, v20
	v_bitop3_b32 v38, v6, v5, s20 bitop3:0x6c
	v_and_b32_e32 v5, 0xffffff80, v19
	v_ashrrev_i32_e32 v6, 31, v19
	v_bitop3_b32 v40, v6, v5, s20 bitop3:0x6c
	v_and_b32_e32 v5, 0xffffff80, v74
	v_ashrrev_i32_e32 v6, 31, v74
	v_bitop3_b32 v62, v6, v5, s20 bitop3:0x6c
	v_and_b32_e32 v5, 0xffffff80, v18
	v_ashrrev_i32_e32 v6, 31, v18
	v_bitop3_b32 v43, v6, v5, s20 bitop3:0x6c
	v_and_b32_e32 v5, 0xffffff80, v73
	v_ashrrev_i32_e32 v6, 31, v73
	v_bitop3_b32 v63, v6, v5, s20 bitop3:0x6c
	v_and_b32_e32 v5, 0xffffff80, v17
	v_ashrrev_i32_e32 v6, 31, v17
	v_bitop3_b32 v45, v6, v5, s20 bitop3:0x6c
	v_and_b32_e32 v5, 0xffffff80, v72
	v_ashrrev_i32_e32 v6, 31, v72
	v_ashrrev_i32_e32 v7, 31, v16
	v_ashrrev_i32_e32 v9, 31, v87
	v_bitop3_b32 v64, v6, v5, s20 bitop3:0x6c
	v_and_b32_e32 v5, 0xffffff80, v16
	v_and_b32_e32 v6, 0xffffff80, v87
	v_and_b32_e32 v7, 0x7fffffff, v7
	v_and_b32_e32 v9, 0x7fffffff, v9
	v_xor_b32_e32 v47, v7, v5
	v_xor_b32_e32 v46, v9, v6
	v_pk_add_f32 v[6:7], v[2:3], v[46:47] op_sel:[1,0] op_sel_hi:[0,1]
	v_ashrrev_i32_e32 v5, 31, v6
	v_and_b32_e32 v6, 0xffffff00, v6
	v_bitop3_b32 v5, v5, v6, s21 bitop3:0x6c
	v_mov_b32_e32 v56, v46
	v_mov_b32_e32 v57, v32
	v_mov_b32_e32 v6, v1
	v_mov_b32_e32 v7, v3
	v_pk_add_f32 v[58:59], v[56:57], v[6:7]
	v_cndmask_b32_e64 v5, 0, v5, s[4:5]
	v_ashrrev_i32_e32 v9, 31, v59
	v_and_b32_e32 v9, 0x7fffff00, v9
	v_and_b32_e32 v14, 0xffffff00, v59
	v_bitop3_b32 v9, v9, 16, v14 bitop3:0xde
	v_and_or_b32 v65, v9, v48, v5
	v_ashrrev_i32_e32 v5, 31, v58
	v_and_b32_e32 v5, 0x7fffff00, v5
	v_and_b32_e32 v9, 0xffffff00, v58
	v_bitop3_b32 v5, v5, 1, v9 bitop3:0xde
; __device__ __forceinline__ int tosort(float f) { int b = __float_as_int(f); return b ^ ((b >> 31) & 0x7fffffff); }
; __device__ __forceinline__ int bsel(int m, int a, int b) { return (a & ~m) | (b & m); }
; __device__ __forceinline__ void phase_select(const Params& p, int layer, char* smraw) {
;     ...
; #pragma unroll
;     for (int c = 0; c < 32; ++c) {
;       constexpr int IMIN = (int)0x80000000;
;       const int ia = candA_i(c), ja = candA_j(c), ib = candB_i(c), jb = candB_j(c);
;       int ka = IMIN, kb2 = IMIN;
;       if (ia >= 0) ka = (tosort(f1[ia >= 0 ? ia : 0] + f2[ja]) & ~255) | (ia << 4) | ja;
;       if (ib >= 0) kb2 = (tosort(f1[ib >= 0 ? ib : 0] + f2[jb]) & ~255) | (ib << 4) | jb;
;       cand[c] = bsel(hmask, ka, kb2);
	v_cndmask_b32_e64 v9, 0, v5, s[4:5]
	v_mov_b32_e32 v5, v1
	v_pk_add_f32 v[58:59], v[56:57], v[4:5]
	v_ashrrev_i32_e32 v35, 31, v27
	v_ashrrev_i32_e32 v5, 31, v59
	v_and_b32_e32 v5, 0x7fffff00, v5
	v_and_b32_e32 v14, 0xffffff00, v59
	v_bitop3_b32 v5, v5, 17, v14 bitop3:0xde
	v_and_or_b32 v66, v5, v48, v9
	v_ashrrev_i32_e32 v5, 31, v58
	v_and_b32_e32 v9, 0xffffff00, v58
	v_mov_b32_e32 v58, v11
	v_mov_b32_e32 v59, v4
	v_and_b32_e32 v5, 0x7fffff00, v5
	v_pk_add_f32 v[58:59], v[56:57], v[58:59]
	v_bitop3_b32 v5, v5, 2, v9 bitop3:0xde
	v_ashrrev_i32_e32 v9, 31, v59
	v_and_b32_e32 v9, 0x7fffff00, v9
	v_and_b32_e32 v14, 0xffffff00, v59
	v_cndmask_b32_e64 v5, 0, v5, s[4:5]
	v_bitop3_b32 v9, v9, 18, v14 bitop3:0xde
	v_and_or_b32 v67, v9, v48, v5
	v_ashrrev_i32_e32 v5, 31, v58
	v_and_b32_e32 v5, 0x7fffff00, v5
	v_and_b32_e32 v9, 0xffffff00, v58
	v_bitop3_b32 v5, v5, 3, v9 bitop3:0xde
	v_and_b32_e32 v9, 0xffffff80, v27
	v_and_b32_e32 v35, 0x7fffffff, v35
	v_xor_b32_e32 v59, v35, v9
	v_mov_b32_e32 v60, v59
	v_mov_b32_e32 v61, v11
	v_ashrrev_i32_e32 v37, 31, v26
	v_pk_add_f32 v[60:61], v[56:57], v[60:61]
	v_and_b32_e32 v14, 0xffffff80, v26
	v_and_b32_e32 v37, 0x7fffffff, v37
	v_ashrrev_i32_e32 v9, 31, v61
	v_xor_b32_e32 v58, v37, v14
	v_and_b32_e32 v9, 0x7fffff00, v9
	v_and_b32_e32 v14, 0xffffff00, v61
	v_cndmask_b32_e64 v5, 0, v5, s[4:5]
	v_bitop3_b32 v9, v9, 19, v14 bitop3:0xde
	v_and_or_b32 v68, v9, v48, v5
	v_ashrrev_i32_e32 v5, 31, v60
	v_and_b32_e32 v5, 0x7fffff00, v5
	v_and_b32_e32 v9, 0xffffff00, v60
	v_pk_add_f32 v[60:61], v[56:57], v[58:59]
	v_bitop3_b32 v5, v5, 4, v9 bitop3:0xde
	v_ashrrev_i32_e32 v9, 31, v61
	v_and_b32_e32 v9, 0x7fffff00, v9
	v_and_b32_e32 v14, 0xffffff00, v61
	v_bitop3_b32 v9, v9, 20, v14 bitop3:0xde
	v_cndmask_b32_e64 v5, 0, v5, s[4:5]
	v_and_or_b32 v69, v9, v48, v5
	v_ashrrev_i32_e32 v5, 31, v60
	v_and_b32_e32 v9, 0xffffff00, v60
	v_mov_b32_e32 v60, v58
	v_mov_b32_e32 v61, v46
	v_and_b32_e32 v5, 0x7fffff00, v5
	v_pk_add_f32 v[60:61], v[32:33], v[60:61]
	v_bitop3_b32 v5, v5, 5, v9 bitop3:0xde
	v_ashrrev_i32_e32 v9, 31, v60
	v_and_b32_e32 v9, 0x7fffff00, v9
	v_and_b32_e32 v14, 0xffffff00, v60
	v_cndmask_b32_e64 v5, 0, v5, s[4:5]
	v_bitop3_b32 v9, v9, 21, v14 bitop3:0xde
	v_and_or_b32 v70, v9, v48, v5
	v_ashrrev_i32_e32 v5, 31, v61
	v_and_b32_e32 v5, 0x7fffff00, v5
	v_and_b32_e32 v9, 0xffffff00, v61
	v_ashrrev_i32_e32 v32, 31, v24
	v_bitop3_b32 v5, v5, 6, v9 bitop3:0xde
	v_and_b32_e32 v9, 0xffffff80, v24
	v_and_b32_e32 v32, 0x7fffffff, v32
	v_xor_b32_e32 v61, v32, v9
	v_mov_b32_e32 v32, v61
	v_ashrrev_i32_e32 v35, 31, v23
	v_pk_add_f32 v[32:33], v[56:57], v[32:33]
	v_and_b32_e32 v14, 0xffffff80, v23
	v_and_b32_e32 v35, 0x7fffffff, v35
	v_ashrrev_i32_e32 v9, 31, v33
	v_xor_b32_e32 v60, v35, v14
	v_and_b32_e32 v9, 0x7fffff00, v9
	v_and_b32_e32 v14, 0xffffff00, v33
	v_cndmask_b32_e64 v5, 0, v5, s[4:5]
	v_bitop3_b32 v9, v9, 22, v14 bitop3:0xde
	v_and_or_b32 v71, v9, v48, v5
	v_ashrrev_i32_e32 v5, 31, v32
	v_and_b32_e32 v5, 0x7fffff00, v5
	v_and_b32_e32 v9, 0xffffff00, v32
	v_pk_add_f32 v[32:33], v[56:57], v[60:61]
	v_bitop3_b32 v5, v5, 7, v9 bitop3:0xde
	v_ashrrev_i32_e32 v9, 31, v33
	v_and_b32_e32 v9, 0x7fffff00, v9
	v_and_b32_e32 v14, 0xffffff00, v33
	v_bitop3_b32 v9, v9, 23, v14 bitop3:0xde
	v_cndmask_b32_e64 v5, 0, v5, s[4:5]
	v_and_or_b32 v56, v9, v48, v5
	v_ashrrev_i32_e32 v5, 31, v32
	v_and_b32_e32 v9, 0xffffff00, v32
	v_mov_b32_e32 v32, v46
	v_mov_b32_e32 v33, v10
	v_mov_b32_e32 v35, v3
	v_and_b32_e32 v5, 0x7fffff00, v5
	v_pk_add_f32 v[34:35], v[32:33], v[34:35]
	v_bitop3_b32 v5, v5, 8, v9 bitop3:0xde
	v_ashrrev_i32_e32 v9, 31, v35
	v_and_b32_e32 v9, 0x7fffff00, v9
	v_and_b32_e32 v14, 0xffffff00, v35
	v_cndmask_b32_e64 v5, 0, v5, s[4:5]
	v_bitop3_b32 v9, v9, 32, v14 bitop3:0xde
	v_and_or_b32 v57, v9, v48, v5
	v_ashrrev_i32_e32 v5, 31, v34
	v_mov_b32_e32 v37, v1
	v_and_b32_e32 v5, 0x7fffff00, v5
	v_and_b32_e32 v9, 0xffffff00, v34
	v_pk_add_f32 v[34:35], v[32:33], v[36:37]
	v_bitop3_b32 v5, v5, 9, v9 bitop3:0xde
	v_ashrrev_i32_e32 v9, 31, v35
	v_and_b32_e32 v9, 0x7fffff00, v9
	v_and_b32_e32 v14, 0xffffff00, v35
	v_cndmask_b32_e64 v5, 0, v5, s[4:5]
	v_bitop3_b32 v9, v9, 33, v14 bitop3:0xde
	v_and_or_b32 v36, v9, v48, v5
	v_ashrrev_i32_e32 v5, 31, v34
	v_mov_b32_e32 v39, v4
	v_and_b32_e32 v5, 0x7fffff00, v5
	v_and_b32_e32 v9, 0xffffff00, v34
	v_pk_add_f32 v[34:35], v[32:33], v[38:39]
	v_bitop3_b32 v5, v5, 10, v9 bitop3:0xde
	v_ashrrev_i32_e32 v9, 31, v35
	v_and_b32_e32 v9, 0x7fffff00, v9
	v_and_b32_e32 v14, 0xffffff00, v35
	v_cndmask_b32_e64 v5, 0, v5, s[4:5]
	v_bitop3_b32 v9, v9, 34, v14 bitop3:0xde
	v_and_or_b32 v35, v9, v48, v5
	v_ashrrev_i32_e32 v5, 31, v34
	v_mov_b32_e32 v41, v11
	v_and_b32_e32 v5, 0x7fffff00, v5
	v_and_b32_e32 v9, 0xffffff00, v34
	v_pk_add_f32 v[32:33], v[32:33], v[40:41]
	v_bitop3_b32 v5, v5, 11, v9 bitop3:0xde
	v_ashrrev_i32_e32 v9, 31, v33
	v_and_b32_e32 v9, 0x7fffff00, v9
	v_and_b32_e32 v14, 0xffffff00, v33
	v_cndmask_b32_e64 v5, 0, v5, s[4:5]
	v_bitop3_b32 v9, v9, 35, v14 bitop3:0xde
	v_and_or_b32 v34, v9, v48, v5
	v_ashrrev_i32_e32 v5, 31, v32
	v_and_b32_e32 v5, 0x7fffff00, v5
	v_and_b32_e32 v9, 0xffffff00, v32
	v_pk_add_f32 v[32:33], v[58:59], v[10:11] op_sel:[1,0] op_sel_hi:[0,1]
	v_bitop3_b32 v5, v5, 12, v9 bitop3:0xde
	v_ashrrev_i32_e32 v9, 31, v32
	v_and_b32_e32 v9, 0x7fffff00, v9
	v_and_b32_e32 v10, 0xffffff00, v32
	v_bitop3_b32 v9, v9, 36, v10 bitop3:0xde
	v_cndmask_b32_e64 v5, 0, v5, s[4:5]
	v_and_or_b32 v37, v9, v48, v5
	v_mov_b32_e32 v9, v46
	v_mov_b32_e32 v42, v3
	v_pk_add_f32 v[32:33], v[42:43], v[8:9]
	v_mov_b32_e32 v44, v1
	v_ashrrev_i32_e32 v5, 31, v33
	v_and_b32_e32 v5, 0x7fffff00, v5
; __device__ __forceinline__ int tosort(float f) { int b = __float_as_int(f); return b ^ ((b >> 31) & 0x7fffffff); }
; __device__ __forceinline__ int bsel(int m, int a, int b) { return (a & ~m) | (b & m); }
; __device__ __forceinline__ void phase_select(const Params& p, int layer, char* smraw) {
;     ...
; #pragma unroll
;     for (int c = 0; c < 32; ++c) {
;       constexpr int IMIN = (int)0x80000000;
;       const int ia = candA_i(c), ja = candA_j(c), ib = candB_i(c), jb = candB_j(c);
;       int ka = IMIN, kb2 = IMIN;
;       if (ia >= 0) ka = (tosort(f1[ia >= 0 ? ia : 0] + f2[ja]) & ~255) | (ia << 4) | ja;
;       if (ib >= 0) kb2 = (tosort(f1[ib >= 0 ? ib : 0] + f2[jb]) & ~255) | (ib << 4) | jb;
;       cand[c] = bsel(hmask, ka, kb2);
;     }
;     sort16_desc<0>(cand); sort16_desc<16>(cand);
;     merge16<0, 16>(cand, cand);
	v_and_b32_e32 v10, 0xffffff00, v33
	v_bitop3_b32 v5, v5, 13, v10 bitop3:0xde
	v_ashrrev_i32_e32 v10, 31, v32
	v_and_b32_e32 v10, 0x7fffff00, v10
	v_and_b32_e32 v14, 0xffffff00, v32
	v_bitop3_b32 v10, v10, 48, v14 bitop3:0xde
	v_cndmask_b32_e64 v5, 0, v5, s[4:5]
	v_pk_add_f32 v[32:33], v[44:45], v[8:9]
	v_and_or_b32 v38, v10, v48, v5
	v_ashrrev_i32_e32 v5, 31, v33
	v_and_b32_e32 v5, 0x7fffff00, v5
	v_and_b32_e32 v10, 0xffffff00, v33
	v_bitop3_b32 v5, v5, 14, v10 bitop3:0xde
	v_ashrrev_i32_e32 v10, 31, v32
	v_and_b32_e32 v10, 0x7fffff00, v10
	v_and_b32_e32 v14, 0xffffff00, v32
	v_bitop3_b32 v10, v10, 49, v14 bitop3:0xde
	v_cndmask_b32_e64 v5, 0, v5, s[4:5]
	v_and_or_b32 v39, v10, v48, v5
	v_mov_b32_e32 v5, v47
	v_pk_add_f32 v[32:33], v[8:9], v[4:5]
	v_min_i32_e32 v40, v56, v71
	v_ashrrev_i32_e32 v5, 31, v33
	v_and_b32_e32 v5, 0x7fffff00, v5
	v_and_b32_e32 v9, 0xffffff00, v33
	v_bitop3_b32 v5, v5, 15, v9 bitop3:0xde
	v_ashrrev_i32_e32 v9, 31, v32
	v_and_b32_e32 v9, 0x7fffff00, v9
	v_and_b32_e32 v10, 0xffffff00, v32
	v_bitop3_b32 v9, v9, 50, v10 bitop3:0xde
	v_cndmask_b32_e64 v5, 0, v5, s[4:5]
	v_and_or_b32 v32, v9, v48, v5
	v_mov_b32_e32 v9, v12
	v_mov_b32_e32 v10, v11
	v_mov_b32_e32 v11, v3
	v_pk_add_f32 v[8:9], v[8:9], v[10:11]
	v_ashrrev_i32_e32 v10, 31, v83
	v_ashrrev_i32_e32 v5, 31, v9
	v_and_b32_e32 v5, 0x7fffff00, v5
	v_and_b32_e32 v9, 0xffffff00, v9
	v_bitop3_b32 v5, v5, s22, v9 bitop3:0xde
	v_ashrrev_i32_e32 v9, 31, v8
	v_and_b32_e32 v9, 0x7fffff00, v9
	v_and_b32_e32 v8, 0xffffff00, v8
	v_bitop3_b32 v8, v9, 51, v8 bitop3:0xde
	v_cndmask_b32_e64 v5, 0, v5, s[4:5]
	v_and_or_b32 v33, v8, v48, v5
	v_and_b32_e32 v8, 0xffffff80, v83
	v_and_b32_e32 v10, 0x7fffffff, v10
	v_xor_b32_e32 v8, v10, v8
	v_ashrrev_i32_e32 v9, 31, v76
	v_mov_b32_e32 v14, v8
	v_and_b32_e32 v5, 0xffffff80, v76
	v_and_b32_e32 v9, 0x7fffffff, v9
	v_pk_add_f32 v[10:11], v[2:3], v[14:15] op_sel:[1,0]
	v_xor_b32_e32 v9, v9, v5
	v_ashrrev_i32_e32 v5, 31, v11
	v_and_b32_e32 v5, 0x7fffff00, v5
	v_and_b32_e32 v11, 0xffffff00, v11
	v_bitop3_b32 v5, v5, s23, v11 bitop3:0xde
	v_ashrrev_i32_e32 v11, 31, v10
	v_and_b32_e32 v11, 0x7fffff00, v11
	v_and_b32_e32 v10, 0xffffff00, v10
	v_cndmask_b32_e64 v5, 0, v5, s[4:5]
	v_bitop3_b32 v10, v11, 64, v10 bitop3:0xde
	v_mov_b32_e32 v12, v8
	v_and_or_b32 v14, v10, v48, v5
	v_pk_add_f32 v[10:11], v[12:13], v[6:7]
	v_min_i32_e32 v13, v69, v70
	v_ashrrev_i32_e32 v5, 31, v11
	v_and_b32_e32 v5, 0x7fffff00, v5
	v_and_b32_e32 v11, 0xffffff00, v11
	v_bitop3_b32 v5, v5, s24, v11 bitop3:0xde
	v_ashrrev_i32_e32 v11, 31, v10
	v_and_b32_e32 v11, 0x7fffff00, v11
	v_and_b32_e32 v10, 0xffffff00, v10
	v_cndmask_b32_e64 v5, 0, v5, s[4:5]
	v_bitop3_b32 v10, v11, s3, v10 bitop3:0xde
	v_and_or_b32 v10, v10, v48, v5
	v_mov_b32_e32 v5, v3
	v_pk_add_f32 v[4:5], v[8:9], v[4:5]
	v_ashrrev_i32_e32 v9, 31, v82
	v_ashrrev_i32_e32 v8, 31, v5
	v_and_b32_e32 v8, 0x7fffff00, v8
	v_and_b32_e32 v5, 0xffffff00, v5
	v_bitop3_b32 v5, v8, s25, v5 bitop3:0xde
	v_ashrrev_i32_e32 v8, 31, v4
	v_and_b32_e32 v8, 0x7fffff00, v8
	v_and_b32_e32 v4, 0xffffff00, v4
	v_bitop3_b32 v4, v8, s8, v4 bitop3:0xde
	v_cndmask_b32_e64 v5, 0, v5, s[4:5]
	v_and_or_b32 v11, v4, v48, v5
	v_ashrrev_i32_e32 v5, 31, v75
	v_and_b32_e32 v4, 0xffffff80, v75
	v_and_b32_e32 v8, 0xffffff80, v82
	v_and_b32_e32 v5, 0x7fffffff, v5
	v_and_b32_e32 v9, 0x7fffffff, v9
	v_xor_b32_e32 v5, v5, v4
	v_xor_b32_e32 v4, v9, v8
	v_pk_add_f32 v[8:9], v[2:3], v[4:5] op_sel:[1,0]
	v_pk_add_f32 v[4:5], v[0:1], v[4:5] op_sel:[1,0] op_sel_hi:[0,1]
	v_ashrrev_i32_e32 v12, 31, v9
	v_and_b32_e32 v12, 0x7fffff00, v12
	v_and_b32_e32 v9, 0xffffff00, v9
	v_bitop3_b32 v9, v12, s26, v9 bitop3:0xde
	v_ashrrev_i32_e32 v12, 31, v8
	v_and_b32_e32 v12, 0x7fffff00, v12
	v_and_b32_e32 v8, 0xffffff00, v8
	v_bitop3_b32 v8, v12, s9, v8 bitop3:0xde
	v_cndmask_b32_e64 v9, 0, v9, s[4:5]
	v_and_or_b32 v8, v8, v48, v9
	v_add_f32_e32 v9, v3, v62
	v_ashrrev_i32_e32 v12, 31, v9
	v_and_b32_e32 v12, 0x7fffff00, v12
	v_and_b32_e32 v9, 0xffffff00, v9
	v_ashrrev_i32_e32 v1, 31, v4
	v_bitop3_b32 v9, v12, s27, v9 bitop3:0xde
	v_and_b32_e32 v1, 0x7fffff00, v1
	v_and_b32_e32 v4, 0xffffff00, v4
	v_bitop3_b32 v1, v1, s10, v4 bitop3:0xde
	v_cndmask_b32_e64 v4, 0, v9, s[4:5]
	v_and_or_b32 v9, v1, v48, v4
	v_mov_b32_e32 v1, v63
	v_pk_add_f32 v[4:5], v[2:3], v[0:1] op_sel:[1,0]
	v_max_i32_e32 v12, v69, v70
	v_ashrrev_i32_e32 v1, 31, v5
	v_and_b32_e32 v1, 0x7fffff00, v1
	v_and_b32_e32 v5, 0xffffff00, v5
	v_bitop3_b32 v1, v1, s35, v5 bitop3:0xde
	v_ashrrev_i32_e32 v5, 31, v4
	v_and_b32_e32 v5, 0x7fffff00, v5
	v_and_b32_e32 v4, 0xffffff00, v4
	v_bitop3_b32 v4, v5, s11, v4 bitop3:0xde
	v_cndmask_b32_e64 v1, 0, v1, s[4:5]
	v_and_or_b32 v4, v4, v48, v1
	v_mov_b32_e32 v1, v64
	v_pk_add_f32 v[0:1], v[0:1], v[6:7]
	v_max_i32_e32 v15, v56, v71
	v_ashrrev_i32_e32 v5, 31, v1
	v_and_b32_e32 v5, 0x7fffff00, v5
	v_and_b32_e32 v1, 0xffffff00, v1
	v_bitop3_b32 v1, v5, s36, v1 bitop3:0xde
	v_ashrrev_i32_e32 v5, 31, v0
	v_and_b32_e32 v5, 0x7fffff00, v5
	v_and_b32_e32 v0, 0xffffff00, v0
	v_bitop3_b32 v0, v5, s12, v0 bitop3:0xde
	v_cndmask_b32_e64 v1, 0, v1, s[4:5]
	v_and_or_b32 v5, v0, v48, v1
	v_pk_add_f32 v[0:1], v[2:3], v[6:7] op_sel_hi:[0,1]
	v_ashrrev_i32_e32 v2, 31, v1
	v_and_b32_e32 v2, 0x7fffff00, v2
	v_and_b32_e32 v1, 0xffffff00, v1
	v_bitop3_b32 v1, v2, s13, v1 bitop3:0xde
	v_ashrrev_i32_e32 v2, 31, v0
	v_and_b32_e32 v2, 0x7fffff00, v2
	v_and_b32_e32 v0, 0xffffff00, v0
	v_bitop3_b32 v0, v2, s16, v0 bitop3:0xde
	v_and_or_b32 v1, v1, v48, v165
	v_and_or_b32 v0, v0, v48, v165
	v_max_i32_e32 v2, v65, v66
	v_min_i32_e32 v3, v65, v66
	v_max_i32_e32 v6, v68, v67
	v_min_i32_e32 v7, v68, v67
; __device__ __forceinline__ float fromsort(int b) { return __int_as_float(b ^ ((b >> 31) & 0x7fffffff)); }
; __device__ __forceinline__ int bsel(int m, int a, int b) { return (a & ~m) | (b & m); }
; template <int OFF>
; __device__ __forceinline__ void sort16_desc(int* a) {
; #pragma unroll
;   for (int ks = 1; ks <= 4; ++ks) {
; #pragma unroll
;     ...
; #pragma unroll
;       for (int i = 0; i < 16; ++i) {
;         const int k = 1 << ks, j = 1 << js;
;         const int l2 = i ^ j;
;         if (l2 > i) { if ((i & k) == 0) cas_desc(a[OFF + i], a[OFF + l2]); else cas_desc(a[OFF + l2], a[OFF + i]); }
;       }
;     }
;   }
; }
; __device__ __forceinline__ void phase_select(const Params& p, int layer, char* smraw) {
;     ...
;     sort16_desc<0>(cand); sort16_desc<16>(cand);
	v_max_i32_e32 v41, v57, v36
	v_min_i32_e32 v36, v57, v36
	v_max_i32_e32 v42, v34, v35
	v_min_i32_e32 v34, v34, v35
	v_max_i32_e32 v35, v37, v38
	v_min_i32_e32 v37, v37, v38
	v_max_i32_e32 v38, v32, v39
	v_min_i32_e32 v32, v32, v39
	v_max_i32_e32 v58, v33, v14
	v_min_i32_e32 v14, v33, v14
	v_max_i32_e32 v33, v11, v10
	v_min_i32_e32 v10, v11, v10
	v_max_i32_e32 v11, v8, v9
	v_min_i32_e32 v8, v8, v9
	v_max_i32_e32 v9, v5, v4
	v_min_i32_e32 v4, v5, v4
	v_max_i32_e32 v5, v1, v0
	v_min_i32_e32 v0, v1, v0
	v_max_i32_e32 v39, v2, v7
	v_min_i32_e32 v2, v2, v7
	v_max_i32_e32 v7, v3, v6
	v_min_i32_e32 v3, v3, v6
	v_max_i32_e32 v6, v40, v12
	v_min_i32_e32 v12, v40, v12
	v_max_i32_e32 v40, v15, v13
	v_min_i32_e32 v13, v15, v13
	v_max_i32_e32 v15, v41, v34
	v_min_i32_e32 v34, v41, v34
	v_max_i32_e32 v41, v36, v42
	v_min_i32_e32 v36, v36, v42
	v_max_i32_e32 v42, v32, v35
	v_min_i32_e32 v32, v32, v35
	v_max_i32_e32 v35, v38, v37
	v_min_i32_e32 v37, v38, v37
	v_max_i32_e32 v1, v58, v10
	v_min_i32_e32 v10, v58, v10
	v_max_i32_e32 v58, v14, v33
	v_min_i32_e32 v14, v14, v33
	v_max_i32_e32 v33, v4, v11
	v_min_i32_e32 v4, v4, v11
	v_max_i32_e32 v11, v9, v8
	v_min_i32_e32 v8, v9, v8
	v_max_i32_e32 v9, v5, v166
	v_min_i32_e32 v5, v5, v166
	v_max_i32_e32 v59, v0, v166
	v_min_i32_e32 v0, v0, v166
	v_max_i32_e32 v38, v39, v7
	v_min_i32_e32 v7, v39, v7
	v_max_i32_e32 v39, v2, v3
	v_min_i32_e32 v2, v2, v3
	v_max_i32_e32 v3, v13, v12
	v_min_i32_e32 v12, v13, v12
	v_max_i32_e32 v13, v40, v6
	v_min_i32_e32 v6, v40, v6
	v_max_i32_e32 v40, v15, v41
	v_min_i32_e32 v15, v15, v41
	v_max_i32_e32 v41, v34, v36
	v_min_i32_e32 v34, v34, v36
	v_max_i32_e32 v36, v37, v32
	v_min_i32_e32 v32, v37, v32
	v_max_i32_e32 v37, v35, v42
	v_min_i32_e32 v35, v35, v42
	v_max_i32_e32 v60, v1, v58
	v_min_i32_e32 v1, v1, v58
	v_max_i32_e32 v58, v10, v14
	v_min_i32_e32 v10, v10, v14
	v_max_i32_e32 v14, v8, v4
	v_min_i32_e32 v4, v8, v4
	v_max_i32_e32 v8, v11, v33
	v_min_i32_e32 v11, v11, v33
	v_max_i32_e32 v33, v9, v59
	v_min_i32_e32 v9, v9, v59
	v_max_i32_e32 v59, v5, v0
	v_min_i32_e32 v0, v5, v0
	v_max_i32_e32 v42, v38, v12
	v_min_i32_e32 v12, v38, v12
	v_max_i32_e32 v38, v7, v3
	v_min_i32_e32 v3, v7, v3
	v_max_i32_e32 v7, v39, v6
	v_min_i32_e32 v6, v39, v6
	v_max_i32_e32 v39, v2, v13
	v_min_i32_e32 v2, v2, v13
	v_max_i32_e32 v13, v32, v40
	v_min_i32_e32 v32, v32, v40
	v_max_i32_e32 v40, v36, v15
	v_min_i32_e32 v15, v36, v15
	v_max_i32_e32 v36, v35, v41
	v_min_i32_e32 v35, v35, v41
	v_max_i32_e32 v41, v37, v34
	v_min_i32_e32 v34, v37, v34
	v_max_i32_e32 v5, v60, v4
	v_min_i32_e32 v4, v60, v4
	v_max_i32_e32 v60, v1, v14
	v_min_i32_e32 v1, v1, v14
	v_max_i32_e32 v14, v58, v11
	v_min_i32_e32 v11, v58, v11
	v_max_i32_e32 v58, v10, v8
	v_min_i32_e32 v8, v10, v8
	v_max_i32_e32 v10, v166, v33
	v_min_i32_e32 v33, v166, v33
	v_max_i32_e32 v61, v166, v9
	v_min_i32_e32 v9, v166, v9
	v_max_i32_e32 v62, v166, v59
	v_min_i32_e32 v59, v166, v59
	v_max_i32_e32 v63, v166, v0
	v_min_i32_e32 v0, v166, v0
	v_max_i32_e32 v37, v42, v7
	v_min_i32_e32 v7, v42, v7
	v_max_i32_e32 v42, v38, v39
	v_min_i32_e32 v38, v38, v39
	v_max_i32_e32 v39, v12, v6
	v_min_i32_e32 v6, v12, v6
	v_max_i32_e32 v12, v3, v2
	v_min_i32_e32 v2, v3, v2
	v_max_i32_e32 v3, v35, v32
	v_min_i32_e32 v32, v35, v32
	v_max_i32_e32 v35, v34, v15
	v_min_i32_e32 v15, v34, v15
	v_max_i32_e32 v34, v36, v13
	v_min_i32_e32 v13, v36, v13
	v_max_i32_e32 v36, v41, v40
	v_min_i32_e32 v40, v41, v40
	v_max_i32_e32 v64, v5, v14
	v_min_i32_e32 v5, v5, v14
	v_max_i32_e32 v14, v60, v58
	v_min_i32_e32 v58, v60, v58
	v_max_i32_e32 v60, v4, v11
	v_min_i32_e32 v4, v4, v11
	v_max_i32_e32 v11, v1, v8
	v_min_i32_e32 v1, v1, v8
	v_max_i32_e32 v8, v59, v33
	v_min_i32_e32 v33, v59, v33
	v_max_i32_e32 v59, v0, v9
	v_min_i32_e32 v0, v0, v9
	v_max_i32_e32 v9, v62, v10
	v_min_i32_e32 v10, v62, v10
	v_max_i32_e32 v62, v63, v61
	v_min_i32_e32 v61, v63, v61
	v_max_i32_e32 v41, v37, v42
	v_min_i32_e32 v37, v37, v42
	v_max_i32_e32 v42, v7, v38
	v_min_i32_e32 v7, v7, v38
	v_max_i32_e32 v38, v39, v12
	v_min_i32_e32 v12, v39, v12
	v_max_i32_e32 v39, v6, v2
	v_min_i32_e32 v2, v6, v2
	v_max_i32_e32 v6, v15, v32
	v_min_i32_e32 v15, v15, v32
	v_max_i32_e32 v32, v35, v3
	v_min_i32_e32 v3, v35, v3
	v_max_i32_e32 v35, v40, v13
	v_min_i32_e32 v13, v40, v13
	v_max_i32_e32 v40, v36, v34
	v_min_i32_e32 v34, v36, v34
	v_max_i32_e32 v63, v64, v14
	v_min_i32_e32 v14, v64, v14
	v_max_i32_e32 v64, v5, v58
	v_min_i32_e32 v5, v5, v58
	v_max_i32_e32 v58, v60, v11
	v_min_i32_e32 v11, v60, v11
	v_max_i32_e32 v60, v4, v1
	v_min_i32_e32 v1, v4, v1
	v_max_i32_e32 v4, v0, v33
	v_min_i32_e32 v0, v0, v33
	v_max_i32_e32 v33, v59, v8
	v_min_i32_e32 v8, v59, v8
	v_max_i32_e32 v59, v61, v10
	v_min_i32_e32 v10, v61, v10
	v_max_i32_e32 v61, v62, v9
	v_min_i32_e32 v9, v62, v9
	v_max_i32_e32 v36, v41, v15
	v_min_i32_e32 v15, v41, v15
	v_max_i32_e32 v41, v37, v6
	v_min_i32_e32 v6, v37, v6
	v_max_i32_e32 v37, v42, v3
	v_min_i32_e32 v3, v42, v3
	v_max_i32_e32 v42, v7, v32
	v_min_i32_e32 v7, v7, v32
	v_max_i32_e32 v32, v38, v13
	v_min_i32_e32 v13, v38, v13
	v_max_i32_e32 v38, v12, v35
	v_min_i32_e32 v12, v12, v35
	v_max_i32_e32 v35, v39, v34
	v_min_i32_e32 v34, v39, v34
	v_max_i32_e32 v39, v2, v40
	v_min_i32_e32 v2, v2, v40
	v_max_i32_e32 v62, v63, v0
	v_min_i32_e32 v0, v63, v0
	v_max_i32_e32 v63, v14, v4
	v_min_i32_e32 v4, v14, v4
	v_max_i32_e32 v14, v64, v8
	v_min_i32_e32 v8, v64, v8
	v_max_i32_e32 v64, v5, v33
	v_min_i32_e32 v5, v5, v33
	v_max_i32_e32 v33, v58, v10
	v_min_i32_e32 v10, v58, v10
	v_max_i32_e32 v58, v11, v59
	v_min_i32_e32 v11, v11, v59
	v_max_i32_e32 v59, v60, v9
	v_min_i32_e32 v9, v60, v9
	v_max_i32_e32 v60, v1, v61
; template <int OFF>
; __device__ __forceinline__ void sort16_desc(int* a) {
;     ...
; }
; template <int OA, int OB>
; __device__ __forceinline__ void merge16(int* a, const int* b) {
; #pragma unroll
;   for (int i = 0; i < 16; ++i) a[OA + i] = max(a[OA + i], b[OB + 15 - i]);
; #pragma unroll
;     ...
; #pragma unroll
;     for (int i = 0; i < 16; ++i) {
;       const int j = 1 << js; const int l2 = i ^ j;
;       if (l2 > i) cas_desc(a[OA + i], a[OA + l2]);
;     }
;   }
; }
; __device__ __forceinline__ void phase_select(const Params& p, int layer, char* smraw) {
;     ...
;     sort16_desc<0>(cand); sort16_desc<16>(cand);
;     merge16<0, 16>(cand, cand);
;     {
;       int other[16];
; #pragma unroll
;       for (int i = 0; i < 16; ++i) other[i] = __shfl_xor(cand[i], 32);
;       merge16<0, 0>(cand, other);
	v_min_i32_e32 v1, v1, v61
	v_max_i32_e32 v40, v36, v32
	v_min_i32_e32 v32, v36, v32
	v_max_i32_e32 v36, v41, v38
	v_min_i32_e32 v38, v41, v38
	v_max_i32_e32 v41, v37, v35
	v_min_i32_e32 v35, v37, v35
	v_max_i32_e32 v37, v42, v39
	v_min_i32_e32 v39, v42, v39
	v_max_i32_e32 v42, v15, v13
	v_min_i32_e32 v13, v15, v13
	v_max_i32_e32 v15, v6, v12
	v_min_i32_e32 v6, v6, v12
	v_max_i32_e32 v12, v3, v34
	v_min_i32_e32 v3, v3, v34
	v_max_i32_e32 v34, v7, v2
	v_min_i32_e32 v2, v7, v2
	v_max_i32_e32 v61, v62, v33
	v_min_i32_e32 v33, v62, v33
	v_max_i32_e32 v62, v63, v58
	v_min_i32_e32 v58, v63, v58
	v_max_i32_e32 v63, v14, v59
	v_min_i32_e32 v14, v14, v59
	v_max_i32_e32 v59, v64, v60
	v_min_i32_e32 v60, v64, v60
	v_max_i32_e32 v64, v0, v10
	v_min_i32_e32 v0, v0, v10
	v_max_i32_e32 v10, v4, v11
	v_min_i32_e32 v4, v4, v11
	v_max_i32_e32 v11, v8, v9
	v_min_i32_e32 v8, v8, v9
	v_max_i32_e32 v9, v5, v1
	v_min_i32_e32 v1, v5, v1
	v_max_i32_e32 v7, v40, v41
	v_min_i32_e32 v40, v40, v41
	v_max_i32_e32 v41, v36, v37
	v_min_i32_e32 v36, v36, v37
	v_max_i32_e32 v37, v32, v35
	v_min_i32_e32 v32, v32, v35
	v_max_i32_e32 v35, v38, v39
	v_min_i32_e32 v38, v38, v39
	v_max_i32_e32 v39, v42, v12
	v_min_i32_e32 v12, v42, v12
	v_max_i32_e32 v42, v15, v34
	v_min_i32_e32 v15, v15, v34
	v_max_i32_e32 v34, v13, v3
	v_min_i32_e32 v3, v13, v3
	v_max_i32_e32 v13, v6, v2
	v_min_i32_e32 v2, v6, v2
	v_max_i32_e32 v5, v61, v63
	v_min_i32_e32 v61, v61, v63
	v_max_i32_e32 v63, v62, v59
	v_min_i32_e32 v59, v62, v59
	v_max_i32_e32 v62, v33, v14
	v_min_i32_e32 v14, v33, v14
	v_max_i32_e32 v33, v58, v60
	v_min_i32_e32 v58, v58, v60
	v_max_i32_e32 v60, v64, v11
	v_min_i32_e32 v11, v64, v11
	v_max_i32_e32 v64, v10, v9
	v_min_i32_e32 v9, v10, v9
	v_max_i32_e32 v10, v0, v8
	v_min_i32_e32 v0, v0, v8
	v_max_i32_e32 v8, v4, v1
	v_min_i32_e32 v1, v4, v1
	v_min_i32_e32 v6, v7, v41
	v_min_i32_e32 v43, v40, v36
	v_min_i32_e32 v44, v37, v35
	v_min_i32_e32 v45, v32, v38
	v_min_i32_e32 v46, v39, v42
	v_min_i32_e32 v47, v12, v15
	v_min_i32_e32 v56, v34, v13
	v_min_i32_e32 v57, v3, v2
	v_min_i32_e32 v4, v5, v63
	v_min_i32_e32 v65, v61, v59
	v_min_i32_e32 v66, v62, v33
	v_min_i32_e32 v67, v14, v58
	v_min_i32_e32 v68, v60, v64
	v_min_i32_e32 v69, v11, v9
	v_min_i32_e32 v70, v10, v8
	v_min_i32_e32 v71, v0, v1
	v_max3_i32 v7, v7, v41, v71
	v_max3_i32 v0, v6, v0, v1
	v_max3_i32 v1, v40, v36, v70
	v_max3_i32 v6, v43, v10, v8
	v_max3_i32 v8, v37, v35, v69
	v_max3_i32 v9, v44, v11, v9
	v_max3_i32 v10, v32, v38, v68
	v_max3_i32 v11, v45, v60, v64
	v_max3_i32 v32, v39, v42, v67
	v_max3_i32 v14, v46, v14, v58
	v_max3_i32 v12, v12, v15, v66
	v_max3_i32 v15, v47, v62, v33
	v_max3_i32 v13, v34, v13, v65
	v_max3_i32 v33, v56, v61, v59
	v_max3_i32 v2, v3, v2, v4
	v_max3_i32 v3, v57, v5, v63
	v_max_i32_e32 v4, v7, v32
	v_min_i32_e32 v5, v7, v32
	v_max_i32_e32 v7, v0, v14
	v_min_i32_e32 v0, v0, v14
	v_max_i32_e32 v14, v1, v12
	v_min_i32_e32 v1, v1, v12
	v_max_i32_e32 v12, v6, v15
	v_min_i32_e32 v6, v6, v15
	v_max_i32_e32 v15, v8, v13
	v_min_i32_e32 v8, v8, v13
	v_max_i32_e32 v13, v9, v33
	v_min_i32_e32 v9, v9, v33
	v_max_i32_e32 v32, v10, v2
	v_min_i32_e32 v2, v10, v2
	v_max_i32_e32 v10, v11, v3
	v_min_i32_e32 v3, v11, v3
	v_max_i32_e32 v11, v4, v15
	v_min_i32_e32 v4, v4, v15
	v_max_i32_e32 v15, v7, v13
	v_min_i32_e32 v7, v7, v13
	v_max_i32_e32 v13, v14, v32
	v_min_i32_e32 v14, v14, v32
	v_max_i32_e32 v32, v12, v10
	v_min_i32_e32 v10, v12, v10
	v_max_i32_e32 v12, v5, v8
	v_min_i32_e32 v5, v5, v8
	v_max_i32_e32 v8, v0, v9
	v_min_i32_e32 v0, v0, v9
	v_max_i32_e32 v9, v1, v2
	v_min_i32_e32 v1, v1, v2
	v_max_i32_e32 v2, v6, v3
	v_min_i32_e32 v3, v6, v3
	v_max_i32_e32 v6, v11, v13
	v_min_i32_e32 v11, v11, v13
	v_max_i32_e32 v13, v15, v32
	v_min_i32_e32 v15, v15, v32
	v_max_i32_e32 v32, v4, v14
	v_min_i32_e32 v4, v4, v14
	v_max_i32_e32 v14, v7, v10
	v_min_i32_e32 v7, v7, v10
	v_max_i32_e32 v10, v12, v9
	v_min_i32_e32 v9, v12, v9
	v_max_i32_e32 v12, v8, v2
	v_min_i32_e32 v2, v8, v2
	v_max_i32_e32 v8, v5, v1
	v_min_i32_e32 v1, v5, v1
	v_max_i32_e32 v5, v0, v3
	v_min_i32_e32 v0, v0, v3
	v_max_i32_e32 v3, v6, v13
	v_min_i32_e32 v6, v6, v13
	v_max_i32_e32 v13, v11, v15
	v_min_i32_e32 v11, v11, v15
	v_max_i32_e32 v15, v32, v14
	v_min_i32_e32 v14, v32, v14
	v_max_i32_e32 v32, v4, v7
	v_min_i32_e32 v4, v4, v7
	v_max_i32_e32 v7, v10, v12
	v_min_i32_e32 v10, v10, v12
	v_max_i32_e32 v12, v9, v2
	v_min_i32_e32 v2, v9, v2
	v_max_i32_e32 v9, v8, v5
	v_min_i32_e32 v5, v8, v5
	v_max_i32_e32 v8, v1, v0
	v_min_i32_e32 v0, v1, v0
	ds_bpermute_b32 v1, v100, v3
	ds_bpermute_b32 v33, v100, v6
	ds_bpermute_b32 v34, v100, v13
	ds_bpermute_b32 v35, v100, v11
	ds_bpermute_b32 v36, v100, v15
	ds_bpermute_b32 v37, v100, v14
	ds_bpermute_b32 v38, v100, v32
	ds_bpermute_b32 v39, v100, v4
	ds_bpermute_b32 v40, v100, v7
	ds_bpermute_b32 v41, v100, v10
	ds_bpermute_b32 v42, v100, v12
	ds_bpermute_b32 v43, v100, v0
	ds_bpermute_b32 v44, v100, v8
	ds_bpermute_b32 v45, v100, v5
	ds_bpermute_b32 v46, v100, v9
	ds_bpermute_b32 v47, v100, v2
	s_waitcnt lgkmcnt(4)
	v_max_i32_e32 v3, v3, v43
	s_waitcnt lgkmcnt(3)
	v_max_i32_e32 v6, v6, v44
	s_waitcnt lgkmcnt(2)
	v_max_i32_e32 v13, v13, v45
	s_waitcnt lgkmcnt(1)
	v_max_i32_e32 v11, v11, v46
	s_waitcnt lgkmcnt(0)
; __device__ __forceinline__ float fromsort(int b) { return __int_as_float(b ^ ((b >> 31) & 0x7fffffff)); }
; __device__ __forceinline__ int bsel(int m, int a, int b) { return (a & ~m) | (b & m); }
; __device__ __forceinline__ void phase_select(const Params& p, int layer, char* smraw) {
;     ...
;       merge16<0, 0>(cand, other);
;     }
;     float g[16]; float gsum = 0.f;
;     const float smax = fromsort(cand[0] & ~255);
; #pragma unroll
;     for (int k = 0; k < 16; ++k) { g[k] = __expf(fromsort(cand[k] & ~255) - smax); gsum += g[k]; }
;     const float ginv = 1.f / gsum;
;     {
;       u32x4 pk;
; #pragma unroll
;       for (int q4 = 0; q4 < 4; ++q4) {
;         unsigned v = 0;
; #pragma unroll
;         for (int m = 0; m < 4; ++m) {
;           int kk = bsel(hmask, lists[q4 * 4 + m], lists[16 + q4 * 4 + m]);
;           v |= (unsigned)(kk & 127) << (8 * m);
;         }
;         pk[q4] = v;
;       }
;       *(u32x4*)(myscr + hf * 16) = pk;
;     }
;     __builtin_amdgcn_fence(__ATOMIC_RELEASE, "wavefront");
;     __builtin_amdgcn_wave_barrier();
;     __builtin_amdgcn_fence(__ATOMIC_ACQUIRE, "wavefront");
;     asm volatile("" ::: "memory");
;     int oi[8]; float ow[8];
; #pragma unroll
;     for (int m = 0; m < 8; ++m) {
;       const int key = bsel(hmask, cand[m], cand[8 + m]);
;       const int i1 = (key >> 4) & 15, j1 = key & 15;
;       const int n1 = myscr[i1], n2 = myscr[16 + j1];
;       oi[m] = n1 * 128 + n2;
;       ow[m] = __int_as_float(bsel(hmask, __float_as_int(g[m]), __float_as_int(g[8 + m]))) * ginv;
;     }
	v_max_i32_e32 v15, v15, v47
	v_max_i32_e32 v14, v14, v42
	v_max_i32_e32 v32, v32, v41
	v_max_i32_e32 v4, v4, v40
	v_max_i32_e32 v7, v7, v39
	v_max_i32_e32 v10, v10, v38
	v_max_i32_e32 v12, v12, v37
	v_max_i32_e32 v2, v2, v36
	v_max_i32_e32 v9, v9, v35
	v_max_i32_e32 v5, v5, v34
	v_max_i32_e32 v8, v8, v33
	v_max_i32_e32 v0, v0, v1
	v_max_i32_e32 v1, v3, v7
	v_min_i32_e32 v3, v3, v7
	v_max_i32_e32 v7, v6, v10
	v_min_i32_e32 v6, v6, v10
	v_max_i32_e32 v10, v13, v12
	v_min_i32_e32 v12, v13, v12
	v_max_i32_e32 v13, v11, v2
	v_min_i32_e32 v2, v11, v2
	v_max_i32_e32 v11, v15, v9
	v_min_i32_e32 v9, v15, v9
	v_max_i32_e32 v15, v14, v5
	v_min_i32_e32 v5, v14, v5
	v_max_i32_e32 v14, v32, v8
	v_min_i32_e32 v8, v32, v8
	v_max_i32_e32 v32, v4, v0
	v_min_i32_e32 v0, v4, v0
	v_max_i32_e32 v4, v1, v11
	v_min_i32_e32 v1, v1, v11
	v_max_i32_e32 v11, v7, v15
	v_min_i32_e32 v7, v7, v15
	v_max_i32_e32 v15, v10, v14
	v_min_i32_e32 v10, v10, v14
	v_max_i32_e32 v14, v13, v32
	v_min_i32_e32 v13, v13, v32
	v_max_i32_e32 v32, v3, v9
	v_min_i32_e32 v3, v3, v9
	v_max_i32_e32 v9, v6, v5
	v_min_i32_e32 v5, v6, v5
	v_max_i32_e32 v6, v12, v8
	v_min_i32_e32 v8, v12, v8
	v_max_i32_e32 v12, v2, v0
	v_min_i32_e32 v0, v2, v0
	v_max_i32_e32 v2, v4, v15
	v_min_i32_e32 v4, v4, v15
	v_max_i32_e32 v15, v11, v14
	v_min_i32_e32 v11, v11, v14
	v_max_i32_e32 v33, v1, v10
	v_min_i32_e32 v1, v1, v10
	v_max_i32_e32 v10, v7, v13
	v_min_i32_e32 v7, v7, v13
	v_max_i32_e32 v34, v32, v6
	v_min_i32_e32 v32, v32, v6
	v_max_i32_e32 v6, v9, v12
	v_min_i32_e32 v35, v9, v12
	v_max_i32_e32 v36, v3, v8
	v_min_i32_e32 v37, v3, v8
	v_max_i32_e32 v3, v5, v0
	v_min_i32_e32 v38, v5, v0
	v_max_i32_e32 v14, v4, v11
	v_min_i32_e32 v13, v4, v11
	v_max_i32_e32 v12, v33, v10
	v_min_i32_e32 v11, v33, v10
	v_max_i32_e32 v10, v1, v7
	v_min_i32_e32 v9, v1, v7
	v_max_i32_e32 v8, v34, v6
	v_min_i32_e32 v7, v34, v6
	v_max_i32_e32 v6, v32, v35
	v_min_i32_e32 v5, v32, v35
	v_cndmask_b32_e64 v32, 0, v87, s[4:5]
	v_and_b32_e32 v31, v31, v48
	v_bitop3_b32 v31, v31, s37, v32 bitop3:0xc8
	v_cndmask_b32_e64 v32, 0, v86, s[4:5]
	v_and_b32_e32 v30, v30, v48
	v_add_lshl_u32 v30, v30, v32, 8
	v_and_or_b32 v30, v30, s38, v31
	v_cndmask_b32_e64 v31, 0, v84, s[4:5]
	v_and_b32_e32 v29, v29, v48
	v_add_lshl_u32 v29, v29, v31, 16
	v_cndmask_b32_e64 v31, 0, v85, s[4:5]
	v_and_b32_e32 v28, v28, v48
	v_add_lshl_u32 v28, v28, v31, 24
	v_and_b32_e32 v29, 0x7f0000, v29
	v_and_b32_e32 v28, 0x7f000000, v28
	v_or3_b32 v28, v30, v29, v28
	v_cndmask_b32_e64 v29, 0, v83, s[4:5]
	v_and_b32_e32 v27, v27, v48
	v_bitop3_b32 v27, v27, s37, v29 bitop3:0xc8
	v_cndmask_b32_e64 v29, 0, v82, s[4:5]
	v_and_b32_e32 v26, v26, v48
	v_add_lshl_u32 v26, v26, v29, 8
	v_and_or_b32 v26, v26, s38, v27
	v_cndmask_b32_e64 v27, 0, v81, s[4:5]
	v_and_b32_e32 v25, v25, v48
	v_add_lshl_u32 v25, v25, v27, 16
	v_cndmask_b32_e64 v27, 0, v80, s[4:5]
	v_and_b32_e32 v24, v24, v48
	v_add_lshl_u32 v24, v24, v27, 24
	v_and_b32_e32 v25, 0x7f0000, v25
	v_and_b32_e32 v24, 0x7f000000, v24
	v_or3_b32 v29, v26, v25, v24
	v_cndmask_b32_e64 v24, 0, v78, s[4:5]
	v_and_b32_e32 v23, v23, v48
	v_bitop3_b32 v23, v23, s37, v24 bitop3:0xc8
	v_cndmask_b32_e64 v24, 0, v79, s[4:5]
	v_and_b32_e32 v22, v22, v48
	v_add_lshl_u32 v22, v22, v24, 8
	v_and_or_b32 v22, v22, s38, v23
	v_cndmask_b32_e64 v23, 0, v77, s[4:5]
	v_and_b32_e32 v21, v21, v48
	v_add_lshl_u32 v21, v21, v23, 16
	v_cndmask_b32_e64 v23, 0, v76, s[4:5]
	v_and_b32_e32 v20, v20, v48
	v_add_lshl_u32 v20, v20, v23, 24
	v_and_b32_e32 v21, 0x7f0000, v21
	v_and_b32_e32 v20, 0x7f000000, v20
	v_or3_b32 v30, v22, v21, v20
	v_cndmask_b32_e64 v20, 0, v75, s[4:5]
	v_and_b32_e32 v19, v19, v48
	v_bitop3_b32 v19, v19, s37, v20 bitop3:0xc8
	v_cndmask_b32_e64 v20, 0, v74, s[4:5]
	v_and_b32_e32 v18, v18, v48
	v_add_lshl_u32 v18, v18, v20, 8
	v_and_or_b32 v18, v18, s38, v19
	v_cndmask_b32_e64 v19, 0, v73, s[4:5]
	v_and_b32_e32 v17, v17, v48
	v_add_lshl_u32 v17, v17, v19, 16
	v_cndmask_b32_e64 v19, 0, v72, s[4:5]
	v_and_b32_e32 v16, v16, v48
	v_add_lshl_u32 v16, v16, v19, 24
	v_max_i32_e32 v0, v2, v15
	v_and_b32_e32 v17, 0x7f0000, v17
	v_and_b32_e32 v16, 0x7f000000, v16
	v_or3_b32 v31, v18, v17, v16
	v_and_b32_e32 v16, v0, v50
	v_and_b32_e32 v17, v8, v48
	v_or_b32_e32 v18, v17, v16
	v_min_i32_e32 v15, v2, v15
	v_bfe_u32 v18, v18, 4, 4
	v_bitop3_b32 v16, v17, 15, v16 bitop3:0xc8
	v_add_u32_e32 v17, v89, v18
	v_and_b32_e32 v18, v15, v50
	v_and_b32_e32 v19, v7, v48
	v_or_b32_e32 v20, v19, v18
	v_bfe_u32 v20, v20, 4, 4
	v_bitop3_b32 v18, v19, 15, v18 bitop3:0xc8
	v_add_u32_e32 v21, v89, v20
	v_and_b32_e32 v19, v14, v50
	v_and_b32_e32 v20, v6, v48
	v_or_b32_e32 v22, v20, v19
	v_bitop3_b32 v19, v20, 15, v19 bitop3:0xc8
	v_bfe_u32 v22, v22, 4, 4
	v_add_u32_e32 v24, v89, v19
	v_and_b32_e32 v19, v13, v50
	v_and_b32_e32 v20, v5, v48
	v_add_u32_e32 v23, v89, v22
	v_or_b32_e32 v22, v20, v19
	v_bfe_u32 v22, v22, 4, 4
	v_bitop3_b32 v19, v20, 15, v19 bitop3:0xc8
	v_max_i32_e32 v4, v36, v3
	ds_write_b128 v169, v[28:31]
	v_add_u32_e32 v16, v89, v16
	v_add_u32_e32 v25, v89, v22
	v_add_u32_e32 v26, v89, v19
	v_add_u32_e32 v18, v89, v18
	ds_read_u8 v19, v17
	ds_read_u8 v20, v16 offset:16
	ds_read_u8 v21, v21
	ds_read_u8 v22, v18 offset:16
	ds_read_u8 v23, v23
	ds_read_u8 v24, v24 offset:16
	ds_read_u8 v25, v25
	ds_read_u8 v26, v26 offset:16
	v_and_b32_e32 v16, v12, v50
	v_and_b32_e32 v17, v4, v48
	v_or_b32_e32 v18, v17, v16
	v_min_i32_e32 v3, v36, v3
	v_bfe_u32 v18, v18, 4, 4
	v_bitop3_b32 v16, v17, 15, v16 bitop3:0xc8
	v_add_u32_e32 v17, v89, v18
	v_and_b32_e32 v18, v11, v50
	v_and_b32_e32 v27, v3, v48
	v_or_b32_e32 v28, v27, v18
	v_max_i32_e32 v2, v37, v38
	v_bfe_u32 v28, v28, 4, 4
	v_bitop3_b32 v18, v27, 15, v18 bitop3:0xc8
	v_add_u32_e32 v29, v89, v28
	v_and_b32_e32 v27, v10, v50
	v_and_b32_e32 v28, v2, v48
	v_min_i32_e32 v1, v37, v38
	v_or_b32_e32 v30, v28, v27
	v_bitop3_b32 v27, v28, 15, v27 bitop3:0xc8
	v_bfe_u32 v30, v30, 4, 4
	v_add_u32_e32 v32, v89, v27
	v_and_b32_e32 v27, v9, v50
	v_and_b32_e32 v28, v1, v48
	v_add_u32_e32 v31, v89, v30
	v_or_b32_e32 v30, v28, v27
	v_add_u32_e32 v16, v89, v16
	v_add_u32_e32 v18, v89, v18
	v_bfe_u32 v30, v30, 4, 4
	v_bitop3_b32 v27, v28, 15, v27 bitop3:0xc8
	v_add_u32_e32 v33, v89, v30
	v_add_u32_e32 v34, v89, v27
	ds_read_u8 v27, v17
	ds_read_u8 v28, v16 offset:16
	ds_read_u8 v29, v29
	ds_read_u8 v30, v18 offset:16
	ds_read_u8 v31, v31
	ds_read_u8 v16, v32 offset:16
	ds_read_u8 v17, v33
	ds_read_u8 v18, v34 offset:16
	s_and_saveexec_b64 s[6:7], vcc
	s_cbranch_execz .LBB0_1225
; __device__ __forceinline__ float fromsort(int b) { return __int_as_float(b ^ ((b >> 31) & 0x7fffffff)); }
; __device__ __forceinline__ int bsel(int m, int a, int b) { return (a & ~m) | (b & m); }
; __device__ __forceinline__ void phase_select(const Params& p, int layer, char* smraw) {
;     ...
;     float g[16]; float gsum = 0.f;
;     const float smax = fromsort(cand[0] & ~255);
; #pragma unroll
;     for (int k = 0; k < 16; ++k) { g[k] = __expf(fromsort(cand[k] & ~255) - smax); gsum += g[k]; }
;     const float ginv = 1.f / gsum;
;     {
;       u32x4 pk;
; #pragma unroll
;       for (int q4 = 0; q4 < 4; ++q4) {
;         unsigned v = 0;
; #pragma unroll
;         for (int m = 0; m < 4; ++m) {
;           int kk = bsel(hmask, lists[q4 * 4 + m], lists[16 + q4 * 4 + m]);
;           v |= (unsigned)(kk & 127) << (8 * m);
;         }
;         pk[q4] = v;
;       }
;       *(u32x4*)(myscr + hf * 16) = pk;
;     }
;     __builtin_amdgcn_fence(__ATOMIC_RELEASE, "wavefront");
;     __builtin_amdgcn_wave_barrier();
;     __builtin_amdgcn_fence(__ATOMIC_ACQUIRE, "wavefront");
;     asm volatile("" ::: "memory");
;     int oi[8]; float ow[8];
; #pragma unroll
;     for (int m = 0; m < 8; ++m) {
;       const int key = bsel(hmask, cand[m], cand[8 + m]);
;       const int i1 = (key >> 4) & 15, j1 = key & 15;
;       const int n1 = myscr[i1], n2 = myscr[16 + j1];
;       oi[m] = n1 * 128 + n2;
;       ow[m] = __int_as_float(bsel(hmask, __float_as_int(g[m]), __float_as_int(g[8 + m]))) * ginv;
;     }
;     asm volatile("" ::: "memory");
;     __builtin_amdgcn_wave_barrier();
;     if (tl < T) {
;       int* di = p.sel_idx + (size_t)t * 128 + hh * 16 + hf * 8;
;       float* dw = p.sel_w + (size_t)t * 128 + hh * 16 + hf * 8;
;       *(u32x4*)di = u32x4{(unsigned)oi[0], (unsigned)oi[1], (unsigned)oi[2], (unsigned)oi[3]};
;       *(u32x4*)(di + 4) = u32x4{(unsigned)oi[4], (unsigned)oi[5], (unsigned)oi[6], (unsigned)oi[7]};
;       *(f32x4*)dw = f32x4{ow[0], ow[1], ow[2], ow[3]};
;       *(f32x4*)(dw + 4) = f32x4{ow[4], ow[5], ow[6], ow[7]};
	v_ashrrev_i32_e32 v34, 31, v15
	v_and_b32_e32 v15, 0xffffff00, v15
	v_bitop3_b32 v15, v34, v15, s20 bitop3:0x6c
	v_ashrrev_i32_e32 v34, 31, v14
	v_and_b32_e32 v14, 0xffffff00, v14
	v_bitop3_b32 v14, v34, v14, s20 bitop3:0x6c
	v_ashrrev_i32_e32 v34, 31, v13
	v_and_b32_e32 v13, 0xffffff00, v13
	v_bitop3_b32 v13, v34, v13, s20 bitop3:0x6c
	v_ashrrev_i32_e32 v34, 31, v12
	v_and_b32_e32 v12, 0xffffff00, v12
	v_bitop3_b32 v12, v34, v12, s20 bitop3:0x6c
	v_ashrrev_i32_e32 v34, 31, v11
	v_and_b32_e32 v11, 0xffffff00, v11
	v_and_b32_e32 v32, 0xffffff00, v0
	v_bitop3_b32 v11, v34, v11, s20 bitop3:0x6c
	v_ashrrev_i32_e32 v34, 31, v10
	v_and_b32_e32 v10, 0xffffff00, v10
	v_ashrrev_i32_e32 v0, 31, v0
	v_bitop3_b32 v10, v34, v10, s20 bitop3:0x6c
	v_ashrrev_i32_e32 v34, 31, v9
	v_and_b32_e32 v9, 0xffffff00, v9
	v_and_b32_e32 v0, 0x7fffffff, v0
	v_bitop3_b32 v9, v34, v9, s20 bitop3:0x6c
	v_ashrrev_i32_e32 v34, 31, v8
	v_and_b32_e32 v8, 0xffffff00, v8
	v_xor_b32_e32 v0, v0, v32
	v_bitop3_b32 v8, v34, v8, s20 bitop3:0x6c
	v_ashrrev_i32_e32 v34, 31, v7
	v_and_b32_e32 v7, 0xffffff00, v7
	v_sub_f32_e32 v32, v0, v0
	v_bitop3_b32 v7, v34, v7, s20 bitop3:0x6c
	v_ashrrev_i32_e32 v34, 31, v6
	v_and_b32_e32 v6, 0xffffff00, v6
	v_mul_f32_e32 v32, 0x3fb8aa3b, v32
	v_sub_f32_e32 v15, v15, v0
	v_bitop3_b32 v6, v34, v6, s20 bitop3:0x6c
	v_ashrrev_i32_e32 v34, 31, v5
	v_and_b32_e32 v5, 0xffffff00, v5
	v_exp_f32_e32 v32, v32
	v_mul_f32_e32 v15, 0x3fb8aa3b, v15
	v_sub_f32_e32 v14, v14, v0
	v_and_b32_e32 v33, 0xffffff00, v1
	v_bitop3_b32 v5, v34, v5, s20 bitop3:0x6c
	v_ashrrev_i32_e32 v34, 31, v4
	v_and_b32_e32 v4, 0xffffff00, v4
	v_ashrrev_i32_e32 v1, 31, v1
	v_exp_f32_e32 v15, v15
	v_mul_f32_e32 v14, 0x3fb8aa3b, v14
	v_sub_f32_e32 v13, v13, v0
	v_bitop3_b32 v4, v34, v4, s20 bitop3:0x6c
	v_ashrrev_i32_e32 v34, 31, v3
	v_and_b32_e32 v3, 0xffffff00, v3
	v_and_b32_e32 v1, 0x7fffffff, v1
	v_exp_f32_e32 v14, v14
	v_mul_f32_e32 v13, 0x3fb8aa3b, v13
	v_sub_f32_e32 v12, v12, v0
	v_bitop3_b32 v3, v34, v3, s20 bitop3:0x6c
	v_ashrrev_i32_e32 v34, 31, v2
	v_and_b32_e32 v2, 0xffffff00, v2
	v_xor_b32_e32 v1, v1, v33
	v_exp_f32_e32 v33, v13
	v_mul_f32_e32 v12, 0x3fb8aa3b, v12
	v_sub_f32_e32 v11, v11, v0
	v_bitop3_b32 v2, v34, v2, s20 bitop3:0x6c
	v_add_f32_e32 v13, 0, v32
	v_exp_f32_e32 v34, v12
	v_mul_f32_e32 v11, 0x3fb8aa3b, v11
	v_sub_f32_e32 v10, v10, v0
	v_add_f32_e32 v13, v15, v13
	v_exp_f32_e32 v35, v11
	v_mul_f32_e32 v10, 0x3fb8aa3b, v10
	v_sub_f32_e32 v9, v9, v0
	v_add_f32_e32 v13, v14, v13
	v_exp_f32_e32 v36, v10
	v_mul_f32_e32 v9, 0x3fb8aa3b, v9
	v_sub_f32_e32 v8, v8, v0
	v_add_f32_e32 v13, v33, v13
	v_exp_f32_e32 v9, v9
	v_mul_f32_e32 v8, 0x3fb8aa3b, v8
	v_sub_f32_e32 v7, v7, v0
	v_add_f32_e32 v10, v34, v13
	v_exp_f32_e32 v37, v8
	v_mul_f32_e32 v7, 0x3fb8aa3b, v7
	v_sub_f32_e32 v6, v6, v0
	v_add_f32_e32 v10, v35, v10
	v_exp_f32_e32 v38, v7
	v_mul_f32_e32 v6, 0x3fb8aa3b, v6
	v_sub_f32_e32 v5, v5, v0
	v_add_f32_e32 v10, v36, v10
	v_exp_f32_e32 v39, v6
	v_mul_f32_e32 v5, 0x3fb8aa3b, v5
	v_sub_f32_e32 v4, v4, v0
	v_add_f32_e32 v10, v9, v10
	v_exp_f32_e32 v40, v5
	v_mul_f32_e32 v4, 0x3fb8aa3b, v4
	v_sub_f32_e32 v3, v3, v0
	v_add_f32_e32 v5, v37, v10
	v_exp_f32_e32 v41, v4
	v_mul_f32_e32 v3, 0x3fb8aa3b, v3
	v_sub_f32_e32 v2, v2, v0
	v_add_f32_e32 v5, v38, v5
	v_exp_f32_e32 v42, v3
	v_mul_f32_e32 v2, 0x3fb8aa3b, v2
	v_sub_f32_e32 v0, v1, v0
	v_add_f32_e32 v5, v39, v5
	v_exp_f32_e32 v43, v2
	v_mul_f32_e32 v0, 0x3fb8aa3b, v0
	v_add_f32_e32 v5, v40, v5
	v_exp_f32_e32 v44, v0
	v_add_f32_e32 v0, v41, v5
	v_add_f32_e32 v0, v42, v0
	v_add_f32_e32 v0, v43, v0
	v_add_f32_e32 v0, v44, v0
	v_div_scale_f32 v1, s[40:41], v0, v0, 1.0
	v_rcp_f32_e32 v2, v1
	v_lshlrev_b64 v[10:11], 9, v[94:95]
	v_lshl_add_u64 v[12:13], s[52:53], 0, v[10:11]
	s_lshl_b32 s0, s39, 6
	v_fma_f32 v6, -v1, v2, 1.0
	v_fmac_f32_e32 v2, v6, v2
	v_div_scale_f32 v6, vcc, 1.0, v0, 1.0
	v_mul_f32_e32 v7, v6, v2
	v_fma_f32 v8, -v1, v7, v6
	v_fmac_f32_e32 v7, v8, v2
	v_fma_f32 v1, -v1, v7, v6
	s_waitcnt lgkmcnt(14)
	v_and_b32_e32 v19, 0xff, v19
	v_and_b32_e32 v20, 0xff, v20
	s_waitcnt lgkmcnt(13)
	v_and_b32_e32 v21, 0xff, v21
	s_waitcnt lgkmcnt(12)
	v_and_b32_e32 v22, 0xff, v22
	s_waitcnt lgkmcnt(11)
	v_and_b32_e32 v23, 0xff, v23
	s_waitcnt lgkmcnt(10)
	v_and_b32_e32 v24, 0xff, v24
	s_waitcnt lgkmcnt(9)
	v_and_b32_e32 v25, 0xff, v25
	s_waitcnt lgkmcnt(8)
	v_and_b32_e32 v26, 0xff, v26
	s_waitcnt lgkmcnt(7)
	v_and_b32_e32 v27, 0xff, v27
	s_waitcnt lgkmcnt(6)
	v_and_b32_e32 v28, 0xff, v28
	s_waitcnt lgkmcnt(5)
	v_and_b32_e32 v29, 0xff, v29
	s_waitcnt lgkmcnt(4)
	v_and_b32_e32 v30, 0xff, v30
	s_waitcnt lgkmcnt(3)
	v_and_b32_e32 v31, 0xff, v31
	s_waitcnt lgkmcnt(2)
	v_and_b32_e32 v4, 0xff, v16
	s_waitcnt lgkmcnt(1)
	v_and_b32_e32 v3, 0xff, v17
	s_waitcnt lgkmcnt(0)
	v_and_b32_e32 v5, 0xff, v18
	v_div_fmas_f32 v1, v1, v2, v7
	v_lshl_add_u64 v[12:13], v[12:13], 0, s[0:1]
	v_lshlrev_b32_e32 v90, 2, v88
	v_div_fixup_f32 v8, v1, v0, 1.0
	v_lshl_add_u32 v3, v3, 7, v5
	v_lshl_add_u32 v2, v31, 7, v4
	v_lshl_add_u32 v1, v29, 7, v30
	v_lshl_add_u32 v0, v27, 7, v28
	v_lshl_add_u32 v7, v25, 7, v26
	v_lshl_add_u32 v6, v23, 7, v24
	v_lshl_add_u32 v5, v21, 7, v22
	v_lshl_add_u32 v4, v19, 7, v20
	v_lshl_add_u64 v[12:13], v[12:13], 0, v[90:91]
	v_lshl_add_u64 v[10:11], s[54:55], 0, v[10:11]
	global_store_dwordx4 v[12:13], v[4:7], off
	global_store_dwordx4 v[12:13], v[0:3], off offset:16
	v_lshl_add_u64 v[10:11], v[10:11], 0, s[0:1]
	v_lshl_add_u64 v[10:11], v[10:11], 0, v[90:91]
	v_and_b32_e32 v2, v54, v14
	v_and_b32_e32 v3, v55, v33
	v_and_b32_e32 v0, v50, v32
	v_and_b32_e32 v1, v53, v15
	v_and_or_b32 v1, v49, v38, v1
	v_and_or_b32 v0, v48, v37, v0
	v_and_or_b32 v3, v51, v40, v3
	v_and_or_b32 v2, v52, v39, v2
	v_pk_mul_f32 v[2:3], v[8:9], v[2:3] op_sel_hi:[0,1]
	v_pk_mul_f32 v[0:1], v[8:9], v[0:1] op_sel_hi:[0,1]
	global_store_dwordx4 v[10:11], v[0:3], off
	s_nop 1
	v_and_b32_e32 v2, v54, v36
	v_and_b32_e32 v3, v55, v9
	v_and_b32_e32 v0, v50, v34
	v_and_b32_e32 v1, v53, v35
	v_and_or_b32 v1, v49, v42, v1
	v_and_or_b32 v0, v48, v41, v0
	v_and_or_b32 v3, v51, v44, v3
	v_and_or_b32 v2, v52, v43, v2
	v_pk_mul_f32 v[2:3], v[8:9], v[2:3] op_sel_hi:[0,1]
	v_pk_mul_f32 v[0:1], v[8:9], v[0:1] op_sel_hi:[0,1]
	global_store_dwordx4 v[10:11], v[0:3], off offset:16
	s_branch .LBB0_1225
